# GEMM K-loops regenerated: in-place accumulators, all LDS/global addresses hoisted, fragment reads software-pipelined across KS, MFMA tail deferred across barriers, counted vmcnt, unconditional stage w
# speedup vs baseline: 1.1001x; 1.0149x over previous
.LBB0_281:
	s_mov_b32 s98, 0
	v_mov_b32_e32 v255, 0x0
	v_bfe_u32 v1, v0, 0, 1
	v_lshlrev_b32_e32 v1, 7, v1
	v_xor_b32_e32 v255, v255, v1
	v_bfe_u32 v1, v0, 1, 3
	v_mul_u32_u24_e32 v1, 0x110, v1
	v_xor_b32_e32 v255, v255, v1
	v_bfe_u32 v1, v0, 4, 2
	v_lshlrev_b32_e32 v1, 4, v1
	v_xor_b32_e32 v255, v255, v1
	v_bfe_u32 v1, v0, 8, 1
	v_lshlrev_b32_e32 v1, 14, v1
	v_xor_b32_e32 v255, v255, v1
	v_mov_b32_e32 v254, 0x10000
	v_bfe_u32 v1, v0, 0, 1
	v_lshlrev_b32_e32 v1, 7, v1
	v_xor_b32_e32 v254, v254, v1
	v_bfe_u32 v1, v0, 1, 3
	v_mul_u32_u24_e32 v1, 0x110, v1
	v_xor_b32_e32 v254, v254, v1
	v_bfe_u32 v1, v0, 4, 2
	v_lshlrev_b32_e32 v1, 4, v1
	v_xor_b32_e32 v254, v254, v1
	v_bfe_u32 v1, v0, 8, 1
	v_lshlrev_b32_e32 v1, 14, v1
	v_xor_b32_e32 v254, v254, v1
	v_mov_b32_e32 v253, 0x880
	v_bfe_u32 v1, v0, 0, 1
	v_lshlrev_b32_e32 v1, 7, v1
	v_xor_b32_e32 v253, v253, v1
	v_bfe_u32 v1, v0, 1, 3
	v_mul_u32_u24_e32 v1, 0x110, v1
	v_xor_b32_e32 v253, v253, v1
	v_bfe_u32 v1, v0, 4, 2
	v_lshlrev_b32_e32 v1, 4, v1
	v_xor_b32_e32 v253, v253, v1
	v_bfe_u32 v1, v0, 8, 1
	v_lshlrev_b32_e32 v1, 14, v1
	v_xor_b32_e32 v253, v253, v1
	v_mov_b32_e32 v252, 0x10880
	v_bfe_u32 v1, v0, 0, 1
	v_lshlrev_b32_e32 v1, 7, v1
	v_xor_b32_e32 v252, v252, v1
	v_bfe_u32 v1, v0, 1, 3
	v_mul_u32_u24_e32 v1, 0x110, v1
	v_xor_b32_e32 v252, v252, v1
	v_bfe_u32 v1, v0, 4, 2
	v_lshlrev_b32_e32 v1, 4, v1
	v_xor_b32_e32 v252, v252, v1
	v_bfe_u32 v1, v0, 8, 1
	v_lshlrev_b32_e32 v1, 14, v1
	v_xor_b32_e32 v252, v252, v1
	v_mov_b32_e32 v251, 0x8000
	v_bfe_u32 v1, v0, 1, 3
	v_lshlrev_b32_e32 v1, 8, v1
	v_add_u32_e32 v251, v251, v1
	v_bfe_u32 v1, v0, 6, 2
	v_mul_u32_u24_e32 v1, 0x1800, v1
	v_add_u32_e32 v251, v251, v1
	v_mov_b32_e32 v2, 0x0
	v_bfe_u32 v1, v0, 0, 1
	v_lshlrev_b32_e32 v1, 7, v1
	v_xor_b32_e32 v2, v2, v1
	v_bfe_u32 v1, v0, 1, 3
	v_lshlrev_b32_e32 v1, 4, v1
	v_xor_b32_e32 v2, v2, v1
	v_bfe_u32 v1, v0, 4, 2
	v_lshlrev_b32_e32 v1, 4, v1
	v_xor_b32_e32 v2, v2, v1
	v_bfe_u32 v1, v0, 6, 1
	v_lshlrev_b32_e32 v1, 7, v1
	v_xor_b32_e32 v2, v2, v1
	v_add_u32_e32 v251, v251, v2
	v_mov_b32_e32 v250, 0x18000
	v_bfe_u32 v1, v0, 1, 3
	v_lshlrev_b32_e32 v1, 8, v1
	v_add_u32_e32 v250, v250, v1
	v_bfe_u32 v1, v0, 6, 2
	v_mul_u32_u24_e32 v1, 0x1800, v1
	v_add_u32_e32 v250, v250, v1
	v_mov_b32_e32 v2, 0x0
	v_bfe_u32 v1, v0, 0, 1
	v_lshlrev_b32_e32 v1, 7, v1
	v_xor_b32_e32 v2, v2, v1
	v_bfe_u32 v1, v0, 1, 3
	v_lshlrev_b32_e32 v1, 4, v1
	v_xor_b32_e32 v2, v2, v1
	v_bfe_u32 v1, v0, 4, 2
	v_lshlrev_b32_e32 v1, 4, v1
	v_xor_b32_e32 v2, v2, v1
	v_bfe_u32 v1, v0, 6, 1
	v_lshlrev_b32_e32 v1, 7, v1
	v_xor_b32_e32 v2, v2, v1
	v_add_u32_e32 v250, v250, v2
	v_mov_b32_e32 v249, 0x8800
	v_bfe_u32 v1, v0, 1, 3
	v_lshlrev_b32_e32 v1, 8, v1
	v_add_u32_e32 v249, v249, v1
	v_bfe_u32 v1, v0, 6, 2
	v_mul_u32_u24_e32 v1, 0x1800, v1
	v_add_u32_e32 v249, v249, v1
	v_mov_b32_e32 v2, 0x80
	v_bfe_u32 v1, v0, 0, 1
	v_lshlrev_b32_e32 v1, 7, v1
	v_xor_b32_e32 v2, v2, v1
	v_bfe_u32 v1, v0, 1, 3
	v_lshlrev_b32_e32 v1, 4, v1
	v_xor_b32_e32 v2, v2, v1
	v_bfe_u32 v1, v0, 4, 2
	v_lshlrev_b32_e32 v1, 4, v1
	v_xor_b32_e32 v2, v2, v1
	v_bfe_u32 v1, v0, 6, 1
	v_lshlrev_b32_e32 v1, 7, v1
	v_xor_b32_e32 v2, v2, v1
	v_add_u32_e32 v249, v249, v2
	v_mov_b32_e32 v248, 0x18800
	v_bfe_u32 v1, v0, 1, 3
	v_lshlrev_b32_e32 v1, 8, v1
	v_add_u32_e32 v248, v248, v1
	v_bfe_u32 v1, v0, 6, 2
	v_mul_u32_u24_e32 v1, 0x1800, v1
	v_add_u32_e32 v248, v248, v1
	v_mov_b32_e32 v2, 0x80
	v_bfe_u32 v1, v0, 0, 1
	v_lshlrev_b32_e32 v1, 7, v1
	v_xor_b32_e32 v2, v2, v1
	v_bfe_u32 v1, v0, 1, 3
	v_lshlrev_b32_e32 v1, 4, v1
	v_xor_b32_e32 v2, v2, v1
	v_bfe_u32 v1, v0, 4, 2
	v_lshlrev_b32_e32 v1, 4, v1
	v_xor_b32_e32 v2, v2, v1
	v_bfe_u32 v1, v0, 6, 1
	v_lshlrev_b32_e32 v1, 7, v1
	v_xor_b32_e32 v2, v2, v1
	v_add_u32_e32 v248, v248, v2
	v_mov_b32_e32 v247, 0x40
	v_bfe_u32 v1, v0, 0, 1
	v_lshlrev_b32_e32 v1, 7, v1
	v_xor_b32_e32 v247, v247, v1
	v_bfe_u32 v1, v0, 1, 3
	v_mul_u32_u24_e32 v1, 0x110, v1
	v_xor_b32_e32 v247, v247, v1
	v_bfe_u32 v1, v0, 4, 2
	v_lshlrev_b32_e32 v1, 4, v1
	v_xor_b32_e32 v247, v247, v1
	v_bfe_u32 v1, v0, 8, 1
	v_lshlrev_b32_e32 v1, 14, v1
	v_xor_b32_e32 v247, v247, v1
	v_mov_b32_e32 v246, 0x10040
	v_bfe_u32 v1, v0, 0, 1
	v_lshlrev_b32_e32 v1, 7, v1
	v_xor_b32_e32 v246, v246, v1
	v_bfe_u32 v1, v0, 1, 3
	v_mul_u32_u24_e32 v1, 0x110, v1
	v_xor_b32_e32 v246, v246, v1
	v_bfe_u32 v1, v0, 4, 2
	v_lshlrev_b32_e32 v1, 4, v1
	v_xor_b32_e32 v246, v246, v1
	v_bfe_u32 v1, v0, 8, 1
	v_lshlrev_b32_e32 v1, 14, v1
	v_xor_b32_e32 v246, v246, v1
	v_mov_b32_e32 v245, 0x8c0
	v_bfe_u32 v1, v0, 0, 1
	v_lshlrev_b32_e32 v1, 7, v1
	v_xor_b32_e32 v245, v245, v1
	v_bfe_u32 v1, v0, 1, 3
	v_mul_u32_u24_e32 v1, 0x110, v1
	v_xor_b32_e32 v245, v245, v1
	v_bfe_u32 v1, v0, 4, 2
	v_lshlrev_b32_e32 v1, 4, v1
	v_xor_b32_e32 v245, v245, v1
	v_bfe_u32 v1, v0, 8, 1
	v_lshlrev_b32_e32 v1, 14, v1
	v_xor_b32_e32 v245, v245, v1
	v_mov_b32_e32 v244, 0x108c0
	v_bfe_u32 v1, v0, 0, 1
	v_lshlrev_b32_e32 v1, 7, v1
	v_xor_b32_e32 v244, v244, v1
	v_bfe_u32 v1, v0, 1, 3
	v_mul_u32_u24_e32 v1, 0x110, v1
	v_xor_b32_e32 v244, v244, v1
	v_bfe_u32 v1, v0, 4, 2
	v_lshlrev_b32_e32 v1, 4, v1
	v_xor_b32_e32 v244, v244, v1
	v_bfe_u32 v1, v0, 8, 1
	v_lshlrev_b32_e32 v1, 14, v1
	v_xor_b32_e32 v244, v244, v1
	v_mov_b32_e32 v243, 0x8000
	v_bfe_u32 v1, v0, 1, 3
	v_lshlrev_b32_e32 v1, 8, v1
	v_add_u32_e32 v243, v243, v1
	v_bfe_u32 v1, v0, 6, 2
	v_mul_u32_u24_e32 v1, 0x1800, v1
	v_add_u32_e32 v243, v243, v1
	v_mov_b32_e32 v2, 0x40
	v_bfe_u32 v1, v0, 0, 1
	v_lshlrev_b32_e32 v1, 7, v1
	v_xor_b32_e32 v2, v2, v1
	v_bfe_u32 v1, v0, 1, 3
	v_lshlrev_b32_e32 v1, 4, v1
	v_xor_b32_e32 v2, v2, v1
	v_bfe_u32 v1, v0, 4, 2
	v_lshlrev_b32_e32 v1, 4, v1
	v_xor_b32_e32 v2, v2, v1
	v_bfe_u32 v1, v0, 6, 1
	v_lshlrev_b32_e32 v1, 7, v1
	v_xor_b32_e32 v2, v2, v1
	v_add_u32_e32 v243, v243, v2
	v_mov_b32_e32 v242, 0x18000
	v_bfe_u32 v1, v0, 1, 3
	v_lshlrev_b32_e32 v1, 8, v1
	v_add_u32_e32 v242, v242, v1
	v_bfe_u32 v1, v0, 6, 2
	v_mul_u32_u24_e32 v1, 0x1800, v1
	v_add_u32_e32 v242, v242, v1
	v_mov_b32_e32 v2, 0x40
	v_bfe_u32 v1, v0, 0, 1
	v_lshlrev_b32_e32 v1, 7, v1
	v_xor_b32_e32 v2, v2, v1
	v_bfe_u32 v1, v0, 1, 3
	v_lshlrev_b32_e32 v1, 4, v1
	v_xor_b32_e32 v2, v2, v1
	v_bfe_u32 v1, v0, 4, 2
	v_lshlrev_b32_e32 v1, 4, v1
	v_xor_b32_e32 v2, v2, v1
	v_bfe_u32 v1, v0, 6, 1
	v_lshlrev_b32_e32 v1, 7, v1
	v_xor_b32_e32 v2, v2, v1
	v_add_u32_e32 v242, v242, v2
	v_mov_b32_e32 v241, 0x8800
	v_bfe_u32 v1, v0, 1, 3
	v_lshlrev_b32_e32 v1, 8, v1
	v_add_u32_e32 v241, v241, v1
	v_bfe_u32 v1, v0, 6, 2
	v_mul_u32_u24_e32 v1, 0x1800, v1
	v_add_u32_e32 v241, v241, v1
	v_mov_b32_e32 v2, 0xc0
	v_bfe_u32 v1, v0, 0, 1
	v_lshlrev_b32_e32 v1, 7, v1
	v_xor_b32_e32 v2, v2, v1
	v_bfe_u32 v1, v0, 1, 3
	v_lshlrev_b32_e32 v1, 4, v1
	v_xor_b32_e32 v2, v2, v1
	v_bfe_u32 v1, v0, 4, 2
	v_lshlrev_b32_e32 v1, 4, v1
	v_xor_b32_e32 v2, v2, v1
	v_bfe_u32 v1, v0, 6, 1
	v_lshlrev_b32_e32 v1, 7, v1
	v_xor_b32_e32 v2, v2, v1
	v_add_u32_e32 v241, v241, v2
	v_mov_b32_e32 v240, 0x18800
	v_bfe_u32 v1, v0, 1, 3
	v_lshlrev_b32_e32 v1, 8, v1
	v_add_u32_e32 v240, v240, v1
	v_bfe_u32 v1, v0, 6, 2
	v_mul_u32_u24_e32 v1, 0x1800, v1
	v_add_u32_e32 v240, v240, v1
	v_mov_b32_e32 v2, 0xc0
	v_bfe_u32 v1, v0, 0, 1
	v_lshlrev_b32_e32 v1, 7, v1
	v_xor_b32_e32 v2, v2, v1
	v_bfe_u32 v1, v0, 1, 3
	v_lshlrev_b32_e32 v1, 4, v1
	v_xor_b32_e32 v2, v2, v1
	v_bfe_u32 v1, v0, 4, 2
	v_lshlrev_b32_e32 v1, 4, v1
	v_xor_b32_e32 v2, v2, v1
	v_bfe_u32 v1, v0, 6, 1
	v_lshlrev_b32_e32 v1, 7, v1
	v_xor_b32_e32 v2, v2, v1
	v_add_u32_e32 v240, v240, v2
	v_mov_b32_e32 v239, 0x0
	v_bfe_u32 v1, v0, 0, 4
	v_lshlrev_b32_e32 v1, 4, v1
	v_xor_b32_e32 v239, v239, v1
	v_bfe_u32 v1, v0, 4, 4
	v_mul_u32_u24_e32 v1, 0x110, v1
	v_xor_b32_e32 v239, v239, v1
	v_bfe_u32 v1, v0, 8, 1
	v_lshlrev_b32_e32 v1, 12, v1
	v_xor_b32_e32 v239, v239, v1
	v_mov_b32_e32 v238, 0x10000
	v_bfe_u32 v1, v0, 0, 4
	v_lshlrev_b32_e32 v1, 4, v1
	v_xor_b32_e32 v238, v238, v1
	v_bfe_u32 v1, v0, 4, 4
	v_mul_u32_u24_e32 v1, 0x110, v1
	v_xor_b32_e32 v238, v238, v1
	v_bfe_u32 v1, v0, 8, 1
	v_lshlrev_b32_e32 v1, 12, v1
	v_xor_b32_e32 v238, v238, v1
	v_mov_b32_e32 v237, 0x0
	v_bfe_u32 v1, v0, 0, 3
	v_lshlrev_b32_e32 v1, 4, v1
	v_add_u32_e32 v237, v237, v1
	v_bfe_u32 v1, v0, 3, 6
	v_lshlrev_b32_e32 v1, 11, v1
	v_add_u32_e32 v237, v237, v1
	v_mov_b32_e32 v236, 0x20000
	v_bfe_u32 v1, v0, 0, 3
	v_lshlrev_b32_e32 v1, 4, v1
	v_add_u32_e32 v236, v236, v1
	v_bfe_u32 v1, v0, 3, 6
	v_lshlrev_b32_e32 v1, 11, v1
	v_add_u32_e32 v236, v236, v1
	v_mov_b32_e32 v235, 0x40000
	v_bfe_u32 v1, v0, 0, 3
	v_lshlrev_b32_e32 v1, 4, v1
	v_add_u32_e32 v235, v235, v1
	v_bfe_u32 v1, v0, 3, 6
	v_lshlrev_b32_e32 v1, 11, v1
	v_add_u32_e32 v235, v235, v1
	v_mov_b32_e32 v234, 0x60000
	v_bfe_u32 v1, v0, 0, 3
	v_lshlrev_b32_e32 v1, 4, v1
	v_add_u32_e32 v234, v234, v1
	v_bfe_u32 v1, v0, 3, 6
	v_lshlrev_b32_e32 v1, 11, v1
	v_add_u32_e32 v234, v234, v1
	v_mov_b32_e32 v1, v0
	s_load_dword s2, s[0:1], 0xe0
	s_mov_b32 s3, s10
	v_mov_b32_e32 v1, v0
	s_waitcnt lgkmcnt(0)
	s_lshr_b32 s11, s2, 3
	v_cvt_f32_u32_e32 v2, s11
	s_mov_b32 s2, s10
	s_ashr_i32 s3, s2, 3
	v_rcp_iflag_f32_e32 v2, v2
	s_ashr_i32 s4, s2, 31
	s_sub_i32 s2, 0, s11
	s_abs_i32 s3, s3
	v_mul_f32_e32 v1, 0x4f7ffffe, v2
	v_cvt_u32_f32_e32 v1, v1
	s_mov_b32 s45, 0
	v_readfirstlane_b32 s5, v1
	s_mul_i32 s2, s2, s5
	s_mul_hi_u32 s2, s5, s2
	s_add_i32 s2, s5, s2
	s_mul_hi_u32 s5, s3, s2
	s_mul_i32 s5, s5, s11
	s_sub_i32 s3, s3, s5
	s_sub_i32 s5, s3, s11
	s_cmp_ge_u32 s3, s11
	s_cselect_b32 s3, s5, s3
	s_sub_i32 s5, s3, s11
	s_cmp_ge_u32 s3, s11
	s_cselect_b32 s3, s5, s3
	s_xor_b32 s3, s3, s4
	s_sub_i32 s24, s3, s4
	s_mov_b32 s3, s10
	s_cmpk_gt_i32 s24, 0x5f
	s_cbranch_scc1 .LBB0_361
	s_load_dwordx2 s[4:5], s[16:17], 0xd0
	s_mov_b32 s3, s10
	v_mov_b32_e32 v54, 0
	v_mov_b32_e32 v1, v0
	s_waitcnt lgkmcnt(0)
	s_add_u32 s25, s4, 0x17f0000
	s_addc_u32 s26, s5, 0
	s_add_u32 s8, s4, 0x37f0000
	s_addc_u32 s9, s5, 0
	s_add_u32 s27, s4, 0x50000
	s_addc_u32 s28, s5, 0
	s_ashr_i32 s4, s24, 31
	s_lshr_b32 s4, s4, 27
	s_add_i32 s4, s24, s4
	s_ashr_i32 s4, s4, 5
	s_lshl_b32 s5, s24, 1
	s_lshl_b32 s12, s4, 6
	s_sub_i32 s5, s5, s12
	s_lshl_b32 s4, s4, 2
	s_and_b32 s12, s24, 3
	s_or_b32 s29, s4, s12
	s_sub_i32 s4, s11, s24
	s_addk_i32 s4, 0x5f
	s_mul_hi_u32 s2, s4, s2
	s_mul_i32 s12, s2, s11
	s_sub_i32 s4, s4, s12
	s_add_i32 s12, s2, 1
	s_sub_i32 s13, s4, s11
	s_cmp_ge_u32 s4, s11
	s_cselect_b32 s2, s12, s2
	s_cselect_b32 s4, s13, s4
	s_add_i32 s12, s2, 1
	s_cmp_ge_u32 s4, s11
	s_cselect_b32 s2, s12, s2
	s_and_b32 s3, s3, 7
	s_and_b32 s4, s5, -8
	s_lshl_b32 s30, s2, 4
	s_mul_i32 s2, s29, 0xc0
	s_or_b32 s31, s3, s4
	s_ashr_i32 s3, s2, 31
	s_lshl_b64 s[2:3], s[2:3], 11
	v_lshlrev_b32_e32 v2, 8, v1
	v_lshlrev_b32_e32 v1, 4, v1
	s_add_u32 s2, s27, s2
	v_and_b32_e32 v1, 0x70, v1
	s_movk_i32 s33, 0xf800
	v_mov_b32_e32 v175, 0
	s_addc_u32 s3, s28, s3
	v_and_or_b32 v174, v2, s33, v1
	s_lshl_b32 s4, s31, 8
	v_lshl_add_u64 v[2:3], s[2:3], 0, v[174:175]
	s_mov_b32 s12, 0x40000
	s_ashr_i32 s5, s4, 31
	v_add_co_u32_e32 v14, vcc, s12, v2
	s_lshl_b64 s[4:5], s[4:5], 11
	s_nop 0
	v_addc_co_u32_e32 v15, vcc, 0, v3, vcc
	s_mov_b32 s34, 0x20000
	s_add_u32 s4, s25, s4
	v_add_co_u32_e32 v16, vcc, s34, v2
	s_addc_u32 s5, s26, s5
	s_nop 0
	v_addc_co_u32_e32 v17, vcc, 0, v3, vcc
	global_load_dwordx4 v[2:5], v[14:15], off
	global_load_dwordx4 v[6:9], v[16:17], off
	global_load_dwordx4 v[10:13], v174, s[2:3]
	v_lshl_add_u64 v[14:15], s[4:5], 0, v[174:175]
	s_mov_b32 s13, 0x60000
	v_add_co_u32_e32 v30, vcc, s13, v14
	v_mov_b32_e32 v1, v0
	s_nop 0
	v_addc_co_u32_e32 v31, vcc, 0, v15, vcc
	v_add_co_u32_e32 v32, vcc, s12, v14
	s_movk_i32 s36, 0xf0
	s_nop 0
	v_addc_co_u32_e32 v33, vcc, 0, v15, vcc
	v_add_co_u32_e32 v34, vcc, s34, v14
	s_mov_b32 s35, 2
	s_nop 0
	v_addc_co_u32_e32 v35, vcc, 0, v15, vcc
	global_load_dwordx4 v[14:17], v174, s[4:5]
	global_load_dwordx4 v[18:21], v[34:35], off
	global_load_dwordx4 v[22:25], v[32:33], off
	global_load_dwordx4 v[26:29], v[30:31], off
	v_mov_b32_e32 v30, v0
	v_ashrrev_i32_e32 v31, 4, v1
	v_xor_b32_e32 v1, v31, v1
	v_lshlrev_b32_e32 v31, 8, v31
	v_lshlrev_b32_e32 v1, 4, v1
	v_and_or_b32 v1, v1, s36, v31
	s_movk_i32 s37, 0xff80
	s_mov_b32 s38, 0x10000
	s_mov_b32 s39, 0x18000
	s_movk_i32 s40, 0x8a0
	s_movk_i32 s41, 0x1140
	v_mov_b32_e32 v176, 0x18000
	s_mov_b32 s22, 2
	s_mov_b32 s42, s24
	s_mov_b32 s43, s29
	s_mov_b32 s44, s31
	v_mov_b32_e32 v55, v54
	v_mov_b32_e32 v56, v54
	v_mov_b32_e32 v57, v54
	v_mov_b32_e32 v82, v54
	v_mov_b32_e32 v83, v54
	v_mov_b32_e32 v84, v54
	v_mov_b32_e32 v85, v54
	v_mov_b32_e32 v86, v54
	v_mov_b32_e32 v87, v54
	v_mov_b32_e32 v88, v54
	v_mov_b32_e32 v89, v54
	v_mov_b32_e32 v90, v54
	v_mov_b32_e32 v91, v54
	v_mov_b32_e32 v92, v54
	v_mov_b32_e32 v93, v54
	v_mov_b32_e32 v94, v54
	v_mov_b32_e32 v95, v54
	v_mov_b32_e32 v96, v54
	v_mov_b32_e32 v97, v54
	s_waitcnt vmcnt(4)
	ds_write_b128 v1, v[10:13] offset:32768
	ds_write_b128 v1, v[6:9] offset:40960
	ds_write_b128 v1, v[2:5] offset:49152
	s_waitcnt vmcnt(3)
	ds_write_b128 v1, v[14:17]
	s_waitcnt vmcnt(2)
	ds_write_b128 v1, v[18:21] offset:8192
	s_waitcnt vmcnt(1)
	ds_write_b128 v1, v[22:25] offset:16384
	s_waitcnt vmcnt(0)
	ds_write_b128 v1, v[26:29] offset:24576
	v_mov_b32_e32 v98, v54
	v_lshlrev_b32_e32 v2, 4, v30
	v_lshlrev_b32_e32 v1, 8, v30
	v_and_b32_e32 v2, 0x70, v2
	v_and_or_b32 v174, v1, s33, v2
	v_lshl_add_u64 v[2:3], s[2:3], 0, v[174:175]
	v_add_co_u32_e32 v10, vcc, s12, v2
	v_mov_b32_e32 v1, 0x10000
	s_nop 0
	v_addc_co_u32_e32 v11, vcc, 0, v3, vcc
	v_add_co_u32_e32 v12, vcc, s34, v2
	v_mov_b32_e32 v99, v54
	s_nop 0
	v_addc_co_u32_e32 v13, vcc, 0, v3, vcc
	global_load_dwordx4 v[2:5], v[10:11], off offset:128
	global_load_dwordx4 v[6:9], v[12:13], off offset:128
	v_lshl_add_u64 v[10:11], s[4:5], 0, v[174:175]
	v_add_co_u32_e32 v12, vcc, s13, v10
	v_mov_b32_e32 v100, v54
	s_nop 0
	v_addc_co_u32_e32 v13, vcc, 0, v11, vcc
	v_add_co_u32_e32 v22, vcc, s12, v10
	v_mov_b32_e32 v101, v54
	s_nop 0
	v_addc_co_u32_e32 v23, vcc, 0, v11, vcc
	v_add_co_u32_e32 v30, vcc, s34, v10
	global_load_dwordx4 v[14:17], v[12:13], off offset:128
	global_load_dwordx4 v[18:21], v[22:23], off offset:128
	v_addc_co_u32_e32 v31, vcc, 0, v11, vcc
	global_load_dwordx4 v[10:13], v174, s[2:3] offset:128
	global_load_dwordx4 v[22:25], v[30:31], off offset:128
	global_load_dwordx4 v[26:29], v174, s[4:5] offset:128
	v_mov_b32_e32 v102, v54
	v_mov_b32_e32 v103, v54
	v_mov_b32_e32 v104, v54
	v_mov_b32_e32 v105, v54
	v_mov_b32_e32 v106, v54
	v_mov_b32_e32 v107, v54
	v_mov_b32_e32 v108, v54
	v_mov_b32_e32 v109, v54
	v_mov_b32_e32 v110, v54
	v_mov_b32_e32 v111, v54
	v_mov_b32_e32 v112, v54
	v_mov_b32_e32 v113, v54
	v_mov_b32_e32 v114, v54
	v_mov_b32_e32 v115, v54
	v_mov_b32_e32 v116, v54
	v_mov_b32_e32 v117, v54
	v_mov_b32_e32 v118, v54
	v_mov_b32_e32 v119, v54
	v_mov_b32_e32 v120, v54
	v_mov_b32_e32 v121, v54
	v_mov_b32_e32 v122, v54
	v_mov_b32_e32 v123, v54
	v_mov_b32_e32 v124, v54
	v_mov_b32_e32 v125, v54
	v_mov_b32_e32 v78, v54
	v_mov_b32_e32 v79, v54
	v_mov_b32_e32 v80, v54
	v_mov_b32_e32 v81, v54
	v_mov_b32_e32 v74, v54
	v_mov_b32_e32 v75, v54
	v_mov_b32_e32 v76, v54
	v_mov_b32_e32 v77, v54
	v_mov_b32_e32 v70, v54
	v_mov_b32_e32 v71, v54
	v_mov_b32_e32 v72, v54
	v_mov_b32_e32 v73, v54
	v_mov_b32_e32 v66, v54
	v_mov_b32_e32 v67, v54
	v_mov_b32_e32 v68, v54
	v_mov_b32_e32 v69, v54
	v_mov_b32_e32 v62, v54
	v_mov_b32_e32 v63, v54
	v_mov_b32_e32 v64, v54
	v_mov_b32_e32 v65, v54
	v_mov_b32_e32 v58, v54
	v_mov_b32_e32 v59, v54
	v_mov_b32_e32 v60, v54
	v_mov_b32_e32 v61, v54
	v_mov_b32_e32 v50, v54
	v_mov_b32_e32 v51, v54
	v_mov_b32_e32 v52, v54
	v_mov_b32_e32 v53, v54
	v_mov_b32_e32 v46, v54
	v_mov_b32_e32 v47, v54
	v_mov_b32_e32 v48, v54
	v_mov_b32_e32 v49, v54
	v_mov_b32_e32 v42, v54
	v_mov_b32_e32 v43, v54
	v_mov_b32_e32 v44, v54
	v_mov_b32_e32 v45, v54
	v_mov_b32_e32 v38, v54
	v_mov_b32_e32 v39, v54
	v_mov_b32_e32 v40, v54
	v_mov_b32_e32 v41, v54
	v_mov_b32_e32 v34, v54
	v_mov_b32_e32 v35, v54
	v_mov_b32_e32 v36, v54
	v_mov_b32_e32 v37, v54
	v_mov_b32_e32 v30, v54
	v_mov_b32_e32 v31, v54
	v_mov_b32_e32 v32, v54
	v_mov_b32_e32 v33, v54
	s_waitcnt lgkmcnt(0)
	s_barrier
	s_waitcnt vmcnt(0)
	s_branch .LBB0_285

.LBB0_285:
	ds_read_b128 v[142:145], v251
	ds_read_b128 v[146:149], v249
	ds_read_b128 v[150:153], v251 offset:4096
	ds_read_b128 v[126:129], v255
	ds_read_b128 v[130:133], v253
	s_cmp_eq_u32 s98, 0
	s_cbranch_scc1 .Lnodef_B0_0
	v_mfma_f32_16x16x32_bf16 v[50:53], v[154:157], v[134:137], v[50:53]
	v_mfma_f32_16x16x32_bf16 v[46:49], v[158:161], v[134:137], v[46:49]
	v_mfma_f32_16x16x32_bf16 v[42:45], v[162:165], v[134:137], v[42:45]
	v_mfma_f32_16x16x32_bf16 v[38:41], v[154:157], v[138:141], v[38:41]
	v_mfma_f32_16x16x32_bf16 v[34:37], v[158:161], v[138:141], v[34:37]
	v_mfma_f32_16x16x32_bf16 v[30:33], v[162:165], v[138:141], v[30:33]
.Lnodef_B0_0:
	ds_read_b128 v[134:137], v255 offset:4096
	ds_read_b128 v[138:141], v253 offset:4096
	s_add_i32 s2, s35, -1
	s_cmp_lt_i32 s2, s30
	s_cselect_b64 s[14:15], -1, 0
	s_cmp_ge_i32 s2, s30
	s_waitcnt lgkmcnt(3)
	v_mfma_f32_16x16x32_bf16 v[122:125], v[142:145], v[126:129], v[122:125]
	v_mfma_f32_16x16x32_bf16 v[118:121], v[146:149], v[126:129], v[118:121]
	v_mfma_f32_16x16x32_bf16 v[114:117], v[150:153], v[126:129], v[114:117]
	ds_read_b128 v[126:129], v255 offset:8192
	s_waitcnt lgkmcnt(3)
	v_mfma_f32_16x16x32_bf16 v[110:113], v[142:145], v[130:133], v[110:113]
	v_mfma_f32_16x16x32_bf16 v[106:109], v[146:149], v[130:133], v[106:109]
	v_mfma_f32_16x16x32_bf16 v[102:105], v[150:153], v[130:133], v[102:105]
	ds_read_b128 v[130:133], v253 offset:8192
	s_waitcnt lgkmcnt(3)
	v_mfma_f32_16x16x32_bf16 v[98:101], v[142:145], v[134:137], v[98:101]
	v_mfma_f32_16x16x32_bf16 v[94:97], v[146:149], v[134:137], v[94:97]
	v_mfma_f32_16x16x32_bf16 v[90:93], v[150:153], v[134:137], v[90:93]
	s_waitcnt vmcnt(5)
	ds_write_b128 v238, v[26:29]
	ds_write_b128 v238, v[22:25] offset:8192
.LBB0_287:
	s_lshl_b32 s2, s44, 8
	s_ashr_i32 s3, s2, 31
	s_lshl_b64 s[4:5], s[2:3], 11
	s_lshl_b32 s2, s22, 6
	s_ashr_i32 s3, s2, 31
	s_add_u32 s20, s25, s4
	s_addc_u32 s21, s26, s5
	s_lshl_b64 s[12:13], s[2:3], 1
	s_add_u32 s20, s20, s12
	s_addc_u32 s21, s21, s13
	global_load_dwordx4 v[22:25], v237, s[20:21]
	global_load_dwordx4 v[26:29], v236, s[20:21]
	s_andn2_b64 vcc, exec, s[14:15]
	ds_read_b128 v[134:137], v255 offset:12288
	s_waitcnt lgkmcnt(5)
	v_mfma_f32_16x16x32_bf16 v[86:89], v[142:145], v[138:141], v[86:89]
	v_mfma_f32_16x16x32_bf16 v[82:85], v[146:149], v[138:141], v[82:85]
	v_mfma_f32_16x16x32_bf16 v[54:57], v[150:153], v[138:141], v[54:57]
	ds_read_b128 v[138:141], v253 offset:12288
	s_waitcnt lgkmcnt(5)
	v_mfma_f32_16x16x32_bf16 v[78:81], v[142:145], v[126:129], v[78:81]
	v_mfma_f32_16x16x32_bf16 v[74:77], v[146:149], v[126:129], v[74:77]
	v_mfma_f32_16x16x32_bf16 v[70:73], v[150:153], v[126:129], v[70:73]
	s_waitcnt lgkmcnt(4)
	v_mfma_f32_16x16x32_bf16 v[66:69], v[142:145], v[130:133], v[66:69]
	v_mfma_f32_16x16x32_bf16 v[62:65], v[146:149], v[130:133], v[62:65]
	v_mfma_f32_16x16x32_bf16 v[58:61], v[150:153], v[130:133], v[58:61]
	s_waitcnt vmcnt(5)
	ds_write_b128 v238, v[18:21] offset:16384
	ds_write_b128 v238, v[14:17] offset:24576
.LBB0_289:
	global_load_dwordx4 v[14:17], v235, s[20:21]
	global_load_dwordx4 v[18:21], v234, s[20:21]
	s_and_b64 vcc, exec, s[2:3]
	ds_read_b128 v[154:157], v243
	ds_read_b128 v[158:161], v241
	ds_read_b128 v[162:165], v243 offset:4096
	ds_read_b128 v[126:129], v247
	ds_read_b128 v[130:133], v245
	s_waitcnt lgkmcnt(8)
	v_mfma_f32_16x16x32_bf16 v[50:53], v[142:145], v[134:137], v[50:53]
	v_mfma_f32_16x16x32_bf16 v[46:49], v[146:149], v[134:137], v[46:49]
	v_mfma_f32_16x16x32_bf16 v[42:45], v[150:153], v[134:137], v[42:45]
	ds_read_b128 v[134:137], v247 offset:4096
	s_waitcnt lgkmcnt(8)
	v_mfma_f32_16x16x32_bf16 v[38:41], v[142:145], v[138:141], v[38:41]
	v_mfma_f32_16x16x32_bf16 v[34:37], v[146:149], v[138:141], v[34:37]
	v_mfma_f32_16x16x32_bf16 v[30:33], v[150:153], v[138:141], v[30:33]
	s_waitcnt vmcnt(5)
	ds_write_b128 v238, v[10:13] offset:32768
	ds_write_b128 v238, v[6:9] offset:40960
.LBB0_291:
	s_mul_i32 s14, s43, 0xc0
	s_ashr_i32 s15, s14, 31
	s_lshl_b64 s[14:15], s[14:15], 11
	s_add_u32 s20, s27, s14
	s_addc_u32 s21, s28, s15
	s_add_u32 s12, s20, s12
	s_addc_u32 s13, s21, s13
	global_load_dwordx4 v[6:9], v237, s[12:13]
	global_load_dwordx4 v[10:13], v236, s[12:13]
	s_and_b64 vcc, exec, s[2:3]
	ds_read_b128 v[138:141], v245 offset:4096
	s_waitcnt lgkmcnt(5)
	v_mfma_f32_16x16x32_bf16 v[122:125], v[154:157], v[126:129], v[122:125]
	v_mfma_f32_16x16x32_bf16 v[118:121], v[158:161], v[126:129], v[118:121]
	v_mfma_f32_16x16x32_bf16 v[114:117], v[162:165], v[126:129], v[114:117]
	ds_read_b128 v[126:129], v247 offset:8192
	s_waitcnt lgkmcnt(5)
	v_mfma_f32_16x16x32_bf16 v[110:113], v[154:157], v[130:133], v[110:113]
	v_mfma_f32_16x16x32_bf16 v[106:109], v[158:161], v[130:133], v[106:109]
	v_mfma_f32_16x16x32_bf16 v[102:105], v[162:165], v[130:133], v[102:105]
	ds_read_b128 v[130:133], v245 offset:8192
	s_waitcnt lgkmcnt(5)
	v_mfma_f32_16x16x32_bf16 v[98:101], v[154:157], v[134:137], v[98:101]
	v_mfma_f32_16x16x32_bf16 v[94:97], v[158:161], v[134:137], v[94:97]
	v_mfma_f32_16x16x32_bf16 v[90:93], v[162:165], v[134:137], v[90:93]
	s_waitcnt vmcnt(6)
	ds_write_b128 v238, v[2:5] offset:49152
.LBB0_293:
	global_load_dwordx4 v[2:5], v235, s[12:13]
	ds_read_b128 v[134:137], v247 offset:12288
	s_waitcnt lgkmcnt(4)
	v_mfma_f32_16x16x32_bf16 v[86:89], v[154:157], v[138:141], v[86:89]
	v_mfma_f32_16x16x32_bf16 v[82:85], v[158:161], v[138:141], v[82:85]
	v_mfma_f32_16x16x32_bf16 v[54:57], v[162:165], v[138:141], v[54:57]
	ds_read_b128 v[138:141], v245 offset:12288
	s_waitcnt lgkmcnt(4)
	v_mfma_f32_16x16x32_bf16 v[78:81], v[154:157], v[126:129], v[78:81]
	v_mfma_f32_16x16x32_bf16 v[74:77], v[158:161], v[126:129], v[74:77]
	v_mfma_f32_16x16x32_bf16 v[70:73], v[162:165], v[126:129], v[70:73]
	s_waitcnt lgkmcnt(3)
	v_mfma_f32_16x16x32_bf16 v[66:69], v[154:157], v[130:133], v[66:69]
	v_mfma_f32_16x16x32_bf16 v[62:65], v[158:161], v[130:133], v[62:65]
	v_mfma_f32_16x16x32_bf16 v[58:61], v[162:165], v[130:133], v[58:61]
	s_add_i32 s46, s22, 1
	s_cmp_lg_u32 s46, 16
	s_cbranch_scc1 .LBB0_297
	s_add_i32 s24, s24, s11
	s_cmpk_gt_i32 s24, 0x5f
	s_cbranch_scc1 .LBB0_296
	s_ashr_i32 s3, s24, 31
	s_lshr_b32 s3, s3, 27
	s_add_i32 s3, s24, s3
	s_ashr_i32 s3, s3, 5
	s_mov_b32 s2, s10
	s_lshl_b32 s4, s3, 6
	s_lshl_b32 s5, s24, 1
	s_sub_i32 s4, s5, s4
	s_and_b32 s2, s2, 7
	s_and_b32 s4, s4, -8
	s_or_b32 s44, s2, s4
	s_lshl_b32 s3, s3, 2
	s_and_b32 s5, s24, 3
	s_lshl_b32 s2, s44, 8
	s_or_b32 s43, s3, s5
	s_ashr_i32 s3, s2, 31
	s_lshl_b64 s[4:5], s[2:3], 11
	s_mul_i32 s2, s43, 0xc0
	s_ashr_i32 s3, s2, 31
	s_lshl_b64 s[14:15], s[2:3], 11

.LBB0_297:
	s_waitcnt lgkmcnt(0)
	s_barrier
	ds_read_b128 v[142:145], v250
	ds_read_b128 v[146:149], v248
	ds_read_b128 v[150:153], v250 offset:4096
	ds_read_b128 v[126:129], v254
	ds_read_b128 v[130:133], v252
	v_mfma_f32_16x16x32_bf16 v[50:53], v[154:157], v[134:137], v[50:53]
	v_mfma_f32_16x16x32_bf16 v[46:49], v[158:161], v[134:137], v[46:49]
	v_mfma_f32_16x16x32_bf16 v[42:45], v[162:165], v[134:137], v[42:45]
	v_mfma_f32_16x16x32_bf16 v[38:41], v[154:157], v[138:141], v[38:41]
	v_mfma_f32_16x16x32_bf16 v[34:37], v[158:161], v[138:141], v[34:37]
	v_mfma_f32_16x16x32_bf16 v[30:33], v[162:165], v[138:141], v[30:33]
	ds_read_b128 v[134:137], v254 offset:4096
	ds_read_b128 v[138:141], v252 offset:4096
	s_cmp_lt_i32 s35, s30
	s_cselect_b64 s[20:21], -1, 0
	s_cmp_ge_i32 s35, s30
	s_cselect_b64 s[12:13], -1, 0
	s_and_b64 vcc, exec, s[12:13]
	s_waitcnt lgkmcnt(3)
	v_mfma_f32_16x16x32_bf16 v[122:125], v[142:145], v[126:129], v[122:125]
	v_mfma_f32_16x16x32_bf16 v[118:121], v[146:149], v[126:129], v[118:121]
	v_mfma_f32_16x16x32_bf16 v[114:117], v[150:153], v[126:129], v[114:117]
	ds_read_b128 v[126:129], v254 offset:8192
	s_waitcnt lgkmcnt(3)
	v_mfma_f32_16x16x32_bf16 v[110:113], v[142:145], v[130:133], v[110:113]
	v_mfma_f32_16x16x32_bf16 v[106:109], v[146:149], v[130:133], v[106:109]
	v_mfma_f32_16x16x32_bf16 v[102:105], v[150:153], v[130:133], v[102:105]
	ds_read_b128 v[130:133], v252 offset:8192
	s_waitcnt lgkmcnt(3)
	v_mfma_f32_16x16x32_bf16 v[98:101], v[142:145], v[134:137], v[98:101]
	v_mfma_f32_16x16x32_bf16 v[94:97], v[146:149], v[134:137], v[94:97]
	v_mfma_f32_16x16x32_bf16 v[90:93], v[150:153], v[134:137], v[90:93]
	s_waitcnt vmcnt(5)
	ds_write_b128 v239, v[22:25]
	ds_write_b128 v239, v[26:29] offset:8192
.LBB0_299:
	s_lshl_b32 s2, s46, 6
	s_ashr_i32 s3, s2, 31
	s_add_u32 s22, s25, s4
	s_addc_u32 s23, s26, s5
	s_lshl_b64 s[4:5], s[2:3], 1
	s_add_u32 s22, s22, s4
	s_addc_u32 s23, s23, s5
	global_load_dwordx4 v[26:29], v237, s[22:23]
	global_load_dwordx4 v[22:25], v236, s[22:23]
	s_andn2_b64 vcc, exec, s[20:21]
	ds_read_b128 v[134:137], v254 offset:12288
	s_waitcnt lgkmcnt(5)
	v_mfma_f32_16x16x32_bf16 v[86:89], v[142:145], v[138:141], v[86:89]
	v_mfma_f32_16x16x32_bf16 v[82:85], v[146:149], v[138:141], v[82:85]
	v_mfma_f32_16x16x32_bf16 v[54:57], v[150:153], v[138:141], v[54:57]
	ds_read_b128 v[138:141], v252 offset:12288
	s_waitcnt lgkmcnt(5)
	v_mfma_f32_16x16x32_bf16 v[78:81], v[142:145], v[126:129], v[78:81]
	v_mfma_f32_16x16x32_bf16 v[74:77], v[146:149], v[126:129], v[74:77]
	v_mfma_f32_16x16x32_bf16 v[70:73], v[150:153], v[126:129], v[70:73]
	s_waitcnt lgkmcnt(4)
	v_mfma_f32_16x16x32_bf16 v[66:69], v[142:145], v[130:133], v[66:69]
	v_mfma_f32_16x16x32_bf16 v[62:65], v[146:149], v[130:133], v[62:65]
	v_mfma_f32_16x16x32_bf16 v[58:61], v[150:153], v[130:133], v[58:61]
	s_waitcnt vmcnt(5)
	ds_write_b128 v239, v[14:17] offset:16384
	ds_write_b128 v239, v[18:21] offset:24576
.LBB0_301:
	global_load_dwordx4 v[18:21], v235, s[22:23]
	global_load_dwordx4 v[14:17], v234, s[22:23]
	s_and_b64 vcc, exec, s[2:3]
	ds_read_b128 v[154:157], v242
	ds_read_b128 v[158:161], v240
	ds_read_b128 v[162:165], v242 offset:4096
	ds_read_b128 v[126:129], v246
	ds_read_b128 v[130:133], v244
	s_waitcnt lgkmcnt(8)
	v_mfma_f32_16x16x32_bf16 v[50:53], v[142:145], v[134:137], v[50:53]
	v_mfma_f32_16x16x32_bf16 v[46:49], v[146:149], v[134:137], v[46:49]
	v_mfma_f32_16x16x32_bf16 v[42:45], v[150:153], v[134:137], v[42:45]
	ds_read_b128 v[134:137], v246 offset:4096
	s_waitcnt lgkmcnt(8)
	v_mfma_f32_16x16x32_bf16 v[38:41], v[142:145], v[138:141], v[38:41]
	v_mfma_f32_16x16x32_bf16 v[34:37], v[146:149], v[138:141], v[34:37]
	v_mfma_f32_16x16x32_bf16 v[30:33], v[150:153], v[138:141], v[30:33]
	s_waitcnt vmcnt(5)
	ds_write_b128 v239, v[6:9] offset:32768
	ds_write_b128 v239, v[10:13] offset:40960
.LBB0_303:
	s_add_u32 s14, s27, s14
	s_addc_u32 s15, s28, s15
	s_add_u32 s4, s14, s4
	s_addc_u32 s5, s15, s5
	global_load_dwordx4 v[10:13], v237, s[4:5]
	global_load_dwordx4 v[6:9], v236, s[4:5]
	s_and_b64 vcc, exec, s[2:3]
	ds_read_b128 v[138:141], v244 offset:4096
	s_waitcnt lgkmcnt(5)
	v_mfma_f32_16x16x32_bf16 v[122:125], v[154:157], v[126:129], v[122:125]
	v_mfma_f32_16x16x32_bf16 v[118:121], v[158:161], v[126:129], v[118:121]
	v_mfma_f32_16x16x32_bf16 v[114:117], v[162:165], v[126:129], v[114:117]
	ds_read_b128 v[126:129], v246 offset:8192
	s_waitcnt lgkmcnt(5)
	v_mfma_f32_16x16x32_bf16 v[110:113], v[154:157], v[130:133], v[110:113]
	v_mfma_f32_16x16x32_bf16 v[106:109], v[158:161], v[130:133], v[106:109]
	v_mfma_f32_16x16x32_bf16 v[102:105], v[162:165], v[130:133], v[102:105]
	ds_read_b128 v[130:133], v244 offset:8192
	s_waitcnt lgkmcnt(5)
	v_mfma_f32_16x16x32_bf16 v[98:101], v[154:157], v[134:137], v[98:101]
	v_mfma_f32_16x16x32_bf16 v[94:97], v[158:161], v[134:137], v[94:97]
	v_mfma_f32_16x16x32_bf16 v[90:93], v[162:165], v[134:137], v[90:93]
	s_waitcnt vmcnt(6)
	ds_write_b128 v239, v[2:5] offset:49152
.LBB0_305:
	global_load_dwordx4 v[2:5], v235, s[4:5]
	ds_read_b128 v[134:137], v246 offset:12288
	s_waitcnt lgkmcnt(4)
	v_mfma_f32_16x16x32_bf16 v[86:89], v[154:157], v[138:141], v[86:89]
	v_mfma_f32_16x16x32_bf16 v[82:85], v[158:161], v[138:141], v[82:85]
	v_mfma_f32_16x16x32_bf16 v[54:57], v[162:165], v[138:141], v[54:57]
	ds_read_b128 v[138:141], v244 offset:12288
	s_waitcnt lgkmcnt(4)
	v_mfma_f32_16x16x32_bf16 v[78:81], v[154:157], v[126:129], v[78:81]
	v_mfma_f32_16x16x32_bf16 v[74:77], v[158:161], v[126:129], v[74:77]
	v_mfma_f32_16x16x32_bf16 v[70:73], v[162:165], v[126:129], v[70:73]
	s_waitcnt lgkmcnt(3)
	v_mfma_f32_16x16x32_bf16 v[66:69], v[154:157], v[130:133], v[66:69]
	v_mfma_f32_16x16x32_bf16 v[62:65], v[158:161], v[130:133], v[62:65]
	v_mfma_f32_16x16x32_bf16 v[58:61], v[162:165], v[130:133], v[58:61]
	s_add_i32 s22, s46, 1
	s_cmp_lg_u32 s22, 16
	s_cbranch_scc1 .LBB0_309
	s_add_i32 s24, s24, s11
	s_cmpk_gt_i32 s24, 0x5f
	s_cbranch_scc1 .LBB0_308
	s_ashr_i32 s3, s24, 31
	s_lshr_b32 s3, s3, 27
	s_add_i32 s3, s24, s3
	s_ashr_i32 s3, s3, 5
	s_mov_b32 s2, s10
	s_lshl_b32 s4, s3, 6
	s_lshl_b32 s5, s24, 1
	s_sub_i32 s4, s5, s4
	s_and_b32 s2, s2, 7
	s_and_b32 s4, s4, -8
	s_lshl_b32 s3, s3, 2
	s_and_b32 s5, s24, 3
	s_or_b32 s43, s3, s5
	s_or_b32 s44, s2, s4

.LBB0_309:
	s_add_i32 s45, s45, 2
	s_cmp_lg_u32 s45, 16
	s_waitcnt lgkmcnt(0)
	s_mov_b32 s98, 1
	s_cbranch_scc1 .LBB0_284
	s_mov_b32 s98, 0
	v_mfma_f32_16x16x32_bf16 v[50:53], v[154:157], v[134:137], v[50:53]
	v_mfma_f32_16x16x32_bf16 v[46:49], v[158:161], v[134:137], v[46:49]
	v_mfma_f32_16x16x32_bf16 v[42:45], v[162:165], v[134:137], v[42:45]
	v_mfma_f32_16x16x32_bf16 v[38:41], v[154:157], v[138:141], v[38:41]
	v_mfma_f32_16x16x32_bf16 v[34:37], v[158:161], v[138:141], v[34:37]
	v_mfma_f32_16x16x32_bf16 v[30:33], v[162:165], v[138:141], v[30:33]
	s_nop 7
	s_nop 7
	v_mov_b32_e32 v127, v0
	s_mul_i32 s2, s29, 0xc0
	s_nop 0
	v_lshrrev_b32_e32 v128, 2, v127
	v_bfe_u32 v126, v127, 6, 2
	v_and_or_b32 v128, v128, 12, s2
	v_mad_u32_u24 v126, v126, 48, v128
	v_ashrrev_i32_e32 v128, 1, v127
	v_and_b32_e32 v128, 0xffffff80, v128
	v_lshl_add_u32 v128, s31, 8, v128
	v_and_or_b32 v128, v127, 15, v128
	v_cmp_gt_i32_e32 vcc, s40, v126
	v_ashrrev_i32_e32 v127, 31, v126
	s_and_saveexec_b64 s[2:3], vcc
	s_cbranch_execz .LBB0_312
	v_cvt_pk_bf16_f32 v122, v122, v123
	v_cvt_pk_bf16_f32 v123, v124, v125
	v_mov_b64_e32 v[124:125], s[8:9]
	v_mad_i64_i32 v[124:125], s[4:5], v128, s41, v[124:125]
	v_lshl_add_u64 v[124:125], v[126:127], 1, v[124:125]
	global_store_dwordx2 v[124:125], v[122:123], off

.LBB0_956:
	s_mov_b32 s98, 0
	v_mov_b32_e32 v255, 0x0
	v_bfe_u32 v1, v0, 0, 1
	v_lshlrev_b32_e32 v1, 7, v1
	v_xor_b32_e32 v255, v255, v1
	v_bfe_u32 v1, v0, 1, 3
	v_mul_u32_u24_e32 v1, 0x110, v1
	v_xor_b32_e32 v255, v255, v1
	v_bfe_u32 v1, v0, 4, 2
	v_lshlrev_b32_e32 v1, 4, v1
	v_xor_b32_e32 v255, v255, v1
	v_bfe_u32 v1, v0, 8, 1
	v_lshlrev_b32_e32 v1, 14, v1
	v_xor_b32_e32 v255, v255, v1
	v_mov_b32_e32 v254, 0x10000
	v_bfe_u32 v1, v0, 0, 1
	v_lshlrev_b32_e32 v1, 7, v1
	v_xor_b32_e32 v254, v254, v1
	v_bfe_u32 v1, v0, 1, 3
	v_mul_u32_u24_e32 v1, 0x110, v1
	v_xor_b32_e32 v254, v254, v1
	v_bfe_u32 v1, v0, 4, 2
	v_lshlrev_b32_e32 v1, 4, v1
	v_xor_b32_e32 v254, v254, v1
	v_bfe_u32 v1, v0, 8, 1
	v_lshlrev_b32_e32 v1, 14, v1
	v_xor_b32_e32 v254, v254, v1
	v_mov_b32_e32 v253, 0x880
	v_bfe_u32 v1, v0, 0, 1
	v_lshlrev_b32_e32 v1, 7, v1
	v_xor_b32_e32 v253, v253, v1
	v_bfe_u32 v1, v0, 1, 3
	v_mul_u32_u24_e32 v1, 0x110, v1
	v_xor_b32_e32 v253, v253, v1
	v_bfe_u32 v1, v0, 4, 2
	v_lshlrev_b32_e32 v1, 4, v1
	v_xor_b32_e32 v253, v253, v1
	v_bfe_u32 v1, v0, 8, 1
	v_lshlrev_b32_e32 v1, 14, v1
	v_xor_b32_e32 v253, v253, v1
	v_mov_b32_e32 v252, 0x10880
	v_bfe_u32 v1, v0, 0, 1
	v_lshlrev_b32_e32 v1, 7, v1
	v_xor_b32_e32 v252, v252, v1
	v_bfe_u32 v1, v0, 1, 3
	v_mul_u32_u24_e32 v1, 0x110, v1
	v_xor_b32_e32 v252, v252, v1
	v_bfe_u32 v1, v0, 4, 2
	v_lshlrev_b32_e32 v1, 4, v1
	v_xor_b32_e32 v252, v252, v1
	v_bfe_u32 v1, v0, 8, 1
	v_lshlrev_b32_e32 v1, 14, v1
	v_xor_b32_e32 v252, v252, v1
	v_mov_b32_e32 v251, 0x8000
	v_bfe_u32 v1, v0, 0, 1
	v_lshlrev_b32_e32 v1, 7, v1
	v_xor_b32_e32 v251, v251, v1
	v_bfe_u32 v1, v0, 1, 3
	v_mul_u32_u24_e32 v1, 0x110, v1
	v_xor_b32_e32 v251, v251, v1
	v_bfe_u32 v1, v0, 4, 2
	v_lshlrev_b32_e32 v1, 4, v1
	v_xor_b32_e32 v251, v251, v1
	v_bfe_u32 v1, v0, 6, 2
	v_lshlrev_b32_e32 v1, 13, v1
	v_xor_b32_e32 v251, v251, v1
	v_mov_b32_e32 v250, 0x18000
	v_bfe_u32 v1, v0, 0, 1
	v_lshlrev_b32_e32 v1, 7, v1
	v_xor_b32_e32 v250, v250, v1
	v_bfe_u32 v1, v0, 1, 3
	v_mul_u32_u24_e32 v1, 0x110, v1
	v_xor_b32_e32 v250, v250, v1
	v_bfe_u32 v1, v0, 4, 2
	v_lshlrev_b32_e32 v1, 4, v1
	v_xor_b32_e32 v250, v250, v1
	v_bfe_u32 v1, v0, 6, 2
	v_lshlrev_b32_e32 v1, 13, v1
	v_xor_b32_e32 v250, v250, v1
	v_mov_b32_e32 v249, 0x8880
	v_bfe_u32 v1, v0, 0, 1
	v_lshlrev_b32_e32 v1, 7, v1
	v_xor_b32_e32 v249, v249, v1
	v_bfe_u32 v1, v0, 1, 3
	v_mul_u32_u24_e32 v1, 0x110, v1
	v_xor_b32_e32 v249, v249, v1
	v_bfe_u32 v1, v0, 4, 2
	v_lshlrev_b32_e32 v1, 4, v1
	v_xor_b32_e32 v249, v249, v1
	v_bfe_u32 v1, v0, 6, 2
	v_lshlrev_b32_e32 v1, 13, v1
	v_xor_b32_e32 v249, v249, v1
	v_mov_b32_e32 v248, 0x18880
	v_bfe_u32 v1, v0, 0, 1
	v_lshlrev_b32_e32 v1, 7, v1
	v_xor_b32_e32 v248, v248, v1
	v_bfe_u32 v1, v0, 1, 3
	v_mul_u32_u24_e32 v1, 0x110, v1
	v_xor_b32_e32 v248, v248, v1
	v_bfe_u32 v1, v0, 4, 2
	v_lshlrev_b32_e32 v1, 4, v1
	v_xor_b32_e32 v248, v248, v1
	v_bfe_u32 v1, v0, 6, 2
	v_lshlrev_b32_e32 v1, 13, v1
	v_xor_b32_e32 v248, v248, v1
	v_mov_b32_e32 v247, 0x40
	v_bfe_u32 v1, v0, 0, 1
	v_lshlrev_b32_e32 v1, 7, v1
	v_xor_b32_e32 v247, v247, v1
	v_bfe_u32 v1, v0, 1, 3
	v_mul_u32_u24_e32 v1, 0x110, v1
	v_xor_b32_e32 v247, v247, v1
	v_bfe_u32 v1, v0, 4, 2
	v_lshlrev_b32_e32 v1, 4, v1
	v_xor_b32_e32 v247, v247, v1
	v_bfe_u32 v1, v0, 8, 1
	v_lshlrev_b32_e32 v1, 14, v1
	v_xor_b32_e32 v247, v247, v1
	v_mov_b32_e32 v246, 0x10040
	v_bfe_u32 v1, v0, 0, 1
	v_lshlrev_b32_e32 v1, 7, v1
	v_xor_b32_e32 v246, v246, v1
	v_bfe_u32 v1, v0, 1, 3
	v_mul_u32_u24_e32 v1, 0x110, v1
	v_xor_b32_e32 v246, v246, v1
	v_bfe_u32 v1, v0, 4, 2
	v_lshlrev_b32_e32 v1, 4, v1
	v_xor_b32_e32 v246, v246, v1
	v_bfe_u32 v1, v0, 8, 1
	v_lshlrev_b32_e32 v1, 14, v1
	v_xor_b32_e32 v246, v246, v1
	v_mov_b32_e32 v245, 0x8c0
	v_bfe_u32 v1, v0, 0, 1
	v_lshlrev_b32_e32 v1, 7, v1
	v_xor_b32_e32 v245, v245, v1
	v_bfe_u32 v1, v0, 1, 3
	v_mul_u32_u24_e32 v1, 0x110, v1
	v_xor_b32_e32 v245, v245, v1
	v_bfe_u32 v1, v0, 4, 2
	v_lshlrev_b32_e32 v1, 4, v1
	v_xor_b32_e32 v245, v245, v1
	v_bfe_u32 v1, v0, 8, 1
	v_lshlrev_b32_e32 v1, 14, v1
	v_xor_b32_e32 v245, v245, v1
	v_mov_b32_e32 v244, 0x108c0
	v_bfe_u32 v1, v0, 0, 1
	v_lshlrev_b32_e32 v1, 7, v1
	v_xor_b32_e32 v244, v244, v1
	v_bfe_u32 v1, v0, 1, 3
	v_mul_u32_u24_e32 v1, 0x110, v1
	v_xor_b32_e32 v244, v244, v1
	v_bfe_u32 v1, v0, 4, 2
	v_lshlrev_b32_e32 v1, 4, v1
	v_xor_b32_e32 v244, v244, v1
	v_bfe_u32 v1, v0, 8, 1
	v_lshlrev_b32_e32 v1, 14, v1
	v_xor_b32_e32 v244, v244, v1
	v_mov_b32_e32 v243, 0x8040
	v_bfe_u32 v1, v0, 0, 1
	v_lshlrev_b32_e32 v1, 7, v1
	v_xor_b32_e32 v243, v243, v1
	v_bfe_u32 v1, v0, 1, 3
	v_mul_u32_u24_e32 v1, 0x110, v1
	v_xor_b32_e32 v243, v243, v1
	v_bfe_u32 v1, v0, 4, 2
	v_lshlrev_b32_e32 v1, 4, v1
	v_xor_b32_e32 v243, v243, v1
	v_bfe_u32 v1, v0, 6, 2
	v_lshlrev_b32_e32 v1, 13, v1
	v_xor_b32_e32 v243, v243, v1
	v_mov_b32_e32 v242, 0x18040
	v_bfe_u32 v1, v0, 0, 1
	v_lshlrev_b32_e32 v1, 7, v1
	v_xor_b32_e32 v242, v242, v1
	v_bfe_u32 v1, v0, 1, 3
	v_mul_u32_u24_e32 v1, 0x110, v1
	v_xor_b32_e32 v242, v242, v1
	v_bfe_u32 v1, v0, 4, 2
	v_lshlrev_b32_e32 v1, 4, v1
	v_xor_b32_e32 v242, v242, v1
	v_bfe_u32 v1, v0, 6, 2
	v_lshlrev_b32_e32 v1, 13, v1
	v_xor_b32_e32 v242, v242, v1
	v_mov_b32_e32 v241, 0x88c0
	v_bfe_u32 v1, v0, 0, 1
	v_lshlrev_b32_e32 v1, 7, v1
	v_xor_b32_e32 v241, v241, v1
	v_bfe_u32 v1, v0, 1, 3
	v_mul_u32_u24_e32 v1, 0x110, v1
	v_xor_b32_e32 v241, v241, v1
	v_bfe_u32 v1, v0, 4, 2
	v_lshlrev_b32_e32 v1, 4, v1
	v_xor_b32_e32 v241, v241, v1
	v_bfe_u32 v1, v0, 6, 2
	v_lshlrev_b32_e32 v1, 13, v1
	v_xor_b32_e32 v241, v241, v1
	v_mov_b32_e32 v237, 0x188c0
	v_bfe_u32 v1, v0, 0, 1
	v_lshlrev_b32_e32 v1, 7, v1
	v_xor_b32_e32 v237, v237, v1
	v_bfe_u32 v1, v0, 1, 3
	v_mul_u32_u24_e32 v1, 0x110, v1
	v_xor_b32_e32 v237, v237, v1
	v_bfe_u32 v1, v0, 4, 2
	v_lshlrev_b32_e32 v1, 4, v1
	v_xor_b32_e32 v237, v237, v1
	v_bfe_u32 v1, v0, 6, 2
	v_lshlrev_b32_e32 v1, 13, v1
	v_xor_b32_e32 v237, v237, v1
	v_mov_b32_e32 v236, 0x0
	v_bfe_u32 v1, v0, 0, 4
	v_lshlrev_b32_e32 v1, 4, v1
	v_xor_b32_e32 v236, v236, v1
	v_bfe_u32 v1, v0, 4, 4
	v_mul_u32_u24_e32 v1, 0x110, v1
	v_xor_b32_e32 v236, v236, v1
	v_bfe_u32 v1, v0, 8, 1
	v_lshlrev_b32_e32 v1, 12, v1
	v_xor_b32_e32 v236, v236, v1
	v_mov_b32_e32 v235, 0x10000
	v_bfe_u32 v1, v0, 0, 4
	v_lshlrev_b32_e32 v1, 4, v1
	v_xor_b32_e32 v235, v235, v1
	v_bfe_u32 v1, v0, 4, 4
	v_mul_u32_u24_e32 v1, 0x110, v1
	v_xor_b32_e32 v235, v235, v1
	v_bfe_u32 v1, v0, 8, 1
	v_lshlrev_b32_e32 v1, 12, v1
	v_xor_b32_e32 v235, v235, v1
	v_mov_b32_e32 v234, 0x0
	v_bfe_u32 v1, v0, 0, 3
	v_lshlrev_b32_e32 v1, 4, v1
	v_add_u32_e32 v234, v234, v1
	v_bfe_u32 v1, v0, 3, 6
	v_lshlrev_b32_e32 v1, 11, v1
	v_add_u32_e32 v234, v234, v1
	v_mov_b32_e32 v233, 0x20000
	v_bfe_u32 v1, v0, 0, 3
	v_lshlrev_b32_e32 v1, 4, v1
	v_add_u32_e32 v233, v233, v1
	v_bfe_u32 v1, v0, 3, 6
	v_lshlrev_b32_e32 v1, 11, v1
	v_add_u32_e32 v233, v233, v1
	v_mov_b32_e32 v232, 0x40000
	v_bfe_u32 v1, v0, 0, 3
	v_lshlrev_b32_e32 v1, 4, v1
	v_add_u32_e32 v232, v232, v1
	v_bfe_u32 v1, v0, 3, 6
	v_lshlrev_b32_e32 v1, 11, v1
	v_add_u32_e32 v232, v232, v1
	v_mov_b32_e32 v231, 0x60000
	v_bfe_u32 v1, v0, 0, 3
	v_lshlrev_b32_e32 v1, 4, v1
	v_add_u32_e32 v231, v231, v1
	v_bfe_u32 v1, v0, 3, 6
	v_lshlrev_b32_e32 v1, 11, v1
	v_add_u32_e32 v231, v231, v1
	v_mov_b32_e32 v1, v0
	s_load_dword s2, s[0:1], 0xe0
	s_mov_b32 s3, s10
	v_mov_b32_e32 v1, v0
	s_waitcnt lgkmcnt(0)
	s_lshr_b32 s11, s2, 3
	s_waitcnt vmcnt(0)
	v_cvt_f32_u32_e32 v2, s11
	s_mov_b32 s2, s10
	s_ashr_i32 s3, s2, 3
	v_rcp_iflag_f32_e32 v2, v2
	s_ashr_i32 s4, s2, 31
	s_sub_i32 s2, 0, s11
	s_abs_i32 s3, s3
	v_mul_f32_e32 v1, 0x4f7ffffe, v2
	v_cvt_u32_f32_e32 v1, v1
	s_mov_b32 s52, 0
	v_readfirstlane_b32 s5, v1
	s_mul_i32 s2, s2, s5
	s_mul_hi_u32 s2, s5, s2
	s_add_i32 s2, s5, s2
	s_mul_hi_u32 s5, s3, s2
	s_mul_i32 s5, s5, s11
	s_sub_i32 s3, s3, s5
	s_sub_i32 s5, s3, s11
	s_cmp_ge_u32 s3, s11
	s_cselect_b32 s3, s5, s3
	s_sub_i32 s5, s3, s11
	s_cmp_ge_u32 s3, s11
	s_cselect_b32 s3, s5, s3
	s_xor_b32 s3, s3, s4
	s_sub_i32 s30, s3, s4
	s_mov_b32 s3, s10
	s_cmp_gt_i32 s30, 31
	s_cbranch_scc1 .LBB0_1020
	s_load_dwordx4 s[4:7], s[16:17], 0xc8
	s_load_dwordx4 s[12:15], s[16:17], 0x0
	s_mov_b32 s3, s10
	v_mov_b32_e32 v82, 0
	s_waitcnt lgkmcnt(0)
	s_add_u32 s31, s6, 0x17f0000
	s_addc_u32 s33, s7, 0
	s_add_u32 s20, s6, 0x6000
	s_addc_u32 s21, s7, 0
	s_add_u32 s34, s6, 0x570000
	s_addc_u32 s35, s7, 0
	s_ashr_i32 s6, s30, 31
	s_lshr_b32 s6, s6, 27
	s_add_i32 s6, s30, s6
	s_ashr_i32 s6, s6, 5
	s_lshl_b32 s7, s6, 6
	s_lshl_b32 s22, s30, 1
	s_sub_i32 s7, s22, s7
	s_lshl_b32 s6, s6, 2
	s_and_b32 s22, s30, 3
	s_or_b32 s36, s6, s22
	s_sub_i32 s6, s11, s30
	s_add_i32 s6, s6, 31
	s_mul_hi_u32 s2, s6, s2
	s_mul_i32 s22, s2, s11
	s_sub_i32 s6, s6, s22
	s_add_i32 s22, s2, 1
	s_sub_i32 s23, s6, s11
	s_cmp_ge_u32 s6, s11
	s_cselect_b32 s2, s22, s2
	s_cselect_b32 s6, s23, s6
	s_add_i32 s22, s2, 1
	s_cmp_ge_u32 s6, s11
	s_cselect_b32 s2, s22, s2
	s_and_b32 s3, s3, 7
	s_and_b32 s6, s7, -8
	s_lshl_b32 s37, s2, 4
	v_mov_b32_e32 v1, v0
	s_lshl_b32 s2, s36, 8
	s_or_b32 s38, s3, s6
	s_ashr_i32 s3, s2, 31
	s_lshl_b64 s[2:3], s[2:3], 11
	v_lshlrev_b32_e32 v2, 8, v1
	v_lshlrev_b32_e32 v1, 4, v1
	s_add_u32 s2, s34, s2
	v_and_b32_e32 v1, 0x70, v1
	s_movk_i32 s39, 0xf800
	v_mov_b32_e32 v239, 0
	s_addc_u32 s3, s35, s3
	v_and_or_b32 v238, v2, s39, v1
	v_lshl_add_u64 v[10:11], s[2:3], 0, v[238:239]
	s_mov_b32 s40, 0x60000
	v_add_co_u32_e32 v12, vcc, s40, v10
	s_lshl_b32 s6, s38, 8
	s_nop 0
	v_addc_co_u32_e32 v13, vcc, 0, v11, vcc
	s_mov_b32 s22, 0x40000
	s_ashr_i32 s7, s6, 31
	v_add_co_u32_e32 v14, vcc, s22, v10
	s_lshl_b64 s[6:7], s[6:7], 11
	s_nop 0
	v_addc_co_u32_e32 v15, vcc, 0, v11, vcc
	s_mov_b32 s41, 0x20000
	s_add_u32 s6, s31, s6
	v_add_co_u32_e32 v18, vcc, s41, v10
	s_addc_u32 s7, s33, s7
	s_nop 0
	v_addc_co_u32_e32 v19, vcc, 0, v11, vcc
	v_lshl_add_u64 v[30:31], s[6:7], 0, v[238:239]
	v_add_co_u32_e32 v32, vcc, s22, v30
	global_load_dwordx4 v[2:5], v[12:13], off
	global_load_dwordx4 v[6:9], v[14:15], off
	v_addc_co_u32_e32 v33, vcc, 0, v31, vcc
	v_add_co_u32_e32 v34, vcc, s41, v30
	global_load_dwordx4 v[10:13], v[18:19], off
	global_load_dwordx4 v[14:17], v238, s[2:3]
	v_addc_co_u32_e32 v35, vcc, 0, v31, vcc
	global_load_dwordx4 v[18:21], v[32:33], off
	global_load_dwordx4 v[22:25], v[34:35], off
	global_load_dwordx4 v[26:29], v238, s[6:7]
	v_add_co_u32_e32 v30, vcc, s40, v30
	v_mov_b32_e32 v1, v0
	s_nop 0
	v_addc_co_u32_e32 v31, vcc, 0, v31, vcc
	global_load_dwordx4 v[30:33], v[30:31], off
	s_movk_i32 s43, 0xf0
	v_ashrrev_i32_e32 v35, 4, v1
	v_xor_b32_e32 v1, v35, v1
	v_lshlrev_b32_e32 v35, 8, v35
	v_lshlrev_b32_e32 v1, 4, v1
	v_mov_b32_e32 v34, v0
	v_and_or_b32 v1, v1, s43, v35
	s_mov_b32 s42, 2
	s_movk_i32 s44, 0xff80
	s_mov_b32 s45, 0x10000
	s_mov_b32 s46, 0x11000
	s_movk_i32 s47, 0x1800
	s_movk_i32 s48, 0x1fff
	v_mov_b32_e32 v240, 0x8040
	s_mov_b32 s28, 2
	s_mov_b32 s49, s30
	s_mov_b32 s50, s36
	s_mov_b32 s51, s38
	v_mov_b32_e32 v83, v82
	v_mov_b32_e32 v84, v82
	v_mov_b32_e32 v85, v82
	v_mov_b32_e32 v102, v82
	v_mov_b32_e32 v103, v82
	v_mov_b32_e32 v104, v82
	v_mov_b32_e32 v105, v82
	v_mov_b32_e32 v106, v82
	v_mov_b32_e32 v107, v82
	v_mov_b32_e32 v108, v82
	v_mov_b32_e32 v109, v82
	v_mov_b32_e32 v110, v82
	s_waitcnt vmcnt(4)
	ds_write_b128 v1, v[14:17] offset:32768
	ds_write_b128 v1, v[10:13] offset:40960
	ds_write_b128 v1, v[6:9] offset:49152
	ds_write_b128 v1, v[2:5] offset:57344
	s_waitcnt vmcnt(1)
	ds_write_b128 v1, v[26:29]
	ds_write_b128 v1, v[22:25] offset:8192
	ds_write_b128 v1, v[18:21] offset:16384
	s_waitcnt vmcnt(0)
	ds_write_b128 v1, v[30:33] offset:24576
	v_mov_b32_e32 v111, v82
	v_lshlrev_b32_e32 v2, 4, v34
	v_lshlrev_b32_e32 v1, 8, v34
	v_and_b32_e32 v2, 0x70, v2
	v_and_or_b32 v238, v1, s39, v2
	v_lshl_add_u64 v[10:11], s[2:3], 0, v[238:239]
	v_add_co_u32_e32 v12, vcc, s40, v10
	v_lshl_add_u64 v[16:17], s[6:7], 0, v[238:239]
	s_nop 0
	v_addc_co_u32_e32 v13, vcc, 0, v11, vcc
	v_add_co_u32_e32 v14, vcc, s22, v10
	v_mov_b32_e32 v1, 0x10000
	s_nop 0
	v_addc_co_u32_e32 v15, vcc, 0, v11, vcc
	global_load_dwordx4 v[2:5], v[12:13], off offset:128
	global_load_dwordx4 v[6:9], v[14:15], off offset:128
	v_add_co_u32_e32 v14, vcc, s41, v10
	v_mov_b32_e32 v112, v82
	s_nop 0
	v_addc_co_u32_e32 v15, vcc, 0, v11, vcc
	v_add_co_u32_e32 v22, vcc, s40, v16
	v_mov_b32_e32 v113, v82
	s_nop 0
	v_addc_co_u32_e32 v23, vcc, 0, v17, vcc
	v_add_co_u32_e32 v34, vcc, s22, v16
	global_load_dwordx4 v[10:13], v[14:15], off offset:128
	global_load_dwordx4 v[18:21], v[22:23], off offset:128
	v_addc_co_u32_e32 v35, vcc, 0, v17, vcc
	v_add_co_u32_e32 v36, vcc, s41, v16
	v_mov_b32_e32 v114, v82
	s_nop 0
	v_addc_co_u32_e32 v37, vcc, 0, v17, vcc
	global_load_dwordx4 v[22:25], v[34:35], off offset:128
	global_load_dwordx4 v[26:29], v[36:37], off offset:128
	global_load_dwordx4 v[14:17], v238, s[2:3] offset:128
	global_load_dwordx4 v[30:33], v238, s[6:7] offset:128
	v_mov_b32_e32 v115, v82
	v_mov_b32_e32 v116, v82
	v_mov_b32_e32 v117, v82
	v_mov_b32_e32 v118, v82
	v_mov_b32_e32 v119, v82
	v_mov_b32_e32 v120, v82
	v_mov_b32_e32 v121, v82
	v_mov_b32_e32 v122, v82
	v_mov_b32_e32 v123, v82
	v_mov_b32_e32 v124, v82
	v_mov_b32_e32 v125, v82
	v_mov_b32_e32 v126, v82
	v_mov_b32_e32 v127, v82
	v_mov_b32_e32 v128, v82
	v_mov_b32_e32 v129, v82
	v_mov_b32_e32 v130, v82
	v_mov_b32_e32 v131, v82
	v_mov_b32_e32 v132, v82
	v_mov_b32_e32 v133, v82
	v_mov_b32_e32 v134, v82
	v_mov_b32_e32 v135, v82
	v_mov_b32_e32 v136, v82
	v_mov_b32_e32 v137, v82
	v_mov_b32_e32 v138, v82
	v_mov_b32_e32 v139, v82
	v_mov_b32_e32 v140, v82
	v_mov_b32_e32 v141, v82
	v_mov_b32_e32 v142, v82
	v_mov_b32_e32 v143, v82
	v_mov_b32_e32 v144, v82
	v_mov_b32_e32 v145, v82
	v_mov_b32_e32 v146, v82
	v_mov_b32_e32 v147, v82
	v_mov_b32_e32 v148, v82
	v_mov_b32_e32 v149, v82
	v_mov_b32_e32 v150, v82
	v_mov_b32_e32 v151, v82
	v_mov_b32_e32 v152, v82
	v_mov_b32_e32 v153, v82
	v_mov_b32_e32 v154, v82
	v_mov_b32_e32 v155, v82
	v_mov_b32_e32 v156, v82
	v_mov_b32_e32 v157, v82
	v_mov_b32_e32 v158, v82
	v_mov_b32_e32 v159, v82
	v_mov_b32_e32 v160, v82
	v_mov_b32_e32 v161, v82
	v_mov_b32_e32 v98, v82
	v_mov_b32_e32 v99, v82
	v_mov_b32_e32 v100, v82
	v_mov_b32_e32 v101, v82
	v_mov_b32_e32 v94, v82
	v_mov_b32_e32 v95, v82
	v_mov_b32_e32 v96, v82
	v_mov_b32_e32 v97, v82
	v_mov_b32_e32 v90, v82
	v_mov_b32_e32 v91, v82
	v_mov_b32_e32 v92, v82
	v_mov_b32_e32 v93, v82
	v_mov_b32_e32 v86, v82
	v_mov_b32_e32 v87, v82
	v_mov_b32_e32 v88, v82
	v_mov_b32_e32 v89, v82
	v_mov_b32_e32 v78, v82
	v_mov_b32_e32 v79, v82
	v_mov_b32_e32 v80, v82
	v_mov_b32_e32 v81, v82
	v_mov_b32_e32 v74, v82
	v_mov_b32_e32 v75, v82
	v_mov_b32_e32 v76, v82
	v_mov_b32_e32 v77, v82
	v_mov_b32_e32 v70, v82
	v_mov_b32_e32 v71, v82
	v_mov_b32_e32 v72, v82
	v_mov_b32_e32 v73, v82
	v_mov_b32_e32 v66, v82
	v_mov_b32_e32 v67, v82
	v_mov_b32_e32 v68, v82
	v_mov_b32_e32 v69, v82
	v_mov_b32_e32 v62, v82
	v_mov_b32_e32 v63, v82
	v_mov_b32_e32 v64, v82
	v_mov_b32_e32 v65, v82
	v_mov_b32_e32 v58, v82
	v_mov_b32_e32 v59, v82
	v_mov_b32_e32 v60, v82
	v_mov_b32_e32 v61, v82
	v_mov_b32_e32 v54, v82
	v_mov_b32_e32 v55, v82
	v_mov_b32_e32 v56, v82
	v_mov_b32_e32 v57, v82
	v_mov_b32_e32 v50, v82
	v_mov_b32_e32 v51, v82
	v_mov_b32_e32 v52, v82
	v_mov_b32_e32 v53, v82
	v_mov_b32_e32 v46, v82
	v_mov_b32_e32 v47, v82
	v_mov_b32_e32 v48, v82
	v_mov_b32_e32 v49, v82
	v_mov_b32_e32 v42, v82
	v_mov_b32_e32 v43, v82
	v_mov_b32_e32 v44, v82
	v_mov_b32_e32 v45, v82
	v_mov_b32_e32 v38, v82
	v_mov_b32_e32 v39, v82
	v_mov_b32_e32 v40, v82
	v_mov_b32_e32 v41, v82
	v_mov_b32_e32 v34, v82
	v_mov_b32_e32 v35, v82
	v_mov_b32_e32 v36, v82
	v_mov_b32_e32 v37, v82
	s_waitcnt lgkmcnt(0)
	s_barrier
	s_waitcnt vmcnt(0)
	s_branch .LBB0_960

.LBB0_960:
	ds_read_b128 v[178:181], v251
	ds_read_b128 v[182:185], v249
	ds_read_b128 v[186:189], v251 offset:4096
	ds_read_b128 v[190:193], v249 offset:4096
	ds_read_b128 v[162:165], v255
	ds_read_b128 v[166:169], v253
	s_cmp_eq_u32 s98, 0
	s_cbranch_scc1 .Lnodef_G0_1
	v_mfma_f32_16x16x32_bf16 v[62:65], v[194:197], v[170:173], v[62:65]
	v_mfma_f32_16x16x32_bf16 v[58:61], v[198:201], v[170:173], v[58:61]
	v_mfma_f32_16x16x32_bf16 v[54:57], v[202:205], v[170:173], v[54:57]
	v_mfma_f32_16x16x32_bf16 v[50:53], v[206:209], v[170:173], v[50:53]
	v_mfma_f32_16x16x32_bf16 v[46:49], v[194:197], v[174:177], v[46:49]
	v_mfma_f32_16x16x32_bf16 v[42:45], v[198:201], v[174:177], v[42:45]
	v_mfma_f32_16x16x32_bf16 v[38:41], v[202:205], v[174:177], v[38:41]
	v_mfma_f32_16x16x32_bf16 v[34:37], v[206:209], v[174:177], v[34:37]
.Lnodef_G0_1:
	ds_read_b128 v[170:173], v255 offset:4096
	ds_read_b128 v[174:177], v253 offset:4096
	s_add_i32 s2, s42, -1
	s_cmp_lt_i32 s2, s37
	s_cselect_b64 s[24:25], -1, 0
	s_cmp_ge_i32 s2, s37
	s_waitcnt lgkmcnt(3)
	v_mfma_f32_16x16x32_bf16 v[158:161], v[178:181], v[162:165], v[158:161]
	v_mfma_f32_16x16x32_bf16 v[154:157], v[182:185], v[162:165], v[154:157]
	v_mfma_f32_16x16x32_bf16 v[150:153], v[186:189], v[162:165], v[150:153]
	v_mfma_f32_16x16x32_bf16 v[146:149], v[190:193], v[162:165], v[146:149]
	ds_read_b128 v[162:165], v255 offset:8192
	s_waitcnt lgkmcnt(3)
	v_mfma_f32_16x16x32_bf16 v[142:145], v[178:181], v[166:169], v[142:145]
	v_mfma_f32_16x16x32_bf16 v[138:141], v[182:185], v[166:169], v[138:141]
	v_mfma_f32_16x16x32_bf16 v[134:137], v[186:189], v[166:169], v[134:137]
	v_mfma_f32_16x16x32_bf16 v[130:133], v[190:193], v[166:169], v[130:133]
	ds_read_b128 v[166:169], v253 offset:8192
	s_waitcnt lgkmcnt(3)
	v_mfma_f32_16x16x32_bf16 v[126:129], v[178:181], v[170:173], v[126:129]
	v_mfma_f32_16x16x32_bf16 v[122:125], v[182:185], v[170:173], v[122:125]
	v_mfma_f32_16x16x32_bf16 v[118:121], v[186:189], v[170:173], v[118:121]
	v_mfma_f32_16x16x32_bf16 v[114:117], v[190:193], v[170:173], v[114:117]
	s_waitcnt vmcnt(6)
	ds_write_b128 v235, v[30:33]
	ds_write_b128 v235, v[26:29] offset:8192
.LBB0_962:
	s_lshl_b32 s6, s51, 8
	s_ashr_i32 s7, s6, 31
	s_lshl_b32 s2, s28, 6
	s_ashr_i32 s3, s2, 31
	s_lshl_b64 s[22:23], s[6:7], 11
	s_add_u32 s26, s31, s22
	s_addc_u32 s27, s33, s23
	s_lshl_b64 s[22:23], s[2:3], 1
	s_add_u32 s26, s26, s22
	s_addc_u32 s27, s27, s23
	global_load_dwordx4 v[30:33], v233, s[26:27]
	global_load_dwordx4 v[26:29], v234, s[26:27]
	s_andn2_b64 vcc, exec, s[24:25]
	ds_read_b128 v[170:173], v255 offset:12288
	s_waitcnt lgkmcnt(5)
	v_mfma_f32_16x16x32_bf16 v[110:113], v[178:181], v[174:177], v[110:113]
	v_mfma_f32_16x16x32_bf16 v[106:109], v[182:185], v[174:177], v[106:109]
	v_mfma_f32_16x16x32_bf16 v[102:105], v[186:189], v[174:177], v[102:105]
	v_mfma_f32_16x16x32_bf16 v[82:85], v[190:193], v[174:177], v[82:85]
	ds_read_b128 v[174:177], v253 offset:12288
	s_waitcnt lgkmcnt(5)
	v_mfma_f32_16x16x32_bf16 v[98:101], v[178:181], v[162:165], v[98:101]
	v_mfma_f32_16x16x32_bf16 v[94:97], v[182:185], v[162:165], v[94:97]
	v_mfma_f32_16x16x32_bf16 v[90:93], v[186:189], v[162:165], v[90:93]
	v_mfma_f32_16x16x32_bf16 v[86:89], v[190:193], v[162:165], v[86:89]
	s_waitcnt lgkmcnt(4)
	v_mfma_f32_16x16x32_bf16 v[78:81], v[178:181], v[166:169], v[78:81]
	v_mfma_f32_16x16x32_bf16 v[74:77], v[182:185], v[166:169], v[74:77]
	v_mfma_f32_16x16x32_bf16 v[70:73], v[186:189], v[166:169], v[70:73]
	v_mfma_f32_16x16x32_bf16 v[66:69], v[190:193], v[166:169], v[66:69]
	s_waitcnt vmcnt(6)
	ds_write_b128 v235, v[22:25] offset:16384
	ds_write_b128 v235, v[18:21] offset:24576
.LBB0_964:
	global_load_dwordx4 v[18:21], v232, s[26:27]
	global_load_dwordx4 v[22:25], v231, s[26:27]
	s_and_b64 vcc, exec, s[2:3]
	ds_read_b128 v[194:197], v243
	ds_read_b128 v[198:201], v241
	ds_read_b128 v[202:205], v243 offset:4096
	ds_read_b128 v[206:209], v241 offset:4096
	ds_read_b128 v[162:165], v247
	ds_read_b128 v[166:169], v245
	s_waitcnt lgkmcnt(9)
	v_mfma_f32_16x16x32_bf16 v[62:65], v[178:181], v[170:173], v[62:65]
	v_mfma_f32_16x16x32_bf16 v[58:61], v[182:185], v[170:173], v[58:61]
	v_mfma_f32_16x16x32_bf16 v[54:57], v[186:189], v[170:173], v[54:57]
	v_mfma_f32_16x16x32_bf16 v[50:53], v[190:193], v[170:173], v[50:53]
	ds_read_b128 v[170:173], v247 offset:4096
	s_waitcnt lgkmcnt(9)
	v_mfma_f32_16x16x32_bf16 v[46:49], v[178:181], v[174:177], v[46:49]
	v_mfma_f32_16x16x32_bf16 v[42:45], v[182:185], v[174:177], v[42:45]
	v_mfma_f32_16x16x32_bf16 v[38:41], v[186:189], v[174:177], v[38:41]
	v_mfma_f32_16x16x32_bf16 v[34:37], v[190:193], v[174:177], v[34:37]
	s_waitcnt vmcnt(6)
	ds_write_b128 v235, v[14:17] offset:32768
	ds_write_b128 v235, v[10:13] offset:40960
.LBB0_966:
	s_lshl_b32 s24, s50, 8
	s_ashr_i32 s25, s24, 31
	s_lshl_b64 s[26:27], s[24:25], 11
	s_add_u32 s26, s34, s26
	s_addc_u32 s27, s35, s27
	s_add_u32 s22, s26, s22
	s_addc_u32 s23, s27, s23
	global_load_dwordx4 v[10:13], v234, s[22:23]
	global_load_dwordx4 v[14:17], v233, s[22:23]
	s_and_b64 vcc, exec, s[2:3]
	ds_read_b128 v[174:177], v245 offset:4096
	s_waitcnt lgkmcnt(5)
	v_mfma_f32_16x16x32_bf16 v[158:161], v[194:197], v[162:165], v[158:161]
	v_mfma_f32_16x16x32_bf16 v[154:157], v[198:201], v[162:165], v[154:157]
	v_mfma_f32_16x16x32_bf16 v[150:153], v[202:205], v[162:165], v[150:153]
	v_mfma_f32_16x16x32_bf16 v[146:149], v[206:209], v[162:165], v[146:149]
	ds_read_b128 v[162:165], v247 offset:8192
	s_waitcnt lgkmcnt(5)
	v_mfma_f32_16x16x32_bf16 v[142:145], v[194:197], v[166:169], v[142:145]
	v_mfma_f32_16x16x32_bf16 v[138:141], v[198:201], v[166:169], v[138:141]
	v_mfma_f32_16x16x32_bf16 v[134:137], v[202:205], v[166:169], v[134:137]
	v_mfma_f32_16x16x32_bf16 v[130:133], v[206:209], v[166:169], v[130:133]
	ds_read_b128 v[166:169], v245 offset:8192
	s_waitcnt lgkmcnt(5)
	v_mfma_f32_16x16x32_bf16 v[126:129], v[194:197], v[170:173], v[126:129]
	v_mfma_f32_16x16x32_bf16 v[122:125], v[198:201], v[170:173], v[122:125]
	v_mfma_f32_16x16x32_bf16 v[118:121], v[202:205], v[170:173], v[118:121]
	v_mfma_f32_16x16x32_bf16 v[114:117], v[206:209], v[170:173], v[114:117]
	s_waitcnt vmcnt(6)
	ds_write_b128 v235, v[6:9] offset:49152
	ds_write_b128 v235, v[2:5] offset:57344
.LBB0_968:
	global_load_dwordx4 v[2:5], v232, s[22:23]
	global_load_dwordx4 v[6:9], v231, s[22:23]
	ds_read_b128 v[170:173], v247 offset:12288
	s_waitcnt lgkmcnt(5)
	v_mfma_f32_16x16x32_bf16 v[110:113], v[194:197], v[174:177], v[110:113]
	v_mfma_f32_16x16x32_bf16 v[106:109], v[198:201], v[174:177], v[106:109]
	v_mfma_f32_16x16x32_bf16 v[102:105], v[202:205], v[174:177], v[102:105]
	v_mfma_f32_16x16x32_bf16 v[82:85], v[206:209], v[174:177], v[82:85]
	ds_read_b128 v[174:177], v245 offset:12288
	s_waitcnt lgkmcnt(5)
	v_mfma_f32_16x16x32_bf16 v[98:101], v[194:197], v[162:165], v[98:101]
	v_mfma_f32_16x16x32_bf16 v[94:97], v[198:201], v[162:165], v[94:97]
	v_mfma_f32_16x16x32_bf16 v[90:93], v[202:205], v[162:165], v[90:93]
	v_mfma_f32_16x16x32_bf16 v[86:89], v[206:209], v[162:165], v[86:89]
	s_waitcnt lgkmcnt(4)
	v_mfma_f32_16x16x32_bf16 v[78:81], v[194:197], v[166:169], v[78:81]
	v_mfma_f32_16x16x32_bf16 v[74:77], v[198:201], v[166:169], v[74:77]
	v_mfma_f32_16x16x32_bf16 v[70:73], v[202:205], v[166:169], v[70:73]
	v_mfma_f32_16x16x32_bf16 v[66:69], v[206:209], v[166:169], v[66:69]
	s_lshl_b64 s[2:3], s[6:7], 10
	s_lshl_b64 s[22:23], s[24:25], 10
	s_add_i32 s53, s28, 1
	s_cmp_lg_u32 s53, 16
	s_cbranch_scc1 .LBB0_972
	s_add_i32 s30, s30, s11
	s_cmp_gt_i32 s30, 31
	s_cbranch_scc1 .LBB0_971
	s_ashr_i32 s3, s30, 31
	s_lshr_b32 s3, s3, 27
	s_add_i32 s3, s30, s3
	s_ashr_i32 s3, s3, 5
	s_mov_b32 s2, s10
	s_lshl_b32 s6, s3, 6
	s_lshl_b32 s7, s30, 1
	s_sub_i32 s6, s7, s6
	s_and_b32 s2, s2, 7
	s_and_b32 s6, s6, -8
	s_lshl_b32 s3, s3, 2
	s_and_b32 s7, s30, 3
	s_or_b32 s50, s3, s7
	s_or_b32 s51, s2, s6
	s_lshl_b32 s2, s51, 8
	s_lshl_b32 s6, s50, 8
	s_ashr_i32 s3, s2, 31
	s_ashr_i32 s7, s6, 31
	s_lshl_b64 s[2:3], s[2:3], 10
	s_lshl_b64 s[22:23], s[6:7], 10

.LBB0_972:
	s_waitcnt lgkmcnt(0)
	s_barrier
	ds_read_b128 v[178:181], v250
	ds_read_b128 v[182:185], v248
	ds_read_b128 v[186:189], v250 offset:4096
	ds_read_b128 v[190:193], v248 offset:4096
	ds_read_b128 v[162:165], v254
	ds_read_b128 v[166:169], v252
	v_mfma_f32_16x16x32_bf16 v[62:65], v[194:197], v[170:173], v[62:65]
	v_mfma_f32_16x16x32_bf16 v[58:61], v[198:201], v[170:173], v[58:61]
	v_mfma_f32_16x16x32_bf16 v[54:57], v[202:205], v[170:173], v[54:57]
	v_mfma_f32_16x16x32_bf16 v[50:53], v[206:209], v[170:173], v[50:53]
	v_mfma_f32_16x16x32_bf16 v[46:49], v[194:197], v[174:177], v[46:49]
	v_mfma_f32_16x16x32_bf16 v[42:45], v[198:201], v[174:177], v[42:45]
	v_mfma_f32_16x16x32_bf16 v[38:41], v[202:205], v[174:177], v[38:41]
	v_mfma_f32_16x16x32_bf16 v[34:37], v[206:209], v[174:177], v[34:37]
	ds_read_b128 v[170:173], v254 offset:4096
	ds_read_b128 v[174:177], v252 offset:4096
	s_cmp_lt_i32 s42, s37
	s_cselect_b64 s[26:27], -1, 0
	s_cmp_ge_i32 s42, s37
	s_cselect_b64 s[6:7], -1, 0
	s_and_b64 vcc, exec, s[6:7]
	s_waitcnt lgkmcnt(3)
	v_mfma_f32_16x16x32_bf16 v[158:161], v[178:181], v[162:165], v[158:161]
	v_mfma_f32_16x16x32_bf16 v[154:157], v[182:185], v[162:165], v[154:157]
	v_mfma_f32_16x16x32_bf16 v[150:153], v[186:189], v[162:165], v[150:153]
	v_mfma_f32_16x16x32_bf16 v[146:149], v[190:193], v[162:165], v[146:149]
	ds_read_b128 v[162:165], v254 offset:8192
	s_waitcnt lgkmcnt(3)
	v_mfma_f32_16x16x32_bf16 v[142:145], v[178:181], v[166:169], v[142:145]
	v_mfma_f32_16x16x32_bf16 v[138:141], v[182:185], v[166:169], v[138:141]
	v_mfma_f32_16x16x32_bf16 v[134:137], v[186:189], v[166:169], v[134:137]
	v_mfma_f32_16x16x32_bf16 v[130:133], v[190:193], v[166:169], v[130:133]
	ds_read_b128 v[166:169], v252 offset:8192
	s_waitcnt lgkmcnt(3)
	v_mfma_f32_16x16x32_bf16 v[126:129], v[178:181], v[170:173], v[126:129]
	v_mfma_f32_16x16x32_bf16 v[122:125], v[182:185], v[170:173], v[122:125]
	v_mfma_f32_16x16x32_bf16 v[118:121], v[186:189], v[170:173], v[118:121]
	v_mfma_f32_16x16x32_bf16 v[114:117], v[190:193], v[170:173], v[114:117]
	s_waitcnt vmcnt(6)
	ds_write_b128 v236, v[26:29]
	ds_write_b128 v236, v[30:33] offset:8192
.LBB0_974:
	s_lshl_b32 s24, s53, 6
	s_ashr_i32 s25, s24, 31
	s_lshl_b64 s[2:3], s[2:3], 1
	s_add_u32 s2, s31, s2
	s_addc_u32 s3, s33, s3
	s_lshl_b64 s[24:25], s[24:25], 1
	s_add_u32 s28, s2, s24
	s_addc_u32 s29, s3, s25
	global_load_dwordx4 v[30:33], v234, s[28:29]
	global_load_dwordx4 v[26:29], v233, s[28:29]
	s_andn2_b64 vcc, exec, s[26:27]
	ds_read_b128 v[170:173], v254 offset:12288
	s_waitcnt lgkmcnt(5)
	v_mfma_f32_16x16x32_bf16 v[110:113], v[178:181], v[174:177], v[110:113]
	v_mfma_f32_16x16x32_bf16 v[106:109], v[182:185], v[174:177], v[106:109]
	v_mfma_f32_16x16x32_bf16 v[102:105], v[186:189], v[174:177], v[102:105]
	v_mfma_f32_16x16x32_bf16 v[82:85], v[190:193], v[174:177], v[82:85]
	ds_read_b128 v[174:177], v252 offset:12288
	s_waitcnt lgkmcnt(5)
	v_mfma_f32_16x16x32_bf16 v[98:101], v[178:181], v[162:165], v[98:101]
	v_mfma_f32_16x16x32_bf16 v[94:97], v[182:185], v[162:165], v[94:97]
	v_mfma_f32_16x16x32_bf16 v[90:93], v[186:189], v[162:165], v[90:93]
	v_mfma_f32_16x16x32_bf16 v[86:89], v[190:193], v[162:165], v[86:89]
	s_waitcnt lgkmcnt(4)
	v_mfma_f32_16x16x32_bf16 v[78:81], v[178:181], v[166:169], v[78:81]
	v_mfma_f32_16x16x32_bf16 v[74:77], v[182:185], v[166:169], v[74:77]
	v_mfma_f32_16x16x32_bf16 v[70:73], v[186:189], v[166:169], v[70:73]
	v_mfma_f32_16x16x32_bf16 v[66:69], v[190:193], v[166:169], v[66:69]
	s_waitcnt vmcnt(6)
	ds_write_b128 v236, v[18:21] offset:16384
	ds_write_b128 v236, v[22:25] offset:24576
.LBB0_976:
	global_load_dwordx4 v[22:25], v232, s[28:29]
	global_load_dwordx4 v[18:21], v231, s[28:29]
	s_and_b64 vcc, exec, s[2:3]
	ds_read_b128 v[194:197], v242
	ds_read_b128 v[198:201], v237
	ds_read_b128 v[202:205], v242 offset:4096
	ds_read_b128 v[206:209], v237 offset:4096
	ds_read_b128 v[162:165], v246
	ds_read_b128 v[166:169], v244
	s_waitcnt lgkmcnt(9)
	v_mfma_f32_16x16x32_bf16 v[62:65], v[178:181], v[170:173], v[62:65]
	v_mfma_f32_16x16x32_bf16 v[58:61], v[182:185], v[170:173], v[58:61]
	v_mfma_f32_16x16x32_bf16 v[54:57], v[186:189], v[170:173], v[54:57]
	v_mfma_f32_16x16x32_bf16 v[50:53], v[190:193], v[170:173], v[50:53]
	ds_read_b128 v[170:173], v246 offset:4096
	s_waitcnt lgkmcnt(9)
	v_mfma_f32_16x16x32_bf16 v[46:49], v[178:181], v[174:177], v[46:49]
	v_mfma_f32_16x16x32_bf16 v[42:45], v[182:185], v[174:177], v[42:45]
	v_mfma_f32_16x16x32_bf16 v[38:41], v[186:189], v[174:177], v[38:41]
	v_mfma_f32_16x16x32_bf16 v[34:37], v[190:193], v[174:177], v[34:37]
	s_waitcnt vmcnt(6)
	ds_write_b128 v236, v[10:13] offset:32768
	ds_write_b128 v236, v[14:17] offset:40960
.LBB0_978:
	s_lshl_b64 s[22:23], s[22:23], 1
	s_add_u32 s22, s34, s22
	s_addc_u32 s23, s35, s23
	s_add_u32 s22, s22, s24
	s_addc_u32 s23, s23, s25
	global_load_dwordx4 v[14:17], v234, s[22:23]
	global_load_dwordx4 v[10:13], v233, s[22:23]
	s_and_b64 vcc, exec, s[2:3]
	ds_read_b128 v[174:177], v244 offset:4096
	s_waitcnt lgkmcnt(5)
	v_mfma_f32_16x16x32_bf16 v[158:161], v[194:197], v[162:165], v[158:161]
	v_mfma_f32_16x16x32_bf16 v[154:157], v[198:201], v[162:165], v[154:157]
	v_mfma_f32_16x16x32_bf16 v[150:153], v[202:205], v[162:165], v[150:153]
	v_mfma_f32_16x16x32_bf16 v[146:149], v[206:209], v[162:165], v[146:149]
	ds_read_b128 v[162:165], v246 offset:8192
	s_waitcnt lgkmcnt(5)
	v_mfma_f32_16x16x32_bf16 v[142:145], v[194:197], v[166:169], v[142:145]
	v_mfma_f32_16x16x32_bf16 v[138:141], v[198:201], v[166:169], v[138:141]
	v_mfma_f32_16x16x32_bf16 v[134:137], v[202:205], v[166:169], v[134:137]
	v_mfma_f32_16x16x32_bf16 v[130:133], v[206:209], v[166:169], v[130:133]
	ds_read_b128 v[166:169], v244 offset:8192
	s_waitcnt lgkmcnt(5)
	v_mfma_f32_16x16x32_bf16 v[126:129], v[194:197], v[170:173], v[126:129]
	v_mfma_f32_16x16x32_bf16 v[122:125], v[198:201], v[170:173], v[122:125]
	v_mfma_f32_16x16x32_bf16 v[118:121], v[202:205], v[170:173], v[118:121]
	v_mfma_f32_16x16x32_bf16 v[114:117], v[206:209], v[170:173], v[114:117]
	s_waitcnt vmcnt(6)
	ds_write_b128 v236, v[2:5] offset:49152
	ds_write_b128 v236, v[6:9] offset:57344
.LBB0_980:
	global_load_dwordx4 v[6:9], v232, s[22:23]
	global_load_dwordx4 v[2:5], v231, s[22:23]
	ds_read_b128 v[170:173], v246 offset:12288
	s_waitcnt lgkmcnt(5)
	v_mfma_f32_16x16x32_bf16 v[110:113], v[194:197], v[174:177], v[110:113]
	v_mfma_f32_16x16x32_bf16 v[106:109], v[198:201], v[174:177], v[106:109]
	v_mfma_f32_16x16x32_bf16 v[102:105], v[202:205], v[174:177], v[102:105]
	v_mfma_f32_16x16x32_bf16 v[82:85], v[206:209], v[174:177], v[82:85]
	ds_read_b128 v[174:177], v244 offset:12288
	s_waitcnt lgkmcnt(5)
	v_mfma_f32_16x16x32_bf16 v[98:101], v[194:197], v[162:165], v[98:101]
	v_mfma_f32_16x16x32_bf16 v[94:97], v[198:201], v[162:165], v[94:97]
	v_mfma_f32_16x16x32_bf16 v[90:93], v[202:205], v[162:165], v[90:93]
	v_mfma_f32_16x16x32_bf16 v[86:89], v[206:209], v[162:165], v[86:89]
	s_waitcnt lgkmcnt(4)
	v_mfma_f32_16x16x32_bf16 v[78:81], v[194:197], v[166:169], v[78:81]
	v_mfma_f32_16x16x32_bf16 v[74:77], v[198:201], v[166:169], v[74:77]
	v_mfma_f32_16x16x32_bf16 v[70:73], v[202:205], v[166:169], v[70:73]
	v_mfma_f32_16x16x32_bf16 v[66:69], v[206:209], v[166:169], v[66:69]
	s_add_i32 s28, s53, 1
	s_cmp_lg_u32 s28, 16
	s_cbranch_scc1 .LBB0_984
	s_add_i32 s30, s30, s11
	s_cmp_gt_i32 s30, 31
	s_cbranch_scc1 .LBB0_983
	s_ashr_i32 s3, s30, 31
	s_lshr_b32 s3, s3, 27
	s_add_i32 s3, s30, s3
	s_ashr_i32 s3, s3, 5
	s_mov_b32 s2, s10
	s_lshl_b32 s22, s3, 6
	s_lshl_b32 s23, s30, 1
	s_sub_i32 s22, s23, s22
	s_and_b32 s2, s2, 7
	s_and_b32 s22, s22, -8
	s_lshl_b32 s3, s3, 2
	s_and_b32 s23, s30, 3
	s_or_b32 s50, s3, s23
	s_or_b32 s51, s2, s22

.LBB0_984:
	s_add_i32 s52, s52, 2
	s_cmp_lg_u32 s52, 16
	s_waitcnt lgkmcnt(0)
	s_mov_b32 s98, 1
	s_cbranch_scc1 .LBB0_959
	s_mov_b32 s98, 0
	v_mfma_f32_16x16x32_bf16 v[62:65], v[194:197], v[170:173], v[62:65]
	v_mfma_f32_16x16x32_bf16 v[58:61], v[198:201], v[170:173], v[58:61]
	v_mfma_f32_16x16x32_bf16 v[54:57], v[202:205], v[170:173], v[54:57]
	v_mfma_f32_16x16x32_bf16 v[50:53], v[206:209], v[170:173], v[50:53]
	v_mfma_f32_16x16x32_bf16 v[46:49], v[194:197], v[174:177], v[46:49]
	v_mfma_f32_16x16x32_bf16 v[42:45], v[198:201], v[174:177], v[42:45]
	v_mfma_f32_16x16x32_bf16 v[38:41], v[202:205], v[174:177], v[38:41]
	v_mfma_f32_16x16x32_bf16 v[34:37], v[206:209], v[174:177], v[34:37]
	s_nop 7
	s_nop 7
	v_mov_b32_e32 v172, v0
	s_nop 0
	v_ashrrev_i32_e32 v162, 1, v172
	v_and_b32_e32 v162, 0xffffff80, v162
	v_lshl_add_u32 v162, s38, 8, v162
	v_and_or_b32 v164, v172, 15, v162
	v_add_u32_e32 v162, 0xffffe000, v162
	v_ashrrev_i32_e32 v162, 11, v162
	v_mad_i32_i24 v162, v162, s47, s47
	v_cmp_lt_i32_e32 vcc, s48, v164
	v_ashrrev_i32_e32 v163, 31, v162
	s_and_saveexec_b64 s[2:3], vcc
	s_xor_b64 s[2:3], exec, s[2:3]
	v_add_u32_e32 v238, 0xffffe000, v164
	v_lshlrev_b64 v[166:167], 12, v[238:239]
	v_mov_b32_e32 v165, v239
	v_lshl_add_u64 v[168:169], s[14:15], 0, v[166:167]
	v_lshlrev_b64 v[170:171], 12, v[164:165]
	v_mov_b64_e32 v[166:167], v[162:163]
	s_andn2_saveexec_b64 s[2:3], s[2:3]
	v_ashrrev_i32_e32 v165, 31, v164
	v_lshlrev_b64 v[170:171], 12, v[164:165]
	v_lshl_add_u64 v[168:169], s[12:13], 0, v[170:171]
	v_mov_b64_e32 v[166:167], 0
	s_or_b64 exec, exec, s[2:3]
	v_and_b32_e32 v165, 0xc0, v172
	v_lshrrev_b32_e32 v172, 2, v172
	s_lshl_b32 s2, s36, 8
	v_and_b32_e32 v172, 12, v172
	v_or3_b32 v172, v165, s2, v172
	v_ashrrev_i32_e32 v173, 31, v172
	v_lshl_add_u64 v[176:177], v[166:167], 2, s[20:21]
	v_lshlrev_b64 v[166:167], 2, v[172:173]
	v_lshl_add_u64 v[180:181], v[168:169], 0, v[166:167]
	v_lshl_add_u64 v[182:183], v[176:177], 0, v[166:167]
	global_load_dwordx4 v[172:175], v[180:181], off
	global_load_dwordx4 v[176:179], v[182:183], off
	v_lshl_add_u64 v[168:169], s[4:5], 0, v[170:171]
	v_lshl_add_u64 v[184:185], v[168:169], 0, v[166:167]
	s_waitcnt vmcnt(0)
	v_pk_fma_f32 v[160:161], v[160:161], v[178:179], v[174:175]
	v_pk_fma_f32 v[158:159], v[158:159], v[176:177], v[172:173]
	global_store_dwordx4 v[184:185], v[158:161], off
	global_load_dwordx4 v[158:161], v[180:181], off offset:64
	s_nop 0
	global_load_dwordx4 v[168:171], v[182:183], off offset:64
	s_waitcnt vmcnt(0)
	v_pk_fma_f32 v[156:157], v[156:157], v[170:171], v[160:161]
	v_pk_fma_f32 v[154:155], v[154:155], v[168:169], v[158:159]
	global_store_dwordx4 v[184:185], v[154:157], off offset:64
	global_load_dwordx4 v[154:157], v[180:181], off offset:128
	s_nop 0
	global_load_dwordx4 v[158:161], v[182:183], off offset:128
	s_waitcnt vmcnt(0)
	v_pk_fma_f32 v[152:153], v[152:153], v[160:161], v[156:157]
	v_pk_fma_f32 v[150:151], v[150:151], v[158:159], v[154:155]
	global_store_dwordx4 v[184:185], v[150:153], off offset:128
	global_load_dwordx4 v[152:155], v[180:181], off offset:192
	s_nop 0
	global_load_dwordx4 v[156:159], v[182:183], off offset:192
	v_or_b32_e32 v150, 16, v164
	v_cmp_lt_i32_e32 vcc, s48, v150
	s_waitcnt vmcnt(0)
	v_pk_fma_f32 v[148:149], v[148:149], v[158:159], v[154:155]
	v_pk_fma_f32 v[146:147], v[146:147], v[156:157], v[152:153]
	global_store_dwordx4 v[184:185], v[146:149], off offset:192
	s_and_saveexec_b64 s[2:3], vcc
	s_xor_b64 s[2:3], exec, s[2:3]
	v_add_u32_e32 v238, 0xffffe010, v164
	v_lshlrev_b64 v[146:147], 12, v[238:239]
	v_mov_b32_e32 v151, v239
	v_lshl_add_u64 v[146:147], s[14:15], 0, v[146:147]
	v_lshlrev_b64 v[148:149], 12, v[150:151]
	v_mov_b64_e32 v[152:153], v[162:163]
	s_andn2_saveexec_b64 s[2:3], s[2:3]
	v_ashrrev_i32_e32 v151, 31, v150
	v_lshlrev_b64 v[148:149], 12, v[150:151]
	v_lshl_add_u64 v[146:147], s[12:13], 0, v[148:149]
	v_mov_b64_e32 v[152:153], 0
	s_or_b64 exec, exec, s[2:3]
	v_lshl_add_u64 v[154:155], v[152:153], 2, s[20:21]
	v_lshl_add_u64 v[158:159], v[146:147], 0, v[166:167]
	v_lshl_add_u64 v[160:161], v[154:155], 0, v[166:167]
	global_load_dwordx4 v[150:153], v[158:159], off
	global_load_dwordx4 v[154:157], v[160:161], off
	v_lshl_add_u64 v[146:147], s[4:5], 0, v[148:149]
	v_lshl_add_u64 v[168:169], v[146:147], 0, v[166:167]
	s_waitcnt vmcnt(0)
	v_pk_fma_f32 v[144:145], v[144:145], v[156:157], v[152:153]
	v_pk_fma_f32 v[142:143], v[142:143], v[154:155], v[150:151]
	global_store_dwordx4 v[168:169], v[142:145], off
	global_load_dwordx4 v[142:145], v[158:159], off offset:64
	s_nop 0
	global_load_dwordx4 v[146:149], v[160:161], off offset:64
	s_waitcnt vmcnt(0)
	v_pk_fma_f32 v[140:141], v[140:141], v[148:149], v[144:145]
	v_pk_fma_f32 v[138:139], v[138:139], v[146:147], v[142:143]
	global_store_dwordx4 v[168:169], v[138:141], off offset:64
	global_load_dwordx4 v[138:141], v[158:159], off offset:128
	s_nop 0
	global_load_dwordx4 v[142:145], v[160:161], off offset:128
	s_waitcnt vmcnt(0)
	v_pk_fma_f32 v[136:137], v[136:137], v[144:145], v[140:141]
	v_pk_fma_f32 v[134:135], v[134:135], v[142:143], v[138:139]
	global_store_dwordx4 v[168:169], v[134:137], off offset:128
	global_load_dwordx4 v[136:139], v[158:159], off offset:192
	s_nop 0
	global_load_dwordx4 v[140:143], v[160:161], off offset:192
	v_or_b32_e32 v134, 32, v164
	v_cmp_lt_i32_e32 vcc, s48, v134
	s_waitcnt vmcnt(0)
	v_pk_fma_f32 v[132:133], v[132:133], v[142:143], v[138:139]
	v_pk_fma_f32 v[130:131], v[130:131], v[140:141], v[136:137]
	global_store_dwordx4 v[168:169], v[130:133], off offset:192
	s_and_saveexec_b64 s[2:3], vcc
	s_xor_b64 s[2:3], exec, s[2:3]
	v_add_u32_e32 v238, 0xffffe020, v164
	v_lshlrev_b64 v[130:131], 12, v[238:239]
	v_mov_b32_e32 v135, v239
	v_lshl_add_u64 v[130:131], s[14:15], 0, v[130:131]
	v_lshlrev_b64 v[132:133], 12, v[134:135]
	v_mov_b64_e32 v[136:137], v[162:163]
	s_andn2_saveexec_b64 s[2:3], s[2:3]
	v_ashrrev_i32_e32 v135, 31, v134
	v_lshlrev_b64 v[132:133], 12, v[134:135]
	v_lshl_add_u64 v[130:131], s[12:13], 0, v[132:133]
	v_mov_b64_e32 v[136:137], 0
	s_or_b64 exec, exec, s[2:3]
	v_lshl_add_u64 v[138:139], v[136:137], 2, s[20:21]
	v_lshl_add_u64 v[142:143], v[130:131], 0, v[166:167]
	v_lshl_add_u64 v[144:145], v[138:139], 0, v[166:167]
	global_load_dwordx4 v[134:137], v[142:143], off
	global_load_dwordx4 v[138:141], v[144:145], off
	v_lshl_add_u64 v[130:131], s[4:5], 0, v[132:133]
	v_lshl_add_u64 v[146:147], v[130:131], 0, v[166:167]
	s_waitcnt vmcnt(0)
	v_pk_fma_f32 v[128:129], v[128:129], v[140:141], v[136:137]
	v_pk_fma_f32 v[126:127], v[126:127], v[138:139], v[134:135]
	global_store_dwordx4 v[146:147], v[126:129], off
	global_load_dwordx4 v[126:129], v[142:143], off offset:64
	s_nop 0
	global_load_dwordx4 v[130:133], v[144:145], off offset:64
	s_waitcnt vmcnt(0)
	v_pk_fma_f32 v[124:125], v[124:125], v[132:133], v[128:129]
	v_pk_fma_f32 v[122:123], v[122:123], v[130:131], v[126:127]
	global_store_dwordx4 v[146:147], v[122:125], off offset:64
	global_load_dwordx4 v[122:125], v[142:143], off offset:128
	s_nop 0
	global_load_dwordx4 v[126:129], v[144:145], off offset:128
	s_waitcnt vmcnt(0)
	v_pk_fma_f32 v[120:121], v[120:121], v[128:129], v[124:125]
	v_pk_fma_f32 v[118:119], v[118:119], v[126:127], v[122:123]
	global_store_dwordx4 v[146:147], v[118:121], off offset:128
	global_load_dwordx4 v[120:123], v[142:143], off offset:192
	s_nop 0
	global_load_dwordx4 v[124:127], v[144:145], off offset:192
	v_or_b32_e32 v118, 48, v164
	v_cmp_lt_i32_e32 vcc, s48, v118
	s_waitcnt vmcnt(0)
	v_pk_fma_f32 v[116:117], v[116:117], v[126:127], v[122:123]
	v_pk_fma_f32 v[114:115], v[114:115], v[124:125], v[120:121]
	global_store_dwordx4 v[146:147], v[114:117], off offset:192
	s_and_saveexec_b64 s[2:3], vcc
	s_xor_b64 s[2:3], exec, s[2:3]
	v_add_u32_e32 v238, 0xffffe030, v164
	v_lshlrev_b64 v[114:115], 12, v[238:239]
	v_mov_b32_e32 v119, v239
	v_lshl_add_u64 v[114:115], s[14:15], 0, v[114:115]
	v_lshlrev_b64 v[116:117], 12, v[118:119]
	v_mov_b64_e32 v[120:121], v[162:163]
	s_andn2_saveexec_b64 s[2:3], s[2:3]
	v_ashrrev_i32_e32 v119, 31, v118
	v_lshlrev_b64 v[116:117], 12, v[118:119]
	v_lshl_add_u64 v[114:115], s[12:13], 0, v[116:117]
	v_mov_b64_e32 v[120:121], 0
	s_or_b64 exec, exec, s[2:3]
	v_lshl_add_u64 v[122:123], v[120:121], 2, s[20:21]
	v_lshl_add_u64 v[126:127], v[114:115], 0, v[166:167]
	v_lshl_add_u64 v[128:129], v[122:123], 0, v[166:167]
	global_load_dwordx4 v[118:121], v[126:127], off
	global_load_dwordx4 v[122:125], v[128:129], off
	v_lshl_add_u64 v[114:115], s[4:5], 0, v[116:117]
	v_lshl_add_u64 v[130:131], v[114:115], 0, v[166:167]
	s_waitcnt vmcnt(0)
	v_pk_fma_f32 v[112:113], v[112:113], v[124:125], v[120:121]
	v_pk_fma_f32 v[110:111], v[110:111], v[122:123], v[118:119]
	global_store_dwordx4 v[130:131], v[110:113], off
	global_load_dwordx4 v[110:113], v[126:127], off offset:64
	s_nop 0
	global_load_dwordx4 v[114:117], v[128:129], off offset:64
	s_waitcnt vmcnt(0)
	v_pk_fma_f32 v[108:109], v[108:109], v[116:117], v[112:113]
	v_pk_fma_f32 v[106:107], v[106:107], v[114:115], v[110:111]
	global_store_dwordx4 v[130:131], v[106:109], off offset:64
	global_load_dwordx4 v[106:109], v[126:127], off offset:128
	s_nop 0
	global_load_dwordx4 v[110:113], v[128:129], off offset:128
	s_waitcnt vmcnt(0)
	v_pk_fma_f32 v[104:105], v[104:105], v[112:113], v[108:109]
	v_pk_fma_f32 v[102:103], v[102:103], v[110:111], v[106:107]
	global_store_dwordx4 v[130:131], v[102:105], off offset:128
	global_load_dwordx4 v[104:107], v[126:127], off offset:192
	s_nop 0
	global_load_dwordx4 v[108:111], v[128:129], off offset:192
	v_or_b32_e32 v102, 64, v164
	v_cmp_lt_i32_e32 vcc, s48, v102
	s_waitcnt vmcnt(0)
	v_pk_fma_f32 v[84:85], v[84:85], v[110:111], v[106:107]
	v_pk_fma_f32 v[82:83], v[82:83], v[108:109], v[104:105]
	global_store_dwordx4 v[130:131], v[82:85], off offset:192
	s_and_saveexec_b64 s[2:3], vcc
	s_xor_b64 s[2:3], exec, s[2:3]
	v_add_u32_e32 v238, 0xffffe040, v164
	v_lshlrev_b64 v[82:83], 12, v[238:239]
	v_mov_b32_e32 v103, v239
	v_lshl_add_u64 v[82:83], s[14:15], 0, v[82:83]
	v_lshlrev_b64 v[84:85], 12, v[102:103]
	v_mov_b64_e32 v[104:105], v[162:163]
	s_andn2_saveexec_b64 s[2:3], s[2:3]
	v_ashrrev_i32_e32 v103, 31, v102
	v_lshlrev_b64 v[84:85], 12, v[102:103]
	v_lshl_add_u64 v[82:83], s[12:13], 0, v[84:85]
	v_mov_b64_e32 v[104:105], 0
	s_or_b64 exec, exec, s[2:3]
	v_lshl_add_u64 v[106:107], v[104:105], 2, s[20:21]
	v_lshl_add_u64 v[110:111], v[82:83], 0, v[166:167]
	v_lshl_add_u64 v[112:113], v[106:107], 0, v[166:167]
	global_load_dwordx4 v[102:105], v[110:111], off
	global_load_dwordx4 v[106:109], v[112:113], off
	v_lshl_add_u64 v[82:83], s[4:5], 0, v[84:85]
	v_lshl_add_u64 v[114:115], v[82:83], 0, v[166:167]
	s_waitcnt vmcnt(0)
	v_pk_fma_f32 v[84:85], v[100:101], v[108:109], v[104:105]
	v_pk_fma_f32 v[82:83], v[98:99], v[106:107], v[102:103]
	global_store_dwordx4 v[114:115], v[82:85], off
	global_load_dwordx4 v[82:85], v[110:111], off offset:64
	s_nop 0
	global_load_dwordx4 v[98:101], v[112:113], off offset:64
	s_waitcnt vmcnt(0)
	v_pk_fma_f32 v[84:85], v[96:97], v[100:101], v[84:85]
	v_pk_fma_f32 v[82:83], v[94:95], v[98:99], v[82:83]
	global_store_dwordx4 v[114:115], v[82:85], off offset:64
	global_load_dwordx4 v[82:85], v[110:111], off offset:128
	s_nop 0
	global_load_dwordx4 v[94:97], v[112:113], off offset:128
	s_waitcnt vmcnt(0)
	v_pk_fma_f32 v[84:85], v[92:93], v[96:97], v[84:85]
	v_pk_fma_f32 v[82:83], v[90:91], v[94:95], v[82:83]
	global_store_dwordx4 v[114:115], v[82:85], off offset:128
	global_load_dwordx4 v[90:93], v[110:111], off offset:192
	global_load_dwordx4 v[94:97], v[112:113], off offset:192
	v_or_b32_e32 v84, 0x50, v164
	v_cmp_lt_i32_e32 vcc, s48, v84
	s_waitcnt vmcnt(0)
	v_pk_fma_f32 v[88:89], v[88:89], v[96:97], v[92:93]
	v_pk_fma_f32 v[86:87], v[86:87], v[94:95], v[90:91]
	global_store_dwordx4 v[114:115], v[86:89], off offset:192
	s_and_saveexec_b64 s[2:3], vcc
	s_xor_b64 s[2:3], exec, s[2:3]
	v_add_u32_e32 v238, 0xffffe050, v164
	v_lshlrev_b64 v[82:83], 12, v[238:239]
	v_mov_b32_e32 v85, v239
	v_lshl_add_u64 v[82:83], s[14:15], 0, v[82:83]
	v_lshlrev_b64 v[86:87], 12, v[84:85]
	v_mov_b64_e32 v[88:89], v[162:163]
	s_andn2_saveexec_b64 s[2:3], s[2:3]
	v_ashrrev_i32_e32 v85, 31, v84
	v_lshlrev_b64 v[86:87], 12, v[84:85]
	v_lshl_add_u64 v[82:83], s[12:13], 0, v[86:87]
	v_mov_b64_e32 v[88:89], 0
	s_or_b64 exec, exec, s[2:3]
	v_lshl_add_u64 v[88:89], v[88:89], 2, s[20:21]
	v_lshl_add_u64 v[92:93], v[82:83], 0, v[166:167]
	v_lshl_add_u64 v[94:95], v[88:89], 0, v[166:167]
	global_load_dwordx4 v[82:85], v[92:93], off
	global_load_dwordx4 v[88:91], v[94:95], off
	v_lshl_add_u64 v[86:87], s[4:5], 0, v[86:87]
	v_lshl_add_u64 v[86:87], v[86:87], 0, v[166:167]
	s_waitcnt vmcnt(0)
	v_pk_fma_f32 v[80:81], v[80:81], v[90:91], v[84:85]
	v_pk_fma_f32 v[78:79], v[78:79], v[88:89], v[82:83]
	global_store_dwordx4 v[86:87], v[78:81], off
	global_load_dwordx4 v[78:81], v[92:93], off offset:64
	s_nop 0
	global_load_dwordx4 v[82:85], v[94:95], off offset:64
	s_waitcnt vmcnt(0)
	v_pk_fma_f32 v[76:77], v[76:77], v[84:85], v[80:81]
	v_pk_fma_f32 v[74:75], v[74:75], v[82:83], v[78:79]
	global_store_dwordx4 v[86:87], v[74:77], off offset:64
	global_load_dwordx4 v[74:77], v[92:93], off offset:128
	s_nop 0
	global_load_dwordx4 v[78:81], v[94:95], off offset:128
	s_waitcnt vmcnt(0)
	v_pk_fma_f32 v[72:73], v[72:73], v[80:81], v[76:77]
	v_pk_fma_f32 v[70:71], v[70:71], v[78:79], v[74:75]
	global_store_dwordx4 v[86:87], v[70:73], off offset:128
	global_load_dwordx4 v[72:75], v[92:93], off offset:192
	s_nop 0
	global_load_dwordx4 v[76:79], v[94:95], off offset:192
	v_or_b32_e32 v70, 0x60, v164
	v_cmp_lt_i32_e32 vcc, s48, v70
	s_waitcnt vmcnt(0)
	v_pk_fma_f32 v[68:69], v[68:69], v[78:79], v[74:75]
	v_pk_fma_f32 v[66:67], v[66:67], v[76:77], v[72:73]
	global_store_dwordx4 v[86:87], v[66:69], off offset:192
	s_and_saveexec_b64 s[2:3], vcc
	s_xor_b64 s[2:3], exec, s[2:3]
	v_add_u32_e32 v238, 0xffffe060, v164
	v_lshlrev_b64 v[66:67], 12, v[238:239]
	v_mov_b32_e32 v71, v239
	v_lshl_add_u64 v[66:67], s[14:15], 0, v[66:67]
	v_lshlrev_b64 v[68:69], 12, v[70:71]
	v_mov_b64_e32 v[72:73], v[162:163]
	s_andn2_saveexec_b64 s[2:3], s[2:3]
	v_ashrrev_i32_e32 v71, 31, v70
	v_lshlrev_b64 v[68:69], 12, v[70:71]
	v_lshl_add_u64 v[66:67], s[12:13], 0, v[68:69]
	v_mov_b64_e32 v[72:73], 0
	s_or_b64 exec, exec, s[2:3]
	v_lshl_add_u64 v[74:75], v[72:73], 2, s[20:21]
	v_lshl_add_u64 v[78:79], v[66:67], 0, v[166:167]
	v_lshl_add_u64 v[80:81], v[74:75], 0, v[166:167]
	global_load_dwordx4 v[70:73], v[78:79], off
	global_load_dwordx4 v[74:77], v[80:81], off
	v_lshl_add_u64 v[66:67], s[4:5], 0, v[68:69]
	v_lshl_add_u64 v[82:83], v[66:67], 0, v[166:167]
	s_waitcnt vmcnt(0)
	v_pk_fma_f32 v[64:65], v[64:65], v[76:77], v[72:73]
	v_pk_fma_f32 v[62:63], v[62:63], v[74:75], v[70:71]
	global_store_dwordx4 v[82:83], v[62:65], off
	global_load_dwordx4 v[62:65], v[78:79], off offset:64
	s_nop 0
	global_load_dwordx4 v[66:69], v[80:81], off offset:64
	s_waitcnt vmcnt(0)
	v_pk_fma_f32 v[60:61], v[60:61], v[68:69], v[64:65]
	v_pk_fma_f32 v[58:59], v[58:59], v[66:67], v[62:63]
	global_store_dwordx4 v[82:83], v[58:61], off offset:64
	global_load_dwordx4 v[58:61], v[78:79], off offset:128
	s_nop 0
	global_load_dwordx4 v[62:65], v[80:81], off offset:128
	s_waitcnt vmcnt(0)
	v_pk_fma_f32 v[56:57], v[56:57], v[64:65], v[60:61]
	v_pk_fma_f32 v[54:55], v[54:55], v[62:63], v[58:59]
	global_store_dwordx4 v[82:83], v[54:57], off offset:128
	global_load_dwordx4 v[56:59], v[78:79], off offset:192
	s_nop 0
	global_load_dwordx4 v[60:63], v[80:81], off offset:192
	v_or_b32_e32 v54, 0x70, v164
	v_cmp_lt_i32_e32 vcc, s48, v54
	s_waitcnt vmcnt(0)
	v_pk_fma_f32 v[52:53], v[52:53], v[62:63], v[58:59]
	v_pk_fma_f32 v[50:51], v[50:51], v[60:61], v[56:57]
	global_store_dwordx4 v[82:83], v[50:53], off offset:192
	s_and_saveexec_b64 s[2:3], vcc
	s_xor_b64 s[2:3], exec, s[2:3]
	v_add_u32_e32 v238, 0xffffe070, v164
	v_lshlrev_b64 v[50:51], 12, v[238:239]
	v_mov_b32_e32 v55, v239
	v_lshl_add_u64 v[50:51], s[14:15], 0, v[50:51]
	v_lshlrev_b64 v[52:53], 12, v[54:55]
	s_andn2_saveexec_b64 s[2:3], s[2:3]
	v_ashrrev_i32_e32 v55, 31, v54
	v_lshlrev_b64 v[52:53], 12, v[54:55]
	v_lshl_add_u64 v[50:51], s[12:13], 0, v[52:53]
	v_mov_b64_e32 v[162:163], 0
	s_or_b64 exec, exec, s[2:3]
	v_lshl_add_u64 v[58:59], v[162:163], 2, s[20:21]
	v_lshl_add_u64 v[62:63], v[50:51], 0, v[166:167]
	v_lshl_add_u64 v[64:65], v[58:59], 0, v[166:167]
	global_load_dwordx4 v[54:57], v[62:63], off
	global_load_dwordx4 v[58:61], v[64:65], off
	v_lshl_add_u64 v[50:51], s[4:5], 0, v[52:53]
	v_lshl_add_u64 v[66:67], v[50:51], 0, v[166:167]
	s_add_i32 s49, s49, s11
	s_cmp_gt_i32 s49, 31
	s_waitcnt vmcnt(0)
	v_pk_fma_f32 v[48:49], v[48:49], v[60:61], v[56:57]
	v_pk_fma_f32 v[46:47], v[46:47], v[58:59], v[54:55]
	global_store_dwordx4 v[66:67], v[46:49], off
	global_load_dwordx4 v[46:49], v[62:63], off offset:64
	s_nop 0
	global_load_dwordx4 v[50:53], v[64:65], off offset:64
	s_waitcnt vmcnt(0)
	v_pk_fma_f32 v[44:45], v[44:45], v[52:53], v[48:49]
	v_pk_fma_f32 v[42:43], v[42:43], v[50:51], v[46:47]
	global_store_dwordx4 v[66:67], v[42:45], off offset:64
	global_load_dwordx4 v[42:45], v[62:63], off offset:128
	s_nop 0
	global_load_dwordx4 v[46:49], v[64:65], off offset:128
	s_waitcnt vmcnt(0)
	v_pk_fma_f32 v[40:41], v[40:41], v[48:49], v[44:45]
	v_pk_fma_f32 v[38:39], v[38:39], v[46:47], v[42:43]
	global_store_dwordx4 v[66:67], v[38:41], off offset:128
	global_load_dwordx4 v[38:41], v[62:63], off offset:192
	s_nop 0
	global_load_dwordx4 v[42:45], v[64:65], off offset:192
	s_waitcnt vmcnt(0)
	v_pk_fma_f32 v[40:41], v[36:37], v[44:45], v[40:41]
	v_pk_fma_f32 v[38:39], v[34:35], v[42:43], v[38:39]
	v_mov_b32_e32 v37, 0
	global_store_dwordx4 v[66:67], v[38:41], off offset:192
	s_cbranch_scc1 .LBB0_958
	s_ashr_i32 s3, s49, 31
	s_lshr_b32 s3, s3, 27
	s_add_i32 s3, s49, s3
	s_ashr_i32 s3, s3, 5
	s_mov_b32 s2, s10
	s_lshl_b32 s22, s3, 6
	s_lshl_b32 s23, s49, 1
	s_sub_i32 s22, s23, s22
	s_and_b32 s2, s2, 7
	s_and_b32 s22, s22, -8
	s_lshl_b32 s3, s3, 2
	s_and_b32 s23, s49, 3
	s_or_b32 s36, s3, s23
	s_or_b32 s38, s2, s22
	s_branch .LBB0_958

.LBB0_1138:
	s_mov_b32 s98, 0
	v_mov_b32_e32 v255, 0x0
	v_bfe_u32 v1, v0, 0, 1
	v_lshlrev_b32_e32 v1, 7, v1
	v_xor_b32_e32 v255, v255, v1
	v_bfe_u32 v1, v0, 1, 3
	v_mul_u32_u24_e32 v1, 0x110, v1
	v_xor_b32_e32 v255, v255, v1
	v_bfe_u32 v1, v0, 4, 2
	v_lshlrev_b32_e32 v1, 4, v1
	v_xor_b32_e32 v255, v255, v1
	v_bfe_u32 v1, v0, 8, 1
	v_lshlrev_b32_e32 v1, 14, v1
	v_xor_b32_e32 v255, v255, v1
	v_mov_b32_e32 v254, 0x10000
	v_bfe_u32 v1, v0, 0, 1
	v_lshlrev_b32_e32 v1, 7, v1
	v_xor_b32_e32 v254, v254, v1
	v_bfe_u32 v1, v0, 1, 3
	v_mul_u32_u24_e32 v1, 0x110, v1
	v_xor_b32_e32 v254, v254, v1
	v_bfe_u32 v1, v0, 4, 2
	v_lshlrev_b32_e32 v1, 4, v1
	v_xor_b32_e32 v254, v254, v1
	v_bfe_u32 v1, v0, 8, 1
	v_lshlrev_b32_e32 v1, 14, v1
	v_xor_b32_e32 v254, v254, v1
	v_mov_b32_e32 v253, 0x880
	v_bfe_u32 v1, v0, 0, 1
	v_lshlrev_b32_e32 v1, 7, v1
	v_xor_b32_e32 v253, v253, v1
	v_bfe_u32 v1, v0, 1, 3
	v_mul_u32_u24_e32 v1, 0x110, v1
	v_xor_b32_e32 v253, v253, v1
	v_bfe_u32 v1, v0, 4, 2
	v_lshlrev_b32_e32 v1, 4, v1
	v_xor_b32_e32 v253, v253, v1
	v_bfe_u32 v1, v0, 8, 1
	v_lshlrev_b32_e32 v1, 14, v1
	v_xor_b32_e32 v253, v253, v1
	v_mov_b32_e32 v252, 0x10880
	v_bfe_u32 v1, v0, 0, 1
	v_lshlrev_b32_e32 v1, 7, v1
	v_xor_b32_e32 v252, v252, v1
	v_bfe_u32 v1, v0, 1, 3
	v_mul_u32_u24_e32 v1, 0x110, v1
	v_xor_b32_e32 v252, v252, v1
	v_bfe_u32 v1, v0, 4, 2
	v_lshlrev_b32_e32 v1, 4, v1
	v_xor_b32_e32 v252, v252, v1
	v_bfe_u32 v1, v0, 8, 1
	v_lshlrev_b32_e32 v1, 14, v1
	v_xor_b32_e32 v252, v252, v1
	v_mov_b32_e32 v251, 0x8000
	v_bfe_u32 v1, v0, 0, 1
	v_lshlrev_b32_e32 v1, 7, v1
	v_xor_b32_e32 v251, v251, v1
	v_bfe_u32 v1, v0, 1, 3
	v_mul_u32_u24_e32 v1, 0x110, v1
	v_xor_b32_e32 v251, v251, v1
	v_bfe_u32 v1, v0, 4, 2
	v_lshlrev_b32_e32 v1, 4, v1
	v_xor_b32_e32 v251, v251, v1
	v_bfe_u32 v1, v0, 6, 2
	v_lshlrev_b32_e32 v1, 13, v1
	v_xor_b32_e32 v251, v251, v1
	v_mov_b32_e32 v250, 0x18000
	v_bfe_u32 v1, v0, 0, 1
	v_lshlrev_b32_e32 v1, 7, v1
	v_xor_b32_e32 v250, v250, v1
	v_bfe_u32 v1, v0, 1, 3
	v_mul_u32_u24_e32 v1, 0x110, v1
	v_xor_b32_e32 v250, v250, v1
	v_bfe_u32 v1, v0, 4, 2
	v_lshlrev_b32_e32 v1, 4, v1
	v_xor_b32_e32 v250, v250, v1
	v_bfe_u32 v1, v0, 6, 2
	v_lshlrev_b32_e32 v1, 13, v1
	v_xor_b32_e32 v250, v250, v1
	v_mov_b32_e32 v249, 0x8880
	v_bfe_u32 v1, v0, 0, 1
	v_lshlrev_b32_e32 v1, 7, v1
	v_xor_b32_e32 v249, v249, v1
	v_bfe_u32 v1, v0, 1, 3
	v_mul_u32_u24_e32 v1, 0x110, v1
	v_xor_b32_e32 v249, v249, v1
	v_bfe_u32 v1, v0, 4, 2
	v_lshlrev_b32_e32 v1, 4, v1
	v_xor_b32_e32 v249, v249, v1
	v_bfe_u32 v1, v0, 6, 2
	v_lshlrev_b32_e32 v1, 13, v1
	v_xor_b32_e32 v249, v249, v1
	v_mov_b32_e32 v248, 0x18880
	v_bfe_u32 v1, v0, 0, 1
	v_lshlrev_b32_e32 v1, 7, v1
	v_xor_b32_e32 v248, v248, v1
	v_bfe_u32 v1, v0, 1, 3
	v_mul_u32_u24_e32 v1, 0x110, v1
	v_xor_b32_e32 v248, v248, v1
	v_bfe_u32 v1, v0, 4, 2
	v_lshlrev_b32_e32 v1, 4, v1
	v_xor_b32_e32 v248, v248, v1
	v_bfe_u32 v1, v0, 6, 2
	v_lshlrev_b32_e32 v1, 13, v1
	v_xor_b32_e32 v248, v248, v1
	v_mov_b32_e32 v247, 0x40
	v_bfe_u32 v1, v0, 0, 1
	v_lshlrev_b32_e32 v1, 7, v1
	v_xor_b32_e32 v247, v247, v1
	v_bfe_u32 v1, v0, 1, 3
	v_mul_u32_u24_e32 v1, 0x110, v1
	v_xor_b32_e32 v247, v247, v1
	v_bfe_u32 v1, v0, 4, 2
	v_lshlrev_b32_e32 v1, 4, v1
	v_xor_b32_e32 v247, v247, v1
	v_bfe_u32 v1, v0, 8, 1
	v_lshlrev_b32_e32 v1, 14, v1
	v_xor_b32_e32 v247, v247, v1
	v_mov_b32_e32 v246, 0x10040
	v_bfe_u32 v1, v0, 0, 1
	v_lshlrev_b32_e32 v1, 7, v1
	v_xor_b32_e32 v246, v246, v1
	v_bfe_u32 v1, v0, 1, 3
	v_mul_u32_u24_e32 v1, 0x110, v1
	v_xor_b32_e32 v246, v246, v1
	v_bfe_u32 v1, v0, 4, 2
	v_lshlrev_b32_e32 v1, 4, v1
	v_xor_b32_e32 v246, v246, v1
	v_bfe_u32 v1, v0, 8, 1
	v_lshlrev_b32_e32 v1, 14, v1
	v_xor_b32_e32 v246, v246, v1
	v_mov_b32_e32 v245, 0x8c0
	v_bfe_u32 v1, v0, 0, 1
	v_lshlrev_b32_e32 v1, 7, v1
	v_xor_b32_e32 v245, v245, v1
	v_bfe_u32 v1, v0, 1, 3
	v_mul_u32_u24_e32 v1, 0x110, v1
	v_xor_b32_e32 v245, v245, v1
	v_bfe_u32 v1, v0, 4, 2
	v_lshlrev_b32_e32 v1, 4, v1
	v_xor_b32_e32 v245, v245, v1
	v_bfe_u32 v1, v0, 8, 1
	v_lshlrev_b32_e32 v1, 14, v1
	v_xor_b32_e32 v245, v245, v1
	v_mov_b32_e32 v244, 0x108c0
	v_bfe_u32 v1, v0, 0, 1
	v_lshlrev_b32_e32 v1, 7, v1
	v_xor_b32_e32 v244, v244, v1
	v_bfe_u32 v1, v0, 1, 3
	v_mul_u32_u24_e32 v1, 0x110, v1
	v_xor_b32_e32 v244, v244, v1
	v_bfe_u32 v1, v0, 4, 2
	v_lshlrev_b32_e32 v1, 4, v1
	v_xor_b32_e32 v244, v244, v1
	v_bfe_u32 v1, v0, 8, 1
	v_lshlrev_b32_e32 v1, 14, v1
	v_xor_b32_e32 v244, v244, v1
	v_mov_b32_e32 v243, 0x8040
	v_bfe_u32 v1, v0, 0, 1
	v_lshlrev_b32_e32 v1, 7, v1
	v_xor_b32_e32 v243, v243, v1
	v_bfe_u32 v1, v0, 1, 3
	v_mul_u32_u24_e32 v1, 0x110, v1
	v_xor_b32_e32 v243, v243, v1
	v_bfe_u32 v1, v0, 4, 2
	v_lshlrev_b32_e32 v1, 4, v1
	v_xor_b32_e32 v243, v243, v1
	v_bfe_u32 v1, v0, 6, 2
	v_lshlrev_b32_e32 v1, 13, v1
	v_xor_b32_e32 v243, v243, v1
	v_mov_b32_e32 v242, 0x18040
	v_bfe_u32 v1, v0, 0, 1
	v_lshlrev_b32_e32 v1, 7, v1
	v_xor_b32_e32 v242, v242, v1
	v_bfe_u32 v1, v0, 1, 3
	v_mul_u32_u24_e32 v1, 0x110, v1
	v_xor_b32_e32 v242, v242, v1
	v_bfe_u32 v1, v0, 4, 2
	v_lshlrev_b32_e32 v1, 4, v1
	v_xor_b32_e32 v242, v242, v1
	v_bfe_u32 v1, v0, 6, 2
	v_lshlrev_b32_e32 v1, 13, v1
	v_xor_b32_e32 v242, v242, v1
	v_mov_b32_e32 v241, 0x88c0
	v_bfe_u32 v1, v0, 0, 1
	v_lshlrev_b32_e32 v1, 7, v1
	v_xor_b32_e32 v241, v241, v1
	v_bfe_u32 v1, v0, 1, 3
	v_mul_u32_u24_e32 v1, 0x110, v1
	v_xor_b32_e32 v241, v241, v1
	v_bfe_u32 v1, v0, 4, 2
	v_lshlrev_b32_e32 v1, 4, v1
	v_xor_b32_e32 v241, v241, v1
	v_bfe_u32 v1, v0, 6, 2
	v_lshlrev_b32_e32 v1, 13, v1
	v_xor_b32_e32 v241, v241, v1
	v_mov_b32_e32 v237, 0x188c0
	v_bfe_u32 v1, v0, 0, 1
	v_lshlrev_b32_e32 v1, 7, v1
	v_xor_b32_e32 v237, v237, v1
	v_bfe_u32 v1, v0, 1, 3
	v_mul_u32_u24_e32 v1, 0x110, v1
	v_xor_b32_e32 v237, v237, v1
	v_bfe_u32 v1, v0, 4, 2
	v_lshlrev_b32_e32 v1, 4, v1
	v_xor_b32_e32 v237, v237, v1
	v_bfe_u32 v1, v0, 6, 2
	v_lshlrev_b32_e32 v1, 13, v1
	v_xor_b32_e32 v237, v237, v1
	v_mov_b32_e32 v236, 0x0
	v_bfe_u32 v1, v0, 0, 4
	v_lshlrev_b32_e32 v1, 4, v1
	v_xor_b32_e32 v236, v236, v1
	v_bfe_u32 v1, v0, 4, 4
	v_mul_u32_u24_e32 v1, 0x110, v1
	v_xor_b32_e32 v236, v236, v1
	v_bfe_u32 v1, v0, 8, 1
	v_lshlrev_b32_e32 v1, 12, v1
	v_xor_b32_e32 v236, v236, v1
	v_mov_b32_e32 v235, 0x10000
	v_bfe_u32 v1, v0, 0, 4
	v_lshlrev_b32_e32 v1, 4, v1
	v_xor_b32_e32 v235, v235, v1
	v_bfe_u32 v1, v0, 4, 4
	v_mul_u32_u24_e32 v1, 0x110, v1
	v_xor_b32_e32 v235, v235, v1
	v_bfe_u32 v1, v0, 8, 1
	v_lshlrev_b32_e32 v1, 12, v1
	v_xor_b32_e32 v235, v235, v1
	v_mov_b32_e32 v234, 0x0
	v_bfe_u32 v1, v0, 0, 3
	v_lshlrev_b32_e32 v1, 4, v1
	v_add_u32_e32 v234, v234, v1
	v_bfe_u32 v1, v0, 3, 6
	v_lshlrev_b32_e32 v1, 11, v1
	v_add_u32_e32 v234, v234, v1
	v_mov_b32_e32 v233, 0x20000
	v_bfe_u32 v1, v0, 0, 3
	v_lshlrev_b32_e32 v1, 4, v1
	v_add_u32_e32 v233, v233, v1
	v_bfe_u32 v1, v0, 3, 6
	v_lshlrev_b32_e32 v1, 11, v1
	v_add_u32_e32 v233, v233, v1
	v_mov_b32_e32 v232, 0x40000
	v_bfe_u32 v1, v0, 0, 3
	v_lshlrev_b32_e32 v1, 4, v1
	v_add_u32_e32 v232, v232, v1
	v_bfe_u32 v1, v0, 3, 6
	v_lshlrev_b32_e32 v1, 11, v1
	v_add_u32_e32 v232, v232, v1
	v_mov_b32_e32 v231, 0x60000
	v_bfe_u32 v1, v0, 0, 3
	v_lshlrev_b32_e32 v1, 4, v1
	v_add_u32_e32 v231, v231, v1
	v_bfe_u32 v1, v0, 3, 6
	v_lshlrev_b32_e32 v1, 11, v1
	v_add_u32_e32 v231, v231, v1
	v_mov_b32_e32 v1, v0
	s_mov_b32 s2, s10
	s_load_dword s8, s[0:1], 0xe0
	s_load_dwordx2 s[2:3], s[16:17], 0xd0
	s_waitcnt vmcnt(0)
	v_mov_b32_e32 v2, v0
	s_mov_b32 s27, 0
	s_waitcnt lgkmcnt(0)
	s_add_u32 s11, s2, 0x17f0000
	s_addc_u32 s24, s3, 0
	s_add_u32 s6, s2, 0x37f0000
	s_addc_u32 s7, s3, 0
	s_add_u32 s25, s2, 0x770000
	s_addc_u32 s26, s3, 0
	s_lshr_b32 s28, s8, 3
	v_cvt_f32_u32_e32 v1, s28
	s_sub_i32 s8, 0, s28
	s_mov_b32 s2, s10
	v_rcp_iflag_f32_e32 v1, v1
	s_ashr_i32 s3, s2, 3
	s_abs_i32 s3, s3
	s_ashr_i32 s2, s2, 31
	v_mul_f32_e32 v1, 0x4f7ffffe, v1
	v_cvt_u32_f32_e32 v1, v1
	s_nop 0
	v_readfirstlane_b32 s30, v1
	s_mul_i32 s8, s8, s30
	s_mul_hi_u32 s8, s30, s8
	s_add_i32 s30, s30, s8
	s_mul_hi_u32 s8, s3, s30
	s_mul_i32 s8, s8, s28
	s_sub_i32 s3, s3, s8
	s_sub_i32 s8, s3, s28
	s_cmp_ge_u32 s3, s28
	s_cselect_b32 s3, s8, s3
	s_sub_i32 s8, s3, s28
	s_cmp_ge_u32 s3, s28
	s_cselect_b32 s3, s8, s3
	s_xor_b32 s3, s3, s2
	s_sub_i32 s31, s3, s2
	s_mul_hi_u32 s3, s30, 0xb0
	s_mul_i32 s3, s3, s28
	s_sub_i32 s3, 0xb0, s3
	s_sub_i32 s8, s3, s28
	s_cmp_ge_u32 s3, s28
	s_cselect_b32 s3, s8, s3
	s_sub_i32 s8, s3, s28
	s_cmp_ge_u32 s3, s28
	s_cselect_b32 s29, s8, s3
	s_sub_i32 s33, 0xb0, s29
	s_mov_b32 s2, s10
	s_cmp_ge_i32 s31, s33
	s_cbranch_scc1 .LBB0_1187
	s_mov_b32 s9, s10
	s_cmpk_gt_i32 s31, 0x9f
	s_cbranch_scc0 .LBB0_1141
	s_lshl_b32 s2, s31, 2
	s_add_i32 s2, s2, 0x7ffffd80
	s_and_b32 s8, s2, 0x7ffffff8
	s_and_b32 s2, s31, 1
	s_or_b32 s34, s2, 20
	s_cbranch_execz .LBB0_1142
	s_branch .LBB0_1143

.LBB0_1143:
	s_not_b32 s3, s31
	s_add_i32 s3, s28, s3
	s_add_i32 s3, s3, s33
	s_and_b32 s2, s9, 7
	s_ashr_i32 s9, s3, 31
	s_abs_i32 s3, s3
	s_mul_hi_u32 s12, s3, s30
	s_mul_i32 s13, s12, s28
	s_sub_i32 s3, s3, s13
	s_add_i32 s13, s12, 1
	s_sub_i32 s14, s3, s28
	s_cmp_ge_u32 s3, s28
	s_cselect_b32 s12, s13, s12
	s_cselect_b32 s3, s14, s3
	s_add_i32 s13, s12, 1
	s_cmp_ge_u32 s3, s28
	s_cselect_b32 s3, s13, s12
	s_xor_b32 s3, s3, s9
	v_mov_b32_e32 v66, 0
	s_or_b32 s38, s8, s2
	v_mov_b32_e32 v1, v0
	s_lshl_b32 s2, s34, 8
	s_sub_i32 s12, s3, s9
	s_ashr_i32 s3, s2, 31
	s_lshl_b64 s[2:3], s[2:3], 11
	v_lshlrev_b32_e32 v2, 8, v1
	v_lshlrev_b32_e32 v1, 4, v1
	s_add_u32 s2, s25, s2
	v_and_b32_e32 v1, 0x70, v1
	s_movk_i32 s35, 0xf800
	v_mov_b32_e32 v239, 0
	s_addc_u32 s3, s26, s3
	v_and_or_b32 v238, v2, s35, v1
	v_lshl_add_u64 v[10:11], s[2:3], 0, v[238:239]
	s_mov_b32 s36, 0x60000
	v_add_co_u32_e32 v12, vcc, s36, v10
	s_lshl_b32 s8, s38, 8
	s_nop 0
	v_addc_co_u32_e32 v13, vcc, 0, v11, vcc
	s_mov_b32 s13, 0x40000
	s_ashr_i32 s9, s8, 31
	v_add_co_u32_e32 v14, vcc, s13, v10
	s_lshl_b64 s[8:9], s[8:9], 11
	s_nop 0
	v_addc_co_u32_e32 v15, vcc, 0, v11, vcc
	s_mov_b32 s37, 0x20000
	s_add_u32 s8, s11, s8
	v_add_co_u32_e32 v18, vcc, s37, v10
	s_addc_u32 s9, s24, s9
	s_nop 0
	v_addc_co_u32_e32 v19, vcc, 0, v11, vcc
	v_lshl_add_u64 v[30:31], s[8:9], 0, v[238:239]
	v_add_co_u32_e32 v32, vcc, s13, v30
	global_load_dwordx4 v[2:5], v[12:13], off
	global_load_dwordx4 v[6:9], v[14:15], off
	v_addc_co_u32_e32 v33, vcc, 0, v31, vcc
	v_add_co_u32_e32 v34, vcc, s37, v30
	global_load_dwordx4 v[10:13], v[18:19], off
	global_load_dwordx4 v[14:17], v238, s[2:3]
	v_addc_co_u32_e32 v35, vcc, 0, v31, vcc
	global_load_dwordx4 v[18:21], v[32:33], off
	global_load_dwordx4 v[22:25], v[34:35], off
	global_load_dwordx4 v[26:29], v238, s[8:9]
	v_add_co_u32_e32 v30, vcc, s36, v30
	v_mov_b32_e32 v1, v0
	s_nop 0
	v_addc_co_u32_e32 v31, vcc, 0, v31, vcc
	global_load_dwordx4 v[30:33], v[30:31], off
	s_movk_i32 s39, 0xf0
	v_ashrrev_i32_e32 v35, 4, v1
	v_xor_b32_e32 v1, v35, v1
	v_lshlrev_b32_e32 v35, 8, v35
	v_lshlrev_b32_e32 v1, 4, v1
	v_mov_b32_e32 v34, v0
	v_and_or_b32 v1, v1, s39, v35
	s_mov_b32 s49, 0
	s_cmp_lt_i32 s12, 1
	s_waitcnt vmcnt(4)
	ds_write_b128 v1, v[14:17] offset:32768
	ds_write_b128 v1, v[10:13] offset:40960
	ds_write_b128 v1, v[6:9] offset:49152
	ds_write_b128 v1, v[2:5] offset:57344
	s_waitcnt vmcnt(1)
	ds_write_b128 v1, v[26:29]
	ds_write_b128 v1, v[22:25] offset:8192
	ds_write_b128 v1, v[18:21] offset:16384
	s_waitcnt vmcnt(0)
	ds_write_b128 v1, v[30:33] offset:24576
	s_nop 0
	v_lshlrev_b32_e32 v2, 4, v34
	v_lshlrev_b32_e32 v1, 8, v34
	v_and_b32_e32 v2, 0x70, v2
	v_and_or_b32 v238, v1, s35, v2
	v_lshl_add_u64 v[10:11], s[2:3], 0, v[238:239]
	v_add_co_u32_e32 v12, vcc, s36, v10
	v_lshl_add_u64 v[16:17], s[8:9], 0, v[238:239]
	s_nop 0
	v_addc_co_u32_e32 v13, vcc, 0, v11, vcc
	v_add_co_u32_e32 v14, vcc, s13, v10
	s_nop 1
	v_addc_co_u32_e32 v15, vcc, 0, v11, vcc
	global_load_dwordx4 v[2:5], v[12:13], off offset:128
	global_load_dwordx4 v[6:9], v[14:15], off offset:128
	v_add_co_u32_e32 v14, vcc, 0x20000, v10
	s_nop 1
	v_addc_co_u32_e32 v15, vcc, 0, v11, vcc
	v_add_co_u32_e32 v22, vcc, s36, v16
	s_nop 1
	v_addc_co_u32_e32 v23, vcc, 0, v17, vcc
	v_add_co_u32_e32 v34, vcc, 0x40000, v16
	global_load_dwordx4 v[10:13], v[14:15], off offset:128
	global_load_dwordx4 v[18:21], v[22:23], off offset:128
	v_addc_co_u32_e32 v35, vcc, 0, v17, vcc
	v_add_co_u32_e32 v36, vcc, 0x20000, v16
	s_nop 1
	v_addc_co_u32_e32 v37, vcc, 0, v17, vcc
	global_load_dwordx4 v[22:25], v[34:35], off offset:128
	global_load_dwordx4 v[26:29], v[36:37], off offset:128
	global_load_dwordx4 v[14:17], v238, s[2:3] offset:128
	global_load_dwordx4 v[30:33], v238, s[8:9] offset:128
	s_waitcnt lgkmcnt(0)
	s_barrier
	s_cbranch_scc1 .LBB0_1186
	s_lshl_b32 s40, s12, 4
	s_mov_b32 s41, 2
	s_movk_i32 s42, 0xff80
	s_mov_b32 s43, 0x10000
	s_mov_b32 s44, 0x11000
	s_movk_i32 s45, 0x1600
	v_mov_b32_e32 v1, 0x10000
	v_mov_b32_e32 v240, 0x8040
	s_mov_b32 s22, 2
	s_mov_b32 s46, s31
	s_mov_b32 s47, s34
	s_mov_b32 s48, s38
	v_mov_b32_e32 v67, v66
	v_mov_b32_e32 v68, v66
	v_mov_b32_e32 v69, v66
	v_mov_b32_e32 v106, v66
	v_mov_b32_e32 v107, v66
	v_mov_b32_e32 v108, v66
	v_mov_b32_e32 v109, v66
	v_mov_b32_e32 v102, v66
	v_mov_b32_e32 v103, v66
	v_mov_b32_e32 v104, v66
	v_mov_b32_e32 v105, v66
	v_mov_b32_e32 v110, v66
	v_mov_b32_e32 v111, v66
	v_mov_b32_e32 v112, v66
	v_mov_b32_e32 v113, v66
	v_mov_b32_e32 v114, v66
	v_mov_b32_e32 v115, v66
	v_mov_b32_e32 v116, v66
	v_mov_b32_e32 v117, v66
	v_mov_b32_e32 v122, v66
	v_mov_b32_e32 v123, v66
	v_mov_b32_e32 v124, v66
	v_mov_b32_e32 v125, v66
	v_mov_b32_e32 v118, v66
	v_mov_b32_e32 v119, v66
	v_mov_b32_e32 v120, v66
	v_mov_b32_e32 v121, v66
	v_mov_b32_e32 v126, v66
	v_mov_b32_e32 v127, v66
	v_mov_b32_e32 v128, v66
	v_mov_b32_e32 v129, v66
	v_mov_b32_e32 v130, v66
	v_mov_b32_e32 v131, v66
	v_mov_b32_e32 v132, v66
	v_mov_b32_e32 v133, v66
	v_mov_b32_e32 v138, v66
	v_mov_b32_e32 v139, v66
	v_mov_b32_e32 v140, v66
	v_mov_b32_e32 v141, v66
	v_mov_b32_e32 v134, v66
	v_mov_b32_e32 v135, v66
	v_mov_b32_e32 v136, v66
	v_mov_b32_e32 v137, v66
	v_mov_b32_e32 v142, v66
	v_mov_b32_e32 v143, v66
	v_mov_b32_e32 v144, v66
	v_mov_b32_e32 v145, v66
	v_mov_b32_e32 v146, v66
	v_mov_b32_e32 v147, v66
	v_mov_b32_e32 v148, v66
	v_mov_b32_e32 v149, v66
	v_mov_b32_e32 v154, v66
	v_mov_b32_e32 v155, v66
	v_mov_b32_e32 v156, v66
	v_mov_b32_e32 v157, v66
	v_mov_b32_e32 v150, v66
	v_mov_b32_e32 v151, v66
	v_mov_b32_e32 v152, v66
	v_mov_b32_e32 v153, v66
	v_mov_b32_e32 v158, v66
	v_mov_b32_e32 v159, v66
	v_mov_b32_e32 v160, v66
	v_mov_b32_e32 v161, v66
	v_mov_b32_e32 v98, v66
	v_mov_b32_e32 v99, v66
	v_mov_b32_e32 v100, v66
	v_mov_b32_e32 v101, v66
	v_mov_b32_e32 v90, v66
	v_mov_b32_e32 v91, v66
	v_mov_b32_e32 v92, v66
	v_mov_b32_e32 v93, v66
	v_mov_b32_e32 v94, v66
	v_mov_b32_e32 v95, v66
	v_mov_b32_e32 v96, v66
	v_mov_b32_e32 v97, v66
	v_mov_b32_e32 v86, v66
	v_mov_b32_e32 v87, v66
	v_mov_b32_e32 v88, v66
	v_mov_b32_e32 v89, v66
	v_mov_b32_e32 v82, v66
	v_mov_b32_e32 v83, v66
	v_mov_b32_e32 v84, v66
	v_mov_b32_e32 v85, v66
	v_mov_b32_e32 v74, v66
	v_mov_b32_e32 v75, v66
	v_mov_b32_e32 v76, v66
	v_mov_b32_e32 v77, v66
	v_mov_b32_e32 v78, v66
	v_mov_b32_e32 v79, v66
	v_mov_b32_e32 v80, v66
	v_mov_b32_e32 v81, v66
	v_mov_b32_e32 v70, v66
	v_mov_b32_e32 v71, v66
	v_mov_b32_e32 v72, v66
	v_mov_b32_e32 v73, v66
	v_mov_b32_e32 v62, v66
	v_mov_b32_e32 v63, v66
	v_mov_b32_e32 v64, v66
	v_mov_b32_e32 v65, v66
	v_mov_b32_e32 v54, v66
	v_mov_b32_e32 v55, v66
	v_mov_b32_e32 v56, v66
	v_mov_b32_e32 v57, v66
	v_mov_b32_e32 v58, v66
	v_mov_b32_e32 v59, v66
	v_mov_b32_e32 v60, v66
	v_mov_b32_e32 v61, v66
	v_mov_b32_e32 v50, v66
	v_mov_b32_e32 v51, v66
	v_mov_b32_e32 v52, v66
	v_mov_b32_e32 v53, v66
	v_mov_b32_e32 v46, v66
	v_mov_b32_e32 v47, v66
	v_mov_b32_e32 v48, v66
	v_mov_b32_e32 v49, v66
	v_mov_b32_e32 v38, v66
	v_mov_b32_e32 v39, v66
	v_mov_b32_e32 v40, v66
	v_mov_b32_e32 v41, v66
	v_mov_b32_e32 v42, v66
	v_mov_b32_e32 v43, v66
	v_mov_b32_e32 v44, v66
	v_mov_b32_e32 v45, v66
	v_mov_b32_e32 v34, v66
	v_mov_b32_e32 v35, v66
	v_mov_b32_e32 v36, v66
	v_mov_b32_e32 v37, v66
	s_waitcnt vmcnt(0)
	s_branch .LBB0_1148

.LBB0_1148:
	ds_read_b128 v[178:181], v251
	ds_read_b128 v[182:185], v249
	ds_read_b128 v[186:189], v251 offset:4096
	ds_read_b128 v[190:193], v249 offset:4096
	ds_read_b128 v[162:165], v255
	ds_read_b128 v[166:169], v253
	s_cmp_eq_u32 s98, 0
	s_cbranch_scc1 .Lnodef_I0_2
	v_mfma_f32_16x16x32_bf16 v[62:65], v[194:197], v[170:173], v[62:65]
	v_mfma_f32_16x16x32_bf16 v[54:57], v[198:201], v[170:173], v[54:57]
	v_mfma_f32_16x16x32_bf16 v[58:61], v[202:205], v[170:173], v[58:61]
	v_mfma_f32_16x16x32_bf16 v[50:53], v[206:209], v[170:173], v[50:53]
	v_mfma_f32_16x16x32_bf16 v[46:49], v[194:197], v[174:177], v[46:49]
	v_mfma_f32_16x16x32_bf16 v[38:41], v[198:201], v[174:177], v[38:41]
	v_mfma_f32_16x16x32_bf16 v[42:45], v[202:205], v[174:177], v[42:45]
	v_mfma_f32_16x16x32_bf16 v[34:37], v[206:209], v[174:177], v[34:37]
.Lnodef_I0_2:
	ds_read_b128 v[170:173], v255 offset:4096
	ds_read_b128 v[174:177], v253 offset:4096
	s_add_i32 s2, s41, -1
	s_cmp_lt_i32 s2, s40
	s_cselect_b64 s[14:15], -1, 0
	s_cmp_ge_i32 s2, s40
	s_waitcnt lgkmcnt(3)
	v_mfma_f32_16x16x32_bf16 v[158:161], v[178:181], v[162:165], v[158:161]
	v_mfma_f32_16x16x32_bf16 v[150:153], v[182:185], v[162:165], v[150:153]
	v_mfma_f32_16x16x32_bf16 v[154:157], v[186:189], v[162:165], v[154:157]
	v_mfma_f32_16x16x32_bf16 v[146:149], v[190:193], v[162:165], v[146:149]
	ds_read_b128 v[162:165], v255 offset:8192
	s_waitcnt lgkmcnt(3)
	v_mfma_f32_16x16x32_bf16 v[142:145], v[178:181], v[166:169], v[142:145]
	v_mfma_f32_16x16x32_bf16 v[134:137], v[182:185], v[166:169], v[134:137]
	v_mfma_f32_16x16x32_bf16 v[138:141], v[186:189], v[166:169], v[138:141]
	v_mfma_f32_16x16x32_bf16 v[130:133], v[190:193], v[166:169], v[130:133]
	ds_read_b128 v[166:169], v253 offset:8192
	s_waitcnt lgkmcnt(3)
	v_mfma_f32_16x16x32_bf16 v[126:129], v[178:181], v[170:173], v[126:129]
	v_mfma_f32_16x16x32_bf16 v[118:121], v[182:185], v[170:173], v[118:121]
	v_mfma_f32_16x16x32_bf16 v[122:125], v[186:189], v[170:173], v[122:125]
	v_mfma_f32_16x16x32_bf16 v[114:117], v[190:193], v[170:173], v[114:117]
	s_waitcnt vmcnt(6)
	ds_write_b128 v235, v[30:33]
	ds_write_b128 v235, v[26:29] offset:8192
.LBB0_1150:
	s_lshl_b32 s2, s48, 8
	s_ashr_i32 s3, s2, 31
	s_lshl_b64 s[12:13], s[2:3], 11
	s_lshl_b32 s2, s22, 6
	s_ashr_i32 s3, s2, 31
	s_add_u32 s20, s11, s12
	s_addc_u32 s21, s24, s13
	s_lshl_b64 s[8:9], s[2:3], 1
	s_add_u32 s20, s20, s8
	s_addc_u32 s21, s21, s9
	global_load_dwordx4 v[30:33], v233, s[20:21]
	global_load_dwordx4 v[26:29], v234, s[20:21]
	s_andn2_b64 vcc, exec, s[14:15]
	ds_read_b128 v[170:173], v255 offset:12288
	s_waitcnt lgkmcnt(5)
	v_mfma_f32_16x16x32_bf16 v[110:113], v[178:181], v[174:177], v[110:113]
	v_mfma_f32_16x16x32_bf16 v[102:105], v[182:185], v[174:177], v[102:105]
	v_mfma_f32_16x16x32_bf16 v[106:109], v[186:189], v[174:177], v[106:109]
	v_mfma_f32_16x16x32_bf16 v[66:69], v[190:193], v[174:177], v[66:69]
	ds_read_b128 v[174:177], v253 offset:12288
	s_waitcnt lgkmcnt(5)
	v_mfma_f32_16x16x32_bf16 v[98:101], v[178:181], v[162:165], v[98:101]
	v_mfma_f32_16x16x32_bf16 v[90:93], v[182:185], v[162:165], v[90:93]
	v_mfma_f32_16x16x32_bf16 v[94:97], v[186:189], v[162:165], v[94:97]
	v_mfma_f32_16x16x32_bf16 v[86:89], v[190:193], v[162:165], v[86:89]
	s_waitcnt lgkmcnt(4)
	v_mfma_f32_16x16x32_bf16 v[82:85], v[178:181], v[166:169], v[82:85]
	v_mfma_f32_16x16x32_bf16 v[74:77], v[182:185], v[166:169], v[74:77]
	v_mfma_f32_16x16x32_bf16 v[78:81], v[186:189], v[166:169], v[78:81]
	v_mfma_f32_16x16x32_bf16 v[70:73], v[190:193], v[166:169], v[70:73]
	s_waitcnt vmcnt(6)
	ds_write_b128 v235, v[22:25] offset:16384
	ds_write_b128 v235, v[18:21] offset:24576
.LBB0_1152:
	global_load_dwordx4 v[18:21], v232, s[20:21]
	global_load_dwordx4 v[22:25], v231, s[20:21]
	s_and_b64 vcc, exec, s[2:3]
	ds_read_b128 v[194:197], v243
	ds_read_b128 v[198:201], v241
	ds_read_b128 v[202:205], v243 offset:4096
	ds_read_b128 v[206:209], v241 offset:4096
	ds_read_b128 v[162:165], v247
	ds_read_b128 v[166:169], v245
	s_waitcnt lgkmcnt(9)
	v_mfma_f32_16x16x32_bf16 v[62:65], v[178:181], v[170:173], v[62:65]
	v_mfma_f32_16x16x32_bf16 v[54:57], v[182:185], v[170:173], v[54:57]
	v_mfma_f32_16x16x32_bf16 v[58:61], v[186:189], v[170:173], v[58:61]
	v_mfma_f32_16x16x32_bf16 v[50:53], v[190:193], v[170:173], v[50:53]
	ds_read_b128 v[170:173], v247 offset:4096
	s_waitcnt lgkmcnt(9)
	v_mfma_f32_16x16x32_bf16 v[46:49], v[178:181], v[174:177], v[46:49]
	v_mfma_f32_16x16x32_bf16 v[38:41], v[182:185], v[174:177], v[38:41]
	v_mfma_f32_16x16x32_bf16 v[42:45], v[186:189], v[174:177], v[42:45]
	v_mfma_f32_16x16x32_bf16 v[34:37], v[190:193], v[174:177], v[34:37]
	s_waitcnt vmcnt(6)
	ds_write_b128 v235, v[14:17] offset:32768
	ds_write_b128 v235, v[10:13] offset:40960
.LBB0_1154:
	s_lshl_b32 s14, s47, 8
	s_ashr_i32 s15, s14, 31
	s_lshl_b64 s[14:15], s[14:15], 11
	s_add_u32 s20, s25, s14
	s_addc_u32 s21, s26, s15
	s_add_u32 s8, s20, s8
	s_addc_u32 s9, s21, s9
	global_load_dwordx4 v[10:13], v234, s[8:9]
	global_load_dwordx4 v[14:17], v233, s[8:9]
	s_and_b64 vcc, exec, s[2:3]
	ds_read_b128 v[174:177], v245 offset:4096
	s_waitcnt lgkmcnt(5)
	v_mfma_f32_16x16x32_bf16 v[158:161], v[194:197], v[162:165], v[158:161]
	v_mfma_f32_16x16x32_bf16 v[150:153], v[198:201], v[162:165], v[150:153]
	v_mfma_f32_16x16x32_bf16 v[154:157], v[202:205], v[162:165], v[154:157]
	v_mfma_f32_16x16x32_bf16 v[146:149], v[206:209], v[162:165], v[146:149]
	ds_read_b128 v[162:165], v247 offset:8192
	s_waitcnt lgkmcnt(5)
	v_mfma_f32_16x16x32_bf16 v[142:145], v[194:197], v[166:169], v[142:145]
	v_mfma_f32_16x16x32_bf16 v[134:137], v[198:201], v[166:169], v[134:137]
	v_mfma_f32_16x16x32_bf16 v[138:141], v[202:205], v[166:169], v[138:141]
	v_mfma_f32_16x16x32_bf16 v[130:133], v[206:209], v[166:169], v[130:133]
	ds_read_b128 v[166:169], v245 offset:8192
	s_waitcnt lgkmcnt(5)
	v_mfma_f32_16x16x32_bf16 v[126:129], v[194:197], v[170:173], v[126:129]
	v_mfma_f32_16x16x32_bf16 v[118:121], v[198:201], v[170:173], v[118:121]
	v_mfma_f32_16x16x32_bf16 v[122:125], v[202:205], v[170:173], v[122:125]
	v_mfma_f32_16x16x32_bf16 v[114:117], v[206:209], v[170:173], v[114:117]
	s_waitcnt vmcnt(6)
	ds_write_b128 v235, v[6:9] offset:49152
	ds_write_b128 v235, v[2:5] offset:57344
.LBB0_1156:
	global_load_dwordx4 v[2:5], v232, s[8:9]
	global_load_dwordx4 v[6:9], v231, s[8:9]
	ds_read_b128 v[170:173], v247 offset:12288
	s_waitcnt lgkmcnt(5)
	v_mfma_f32_16x16x32_bf16 v[110:113], v[194:197], v[174:177], v[110:113]
	v_mfma_f32_16x16x32_bf16 v[102:105], v[198:201], v[174:177], v[102:105]
	v_mfma_f32_16x16x32_bf16 v[106:109], v[202:205], v[174:177], v[106:109]
	v_mfma_f32_16x16x32_bf16 v[66:69], v[206:209], v[174:177], v[66:69]
	ds_read_b128 v[174:177], v245 offset:12288
	s_waitcnt lgkmcnt(5)
	v_mfma_f32_16x16x32_bf16 v[98:101], v[194:197], v[162:165], v[98:101]
	v_mfma_f32_16x16x32_bf16 v[90:93], v[198:201], v[162:165], v[90:93]
	v_mfma_f32_16x16x32_bf16 v[94:97], v[202:205], v[162:165], v[94:97]
	v_mfma_f32_16x16x32_bf16 v[86:89], v[206:209], v[162:165], v[86:89]
	s_waitcnt lgkmcnt(4)
	v_mfma_f32_16x16x32_bf16 v[82:85], v[194:197], v[166:169], v[82:85]
	v_mfma_f32_16x16x32_bf16 v[74:77], v[198:201], v[166:169], v[74:77]
	v_mfma_f32_16x16x32_bf16 v[78:81], v[202:205], v[166:169], v[78:81]
	v_mfma_f32_16x16x32_bf16 v[70:73], v[206:209], v[166:169], v[70:73]
	s_add_i32 s50, s22, 1
	s_cmp_lg_u32 s50, 16
	s_cbranch_scc1 .LBB0_1164
	s_add_i32 s31, s31, s28
	s_cmp_ge_i32 s31, s33
	s_cbranch_scc1 .LBB0_1163
	s_mov_b32 s8, s10
	s_cmpk_gt_i32 s31, 0x9f
	s_mov_b64 s[2:3], -1
	s_cbranch_scc0 .LBB0_1160
	s_lshl_b32 s2, s31, 2
	s_add_i32 s2, s2, 0x7ffffd80
	s_and_b32 s9, s2, 0x7ffffff8
	s_and_b32 s2, s31, 1
	s_or_b32 s47, s2, 20
	s_mov_b64 s[2:3], 0

.LBB0_1164:
	s_waitcnt lgkmcnt(0)
	s_barrier
	ds_read_b128 v[178:181], v250
	ds_read_b128 v[182:185], v248
	ds_read_b128 v[186:189], v250 offset:4096
	ds_read_b128 v[190:193], v248 offset:4096
	ds_read_b128 v[162:165], v254
	ds_read_b128 v[166:169], v252
	v_mfma_f32_16x16x32_bf16 v[62:65], v[194:197], v[170:173], v[62:65]
	v_mfma_f32_16x16x32_bf16 v[54:57], v[198:201], v[170:173], v[54:57]
	v_mfma_f32_16x16x32_bf16 v[58:61], v[202:205], v[170:173], v[58:61]
	v_mfma_f32_16x16x32_bf16 v[50:53], v[206:209], v[170:173], v[50:53]
	v_mfma_f32_16x16x32_bf16 v[46:49], v[194:197], v[174:177], v[46:49]
	v_mfma_f32_16x16x32_bf16 v[38:41], v[198:201], v[174:177], v[38:41]
	v_mfma_f32_16x16x32_bf16 v[42:45], v[202:205], v[174:177], v[42:45]
	v_mfma_f32_16x16x32_bf16 v[34:37], v[206:209], v[174:177], v[34:37]
	ds_read_b128 v[170:173], v254 offset:4096
	ds_read_b128 v[174:177], v252 offset:4096
	s_cmp_lt_i32 s41, s40
	s_cselect_b64 s[20:21], -1, 0
	s_cmp_ge_i32 s41, s40
	s_cselect_b64 s[8:9], -1, 0
	s_and_b64 vcc, exec, s[8:9]
	s_waitcnt lgkmcnt(3)
	v_mfma_f32_16x16x32_bf16 v[158:161], v[178:181], v[162:165], v[158:161]
	v_mfma_f32_16x16x32_bf16 v[150:153], v[182:185], v[162:165], v[150:153]
	v_mfma_f32_16x16x32_bf16 v[154:157], v[186:189], v[162:165], v[154:157]
	v_mfma_f32_16x16x32_bf16 v[146:149], v[190:193], v[162:165], v[146:149]
	ds_read_b128 v[162:165], v254 offset:8192
	s_waitcnt lgkmcnt(3)
	v_mfma_f32_16x16x32_bf16 v[142:145], v[178:181], v[166:169], v[142:145]
	v_mfma_f32_16x16x32_bf16 v[134:137], v[182:185], v[166:169], v[134:137]
	v_mfma_f32_16x16x32_bf16 v[138:141], v[186:189], v[166:169], v[138:141]
	v_mfma_f32_16x16x32_bf16 v[130:133], v[190:193], v[166:169], v[130:133]
	ds_read_b128 v[166:169], v252 offset:8192
	s_waitcnt lgkmcnt(3)
	v_mfma_f32_16x16x32_bf16 v[126:129], v[178:181], v[170:173], v[126:129]
	v_mfma_f32_16x16x32_bf16 v[118:121], v[182:185], v[170:173], v[118:121]
	v_mfma_f32_16x16x32_bf16 v[122:125], v[186:189], v[170:173], v[122:125]
	v_mfma_f32_16x16x32_bf16 v[114:117], v[190:193], v[170:173], v[114:117]
	s_waitcnt vmcnt(6)
	ds_write_b128 v236, v[26:29]
	ds_write_b128 v236, v[30:33] offset:8192
.LBB0_1166:
	s_lshl_b32 s2, s50, 6
	s_ashr_i32 s3, s2, 31
	s_add_u32 s22, s11, s12
	s_addc_u32 s23, s24, s13
	s_lshl_b64 s[12:13], s[2:3], 1
	s_add_u32 s22, s22, s12
	s_addc_u32 s23, s23, s13
	global_load_dwordx4 v[30:33], v234, s[22:23]
	global_load_dwordx4 v[26:29], v233, s[22:23]
	s_andn2_b64 vcc, exec, s[20:21]
	ds_read_b128 v[170:173], v254 offset:12288
	s_waitcnt lgkmcnt(5)
	v_mfma_f32_16x16x32_bf16 v[110:113], v[178:181], v[174:177], v[110:113]
	v_mfma_f32_16x16x32_bf16 v[102:105], v[182:185], v[174:177], v[102:105]
	v_mfma_f32_16x16x32_bf16 v[106:109], v[186:189], v[174:177], v[106:109]
	v_mfma_f32_16x16x32_bf16 v[66:69], v[190:193], v[174:177], v[66:69]
	ds_read_b128 v[174:177], v252 offset:12288
	s_waitcnt lgkmcnt(5)
	v_mfma_f32_16x16x32_bf16 v[98:101], v[178:181], v[162:165], v[98:101]
	v_mfma_f32_16x16x32_bf16 v[90:93], v[182:185], v[162:165], v[90:93]
	v_mfma_f32_16x16x32_bf16 v[94:97], v[186:189], v[162:165], v[94:97]
	v_mfma_f32_16x16x32_bf16 v[86:89], v[190:193], v[162:165], v[86:89]
	s_waitcnt lgkmcnt(4)
	v_mfma_f32_16x16x32_bf16 v[82:85], v[178:181], v[166:169], v[82:85]
	v_mfma_f32_16x16x32_bf16 v[74:77], v[182:185], v[166:169], v[74:77]
	v_mfma_f32_16x16x32_bf16 v[78:81], v[186:189], v[166:169], v[78:81]
	v_mfma_f32_16x16x32_bf16 v[70:73], v[190:193], v[166:169], v[70:73]
	s_waitcnt vmcnt(6)
	ds_write_b128 v236, v[18:21] offset:16384
	ds_write_b128 v236, v[22:25] offset:24576
.LBB0_1168:
	global_load_dwordx4 v[22:25], v232, s[22:23]
	global_load_dwordx4 v[18:21], v231, s[22:23]
	s_and_b64 vcc, exec, s[2:3]
	ds_read_b128 v[194:197], v242
	ds_read_b128 v[198:201], v237
	ds_read_b128 v[202:205], v242 offset:4096
	ds_read_b128 v[206:209], v237 offset:4096
	ds_read_b128 v[162:165], v246
	ds_read_b128 v[166:169], v244
	s_waitcnt lgkmcnt(9)
	v_mfma_f32_16x16x32_bf16 v[62:65], v[178:181], v[170:173], v[62:65]
	v_mfma_f32_16x16x32_bf16 v[54:57], v[182:185], v[170:173], v[54:57]
	v_mfma_f32_16x16x32_bf16 v[58:61], v[186:189], v[170:173], v[58:61]
	v_mfma_f32_16x16x32_bf16 v[50:53], v[190:193], v[170:173], v[50:53]
	ds_read_b128 v[170:173], v246 offset:4096
	s_waitcnt lgkmcnt(9)
	v_mfma_f32_16x16x32_bf16 v[46:49], v[178:181], v[174:177], v[46:49]
	v_mfma_f32_16x16x32_bf16 v[38:41], v[182:185], v[174:177], v[38:41]
	v_mfma_f32_16x16x32_bf16 v[42:45], v[186:189], v[174:177], v[42:45]
	v_mfma_f32_16x16x32_bf16 v[34:37], v[190:193], v[174:177], v[34:37]
	s_waitcnt vmcnt(6)
	ds_write_b128 v236, v[10:13] offset:32768
	ds_write_b128 v236, v[14:17] offset:40960
.LBB0_1170:
	s_add_u32 s14, s25, s14
	s_addc_u32 s15, s26, s15
	s_add_u32 s12, s14, s12
	s_addc_u32 s13, s15, s13
	global_load_dwordx4 v[14:17], v234, s[12:13]
	global_load_dwordx4 v[10:13], v233, s[12:13]
	s_and_b64 vcc, exec, s[2:3]
	ds_read_b128 v[174:177], v244 offset:4096
	s_waitcnt lgkmcnt(5)
	v_mfma_f32_16x16x32_bf16 v[158:161], v[194:197], v[162:165], v[158:161]
	v_mfma_f32_16x16x32_bf16 v[150:153], v[198:201], v[162:165], v[150:153]
	v_mfma_f32_16x16x32_bf16 v[154:157], v[202:205], v[162:165], v[154:157]
	v_mfma_f32_16x16x32_bf16 v[146:149], v[206:209], v[162:165], v[146:149]
	ds_read_b128 v[162:165], v246 offset:8192
	s_waitcnt lgkmcnt(5)
	v_mfma_f32_16x16x32_bf16 v[142:145], v[194:197], v[166:169], v[142:145]
	v_mfma_f32_16x16x32_bf16 v[134:137], v[198:201], v[166:169], v[134:137]
	v_mfma_f32_16x16x32_bf16 v[138:141], v[202:205], v[166:169], v[138:141]
	v_mfma_f32_16x16x32_bf16 v[130:133], v[206:209], v[166:169], v[130:133]
	ds_read_b128 v[166:169], v244 offset:8192
	s_waitcnt lgkmcnt(5)
	v_mfma_f32_16x16x32_bf16 v[126:129], v[194:197], v[170:173], v[126:129]
	v_mfma_f32_16x16x32_bf16 v[118:121], v[198:201], v[170:173], v[118:121]
	v_mfma_f32_16x16x32_bf16 v[122:125], v[202:205], v[170:173], v[122:125]
	v_mfma_f32_16x16x32_bf16 v[114:117], v[206:209], v[170:173], v[114:117]
	s_waitcnt vmcnt(6)
	ds_write_b128 v236, v[2:5] offset:49152
	ds_write_b128 v236, v[6:9] offset:57344
.LBB0_1172:
	global_load_dwordx4 v[6:9], v232, s[12:13]
	global_load_dwordx4 v[2:5], v231, s[12:13]
	ds_read_b128 v[170:173], v246 offset:12288
	s_waitcnt lgkmcnt(5)
	v_mfma_f32_16x16x32_bf16 v[110:113], v[194:197], v[174:177], v[110:113]
	v_mfma_f32_16x16x32_bf16 v[102:105], v[198:201], v[174:177], v[102:105]
	v_mfma_f32_16x16x32_bf16 v[106:109], v[202:205], v[174:177], v[106:109]
	v_mfma_f32_16x16x32_bf16 v[66:69], v[206:209], v[174:177], v[66:69]
	ds_read_b128 v[174:177], v244 offset:12288
	s_waitcnt lgkmcnt(5)
	v_mfma_f32_16x16x32_bf16 v[98:101], v[194:197], v[162:165], v[98:101]
	v_mfma_f32_16x16x32_bf16 v[90:93], v[198:201], v[162:165], v[90:93]
	v_mfma_f32_16x16x32_bf16 v[94:97], v[202:205], v[162:165], v[94:97]
	v_mfma_f32_16x16x32_bf16 v[86:89], v[206:209], v[162:165], v[86:89]
	s_waitcnt lgkmcnt(4)
	v_mfma_f32_16x16x32_bf16 v[82:85], v[194:197], v[166:169], v[82:85]
	v_mfma_f32_16x16x32_bf16 v[74:77], v[198:201], v[166:169], v[74:77]
	v_mfma_f32_16x16x32_bf16 v[78:81], v[202:205], v[166:169], v[78:81]
	v_mfma_f32_16x16x32_bf16 v[70:73], v[206:209], v[166:169], v[70:73]
	s_add_i32 s22, s50, 1
	s_cmp_lg_u32 s22, 16
	s_cbranch_scc1 .LBB0_1180
	s_add_i32 s31, s31, s28
	s_cmp_ge_i32 s31, s33
	s_cbranch_scc1 .LBB0_1179
	s_mov_b32 s12, s10
	s_cmpk_gt_i32 s31, 0x9f
	s_mov_b64 s[2:3], -1
	s_cbranch_scc0 .LBB0_1176
	s_lshl_b32 s2, s31, 2
	s_add_i32 s2, s2, 0x7ffffd80
	s_and_b32 s13, s2, 0x7ffffff8
	s_and_b32 s2, s31, 1
	s_or_b32 s47, s2, 20
	s_mov_b64 s[2:3], 0

.LBB0_1180:
	s_add_i32 s49, s49, 2
	s_cmp_lg_u32 s49, 16
	s_waitcnt lgkmcnt(0)
	s_mov_b32 s98, 1
	s_cbranch_scc1 .LBB0_1147
	s_mov_b32 s98, 0
	v_mfma_f32_16x16x32_bf16 v[62:65], v[194:197], v[170:173], v[62:65]
	v_mfma_f32_16x16x32_bf16 v[54:57], v[198:201], v[170:173], v[54:57]
	v_mfma_f32_16x16x32_bf16 v[58:61], v[202:205], v[170:173], v[58:61]
	v_mfma_f32_16x16x32_bf16 v[50:53], v[206:209], v[170:173], v[50:53]
	v_mfma_f32_16x16x32_bf16 v[46:49], v[194:197], v[174:177], v[46:49]
	v_mfma_f32_16x16x32_bf16 v[38:41], v[198:201], v[174:177], v[38:41]
	v_mfma_f32_16x16x32_bf16 v[42:45], v[202:205], v[174:177], v[42:45]
	v_mfma_f32_16x16x32_bf16 v[34:37], v[206:209], v[174:177], v[34:37]
	s_nop 7
	s_nop 7
	v_mul_f32_e32 v165, 0xbfb8aa3b, v158
	v_exp_f32_e32 v165, v165
	v_mov_b32_e32 v163, v0
	v_mul_f32_e32 v166, 0xbfb8aa3b, v159
	v_add_f32_e32 v165, 1.0, v165
	v_rcp_f32_e32 v165, v165
	v_ashrrev_i32_e32 v162, 1, v163
	v_exp_f32_e32 v166, v166
	v_and_b32_e32 v164, 0xc0, v163
	v_and_b32_e32 v162, 0xffffff80, v162
	v_lshl_add_u32 v162, s38, 8, v162
	v_lshl_or_b32 v164, s34, 8, v164
	v_and_or_b32 v162, v163, 15, v162
	v_ashrrev_i32_e32 v164, 1, v164
	v_lshrrev_b32_e32 v163, 2, v163
	v_mul_f32_e32 v158, v158, v165
	v_and_or_b32 v164, v163, 12, v164
	v_mul_f32_e32 v154, v154, v158
	v_add_f32_e32 v158, 1.0, v166
	v_mul_f32_e32 v163, 0xbfb8aa3b, v160
	v_rcp_f32_e32 v158, v158
	v_exp_f32_e32 v163, v163
	v_mul_f32_e32 v165, 0xbfb8aa3b, v161
	v_exp_f32_e32 v165, v165
	v_mul_f32_e32 v158, v159, v158
	v_add_f32_e32 v159, 1.0, v163
	v_rcp_f32_e32 v159, v159
	v_add_f32_e32 v163, 1.0, v165
	v_rcp_f32_e32 v163, v163
	v_mul_f32_e32 v155, v155, v158
	v_mul_f32_e32 v158, v160, v159
	v_mul_f32_e32 v156, v156, v158
	v_mul_f32_e32 v158, v161, v163
	v_mul_f32_e32 v157, v157, v158
	v_cvt_pk_bf16_f32 v159, v156, v157
	v_mul_f32_e32 v156, 0xbfb8aa3b, v150
	v_exp_f32_e32 v163, v156
	v_ashrrev_i32_e32 v165, 31, v164
	v_lshlrev_b64 v[156:157], 1, v[164:165]
	v_mul_f32_e32 v164, 0xbfb8aa3b, v151
	v_add_f32_e32 v163, 1.0, v163
	v_rcp_f32_e32 v163, v163
	v_exp_f32_e32 v164, v164
	v_cvt_pk_bf16_f32 v158, v154, v155
	v_mov_b64_e32 v[154:155], s[6:7]
	v_mad_i64_i32 v[160:161], s[2:3], v162, s45, v[154:155]
	v_lshl_add_u64 v[160:161], v[160:161], 0, v[156:157]
	v_mul_f32_e32 v150, v150, v163
	global_store_dwordx2 v[160:161], v[158:159], off
	v_mul_f32_e32 v146, v146, v150
	v_add_f32_e32 v150, 1.0, v164
	v_mul_f32_e32 v158, 0xbfb8aa3b, v152
	v_rcp_f32_e32 v150, v150
	v_exp_f32_e32 v158, v158
	v_mul_f32_e32 v159, 0xbfb8aa3b, v153
	v_exp_f32_e32 v159, v159
	v_mul_f32_e32 v150, v151, v150
	v_add_f32_e32 v151, 1.0, v158
	v_rcp_f32_e32 v151, v151
	v_add_f32_e32 v158, 1.0, v159
	v_rcp_f32_e32 v158, v158
	v_mul_f32_e32 v147, v147, v150
	v_mul_f32_e32 v150, v152, v151
	v_mul_f32_e32 v148, v148, v150
	v_mul_f32_e32 v150, v153, v158
	v_mul_f32_e32 v149, v149, v150
	v_mul_f32_e32 v150, 0xbfb8aa3b, v142
	v_exp_f32_e32 v150, v150
	v_cvt_pk_bf16_f32 v146, v146, v147
	v_cvt_pk_bf16_f32 v147, v148, v149
	global_store_dwordx2 v[160:161], v[146:147], off offset:32
	v_add_f32_e32 v146, 1.0, v150
	v_rcp_f32_e32 v146, v146
	v_mul_f32_e32 v147, 0xbfb8aa3b, v143
	v_exp_f32_e32 v147, v147
	v_or_b32_e32 v148, 16, v162
	v_mul_f32_e32 v142, v142, v146
	v_mul_f32_e32 v138, v138, v142
	v_add_f32_e32 v142, 1.0, v147
	v_mul_f32_e32 v146, 0xbfb8aa3b, v144
	v_rcp_f32_e32 v142, v142
	v_exp_f32_e32 v146, v146
	v_mul_f32_e32 v147, 0xbfb8aa3b, v145
	v_exp_f32_e32 v147, v147
	v_mul_f32_e32 v142, v143, v142
	v_add_f32_e32 v143, 1.0, v146
	v_rcp_f32_e32 v143, v143
	v_add_f32_e32 v146, 1.0, v147
	v_rcp_f32_e32 v146, v146
	v_mul_f32_e32 v139, v139, v142
	v_mul_f32_e32 v142, v144, v143
	v_mul_f32_e32 v140, v140, v142
	v_mul_f32_e32 v142, v145, v146
	v_mul_f32_e32 v141, v141, v142
	v_cvt_pk_bf16_f32 v138, v138, v139
	v_cvt_pk_bf16_f32 v139, v140, v141
	v_mul_f32_e32 v140, 0xbfb8aa3b, v134
	v_exp_f32_e32 v142, v140
	v_mul_f32_e32 v143, 0xbfb8aa3b, v135
	v_exp_f32_e32 v143, v143
	v_mad_i64_i32 v[140:141], s[2:3], v148, s45, v[154:155]
	v_add_f32_e32 v142, 1.0, v142
	v_rcp_f32_e32 v142, v142
	v_lshl_add_u64 v[140:141], v[140:141], 0, v[156:157]
	global_store_dwordx2 v[140:141], v[138:139], off
	v_mul_f32_e32 v138, 0xbfb8aa3b, v136
	v_mul_f32_e32 v134, v134, v142
	v_mul_f32_e32 v130, v130, v134
	v_add_f32_e32 v134, 1.0, v143
	v_rcp_f32_e32 v134, v134
	v_exp_f32_e32 v138, v138
	v_mul_f32_e32 v139, 0xbfb8aa3b, v137
	v_exp_f32_e32 v139, v139
	v_mul_f32_e32 v134, v135, v134
	v_add_f32_e32 v135, 1.0, v138
	v_rcp_f32_e32 v135, v135
	v_add_f32_e32 v138, 1.0, v139
	v_rcp_f32_e32 v138, v138
	v_mul_f32_e32 v131, v131, v134
	v_mul_f32_e32 v134, v136, v135
	v_mul_f32_e32 v132, v132, v134
	v_mul_f32_e32 v134, v137, v138
	v_mul_f32_e32 v133, v133, v134
	v_mul_f32_e32 v134, 0xbfb8aa3b, v126
	v_exp_f32_e32 v134, v134
	v_cvt_pk_bf16_f32 v130, v130, v131
	v_cvt_pk_bf16_f32 v131, v132, v133
	global_store_dwordx2 v[140:141], v[130:131], off offset:32
	v_add_f32_e32 v130, 1.0, v134
	v_rcp_f32_e32 v130, v130
	v_mul_f32_e32 v131, 0xbfb8aa3b, v127
	v_exp_f32_e32 v131, v131
	v_or_b32_e32 v132, 32, v162
	v_mul_f32_e32 v126, v126, v130
	v_mul_f32_e32 v122, v122, v126
	v_add_f32_e32 v126, 1.0, v131
	v_mul_f32_e32 v130, 0xbfb8aa3b, v128
	v_rcp_f32_e32 v126, v126
	v_exp_f32_e32 v130, v130
	v_mul_f32_e32 v131, 0xbfb8aa3b, v129
	v_exp_f32_e32 v131, v131
	v_mul_f32_e32 v126, v127, v126
	v_add_f32_e32 v127, 1.0, v130
	v_rcp_f32_e32 v127, v127
	v_add_f32_e32 v130, 1.0, v131
	v_rcp_f32_e32 v130, v130
	v_mul_f32_e32 v123, v123, v126
	v_mul_f32_e32 v126, v128, v127
	v_mul_f32_e32 v124, v124, v126
	v_mul_f32_e32 v126, v129, v130
	v_mul_f32_e32 v125, v125, v126
	v_cvt_pk_bf16_f32 v122, v122, v123
	v_cvt_pk_bf16_f32 v123, v124, v125
	v_mul_f32_e32 v124, 0xbfb8aa3b, v118
	v_exp_f32_e32 v126, v124
	v_mul_f32_e32 v127, 0xbfb8aa3b, v119
	v_exp_f32_e32 v127, v127
	v_mad_i64_i32 v[124:125], s[2:3], v132, s45, v[154:155]
	v_add_f32_e32 v126, 1.0, v126
	v_rcp_f32_e32 v126, v126
	v_lshl_add_u64 v[124:125], v[124:125], 0, v[156:157]
	global_store_dwordx2 v[124:125], v[122:123], off
	v_mul_f32_e32 v122, 0xbfb8aa3b, v120
	v_mul_f32_e32 v118, v118, v126
	v_mul_f32_e32 v114, v114, v118
	v_add_f32_e32 v118, 1.0, v127
	v_rcp_f32_e32 v118, v118
	v_exp_f32_e32 v122, v122
	v_mul_f32_e32 v123, 0xbfb8aa3b, v121
	v_exp_f32_e32 v123, v123
	v_mul_f32_e32 v118, v119, v118
	v_add_f32_e32 v119, 1.0, v122
	v_rcp_f32_e32 v119, v119
	v_add_f32_e32 v122, 1.0, v123
	v_rcp_f32_e32 v122, v122
	v_mul_f32_e32 v115, v115, v118
	v_mul_f32_e32 v118, v120, v119
	v_mul_f32_e32 v116, v116, v118
	v_mul_f32_e32 v118, v121, v122
	v_mul_f32_e32 v117, v117, v118
	v_mul_f32_e32 v118, 0xbfb8aa3b, v110
	v_exp_f32_e32 v118, v118
	v_cvt_pk_bf16_f32 v114, v114, v115
	v_cvt_pk_bf16_f32 v115, v116, v117
	global_store_dwordx2 v[124:125], v[114:115], off offset:32
	v_add_f32_e32 v114, 1.0, v118
	v_rcp_f32_e32 v114, v114
	v_mul_f32_e32 v115, 0xbfb8aa3b, v111
	v_exp_f32_e32 v115, v115
	v_or_b32_e32 v116, 48, v162
	v_mul_f32_e32 v110, v110, v114
	v_mul_f32_e32 v106, v106, v110
	v_add_f32_e32 v110, 1.0, v115
	v_mul_f32_e32 v114, 0xbfb8aa3b, v112
	v_rcp_f32_e32 v110, v110
	v_exp_f32_e32 v114, v114
	v_mul_f32_e32 v115, 0xbfb8aa3b, v113
	v_exp_f32_e32 v115, v115
	v_mul_f32_e32 v110, v111, v110
	v_add_f32_e32 v111, 1.0, v114
	v_rcp_f32_e32 v111, v111
	v_add_f32_e32 v114, 1.0, v115
	v_rcp_f32_e32 v114, v114
	v_mul_f32_e32 v107, v107, v110
	v_mul_f32_e32 v110, v112, v111
	v_mul_f32_e32 v108, v108, v110
	v_mul_f32_e32 v110, v113, v114
	v_mul_f32_e32 v109, v109, v110
	v_cvt_pk_bf16_f32 v106, v106, v107
	v_cvt_pk_bf16_f32 v107, v108, v109
	v_mul_f32_e32 v108, 0xbfb8aa3b, v102
	v_exp_f32_e32 v110, v108
	v_mul_f32_e32 v111, 0xbfb8aa3b, v103
	v_exp_f32_e32 v111, v111
	v_mad_i64_i32 v[108:109], s[2:3], v116, s45, v[154:155]
	v_add_f32_e32 v110, 1.0, v110
	v_rcp_f32_e32 v110, v110
	v_lshl_add_u64 v[108:109], v[108:109], 0, v[156:157]
	global_store_dwordx2 v[108:109], v[106:107], off
	v_mul_f32_e32 v106, 0xbfb8aa3b, v104
	v_mul_f32_e32 v102, v102, v110
	v_mul_f32_e32 v66, v66, v102
	v_add_f32_e32 v102, 1.0, v111
	v_rcp_f32_e32 v102, v102
	v_exp_f32_e32 v106, v106
	v_mul_f32_e32 v107, 0xbfb8aa3b, v105
	v_exp_f32_e32 v107, v107
	v_mul_f32_e32 v102, v103, v102
	v_add_f32_e32 v103, 1.0, v106
	v_rcp_f32_e32 v103, v103
	v_add_f32_e32 v106, 1.0, v107
	v_rcp_f32_e32 v106, v106
	v_mul_f32_e32 v67, v67, v102
	v_mul_f32_e32 v102, v104, v103
	v_mul_f32_e32 v68, v68, v102
	v_mul_f32_e32 v102, v105, v106
	v_mul_f32_e32 v69, v69, v102
	v_mul_f32_e32 v102, 0xbfb8aa3b, v98
	v_exp_f32_e32 v102, v102
	v_cvt_pk_bf16_f32 v66, v66, v67
	v_cvt_pk_bf16_f32 v67, v68, v69
	global_store_dwordx2 v[108:109], v[66:67], off offset:32
	v_add_f32_e32 v66, 1.0, v102
	v_rcp_f32_e32 v66, v66
	v_mul_f32_e32 v67, 0xbfb8aa3b, v99
	v_mul_f32_e32 v69, 0xbfb8aa3b, v100
	v_exp_f32_e32 v67, v67
	v_mul_f32_e32 v66, v98, v66
	v_mul_f32_e32 v66, v94, v66
	v_exp_f32_e32 v69, v69
	v_mul_f32_e32 v94, 0xbfb8aa3b, v101
	v_exp_f32_e32 v94, v94
	v_add_f32_e32 v67, 1.0, v67
	v_add_f32_e32 v69, 1.0, v69
	v_rcp_f32_e32 v67, v67
	v_rcp_f32_e32 v69, v69
	v_add_f32_e32 v94, 1.0, v94
	v_rcp_f32_e32 v94, v94
	v_mul_f32_e32 v67, v99, v67
	v_mul_f32_e32 v69, v100, v69
	v_mul_f32_e32 v67, v95, v67
	v_mul_f32_e32 v69, v96, v69
	v_mul_f32_e32 v94, v101, v94
	v_mul_f32_e32 v94, v97, v94
	v_cvt_pk_bf16_f32 v66, v66, v67
	v_cvt_pk_bf16_f32 v67, v69, v94
	v_mul_f32_e32 v69, 0xbfb8aa3b, v90
	v_exp_f32_e32 v94, v69
	v_or_b32_e32 v68, 64, v162
	v_mad_i64_i32 v[68:69], s[2:3], v68, s45, v[154:155]
	v_add_f32_e32 v94, 1.0, v94
	v_rcp_f32_e32 v94, v94
	v_lshl_add_u64 v[68:69], v[68:69], 0, v[156:157]
	global_store_dwordx2 v[68:69], v[66:67], off
	v_mul_f32_e32 v95, 0xbfb8aa3b, v91
	v_mul_f32_e32 v66, v90, v94
	v_mul_f32_e32 v66, v86, v66
	v_mul_f32_e32 v86, 0xbfb8aa3b, v92
	v_exp_f32_e32 v86, v86
	v_exp_f32_e32 v95, v95
	v_mul_f32_e32 v90, 0xbfb8aa3b, v93
	v_exp_f32_e32 v90, v90
	v_add_f32_e32 v86, 1.0, v86
	v_rcp_f32_e32 v86, v86
	v_add_f32_e32 v67, 1.0, v95
	v_rcp_f32_e32 v67, v67
	v_add_f32_e32 v90, 1.0, v90
	v_mul_f32_e32 v86, v92, v86
	v_rcp_f32_e32 v90, v90
	v_mul_f32_e32 v86, v88, v86
	v_mul_f32_e32 v88, 0xbfb8aa3b, v82
	v_exp_f32_e32 v88, v88
	v_mul_f32_e32 v67, v91, v67
	v_mul_f32_e32 v67, v87, v67
	v_mul_f32_e32 v87, v93, v90
	v_cvt_pk_bf16_f32 v66, v66, v67
	v_mul_f32_e32 v87, v89, v87
	v_cvt_pk_bf16_f32 v67, v86, v87
	global_store_dwordx2 v[68:69], v[66:67], off offset:32
	v_add_f32_e32 v66, 1.0, v88
	v_rcp_f32_e32 v66, v66
	v_mul_f32_e32 v67, 0xbfb8aa3b, v83
	v_mul_f32_e32 v69, 0xbfb8aa3b, v84
	v_exp_f32_e32 v67, v67
	v_mul_f32_e32 v66, v82, v66
	v_mul_f32_e32 v66, v78, v66
	v_exp_f32_e32 v69, v69
	v_mul_f32_e32 v78, 0xbfb8aa3b, v85
	v_exp_f32_e32 v78, v78
	v_add_f32_e32 v67, 1.0, v67
	v_add_f32_e32 v69, 1.0, v69
	v_rcp_f32_e32 v67, v67
	v_rcp_f32_e32 v69, v69
	v_add_f32_e32 v78, 1.0, v78
	v_rcp_f32_e32 v78, v78
	v_mul_f32_e32 v67, v83, v67
	v_mul_f32_e32 v69, v84, v69
	v_mul_f32_e32 v67, v79, v67
	v_mul_f32_e32 v69, v80, v69
	v_mul_f32_e32 v78, v85, v78
	v_mul_f32_e32 v78, v81, v78
	v_cvt_pk_bf16_f32 v66, v66, v67
	v_cvt_pk_bf16_f32 v67, v69, v78
	v_mul_f32_e32 v69, 0xbfb8aa3b, v74
	v_exp_f32_e32 v78, v69
	v_or_b32_e32 v68, 0x50, v162
	v_mad_i64_i32 v[68:69], s[2:3], v68, s45, v[154:155]
	v_add_f32_e32 v78, 1.0, v78
	v_rcp_f32_e32 v78, v78
	v_lshl_add_u64 v[68:69], v[68:69], 0, v[156:157]
	global_store_dwordx2 v[68:69], v[66:67], off
	v_mul_f32_e32 v79, 0xbfb8aa3b, v75
	v_mul_f32_e32 v66, v74, v78
	v_mul_f32_e32 v66, v70, v66
	v_mul_f32_e32 v70, 0xbfb8aa3b, v76
	v_exp_f32_e32 v70, v70
	v_exp_f32_e32 v79, v79
	v_mul_f32_e32 v74, 0xbfb8aa3b, v77
	v_exp_f32_e32 v74, v74
	v_add_f32_e32 v70, 1.0, v70
	v_rcp_f32_e32 v70, v70
	v_add_f32_e32 v67, 1.0, v79
	v_rcp_f32_e32 v67, v67
	v_add_f32_e32 v74, 1.0, v74
	v_mul_f32_e32 v70, v76, v70
	v_rcp_f32_e32 v74, v74
	v_mul_f32_e32 v70, v72, v70
	v_mul_f32_e32 v72, 0xbfb8aa3b, v62
	v_exp_f32_e32 v72, v72
	v_mul_f32_e32 v67, v75, v67
	v_mul_f32_e32 v67, v71, v67
	v_mul_f32_e32 v71, v77, v74
	v_cvt_pk_bf16_f32 v66, v66, v67
	v_mul_f32_e32 v71, v73, v71
	v_cvt_pk_bf16_f32 v67, v70, v71
	global_store_dwordx2 v[68:69], v[66:67], off offset:32
	v_add_f32_e32 v66, 1.0, v72
	v_rcp_f32_e32 v66, v66
	v_mul_f32_e32 v67, 0xbfb8aa3b, v63
	v_exp_f32_e32 v67, v67
	v_or_b32_e32 v68, 0x60, v162
	v_mul_f32_e32 v62, v62, v66
	v_mul_f32_e32 v58, v58, v62
	v_add_f32_e32 v62, 1.0, v67
	v_mul_f32_e32 v66, 0xbfb8aa3b, v64
	v_rcp_f32_e32 v62, v62
	v_exp_f32_e32 v66, v66
	v_mul_f32_e32 v67, 0xbfb8aa3b, v65
	v_exp_f32_e32 v67, v67
	v_mul_f32_e32 v62, v63, v62
	v_add_f32_e32 v63, 1.0, v66
	v_rcp_f32_e32 v63, v63
	v_add_f32_e32 v66, 1.0, v67
	v_rcp_f32_e32 v66, v66
	v_mul_f32_e32 v59, v59, v62
	v_mul_f32_e32 v62, v64, v63
	v_mul_f32_e32 v60, v60, v62
	v_mul_f32_e32 v62, v65, v66
	v_mul_f32_e32 v61, v61, v62
	v_cvt_pk_bf16_f32 v58, v58, v59
	v_cvt_pk_bf16_f32 v59, v60, v61
	v_mul_f32_e32 v60, 0xbfb8aa3b, v54
	v_exp_f32_e32 v62, v60
	v_mul_f32_e32 v63, 0xbfb8aa3b, v55
	v_exp_f32_e32 v63, v63
	v_mad_i64_i32 v[60:61], s[2:3], v68, s45, v[154:155]
	v_add_f32_e32 v62, 1.0, v62
	v_rcp_f32_e32 v62, v62
	v_lshl_add_u64 v[60:61], v[60:61], 0, v[156:157]
	global_store_dwordx2 v[60:61], v[58:59], off
	v_mul_f32_e32 v58, 0xbfb8aa3b, v56
	v_mul_f32_e32 v54, v54, v62
	v_mul_f32_e32 v50, v50, v54
	v_add_f32_e32 v54, 1.0, v63
	v_rcp_f32_e32 v54, v54
	v_exp_f32_e32 v58, v58
	v_mul_f32_e32 v59, 0xbfb8aa3b, v57
	v_exp_f32_e32 v59, v59
	v_mul_f32_e32 v54, v55, v54
	v_add_f32_e32 v55, 1.0, v58
	v_rcp_f32_e32 v55, v55
	v_add_f32_e32 v58, 1.0, v59
	v_rcp_f32_e32 v58, v58
	v_mul_f32_e32 v51, v51, v54
	v_mul_f32_e32 v54, v56, v55
	v_mul_f32_e32 v52, v52, v54
	v_mul_f32_e32 v54, v57, v58
	v_mul_f32_e32 v53, v53, v54
	v_mul_f32_e32 v54, 0xbfb8aa3b, v46
	v_exp_f32_e32 v54, v54
	v_cvt_pk_bf16_f32 v50, v50, v51
	v_cvt_pk_bf16_f32 v51, v52, v53
	global_store_dwordx2 v[60:61], v[50:51], off offset:32
	v_add_f32_e32 v50, 1.0, v54
	v_rcp_f32_e32 v50, v50
	v_mul_f32_e32 v51, 0xbfb8aa3b, v47
	v_exp_f32_e32 v51, v51
	v_or_b32_e32 v52, 0x70, v162
	v_mul_f32_e32 v46, v46, v50
	v_mul_f32_e32 v42, v42, v46
	v_add_f32_e32 v46, 1.0, v51
	v_mul_f32_e32 v50, 0xbfb8aa3b, v48
	v_rcp_f32_e32 v46, v46
	v_exp_f32_e32 v50, v50
	v_mul_f32_e32 v51, 0xbfb8aa3b, v49
	v_exp_f32_e32 v51, v51
	v_mul_f32_e32 v46, v47, v46
	v_add_f32_e32 v47, 1.0, v50
	v_rcp_f32_e32 v47, v47
	v_add_f32_e32 v50, 1.0, v51
	v_rcp_f32_e32 v50, v50
	v_mul_f32_e32 v43, v43, v46
	v_mul_f32_e32 v46, v48, v47
	v_mul_f32_e32 v44, v44, v46
	v_mul_f32_e32 v46, v49, v50
	v_mul_f32_e32 v45, v45, v46
	v_cvt_pk_bf16_f32 v42, v42, v43
	v_cvt_pk_bf16_f32 v43, v44, v45
	v_mul_f32_e32 v44, 0xbfb8aa3b, v38
	v_exp_f32_e32 v46, v44
	v_mul_f32_e32 v47, 0xbfb8aa3b, v39
	v_exp_f32_e32 v47, v47
	v_mad_i64_i32 v[44:45], s[2:3], v52, s45, v[154:155]
	v_add_f32_e32 v46, 1.0, v46
	v_rcp_f32_e32 v46, v46
	v_lshl_add_u64 v[44:45], v[44:45], 0, v[156:157]
	global_store_dwordx2 v[44:45], v[42:43], off
	v_mul_f32_e32 v42, 0xbfb8aa3b, v40
	v_mul_f32_e32 v38, v38, v46
	v_mul_f32_e32 v34, v34, v38
	v_add_f32_e32 v38, 1.0, v47
	v_rcp_f32_e32 v38, v38
	v_exp_f32_e32 v42, v42
	v_mul_f32_e32 v43, 0xbfb8aa3b, v41
	v_exp_f32_e32 v43, v43
	v_mul_f32_e32 v38, v39, v38
	v_add_f32_e32 v39, 1.0, v42
	v_rcp_f32_e32 v39, v39
	v_add_f32_e32 v42, 1.0, v43
	v_rcp_f32_e32 v42, v42
	v_mul_f32_e32 v35, v35, v38
	v_mul_f32_e32 v38, v40, v39
	v_mul_f32_e32 v36, v36, v38
	v_mul_f32_e32 v38, v41, v42
	v_mul_f32_e32 v37, v37, v38
	s_add_i32 s46, s46, s28
	v_cvt_pk_bf16_f32 v34, v34, v35
	v_cvt_pk_bf16_f32 v35, v36, v37
	v_mov_b32_e32 v37, 0
	s_cmp_ge_i32 s46, s33
	global_store_dwordx2 v[44:45], v[34:35], off offset:32
	s_cbranch_scc1 .LBB0_1146
	s_mov_b32 s12, s10
	s_cmpk_gt_i32 s46, 0x9f
	s_mov_b64 s[2:3], -1
	s_cbranch_scc0 .LBB0_1184
	s_lshl_b32 s2, s46, 2
	s_add_i32 s2, s2, 0x7ffffd80
	s_and_b32 s13, s2, 0x7ffffff8
	s_and_b32 s2, s46, 1
	s_or_b32 s34, s2, 20
	s_mov_b64 s[2:3], 0

.LBB0_1187:
	s_mov_b32 s98, 0
	v_mov_b32_e32 v255, 0x0
	v_bfe_u32 v1, v0, 0, 1
	v_lshlrev_b32_e32 v1, 7, v1
	v_xor_b32_e32 v255, v255, v1
	v_bfe_u32 v1, v0, 1, 3
	v_mul_u32_u24_e32 v1, 0x110, v1
	v_xor_b32_e32 v255, v255, v1
	v_bfe_u32 v1, v0, 4, 2
	v_lshlrev_b32_e32 v1, 4, v1
	v_xor_b32_e32 v255, v255, v1
	v_bfe_u32 v1, v0, 8, 1
	v_lshlrev_b32_e32 v1, 13, v1
	v_xor_b32_e32 v255, v255, v1
	v_mov_b32_e32 v254, 0x10000
	v_bfe_u32 v1, v0, 0, 1
	v_lshlrev_b32_e32 v1, 7, v1
	v_xor_b32_e32 v254, v254, v1
	v_bfe_u32 v1, v0, 1, 3
	v_mul_u32_u24_e32 v1, 0x110, v1
	v_xor_b32_e32 v254, v254, v1
	v_bfe_u32 v1, v0, 4, 2
	v_lshlrev_b32_e32 v1, 4, v1
	v_xor_b32_e32 v254, v254, v1
	v_bfe_u32 v1, v0, 8, 1
	v_lshlrev_b32_e32 v1, 13, v1
	v_xor_b32_e32 v254, v254, v1
	v_mov_b32_e32 v253, 0x880
	v_bfe_u32 v1, v0, 0, 1
	v_lshlrev_b32_e32 v1, 7, v1
	v_xor_b32_e32 v253, v253, v1
	v_bfe_u32 v1, v0, 1, 3
	v_mul_u32_u24_e32 v1, 0x110, v1
	v_xor_b32_e32 v253, v253, v1
	v_bfe_u32 v1, v0, 4, 2
	v_lshlrev_b32_e32 v1, 4, v1
	v_xor_b32_e32 v253, v253, v1
	v_bfe_u32 v1, v0, 8, 1
	v_lshlrev_b32_e32 v1, 13, v1
	v_xor_b32_e32 v253, v253, v1
	v_mov_b32_e32 v252, 0x10880
	v_bfe_u32 v1, v0, 0, 1
	v_lshlrev_b32_e32 v1, 7, v1
	v_xor_b32_e32 v252, v252, v1
	v_bfe_u32 v1, v0, 1, 3
	v_mul_u32_u24_e32 v1, 0x110, v1
	v_xor_b32_e32 v252, v252, v1
	v_bfe_u32 v1, v0, 4, 2
	v_lshlrev_b32_e32 v1, 4, v1
	v_xor_b32_e32 v252, v252, v1
	v_bfe_u32 v1, v0, 8, 1
	v_lshlrev_b32_e32 v1, 13, v1
	v_xor_b32_e32 v252, v252, v1
	v_mov_b32_e32 v251, 0x8000
	v_bfe_u32 v1, v0, 0, 1
	v_lshlrev_b32_e32 v1, 7, v1
	v_xor_b32_e32 v251, v251, v1
	v_bfe_u32 v1, v0, 1, 3
	v_mul_u32_u24_e32 v1, 0x110, v1
	v_xor_b32_e32 v251, v251, v1
	v_bfe_u32 v1, v0, 4, 2
	v_lshlrev_b32_e32 v1, 4, v1
	v_xor_b32_e32 v251, v251, v1
	v_bfe_u32 v1, v0, 6, 2
	v_lshlrev_b32_e32 v1, 13, v1
	v_xor_b32_e32 v251, v251, v1
	v_mov_b32_e32 v250, 0x18000
	v_bfe_u32 v1, v0, 0, 1
	v_lshlrev_b32_e32 v1, 7, v1
	v_xor_b32_e32 v250, v250, v1
	v_bfe_u32 v1, v0, 1, 3
	v_mul_u32_u24_e32 v1, 0x110, v1
	v_xor_b32_e32 v250, v250, v1
	v_bfe_u32 v1, v0, 4, 2
	v_lshlrev_b32_e32 v1, 4, v1
	v_xor_b32_e32 v250, v250, v1
	v_bfe_u32 v1, v0, 6, 2
	v_lshlrev_b32_e32 v1, 13, v1
	v_xor_b32_e32 v250, v250, v1
	v_mov_b32_e32 v249, 0x8880
	v_bfe_u32 v1, v0, 0, 1
	v_lshlrev_b32_e32 v1, 7, v1
	v_xor_b32_e32 v249, v249, v1
	v_bfe_u32 v1, v0, 1, 3
	v_mul_u32_u24_e32 v1, 0x110, v1
	v_xor_b32_e32 v249, v249, v1
	v_bfe_u32 v1, v0, 4, 2
	v_lshlrev_b32_e32 v1, 4, v1
	v_xor_b32_e32 v249, v249, v1
	v_bfe_u32 v1, v0, 6, 2
	v_lshlrev_b32_e32 v1, 13, v1
	v_xor_b32_e32 v249, v249, v1
	v_mov_b32_e32 v248, 0x18880
	v_bfe_u32 v1, v0, 0, 1
	v_lshlrev_b32_e32 v1, 7, v1
	v_xor_b32_e32 v248, v248, v1
	v_bfe_u32 v1, v0, 1, 3
	v_mul_u32_u24_e32 v1, 0x110, v1
	v_xor_b32_e32 v248, v248, v1
	v_bfe_u32 v1, v0, 4, 2
	v_lshlrev_b32_e32 v1, 4, v1
	v_xor_b32_e32 v248, v248, v1
	v_bfe_u32 v1, v0, 6, 2
	v_lshlrev_b32_e32 v1, 13, v1
	v_xor_b32_e32 v248, v248, v1
	v_mov_b32_e32 v247, 0x40
	v_bfe_u32 v1, v0, 0, 1
	v_lshlrev_b32_e32 v1, 7, v1
	v_xor_b32_e32 v247, v247, v1
	v_bfe_u32 v1, v0, 1, 3
	v_mul_u32_u24_e32 v1, 0x110, v1
	v_xor_b32_e32 v247, v247, v1
	v_bfe_u32 v1, v0, 4, 2
	v_lshlrev_b32_e32 v1, 4, v1
	v_xor_b32_e32 v247, v247, v1
	v_bfe_u32 v1, v0, 8, 1
	v_lshlrev_b32_e32 v1, 13, v1
	v_xor_b32_e32 v247, v247, v1
	v_mov_b32_e32 v246, 0x10040
	v_bfe_u32 v1, v0, 0, 1
	v_lshlrev_b32_e32 v1, 7, v1
	v_xor_b32_e32 v246, v246, v1
	v_bfe_u32 v1, v0, 1, 3
	v_mul_u32_u24_e32 v1, 0x110, v1
	v_xor_b32_e32 v246, v246, v1
	v_bfe_u32 v1, v0, 4, 2
	v_lshlrev_b32_e32 v1, 4, v1
	v_xor_b32_e32 v246, v246, v1
	v_bfe_u32 v1, v0, 8, 1
	v_lshlrev_b32_e32 v1, 13, v1
	v_xor_b32_e32 v246, v246, v1
	v_mov_b32_e32 v245, 0x8c0
	v_bfe_u32 v1, v0, 0, 1
	v_lshlrev_b32_e32 v1, 7, v1
	v_xor_b32_e32 v245, v245, v1
	v_bfe_u32 v1, v0, 1, 3
	v_mul_u32_u24_e32 v1, 0x110, v1
	v_xor_b32_e32 v245, v245, v1
	v_bfe_u32 v1, v0, 4, 2
	v_lshlrev_b32_e32 v1, 4, v1
	v_xor_b32_e32 v245, v245, v1
	v_bfe_u32 v1, v0, 8, 1
	v_lshlrev_b32_e32 v1, 13, v1
	v_xor_b32_e32 v245, v245, v1
	v_mov_b32_e32 v244, 0x108c0
	v_bfe_u32 v1, v0, 0, 1
	v_lshlrev_b32_e32 v1, 7, v1
	v_xor_b32_e32 v244, v244, v1
	v_bfe_u32 v1, v0, 1, 3
	v_mul_u32_u24_e32 v1, 0x110, v1
	v_xor_b32_e32 v244, v244, v1
	v_bfe_u32 v1, v0, 4, 2
	v_lshlrev_b32_e32 v1, 4, v1
	v_xor_b32_e32 v244, v244, v1
	v_bfe_u32 v1, v0, 8, 1
	v_lshlrev_b32_e32 v1, 13, v1
	v_xor_b32_e32 v244, v244, v1
	v_mov_b32_e32 v243, 0x8040
	v_bfe_u32 v1, v0, 0, 1
	v_lshlrev_b32_e32 v1, 7, v1
	v_xor_b32_e32 v243, v243, v1
	v_bfe_u32 v1, v0, 1, 3
	v_mul_u32_u24_e32 v1, 0x110, v1
	v_xor_b32_e32 v243, v243, v1
	v_bfe_u32 v1, v0, 4, 2
	v_lshlrev_b32_e32 v1, 4, v1
	v_xor_b32_e32 v243, v243, v1
	v_bfe_u32 v1, v0, 6, 2
	v_lshlrev_b32_e32 v1, 13, v1
	v_xor_b32_e32 v243, v243, v1
	v_mov_b32_e32 v242, 0x18040
	v_bfe_u32 v1, v0, 0, 1
	v_lshlrev_b32_e32 v1, 7, v1
	v_xor_b32_e32 v242, v242, v1
	v_bfe_u32 v1, v0, 1, 3
	v_mul_u32_u24_e32 v1, 0x110, v1
	v_xor_b32_e32 v242, v242, v1
	v_bfe_u32 v1, v0, 4, 2
	v_lshlrev_b32_e32 v1, 4, v1
	v_xor_b32_e32 v242, v242, v1
	v_bfe_u32 v1, v0, 6, 2
	v_lshlrev_b32_e32 v1, 13, v1
	v_xor_b32_e32 v242, v242, v1
	v_mov_b32_e32 v241, 0x88c0
	v_bfe_u32 v1, v0, 0, 1
	v_lshlrev_b32_e32 v1, 7, v1
	v_xor_b32_e32 v241, v241, v1
	v_bfe_u32 v1, v0, 1, 3
	v_mul_u32_u24_e32 v1, 0x110, v1
	v_xor_b32_e32 v241, v241, v1
	v_bfe_u32 v1, v0, 4, 2
	v_lshlrev_b32_e32 v1, 4, v1
	v_xor_b32_e32 v241, v241, v1
	v_bfe_u32 v1, v0, 6, 2
	v_lshlrev_b32_e32 v1, 13, v1
	v_xor_b32_e32 v241, v241, v1
	v_mov_b32_e32 v240, 0x188c0
	v_bfe_u32 v1, v0, 0, 1
	v_lshlrev_b32_e32 v1, 7, v1
	v_xor_b32_e32 v240, v240, v1
	v_bfe_u32 v1, v0, 1, 3
	v_mul_u32_u24_e32 v1, 0x110, v1
	v_xor_b32_e32 v240, v240, v1
	v_bfe_u32 v1, v0, 4, 2
	v_lshlrev_b32_e32 v1, 4, v1
	v_xor_b32_e32 v240, v240, v1
	v_bfe_u32 v1, v0, 6, 2
	v_lshlrev_b32_e32 v1, 13, v1
	v_xor_b32_e32 v240, v240, v1
	v_mov_b32_e32 v239, 0x0
	v_bfe_u32 v1, v0, 0, 4
	v_lshlrev_b32_e32 v1, 4, v1
	v_xor_b32_e32 v239, v239, v1
	v_bfe_u32 v1, v0, 4, 4
	v_mul_u32_u24_e32 v1, 0x110, v1
	v_xor_b32_e32 v239, v239, v1
	v_bfe_u32 v1, v0, 8, 1
	v_lshlrev_b32_e32 v1, 12, v1
	v_xor_b32_e32 v239, v239, v1
	v_mov_b32_e32 v238, 0x10000
	v_bfe_u32 v1, v0, 0, 4
	v_lshlrev_b32_e32 v1, 4, v1
	v_xor_b32_e32 v238, v238, v1
	v_bfe_u32 v1, v0, 4, 4
	v_mul_u32_u24_e32 v1, 0x110, v1
	v_xor_b32_e32 v238, v238, v1
	v_bfe_u32 v1, v0, 8, 1
	v_lshlrev_b32_e32 v1, 12, v1
	v_xor_b32_e32 v238, v238, v1
	v_mov_b32_e32 v237, 0x0
	v_bfe_u32 v1, v0, 0, 3
	v_lshlrev_b32_e32 v1, 4, v1
	v_add_u32_e32 v237, v237, v1
	v_bfe_u32 v1, v0, 3, 6
	v_lshlrev_b32_e32 v1, 11, v1
	v_add_u32_e32 v237, v237, v1
	v_mov_b32_e32 v236, 0x20000
	v_bfe_u32 v1, v0, 0, 3
	v_lshlrev_b32_e32 v1, 4, v1
	v_add_u32_e32 v236, v236, v1
	v_bfe_u32 v1, v0, 3, 6
	v_lshlrev_b32_e32 v1, 11, v1
	v_add_u32_e32 v236, v236, v1
	v_mov_b32_e32 v235, 0x40000
	v_bfe_u32 v1, v0, 0, 3
	v_lshlrev_b32_e32 v1, 4, v1
	v_add_u32_e32 v235, v235, v1
	v_bfe_u32 v1, v0, 3, 6
	v_lshlrev_b32_e32 v1, 11, v1
	v_add_u32_e32 v235, v235, v1
	v_mov_b32_e32 v234, 0x60000
	v_bfe_u32 v1, v0, 0, 3
	v_lshlrev_b32_e32 v1, 4, v1
	v_add_u32_e32 v234, v234, v1
	v_bfe_u32 v1, v0, 3, 6
	v_lshlrev_b32_e32 v1, 11, v1
	v_add_u32_e32 v234, v234, v1
	v_mov_b32_e32 v1, v0
	s_mov_b32 s2, s10
	s_ashr_i32 s3, s2, 3
	s_abs_i32 s3, s3
	s_mul_hi_u32 s8, s3, s30
	s_mul_i32 s8, s8, s28
	s_sub_i32 s3, s3, s8
	s_ashr_i32 s2, s2, 31
	s_sub_i32 s8, s3, s28
	s_cmp_ge_u32 s3, s28
	s_cselect_b32 s3, s8, s3
	s_sub_i32 s8, s3, s28
	s_cmp_ge_u32 s3, s28
	s_cselect_b32 s3, s8, s3
	s_xor_b32 s3, s3, s2
	s_sub_i32 s22, s3, s2
	s_mov_b32 s2, s10
	s_lshl_b32 s8, s29, 1
	s_cmp_lt_i32 s22, s8
	s_cselect_b64 s[2:3], -1, 0
	s_cmp_ge_i32 s22, s8
	s_mov_b32 s23, 1
	s_cbranch_scc1 .LBB0_1189
	s_lshl_b32 s8, s22, 7
	s_and_b32 s27, s8, 0x80
	s_ashr_i32 s8, s22, 1
	s_sub_i32 s8, s8, s29
	s_add_i32 s29, s8, 0xb1
	s_add_i32 s22, s8, 0xb0
	s_branch .LBB0_1190

.LBB0_1197:
	s_andn2_b64 vcc, exec, s[2:3]
	s_cbranch_vccnz .LBB0_1241
	v_cvt_f32_u32_e32 v1, s23
	s_not_b32 s2, s22
	s_sub_i32 s3, 0, s23
	s_add_i32 s2, s29, s2
	v_rcp_iflag_f32_e32 v1, v1
	s_add_i32 s2, s2, s23
	s_ashr_i32 s8, s2, 31
	s_abs_i32 s2, s2
	v_mul_f32_e32 v1, 0x4f7ffffe, v1
	v_cvt_u32_f32_e32 v1, v1
	v_mov_b32_e32 v58, 0
	s_movk_i32 s31, 0xf800
	v_readfirstlane_b32 s9, v1
	s_mul_i32 s3, s3, s9
	s_mul_hi_u32 s3, s9, s3
	s_add_i32 s9, s9, s3
	s_mul_hi_u32 s3, s2, s9
	s_mul_i32 s9, s3, s23
	s_sub_i32 s2, s2, s9
	s_add_i32 s12, s3, 1
	s_sub_i32 s9, s2, s23
	s_cmp_ge_u32 s2, s23
	s_cselect_b32 s3, s12, s3
	s_cselect_b32 s2, s9, s2
	s_add_i32 s9, s3, 1
	s_cmp_ge_u32 s2, s23
	s_cselect_b32 s2, s9, s3
	s_xor_b32 s2, s2, s8
	s_sub_i32 s8, s2, s8
	v_mov_b32_e32 v1, v0
	s_lshl_b32 s2, s28, 8
	s_ashr_i32 s3, s2, 31
	s_lshl_b64 s[2:3], s[2:3], 11
	s_waitcnt vmcnt(0)
	v_lshlrev_b32_e32 v2, 8, v1
	v_lshlrev_b32_e32 v1, 4, v1
	s_add_u32 s2, s25, s2
	v_and_b32_e32 v1, 0x70, v1
	v_mov_b32_e32 v147, 0
	s_addc_u32 s3, s26, s3
	v_and_or_b32 v146, v2, s31, v1
	v_lshl_add_u64 v[10:11], s[2:3], 0, v[146:147]
	s_mov_b32 s9, 0x60000
	v_add_co_u32_e32 v12, vcc, s9, v10
	s_lshl_b32 s12, s30, 8
	s_nop 0
	v_addc_co_u32_e32 v13, vcc, 0, v11, vcc
	s_mov_b32 s14, 0x40000
	s_or_b32 s12, s12, s27
	v_add_co_u32_e32 v14, vcc, s14, v10
	s_ashr_i32 s13, s12, 31
	s_nop 0
	v_addc_co_u32_e32 v15, vcc, 0, v11, vcc
	s_mov_b32 s33, 0x20000
	s_lshl_b64 s[12:13], s[12:13], 11
	v_add_co_u32_e32 v18, vcc, s33, v10
	s_add_u32 s12, s11, s12
	s_nop 0
	v_addc_co_u32_e32 v19, vcc, 0, v11, vcc
	s_addc_u32 s13, s24, s13
	global_load_dwordx4 v[2:5], v[12:13], off
	global_load_dwordx4 v[6:9], v[14:15], off
	s_nop 0
	global_load_dwordx4 v[10:13], v[18:19], off
	global_load_dwordx4 v[14:17], v146, s[2:3]
	v_lshl_add_u64 v[18:19], s[12:13], 0, v[146:147]
	v_add_co_u32_e32 v26, vcc, s33, v18
	v_mov_b32_e32 v1, v0
	s_nop 0
	v_addc_co_u32_e32 v27, vcc, 0, v19, vcc
	global_load_dwordx4 v[18:21], v146, s[12:13]
	global_load_dwordx4 v[22:25], v[26:27], off
	s_movk_i32 s34, 0xf0
	v_ashrrev_i32_e32 v27, 4, v1
	v_xor_b32_e32 v1, v27, v1
	v_lshlrev_b32_e32 v27, 8, v27
	v_lshlrev_b32_e32 v1, 4, v1
	v_mov_b32_e32 v26, v0
	v_and_or_b32 v1, v1, s34, v27
	s_mov_b32 s44, 0
	s_cmp_lt_i32 s8, 1
	s_waitcnt vmcnt(2)
	ds_write_b128 v1, v[14:17] offset:32768
	ds_write_b128 v1, v[10:13] offset:40960
	ds_write_b128 v1, v[6:9] offset:49152
	ds_write_b128 v1, v[2:5] offset:57344
	s_waitcnt vmcnt(1)
	ds_write_b128 v1, v[18:21]
	s_waitcnt vmcnt(0)
	ds_write_b128 v1, v[22:25] offset:8192
	s_nop 0
	v_lshlrev_b32_e32 v2, 4, v26
	v_lshlrev_b32_e32 v1, 8, v26
	v_and_b32_e32 v2, 0x70, v2
	v_and_or_b32 v146, v1, s31, v2
	v_lshl_add_u64 v[10:11], s[2:3], 0, v[146:147]
	v_add_co_u32_e32 v14, vcc, s9, v10
	v_lshl_add_u64 v[12:13], s[12:13], 0, v[146:147]
	s_nop 0
	v_addc_co_u32_e32 v15, vcc, 0, v11, vcc
	v_add_co_u32_e32 v16, vcc, s14, v10
	s_nop 1
	v_addc_co_u32_e32 v17, vcc, 0, v11, vcc
	v_add_co_u32_e32 v26, vcc, s33, v10
	global_load_dwordx4 v[2:5], v[14:15], off offset:128
	global_load_dwordx4 v[6:9], v[16:17], off offset:128
	v_addc_co_u32_e32 v27, vcc, 0, v11, vcc
	v_add_co_u32_e32 v28, vcc, 0x20000, v12
	s_nop 1
	v_addc_co_u32_e32 v29, vcc, 0, v13, vcc
	global_load_dwordx4 v[10:13], v[26:27], off offset:128
	global_load_dwordx4 v[18:21], v[28:29], off offset:128
	global_load_dwordx4 v[14:17], v146, s[2:3] offset:128
	global_load_dwordx4 v[22:25], v146, s[12:13] offset:128
	s_waitcnt lgkmcnt(0)
	s_barrier
	s_cbranch_scc1 .LBB0_1240
	s_lshl_b32 s35, s8, 4
	s_mov_b32 s36, 2
	s_movk_i32 s37, 0xffc0
	s_mov_b32 s38, 0x10000
	s_mov_b32 s39, 0x11000
	s_movk_i32 s40, 0x1600
	v_mov_b32_e32 v1, 0x8040
	v_mov_b32_e32 v148, 0x10000
	s_mov_b32 s45, 2
	s_mov_b32 s41, s22
	s_mov_b32 s42, s28
	s_mov_b32 s43, s30
	v_mov_b32_e32 v59, v58
	v_mov_b32_e32 v60, v58
	v_mov_b32_e32 v61, v58
	v_mov_b32_e32 v82, v58
	v_mov_b32_e32 v83, v58
	v_mov_b32_e32 v84, v58
	v_mov_b32_e32 v85, v58
	v_mov_b32_e32 v86, v58
	v_mov_b32_e32 v87, v58
	v_mov_b32_e32 v88, v58
	v_mov_b32_e32 v89, v58
	v_mov_b32_e32 v78, v58
	v_mov_b32_e32 v79, v58
	v_mov_b32_e32 v80, v58
	v_mov_b32_e32 v81, v58
	v_mov_b32_e32 v74, v58
	v_mov_b32_e32 v75, v58
	v_mov_b32_e32 v76, v58
	v_mov_b32_e32 v77, v58
	v_mov_b32_e32 v66, v58
	v_mov_b32_e32 v67, v58
	v_mov_b32_e32 v68, v58
	v_mov_b32_e32 v69, v58
	v_mov_b32_e32 v70, v58
	v_mov_b32_e32 v71, v58
	v_mov_b32_e32 v72, v58
	v_mov_b32_e32 v73, v58
	v_mov_b32_e32 v62, v58
	v_mov_b32_e32 v63, v58
	v_mov_b32_e32 v64, v58
	v_mov_b32_e32 v65, v58
	v_mov_b32_e32 v54, v58
	v_mov_b32_e32 v55, v58
	v_mov_b32_e32 v56, v58
	v_mov_b32_e32 v57, v58
	v_mov_b32_e32 v46, v58
	v_mov_b32_e32 v47, v58
	v_mov_b32_e32 v48, v58
	v_mov_b32_e32 v49, v58
	v_mov_b32_e32 v50, v58
	v_mov_b32_e32 v51, v58
	v_mov_b32_e32 v52, v58
	v_mov_b32_e32 v53, v58
	v_mov_b32_e32 v42, v58
	v_mov_b32_e32 v43, v58
	v_mov_b32_e32 v44, v58
	v_mov_b32_e32 v45, v58
	v_mov_b32_e32 v34, v58
	v_mov_b32_e32 v35, v58
	v_mov_b32_e32 v36, v58
	v_mov_b32_e32 v37, v58
	v_mov_b32_e32 v30, v58
	v_mov_b32_e32 v31, v58
	v_mov_b32_e32 v32, v58
	v_mov_b32_e32 v33, v58
	v_mov_b32_e32 v38, v58
	v_mov_b32_e32 v39, v58
	v_mov_b32_e32 v40, v58
	v_mov_b32_e32 v41, v58
	v_mov_b32_e32 v26, v58
	v_mov_b32_e32 v27, v58
	v_mov_b32_e32 v28, v58
	v_mov_b32_e32 v29, v58
	s_waitcnt vmcnt(0)
	s_branch .LBB0_1203

.LBB0_1203:
	ds_read_b128 v[106:109], v251
	ds_read_b128 v[110:113], v249
	ds_read_b128 v[114:117], v251 offset:4096
	ds_read_b128 v[118:121], v249 offset:4096
	ds_read_b128 v[90:93], v255
	ds_read_b128 v[94:97], v253
	s_cmp_eq_u32 s98, 0
	s_cbranch_scc1 .Lnodef_I0_3
	v_mfma_f32_16x16x32_bf16 v[54:57], v[122:125], v[98:101], v[54:57]
	v_mfma_f32_16x16x32_bf16 v[46:49], v[126:129], v[98:101], v[46:49]
	v_mfma_f32_16x16x32_bf16 v[50:53], v[130:133], v[98:101], v[50:53]
	v_mfma_f32_16x16x32_bf16 v[42:45], v[134:137], v[98:101], v[42:45]
	v_mfma_f32_16x16x32_bf16 v[34:37], v[122:125], v[102:105], v[34:37]
	v_mfma_f32_16x16x32_bf16 v[30:33], v[126:129], v[102:105], v[30:33]
	v_mfma_f32_16x16x32_bf16 v[38:41], v[130:133], v[102:105], v[38:41]
	v_mfma_f32_16x16x32_bf16 v[26:29], v[134:137], v[102:105], v[26:29]
.Lnodef_I0_3:
	ds_read_b128 v[98:101], v255 offset:4096
	ds_read_b128 v[102:105], v253 offset:4096
	s_add_i32 s2, s36, -1
	s_cmp_lt_i32 s2, s35
	s_cselect_b64 s[8:9], -1, 0
	s_cmp_ge_i32 s2, s35
	s_waitcnt lgkmcnt(3)
	v_mfma_f32_16x16x32_bf16 v[58:61], v[106:109], v[90:93], v[58:61]
	v_mfma_f32_16x16x32_bf16 v[82:85], v[110:113], v[90:93], v[82:85]
	v_mfma_f32_16x16x32_bf16 v[86:89], v[114:117], v[90:93], v[86:89]
	v_mfma_f32_16x16x32_bf16 v[78:81], v[118:121], v[90:93], v[78:81]
	s_waitcnt lgkmcnt(2)
	v_mfma_f32_16x16x32_bf16 v[74:77], v[106:109], v[94:97], v[74:77]
	v_mfma_f32_16x16x32_bf16 v[66:69], v[110:113], v[94:97], v[66:69]
	v_mfma_f32_16x16x32_bf16 v[70:73], v[114:117], v[94:97], v[70:73]
	v_mfma_f32_16x16x32_bf16 v[62:65], v[118:121], v[94:97], v[62:65]
	s_waitcnt vmcnt(4)
	ds_write_b128 v238, v[22:25]
	ds_write_b128 v238, v[18:21] offset:8192
.LBB0_1205:
	s_lshl_b32 s2, s43, 8
	s_or_b32 s2, s2, s27
	s_ashr_i32 s3, s2, 31
	s_lshl_b64 s[12:13], s[2:3], 11
	s_lshl_b32 s2, s45, 6
	s_ashr_i32 s3, s2, 31
	s_add_u32 s14, s11, s12
	s_addc_u32 s15, s24, s13
	s_lshl_b64 s[20:21], s[2:3], 1
	s_add_u32 s2, s14, s20
	s_addc_u32 s3, s15, s21
	global_load_dwordx4 v[18:21], v237, s[2:3]
	global_load_dwordx4 v[22:25], v236, s[2:3]
	s_andn2_b64 vcc, exec, s[8:9]
	ds_read_b128 v[122:125], v243
	ds_read_b128 v[126:129], v241
	ds_read_b128 v[130:133], v243 offset:4096
	ds_read_b128 v[134:137], v241 offset:4096
	ds_read_b128 v[90:93], v247
	ds_read_b128 v[94:97], v245
	s_waitcnt lgkmcnt(9)
	v_mfma_f32_16x16x32_bf16 v[54:57], v[106:109], v[98:101], v[54:57]
	v_mfma_f32_16x16x32_bf16 v[46:49], v[110:113], v[98:101], v[46:49]
	v_mfma_f32_16x16x32_bf16 v[50:53], v[114:117], v[98:101], v[50:53]
	v_mfma_f32_16x16x32_bf16 v[42:45], v[118:121], v[98:101], v[42:45]
	s_waitcnt vmcnt(4)
	ds_write_b128 v238, v[14:17] offset:32768
	ds_write_b128 v238, v[10:13] offset:40960
.LBB0_1207:
	s_lshl_b32 s8, s42, 8
	s_ashr_i32 s9, s8, 31
	s_lshl_b64 s[14:15], s[8:9], 11
	s_add_u32 s8, s25, s14
	s_addc_u32 s9, s26, s15
	s_add_u32 s8, s8, s20
	s_addc_u32 s9, s9, s21
	global_load_dwordx4 v[10:13], v237, s[8:9]
	global_load_dwordx4 v[14:17], v236, s[8:9]
	s_and_b64 vcc, exec, s[2:3]
	ds_read_b128 v[98:101], v247 offset:4096
	s_waitcnt lgkmcnt(11)
	v_mfma_f32_16x16x32_bf16 v[34:37], v[106:109], v[102:105], v[34:37]
	v_mfma_f32_16x16x32_bf16 v[30:33], v[110:113], v[102:105], v[30:33]
	v_mfma_f32_16x16x32_bf16 v[38:41], v[114:117], v[102:105], v[38:41]
	v_mfma_f32_16x16x32_bf16 v[26:29], v[118:121], v[102:105], v[26:29]
	s_waitcnt vmcnt(4)
	ds_write_b128 v238, v[6:9] offset:49152
	ds_write_b128 v238, v[2:5] offset:57344
.LBB0_1209:
	global_load_dwordx4 v[2:5], v235, s[8:9]
	global_load_dwordx4 v[6:9], v234, s[8:9]
	ds_read_b128 v[102:105], v245 offset:4096
	s_waitcnt lgkmcnt(7)
	v_mfma_f32_16x16x32_bf16 v[58:61], v[122:125], v[90:93], v[58:61]
	v_mfma_f32_16x16x32_bf16 v[82:85], v[126:129], v[90:93], v[82:85]
	v_mfma_f32_16x16x32_bf16 v[86:89], v[130:133], v[90:93], v[86:89]
	v_mfma_f32_16x16x32_bf16 v[78:81], v[134:137], v[90:93], v[78:81]
	s_waitcnt lgkmcnt(6)
	v_mfma_f32_16x16x32_bf16 v[74:77], v[122:125], v[94:97], v[74:77]
	v_mfma_f32_16x16x32_bf16 v[66:69], v[126:129], v[94:97], v[66:69]
	v_mfma_f32_16x16x32_bf16 v[70:73], v[130:133], v[94:97], v[70:73]
	v_mfma_f32_16x16x32_bf16 v[62:65], v[134:137], v[94:97], v[62:65]
	s_add_i32 s45, s45, 1
	s_cmp_lg_u32 s45, 16
	s_cbranch_scc1 .LBB0_1218
	s_add_i32 s22, s22, s23
	s_cmp_ge_i32 s22, s29
	s_cbranch_scc1 .LBB0_1217
	s_mov_b32 s8, s10
	s_cmpk_gt_i32 s22, 0xaf
	s_cbranch_scc1 .LBB0_1217
	s_cmpk_gt_i32 s22, 0x9f
	s_mov_b64 s[2:3], -1
	s_cbranch_scc0 .LBB0_1214
	s_lshl_b32 s2, s22, 2
	s_add_i32 s2, s2, 0x7ffffd80
	s_and_b32 s9, s2, 0x7ffffff8
	s_and_b32 s2, s22, 1
	s_or_b32 s42, s2, 20
	s_mov_b64 s[2:3], 0

.LBB0_1218:
	s_waitcnt lgkmcnt(0)
	s_barrier
	ds_read_b128 v[106:109], v250
	ds_read_b128 v[110:113], v248
	ds_read_b128 v[114:117], v250 offset:4096
	ds_read_b128 v[118:121], v248 offset:4096
	ds_read_b128 v[90:93], v254
	ds_read_b128 v[94:97], v252
	v_mfma_f32_16x16x32_bf16 v[54:57], v[122:125], v[98:101], v[54:57]
	v_mfma_f32_16x16x32_bf16 v[46:49], v[126:129], v[98:101], v[46:49]
	v_mfma_f32_16x16x32_bf16 v[50:53], v[130:133], v[98:101], v[50:53]
	v_mfma_f32_16x16x32_bf16 v[42:45], v[134:137], v[98:101], v[42:45]
	v_mfma_f32_16x16x32_bf16 v[34:37], v[122:125], v[102:105], v[34:37]
	v_mfma_f32_16x16x32_bf16 v[30:33], v[126:129], v[102:105], v[30:33]
	v_mfma_f32_16x16x32_bf16 v[38:41], v[130:133], v[102:105], v[38:41]
	v_mfma_f32_16x16x32_bf16 v[26:29], v[134:137], v[102:105], v[26:29]
	ds_read_b128 v[98:101], v254 offset:4096
	ds_read_b128 v[102:105], v252 offset:4096
	s_cmp_lt_i32 s36, s35
	s_cselect_b64 s[20:21], -1, 0
	s_cmp_ge_i32 s36, s35
	s_cselect_b64 s[8:9], -1, 0
	s_and_b64 vcc, exec, s[8:9]
	s_waitcnt lgkmcnt(3)
	v_mfma_f32_16x16x32_bf16 v[58:61], v[106:109], v[90:93], v[58:61]
	v_mfma_f32_16x16x32_bf16 v[82:85], v[110:113], v[90:93], v[82:85]
	v_mfma_f32_16x16x32_bf16 v[86:89], v[114:117], v[90:93], v[86:89]
	v_mfma_f32_16x16x32_bf16 v[78:81], v[118:121], v[90:93], v[78:81]
	s_waitcnt lgkmcnt(2)
	v_mfma_f32_16x16x32_bf16 v[74:77], v[106:109], v[94:97], v[74:77]
	v_mfma_f32_16x16x32_bf16 v[66:69], v[110:113], v[94:97], v[66:69]
	v_mfma_f32_16x16x32_bf16 v[70:73], v[114:117], v[94:97], v[70:73]
	v_mfma_f32_16x16x32_bf16 v[62:65], v[118:121], v[94:97], v[62:65]
	s_waitcnt vmcnt(4)
	ds_write_b128 v239, v[18:21]
	ds_write_b128 v239, v[22:25] offset:8192
.LBB0_1220:
	s_lshl_b32 s2, s45, 6
	s_ashr_i32 s3, s2, 31
	s_add_u32 s46, s11, s12
	s_addc_u32 s47, s24, s13
	s_lshl_b64 s[12:13], s[2:3], 1
	s_add_u32 s2, s46, s12
	s_addc_u32 s3, s47, s13
	global_load_dwordx4 v[22:25], v237, s[2:3]
	global_load_dwordx4 v[18:21], v236, s[2:3]
	s_andn2_b64 vcc, exec, s[20:21]
	ds_read_b128 v[122:125], v242
	ds_read_b128 v[126:129], v240
	ds_read_b128 v[130:133], v242 offset:4096
	ds_read_b128 v[134:137], v240 offset:4096
	ds_read_b128 v[90:93], v246
	ds_read_b128 v[94:97], v244
	s_waitcnt lgkmcnt(9)
	v_mfma_f32_16x16x32_bf16 v[54:57], v[106:109], v[98:101], v[54:57]
	v_mfma_f32_16x16x32_bf16 v[46:49], v[110:113], v[98:101], v[46:49]
	v_mfma_f32_16x16x32_bf16 v[50:53], v[114:117], v[98:101], v[50:53]
	v_mfma_f32_16x16x32_bf16 v[42:45], v[118:121], v[98:101], v[42:45]
	s_waitcnt vmcnt(4)
	ds_write_b128 v239, v[10:13] offset:32768
	ds_write_b128 v239, v[14:17] offset:40960
.LBB0_1222:
	s_add_u32 s14, s25, s14
	s_addc_u32 s15, s26, s15
	s_add_u32 s12, s14, s12
	s_addc_u32 s13, s15, s13
	global_load_dwordx4 v[14:17], v237, s[12:13]
	global_load_dwordx4 v[10:13], v236, s[12:13]
	s_and_b64 vcc, exec, s[2:3]
	ds_read_b128 v[98:101], v246 offset:4096
	s_waitcnt lgkmcnt(11)
	v_mfma_f32_16x16x32_bf16 v[34:37], v[106:109], v[102:105], v[34:37]
	v_mfma_f32_16x16x32_bf16 v[30:33], v[110:113], v[102:105], v[30:33]
	v_mfma_f32_16x16x32_bf16 v[38:41], v[114:117], v[102:105], v[38:41]
	v_mfma_f32_16x16x32_bf16 v[26:29], v[118:121], v[102:105], v[26:29]
	s_waitcnt vmcnt(4)
	ds_write_b128 v239, v[2:5] offset:49152
	ds_write_b128 v239, v[6:9] offset:57344
.LBB0_1224:
	global_load_dwordx4 v[6:9], v235, s[12:13]
	global_load_dwordx4 v[2:5], v234, s[12:13]
	ds_read_b128 v[102:105], v244 offset:4096
	s_waitcnt lgkmcnt(7)
	v_mfma_f32_16x16x32_bf16 v[58:61], v[122:125], v[90:93], v[58:61]
	v_mfma_f32_16x16x32_bf16 v[82:85], v[126:129], v[90:93], v[82:85]
	v_mfma_f32_16x16x32_bf16 v[86:89], v[130:133], v[90:93], v[86:89]
	v_mfma_f32_16x16x32_bf16 v[78:81], v[134:137], v[90:93], v[78:81]
	s_waitcnt lgkmcnt(6)
	v_mfma_f32_16x16x32_bf16 v[74:77], v[122:125], v[94:97], v[74:77]
	v_mfma_f32_16x16x32_bf16 v[66:69], v[126:129], v[94:97], v[66:69]
	v_mfma_f32_16x16x32_bf16 v[70:73], v[130:133], v[94:97], v[70:73]
	v_mfma_f32_16x16x32_bf16 v[62:65], v[134:137], v[94:97], v[62:65]
	s_add_i32 s45, s45, 1
	s_cmp_lg_u32 s45, 16
	s_cbranch_scc1 .LBB0_1233
	s_add_i32 s22, s22, s23
	s_cmp_ge_i32 s22, s29
	s_cbranch_scc1 .LBB0_1232
	s_mov_b32 s12, s10
	s_cmpk_gt_i32 s22, 0xaf
	s_cbranch_scc1 .LBB0_1232
	s_cmpk_gt_i32 s22, 0x9f
	s_mov_b64 s[2:3], -1
	s_cbranch_scc0 .LBB0_1229
	s_lshl_b32 s2, s22, 2
	s_add_i32 s2, s2, 0x7ffffd80
	s_and_b32 s13, s2, 0x7ffffff8
	s_and_b32 s2, s22, 1
	s_or_b32 s42, s2, 20
	s_mov_b64 s[2:3], 0

.LBB0_1233:
	s_add_i32 s44, s44, 2
	s_cmp_lg_u32 s44, 16
	s_waitcnt lgkmcnt(0)
	s_mov_b32 s98, 1
	s_cbranch_scc1 .LBB0_1202
	s_mov_b32 s98, 0
	v_mfma_f32_16x16x32_bf16 v[54:57], v[122:125], v[98:101], v[54:57]
	v_mfma_f32_16x16x32_bf16 v[46:49], v[126:129], v[98:101], v[46:49]
	v_mfma_f32_16x16x32_bf16 v[50:53], v[130:133], v[98:101], v[50:53]
	v_mfma_f32_16x16x32_bf16 v[42:45], v[134:137], v[98:101], v[42:45]
	v_mfma_f32_16x16x32_bf16 v[34:37], v[122:125], v[102:105], v[34:37]
	v_mfma_f32_16x16x32_bf16 v[30:33], v[126:129], v[102:105], v[30:33]
	v_mfma_f32_16x16x32_bf16 v[38:41], v[130:133], v[102:105], v[38:41]
	v_mfma_f32_16x16x32_bf16 v[26:29], v[134:137], v[102:105], v[26:29]
	s_nop 7
	s_nop 7
	v_mov_b32_e32 v90, v0
	v_mul_f32_e32 v94, 0xbfb8aa3b, v59
	v_and_b32_e32 v91, 15, v90
	v_ashrrev_i32_e32 v93, 2, v90
	v_lshl_or_b32 v91, s30, 8, v91
	v_and_b32_e32 v92, 0xc0, v90
	v_and_b32_e32 v93, 0xffffffc0, v93
	v_or_b32_e32 v91, s27, v91
	v_add_u32_e32 v96, v91, v93
	v_lshl_or_b32 v91, s28, 8, v92
	v_mul_f32_e32 v92, 0xbfb8aa3b, v58
	v_exp_f32_e32 v93, v92
	v_exp_f32_e32 v97, v94
	v_ashrrev_i32_e32 v91, 1, v91
	v_lshrrev_b32_e32 v90, 2, v90
	v_add_f32_e32 v93, 1.0, v93
	v_rcp_f32_e32 v93, v93
	v_and_or_b32 v92, v90, 12, v91
	v_mov_b64_e32 v[90:91], s[6:7]
	v_mad_i64_i32 v[94:95], s[2:3], v96, s40, v[90:91]
	v_mul_f32_e32 v58, v58, v93
	v_mul_f32_e32 v58, v86, v58
	v_add_f32_e32 v86, 1.0, v97
	v_mul_f32_e32 v93, 0xbfb8aa3b, v60
	v_rcp_f32_e32 v86, v86
	v_exp_f32_e32 v93, v93
	v_mul_f32_e32 v97, 0xbfb8aa3b, v61
	v_exp_f32_e32 v97, v97
	v_mul_f32_e32 v59, v59, v86
	v_add_f32_e32 v86, 1.0, v93
	v_rcp_f32_e32 v86, v86
	v_add_f32_e32 v93, 1.0, v97
	v_rcp_f32_e32 v93, v93
	v_mul_f32_e32 v59, v87, v59
	v_mul_f32_e32 v60, v60, v86
	v_mul_f32_e32 v60, v88, v60
	v_mul_f32_e32 v61, v61, v93
	v_mul_f32_e32 v61, v89, v61
	v_cvt_pk_bf16_f32 v58, v58, v59
	v_cvt_pk_bf16_f32 v59, v60, v61
	v_mul_f32_e32 v60, 0xbfb8aa3b, v82
	v_exp_f32_e32 v88, v60
	v_ashrrev_i32_e32 v93, 31, v92
	v_lshlrev_b64 v[60:61], 1, v[92:93]
	v_lshl_add_u64 v[86:87], v[94:95], 0, v[60:61]
	v_add_f32_e32 v88, 1.0, v88
	v_rcp_f32_e32 v88, v88
	v_mul_f32_e32 v89, 0xbfb8aa3b, v83
	v_exp_f32_e32 v89, v89
	global_store_dwordx2 v[86:87], v[58:59], off
	v_mul_f32_e32 v58, v82, v88
	v_mul_f32_e32 v58, v78, v58
	v_mul_f32_e32 v78, 0xbfb8aa3b, v84
	v_exp_f32_e32 v78, v78
	v_add_f32_e32 v59, 1.0, v89
	v_mul_f32_e32 v82, 0xbfb8aa3b, v85
	v_rcp_f32_e32 v59, v59
	v_exp_f32_e32 v82, v82
	v_add_f32_e32 v78, 1.0, v78
	v_rcp_f32_e32 v78, v78
	v_mul_f32_e32 v59, v83, v59
	v_add_f32_e32 v82, 1.0, v82
	v_rcp_f32_e32 v82, v82
	v_mul_f32_e32 v59, v79, v59
	v_mul_f32_e32 v78, v84, v78
	v_cvt_pk_bf16_f32 v58, v58, v59
	v_mul_f32_e32 v59, 0xbfb8aa3b, v74
	v_mul_f32_e32 v78, v80, v78
	v_exp_f32_e32 v80, v59
	v_mul_f32_e32 v79, v85, v82
	v_mul_f32_e32 v79, v81, v79
	v_cvt_pk_bf16_f32 v59, v78, v79
	global_store_dwordx2 v[86:87], v[58:59], off offset:32
	v_add_f32_e32 v59, 1.0, v80
	v_rcp_f32_e32 v78, v59
	v_mul_f32_e32 v59, 0xbfb8aa3b, v75
	v_exp_f32_e32 v79, v59
	v_or_b32_e32 v58, 16, v96
	v_mul_f32_e32 v74, v74, v78
	v_mul_f32_e32 v70, v70, v74
	v_add_f32_e32 v74, 1.0, v79
	v_mul_f32_e32 v78, 0xbfb8aa3b, v76
	v_rcp_f32_e32 v74, v74
	v_exp_f32_e32 v78, v78
	v_mul_f32_e32 v79, 0xbfb8aa3b, v77
	v_exp_f32_e32 v79, v79
	v_mul_f32_e32 v74, v75, v74
	v_add_f32_e32 v75, 1.0, v78
	v_rcp_f32_e32 v75, v75
	v_add_f32_e32 v78, 1.0, v79
	v_rcp_f32_e32 v78, v78
	v_mul_f32_e32 v71, v71, v74
	v_mul_f32_e32 v74, v76, v75
	v_mul_f32_e32 v72, v72, v74
	v_mul_f32_e32 v74, v77, v78
	v_mul_f32_e32 v73, v73, v74
	v_mul_f32_e32 v74, 0xbfb8aa3b, v66
	v_exp_f32_e32 v74, v74
	v_cvt_pk_bf16_f32 v70, v70, v71
	v_cvt_pk_bf16_f32 v71, v72, v73
	v_mul_f32_e32 v73, 0xbfb8aa3b, v67
	v_add_f32_e32 v72, 1.0, v74
	v_rcp_f32_e32 v72, v72
	v_exp_f32_e32 v73, v73
	v_mad_i64_i32 v[58:59], s[2:3], v58, s40, v[90:91]
	v_lshl_add_u64 v[58:59], v[58:59], 0, v[60:61]
	v_mul_f32_e32 v66, v66, v72
	global_store_dwordx2 v[58:59], v[70:71], off
	v_mul_f32_e32 v62, v62, v66
	v_add_f32_e32 v66, 1.0, v73
	v_mul_f32_e32 v70, 0xbfb8aa3b, v68
	v_rcp_f32_e32 v66, v66
	v_exp_f32_e32 v70, v70
	v_mul_f32_e32 v71, 0xbfb8aa3b, v69
	v_exp_f32_e32 v71, v71
	v_mul_f32_e32 v66, v67, v66
	v_add_f32_e32 v67, 1.0, v70
	v_rcp_f32_e32 v67, v67
	v_add_f32_e32 v70, 1.0, v71
	v_rcp_f32_e32 v70, v70
	v_mul_f32_e32 v63, v63, v66
	v_mul_f32_e32 v66, v68, v67
	v_mul_f32_e32 v64, v64, v66
	v_mul_f32_e32 v66, v69, v70
	v_cvt_pk_bf16_f32 v62, v62, v63
	v_mul_f32_e32 v63, 0xbfb8aa3b, v54
	v_mul_f32_e32 v65, v65, v66
	v_exp_f32_e32 v66, v63
	v_cvt_pk_bf16_f32 v63, v64, v65
	global_store_dwordx2 v[58:59], v[62:63], off offset:32
	v_or_b32_e32 v58, 32, v96
	v_add_f32_e32 v59, 1.0, v66
	v_rcp_f32_e32 v62, v59
	v_mul_f32_e32 v59, 0xbfb8aa3b, v55
	v_exp_f32_e32 v63, v59
	v_mad_i64_i32 v[58:59], s[2:3], v58, s40, v[90:91]
	v_mul_f32_e32 v54, v54, v62
	v_mul_f32_e32 v50, v50, v54
	v_add_f32_e32 v54, 1.0, v63
	v_mul_f32_e32 v62, 0xbfb8aa3b, v56
	v_rcp_f32_e32 v54, v54
	v_exp_f32_e32 v62, v62
	v_mul_f32_e32 v63, 0xbfb8aa3b, v57
	v_exp_f32_e32 v63, v63
	v_mul_f32_e32 v54, v55, v54
	v_add_f32_e32 v55, 1.0, v62
	v_rcp_f32_e32 v55, v55
	v_add_f32_e32 v62, 1.0, v63
	v_rcp_f32_e32 v62, v62
	v_mul_f32_e32 v51, v51, v54
	v_mul_f32_e32 v54, v56, v55
	v_mul_f32_e32 v52, v52, v54
	v_mul_f32_e32 v54, v57, v62
	v_mul_f32_e32 v53, v53, v54
	v_mul_f32_e32 v54, 0xbfb8aa3b, v46
	v_exp_f32_e32 v54, v54
	v_mul_f32_e32 v55, 0xbfb8aa3b, v47
	v_exp_f32_e32 v55, v55
	v_cvt_pk_bf16_f32 v50, v50, v51
	v_add_f32_e32 v54, 1.0, v54
	v_rcp_f32_e32 v54, v54
	v_cvt_pk_bf16_f32 v51, v52, v53
	v_lshl_add_u64 v[52:53], v[58:59], 0, v[60:61]
	global_store_dwordx2 v[52:53], v[50:51], off
	v_mul_f32_e32 v46, v46, v54
	v_mul_f32_e32 v42, v42, v46
	v_add_f32_e32 v46, 1.0, v55
	v_mul_f32_e32 v50, 0xbfb8aa3b, v48
	v_rcp_f32_e32 v46, v46
	v_exp_f32_e32 v50, v50
	v_mul_f32_e32 v51, 0xbfb8aa3b, v49
	v_exp_f32_e32 v51, v51
	v_mul_f32_e32 v46, v47, v46
	v_add_f32_e32 v47, 1.0, v50
	v_rcp_f32_e32 v47, v47
	v_add_f32_e32 v50, 1.0, v51
	v_rcp_f32_e32 v50, v50
	v_mul_f32_e32 v43, v43, v46
	v_mul_f32_e32 v46, v48, v47
	v_mul_f32_e32 v44, v44, v46
	v_mul_f32_e32 v46, v49, v50
	v_cvt_pk_bf16_f32 v42, v42, v43
	v_mul_f32_e32 v43, 0xbfb8aa3b, v34
	v_mul_f32_e32 v45, v45, v46
	v_exp_f32_e32 v46, v43
	v_cvt_pk_bf16_f32 v43, v44, v45
	global_store_dwordx2 v[52:53], v[42:43], off offset:32
	v_or_b32_e32 v42, 48, v96
	v_add_f32_e32 v43, 1.0, v46
	v_rcp_f32_e32 v44, v43
	v_mul_f32_e32 v43, 0xbfb8aa3b, v35
	v_exp_f32_e32 v45, v43
	v_mad_i64_i32 v[42:43], s[2:3], v42, s40, v[90:91]
	v_mul_f32_e32 v34, v34, v44
	v_mul_f32_e32 v34, v38, v34
	v_add_f32_e32 v38, 1.0, v45
	v_mul_f32_e32 v44, 0xbfb8aa3b, v36
	v_rcp_f32_e32 v38, v38
	v_exp_f32_e32 v44, v44
	v_mul_f32_e32 v45, 0xbfb8aa3b, v37
	v_exp_f32_e32 v45, v45
	v_mul_f32_e32 v35, v35, v38
	v_add_f32_e32 v38, 1.0, v44
	v_rcp_f32_e32 v38, v38
	v_add_f32_e32 v44, 1.0, v45
	v_rcp_f32_e32 v44, v44
	v_mul_f32_e32 v35, v39, v35
	v_mul_f32_e32 v36, v36, v38
	v_mul_f32_e32 v38, 0xbfb8aa3b, v30
	v_exp_f32_e32 v38, v38
	v_mul_f32_e32 v39, 0xbfb8aa3b, v31
	v_exp_f32_e32 v39, v39
	v_mul_f32_e32 v37, v37, v44
	v_add_f32_e32 v38, 1.0, v38
	v_rcp_f32_e32 v38, v38
	v_mul_f32_e32 v36, v40, v36
	v_mul_f32_e32 v37, v41, v37
	v_cvt_pk_bf16_f32 v34, v34, v35
	v_cvt_pk_bf16_f32 v35, v36, v37
	v_lshl_add_u64 v[36:37], v[42:43], 0, v[60:61]
	v_mul_f32_e32 v30, v30, v38
	global_store_dwordx2 v[36:37], v[34:35], off
	v_mul_f32_e32 v26, v26, v30
	v_add_f32_e32 v30, 1.0, v39
	v_mul_f32_e32 v34, 0xbfb8aa3b, v32
	v_rcp_f32_e32 v30, v30
	v_exp_f32_e32 v34, v34
	v_mul_f32_e32 v35, 0xbfb8aa3b, v33
	v_exp_f32_e32 v35, v35
	v_mul_f32_e32 v30, v31, v30
	v_add_f32_e32 v31, 1.0, v34
	v_rcp_f32_e32 v31, v31
	v_add_f32_e32 v34, 1.0, v35
	v_rcp_f32_e32 v34, v34
	v_mul_f32_e32 v27, v27, v30
	v_mul_f32_e32 v30, v32, v31
	v_mul_f32_e32 v28, v28, v30
	v_mul_f32_e32 v30, v33, v34
	v_mul_f32_e32 v29, v29, v30
	s_add_i32 s41, s41, s23
	v_cvt_pk_bf16_f32 v26, v26, v27
	v_cvt_pk_bf16_f32 v27, v28, v29
	v_mov_b32_e32 v29, 0
	s_cmp_ge_i32 s41, s29
	global_store_dwordx2 v[36:37], v[26:27], off offset:32
	s_cbranch_scc1 .LBB0_1201
	s_mov_b32 s12, s10
	s_cmpk_gt_i32 s41, 0xaf
	s_cbranch_scc1 .LBB0_1201
	s_cmpk_gt_i32 s41, 0x9f
	s_mov_b64 s[2:3], -1
	s_cbranch_scc0 .LBB0_1238
	s_lshl_b32 s2, s41, 2
	s_add_i32 s2, s2, 0x7ffffd80
	s_and_b32 s13, s2, 0x7ffffff8
	s_and_b32 s2, s41, 1
	s_or_b32 s28, s2, 20
	s_mov_b64 s[2:3], 0

.LBB0_1298:
	s_mov_b32 s98, 0
	v_mov_b32_e32 v255, 0x0
	v_bfe_u32 v1, v0, 0, 1
	v_lshlrev_b32_e32 v1, 7, v1
	v_xor_b32_e32 v255, v255, v1
	v_bfe_u32 v1, v0, 1, 3
	v_mul_u32_u24_e32 v1, 0x110, v1
	v_xor_b32_e32 v255, v255, v1
	v_bfe_u32 v1, v0, 4, 2
	v_lshlrev_b32_e32 v1, 4, v1
	v_xor_b32_e32 v255, v255, v1
	v_bfe_u32 v1, v0, 8, 1
	v_lshlrev_b32_e32 v1, 14, v1
	v_xor_b32_e32 v255, v255, v1
	v_mov_b32_e32 v254, 0x10000
	v_bfe_u32 v1, v0, 0, 1
	v_lshlrev_b32_e32 v1, 7, v1
	v_xor_b32_e32 v254, v254, v1
	v_bfe_u32 v1, v0, 1, 3
	v_mul_u32_u24_e32 v1, 0x110, v1
	v_xor_b32_e32 v254, v254, v1
	v_bfe_u32 v1, v0, 4, 2
	v_lshlrev_b32_e32 v1, 4, v1
	v_xor_b32_e32 v254, v254, v1
	v_bfe_u32 v1, v0, 8, 1
	v_lshlrev_b32_e32 v1, 14, v1
	v_xor_b32_e32 v254, v254, v1
	v_mov_b32_e32 v253, 0x880
	v_bfe_u32 v1, v0, 0, 1
	v_lshlrev_b32_e32 v1, 7, v1
	v_xor_b32_e32 v253, v253, v1
	v_bfe_u32 v1, v0, 1, 3
	v_mul_u32_u24_e32 v1, 0x110, v1
	v_xor_b32_e32 v253, v253, v1
	v_bfe_u32 v1, v0, 4, 2
	v_lshlrev_b32_e32 v1, 4, v1
	v_xor_b32_e32 v253, v253, v1
	v_bfe_u32 v1, v0, 8, 1
	v_lshlrev_b32_e32 v1, 14, v1
	v_xor_b32_e32 v253, v253, v1
	v_mov_b32_e32 v252, 0x10880
	v_bfe_u32 v1, v0, 0, 1
	v_lshlrev_b32_e32 v1, 7, v1
	v_xor_b32_e32 v252, v252, v1
	v_bfe_u32 v1, v0, 1, 3
	v_mul_u32_u24_e32 v1, 0x110, v1
	v_xor_b32_e32 v252, v252, v1
	v_bfe_u32 v1, v0, 4, 2
	v_lshlrev_b32_e32 v1, 4, v1
	v_xor_b32_e32 v252, v252, v1
	v_bfe_u32 v1, v0, 8, 1
	v_lshlrev_b32_e32 v1, 14, v1
	v_xor_b32_e32 v252, v252, v1
	v_mov_b32_e32 v251, 0x8000
	v_bfe_u32 v1, v0, 0, 1
	v_lshlrev_b32_e32 v1, 7, v1
	v_xor_b32_e32 v251, v251, v1
	v_bfe_u32 v1, v0, 1, 3
	v_mul_u32_u24_e32 v1, 0x110, v1
	v_xor_b32_e32 v251, v251, v1
	v_bfe_u32 v1, v0, 4, 2
	v_lshlrev_b32_e32 v1, 4, v1
	v_xor_b32_e32 v251, v251, v1
	v_bfe_u32 v1, v0, 6, 2
	v_lshlrev_b32_e32 v1, 13, v1
	v_xor_b32_e32 v251, v251, v1
	v_mov_b32_e32 v250, 0x18000
	v_bfe_u32 v1, v0, 0, 1
	v_lshlrev_b32_e32 v1, 7, v1
	v_xor_b32_e32 v250, v250, v1
	v_bfe_u32 v1, v0, 1, 3
	v_mul_u32_u24_e32 v1, 0x110, v1
	v_xor_b32_e32 v250, v250, v1
	v_bfe_u32 v1, v0, 4, 2
	v_lshlrev_b32_e32 v1, 4, v1
	v_xor_b32_e32 v250, v250, v1
	v_bfe_u32 v1, v0, 6, 2
	v_lshlrev_b32_e32 v1, 13, v1
	v_xor_b32_e32 v250, v250, v1
	v_mov_b32_e32 v249, 0x8880
	v_bfe_u32 v1, v0, 0, 1
	v_lshlrev_b32_e32 v1, 7, v1
	v_xor_b32_e32 v249, v249, v1
	v_bfe_u32 v1, v0, 1, 3
	v_mul_u32_u24_e32 v1, 0x110, v1
	v_xor_b32_e32 v249, v249, v1
	v_bfe_u32 v1, v0, 4, 2
	v_lshlrev_b32_e32 v1, 4, v1
	v_xor_b32_e32 v249, v249, v1
	v_bfe_u32 v1, v0, 6, 2
	v_lshlrev_b32_e32 v1, 13, v1
	v_xor_b32_e32 v249, v249, v1
	v_mov_b32_e32 v248, 0x18880
	v_bfe_u32 v1, v0, 0, 1
	v_lshlrev_b32_e32 v1, 7, v1
	v_xor_b32_e32 v248, v248, v1
	v_bfe_u32 v1, v0, 1, 3
	v_mul_u32_u24_e32 v1, 0x110, v1
	v_xor_b32_e32 v248, v248, v1
	v_bfe_u32 v1, v0, 4, 2
	v_lshlrev_b32_e32 v1, 4, v1
	v_xor_b32_e32 v248, v248, v1
	v_bfe_u32 v1, v0, 6, 2
	v_lshlrev_b32_e32 v1, 13, v1
	v_xor_b32_e32 v248, v248, v1
	v_mov_b32_e32 v247, 0x40
	v_bfe_u32 v1, v0, 0, 1
	v_lshlrev_b32_e32 v1, 7, v1
	v_xor_b32_e32 v247, v247, v1
	v_bfe_u32 v1, v0, 1, 3
	v_mul_u32_u24_e32 v1, 0x110, v1
	v_xor_b32_e32 v247, v247, v1
	v_bfe_u32 v1, v0, 4, 2
	v_lshlrev_b32_e32 v1, 4, v1
	v_xor_b32_e32 v247, v247, v1
	v_bfe_u32 v1, v0, 8, 1
	v_lshlrev_b32_e32 v1, 14, v1
	v_xor_b32_e32 v247, v247, v1
	v_mov_b32_e32 v246, 0x10040
	v_bfe_u32 v1, v0, 0, 1
	v_lshlrev_b32_e32 v1, 7, v1
	v_xor_b32_e32 v246, v246, v1
	v_bfe_u32 v1, v0, 1, 3
	v_mul_u32_u24_e32 v1, 0x110, v1
	v_xor_b32_e32 v246, v246, v1
	v_bfe_u32 v1, v0, 4, 2
	v_lshlrev_b32_e32 v1, 4, v1
	v_xor_b32_e32 v246, v246, v1
	v_bfe_u32 v1, v0, 8, 1
	v_lshlrev_b32_e32 v1, 14, v1
	v_xor_b32_e32 v246, v246, v1
	v_mov_b32_e32 v245, 0x8c0
	v_bfe_u32 v1, v0, 0, 1
	v_lshlrev_b32_e32 v1, 7, v1
	v_xor_b32_e32 v245, v245, v1
	v_bfe_u32 v1, v0, 1, 3
	v_mul_u32_u24_e32 v1, 0x110, v1
	v_xor_b32_e32 v245, v245, v1
	v_bfe_u32 v1, v0, 4, 2
	v_lshlrev_b32_e32 v1, 4, v1
	v_xor_b32_e32 v245, v245, v1
	v_bfe_u32 v1, v0, 8, 1
	v_lshlrev_b32_e32 v1, 14, v1
	v_xor_b32_e32 v245, v245, v1
	v_mov_b32_e32 v244, 0x108c0
	v_bfe_u32 v1, v0, 0, 1
	v_lshlrev_b32_e32 v1, 7, v1
	v_xor_b32_e32 v244, v244, v1
	v_bfe_u32 v1, v0, 1, 3
	v_mul_u32_u24_e32 v1, 0x110, v1
	v_xor_b32_e32 v244, v244, v1
	v_bfe_u32 v1, v0, 4, 2
	v_lshlrev_b32_e32 v1, 4, v1
	v_xor_b32_e32 v244, v244, v1
	v_bfe_u32 v1, v0, 8, 1
	v_lshlrev_b32_e32 v1, 14, v1
	v_xor_b32_e32 v244, v244, v1
	v_mov_b32_e32 v243, 0x8040
	v_bfe_u32 v1, v0, 0, 1
	v_lshlrev_b32_e32 v1, 7, v1
	v_xor_b32_e32 v243, v243, v1
	v_bfe_u32 v1, v0, 1, 3
	v_mul_u32_u24_e32 v1, 0x110, v1
	v_xor_b32_e32 v243, v243, v1
	v_bfe_u32 v1, v0, 4, 2
	v_lshlrev_b32_e32 v1, 4, v1
	v_xor_b32_e32 v243, v243, v1
	v_bfe_u32 v1, v0, 6, 2
	v_lshlrev_b32_e32 v1, 13, v1
	v_xor_b32_e32 v243, v243, v1
	v_mov_b32_e32 v242, 0x18040
	v_bfe_u32 v1, v0, 0, 1
	v_lshlrev_b32_e32 v1, 7, v1
	v_xor_b32_e32 v242, v242, v1
	v_bfe_u32 v1, v0, 1, 3
	v_mul_u32_u24_e32 v1, 0x110, v1
	v_xor_b32_e32 v242, v242, v1
	v_bfe_u32 v1, v0, 4, 2
	v_lshlrev_b32_e32 v1, 4, v1
	v_xor_b32_e32 v242, v242, v1
	v_bfe_u32 v1, v0, 6, 2
	v_lshlrev_b32_e32 v1, 13, v1
	v_xor_b32_e32 v242, v242, v1
	v_mov_b32_e32 v241, 0x88c0
	v_bfe_u32 v1, v0, 0, 1
	v_lshlrev_b32_e32 v1, 7, v1
	v_xor_b32_e32 v241, v241, v1
	v_bfe_u32 v1, v0, 1, 3
	v_mul_u32_u24_e32 v1, 0x110, v1
	v_xor_b32_e32 v241, v241, v1
	v_bfe_u32 v1, v0, 4, 2
	v_lshlrev_b32_e32 v1, 4, v1
	v_xor_b32_e32 v241, v241, v1
	v_bfe_u32 v1, v0, 6, 2
	v_lshlrev_b32_e32 v1, 13, v1
	v_xor_b32_e32 v241, v241, v1
	v_mov_b32_e32 v237, 0x188c0
	v_bfe_u32 v1, v0, 0, 1
	v_lshlrev_b32_e32 v1, 7, v1
	v_xor_b32_e32 v237, v237, v1
	v_bfe_u32 v1, v0, 1, 3
	v_mul_u32_u24_e32 v1, 0x110, v1
	v_xor_b32_e32 v237, v237, v1
	v_bfe_u32 v1, v0, 4, 2
	v_lshlrev_b32_e32 v1, 4, v1
	v_xor_b32_e32 v237, v237, v1
	v_bfe_u32 v1, v0, 6, 2
	v_lshlrev_b32_e32 v1, 13, v1
	v_xor_b32_e32 v237, v237, v1
	v_mov_b32_e32 v236, 0x0
	v_bfe_u32 v1, v0, 0, 4
	v_lshlrev_b32_e32 v1, 4, v1
	v_xor_b32_e32 v236, v236, v1
	v_bfe_u32 v1, v0, 4, 4
	v_mul_u32_u24_e32 v1, 0x110, v1
	v_xor_b32_e32 v236, v236, v1
	v_bfe_u32 v1, v0, 8, 1
	v_lshlrev_b32_e32 v1, 12, v1
	v_xor_b32_e32 v236, v236, v1
	v_mov_b32_e32 v235, 0x10000
	v_bfe_u32 v1, v0, 0, 4
	v_lshlrev_b32_e32 v1, 4, v1
	v_xor_b32_e32 v235, v235, v1
	v_bfe_u32 v1, v0, 4, 4
	v_mul_u32_u24_e32 v1, 0x110, v1
	v_xor_b32_e32 v235, v235, v1
	v_bfe_u32 v1, v0, 8, 1
	v_lshlrev_b32_e32 v1, 12, v1
	v_xor_b32_e32 v235, v235, v1
	v_mov_b32_e32 v234, 0x0
	v_bfe_u32 v1, v0, 0, 3
	v_lshlrev_b32_e32 v1, 4, v1
	v_add_u32_e32 v234, v234, v1
	v_bfe_u32 v1, v0, 3, 6
	v_mul_u32_u24_e32 v1, 0x1600, v1
	v_add_u32_e32 v234, v234, v1
	v_mov_b32_e32 v233, 0x58000
	v_bfe_u32 v1, v0, 0, 3
	v_lshlrev_b32_e32 v1, 4, v1
	v_add_u32_e32 v233, v233, v1
	v_bfe_u32 v1, v0, 3, 6
	v_mul_u32_u24_e32 v1, 0x1600, v1
	v_add_u32_e32 v233, v233, v1
	v_mov_b32_e32 v232, 0xb0000
	v_bfe_u32 v1, v0, 0, 3
	v_lshlrev_b32_e32 v1, 4, v1
	v_add_u32_e32 v232, v232, v1
	v_bfe_u32 v1, v0, 3, 6
	v_mul_u32_u24_e32 v1, 0x1600, v1
	v_add_u32_e32 v232, v232, v1
	v_mov_b32_e32 v231, 0x108000
	v_bfe_u32 v1, v0, 0, 3
	v_lshlrev_b32_e32 v1, 4, v1
	v_add_u32_e32 v231, v231, v1
	v_bfe_u32 v1, v0, 3, 6
	v_mul_u32_u24_e32 v1, 0x1600, v1
	v_add_u32_e32 v231, v231, v1
	v_mov_b32_e32 v1, v0
	s_load_dword s2, s[0:1], 0xe0
	s_mov_b32 s3, s10
	v_mov_b32_e32 v1, v0
	s_waitcnt lgkmcnt(0)
	s_lshr_b32 s11, s2, 3
	s_waitcnt vmcnt(0)
	v_cvt_f32_u32_e32 v2, s11
	s_mov_b32 s2, s10
	s_ashr_i32 s3, s2, 3
	v_rcp_iflag_f32_e32 v2, v2
	s_ashr_i32 s4, s2, 31
	s_sub_i32 s2, 0, s11
	s_abs_i32 s3, s3
	v_mul_f32_e32 v1, 0x4f7ffffe, v2
	v_cvt_u32_f32_e32 v1, v1
	s_mov_b32 s50, 0
	v_readfirstlane_b32 s5, v1
	s_mul_i32 s2, s2, s5
	s_mul_hi_u32 s2, s5, s2
	s_add_i32 s2, s5, s2
	s_mul_hi_u32 s5, s3, s2
	s_mul_i32 s5, s5, s11
	s_sub_i32 s3, s3, s5
	s_sub_i32 s5, s3, s11
	s_cmp_ge_u32 s3, s11
	s_cselect_b32 s3, s5, s3
	s_sub_i32 s5, s3, s11
	s_cmp_ge_u32 s3, s11
	s_cselect_b32 s3, s5, s3
	s_xor_b32 s3, s3, s4
	s_sub_i32 s28, s3, s4
	s_mov_b32 s3, s10
	s_cmp_gt_i32 s28, 31
	s_cbranch_scc1 .LBB0_1362
	s_load_dwordx4 s[4:7], s[16:17], 0xc8
	s_mov_b32 s3, s10
	v_mov_b32_e32 v82, 0
	v_mov_b32_e32 v1, v0
	s_waitcnt lgkmcnt(0)
	s_add_u32 s12, s4, 0x2000000
	s_addc_u32 s13, s5, 0
	s_add_u32 s14, s6, 0x9000
	s_addc_u32 s15, s7, 0
	s_add_u32 s29, s6, 0x37f0000
	s_addc_u32 s30, s7, 0
	s_add_u32 s31, s6, 0x1270000
	s_addc_u32 s33, s7, 0
	s_ashr_i32 s6, s28, 31
	s_lshr_b32 s6, s6, 27
	s_add_i32 s6, s28, s6
	s_ashr_i32 s6, s6, 5
	s_lshl_b32 s7, s28, 1
	s_lshl_b32 s20, s6, 6
	s_sub_i32 s7, s7, s20
	s_lshl_b32 s6, s6, 2
	s_and_b32 s20, s28, 3
	s_or_b32 s34, s6, s20
	s_sub_i32 s6, s11, s28
	s_add_i32 s6, s6, 31
	s_mul_hi_u32 s2, s6, s2
	s_mul_i32 s20, s2, s11
	s_sub_i32 s6, s6, s20
	s_add_i32 s20, s2, 1
	s_sub_i32 s21, s6, s11
	s_cmp_ge_u32 s6, s11
	s_cselect_b32 s2, s20, s2
	s_cselect_b32 s6, s21, s6
	s_add_i32 s20, s2, 1
	s_cmp_ge_u32 s6, s11
	s_cselect_b32 s41, s20, s2
	s_and_b32 s2, s3, 7
	s_and_b32 s3, s7, -8
	s_movk_i32 s35, 0xb00
	v_lshrrev_b32_e32 v2, 3, v1
	s_or_b32 s36, s2, s3
	s_lshl_b32 s2, s34, 8
	s_mul_i32 s3, s34, 0x160000
	v_mul_lo_u32 v2, v2, s35
	v_lshlrev_b32_e32 v1, 3, v1
	s_mul_hi_i32 s6, s2, 0x1600
	s_add_u32 s2, s31, s3
	v_and_or_b32 v1, v1, 56, v2
	v_mov_b32_e32 v239, 0
	s_addc_u32 s3, s33, s6
	v_lshlrev_b32_e32 v238, 1, v1
	v_lshl_add_u64 v[2:3], s[2:3], 0, v[238:239]
	s_mov_b32 s37, 0x108000
	v_add_co_u32_e32 v34, vcc, s37, v2
	s_mov_b32 s20, 0xb0000
	s_nop 0
	v_addc_co_u32_e32 v35, vcc, 0, v3, vcc
	v_add_co_u32_e32 v36, vcc, s20, v2
	s_lshl_b32 s6, s36, 8
	s_mul_i32 s7, s36, 0x160000
	v_addc_co_u32_e32 v37, vcc, 0, v3, vcc
	s_mov_b32 s38, 0x58000
	s_mul_hi_i32 s21, s6, 0x1600
	s_add_u32 s6, s29, s7
	v_add_co_u32_e32 v2, vcc, s38, v2
	s_addc_u32 s7, s30, s21
	s_nop 0
	v_addc_co_u32_e32 v3, vcc, 0, v3, vcc
	v_lshl_add_u64 v[22:23], s[6:7], 0, v[238:239]
	v_add_co_u32_e32 v24, vcc, s20, v22
	global_load_dwordx4 v[2:5], v[2:3], off
	s_nop 0
	v_addc_co_u32_e32 v25, vcc, 0, v23, vcc
	v_add_co_u32_e32 v26, vcc, s38, v22
	v_mov_b32_e32 v1, v0
	s_nop 0
	v_addc_co_u32_e32 v27, vcc, 0, v23, vcc
	v_add_co_u32_e32 v38, vcc, s37, v22
	global_load_dwordx4 v[6:9], v[24:25], off
	global_load_dwordx4 v[10:13], v[26:27], off
	global_load_dwordx4 v[14:17], v238, s[2:3]
	global_load_dwordx4 v[18:21], v238, s[6:7]
	v_addc_co_u32_e32 v39, vcc, 0, v23, vcc
	global_load_dwordx4 v[22:25], v[38:39], off
	global_load_dwordx4 v[26:29], v[36:37], off
	global_load_dwordx4 v[30:33], v[34:35], off
	s_movk_i32 s40, 0xf0
	v_ashrrev_i32_e32 v34, 4, v1
	v_xor_b32_e32 v1, v34, v1
	v_lshlrev_b32_e32 v34, 8, v34
	v_lshlrev_b32_e32 v1, 4, v1
	v_and_or_b32 v1, v1, s40, v34
	s_mov_b32 s39, 2
	s_mul_i32 s41, s41, 44
	s_movk_i32 s42, 0xff80
	s_mov_b32 s43, 0x10000
	s_mov_b32 s44, 0x11000
	s_movk_i32 s45, 0x1800
	s_movk_i32 s46, 0x1fff
	v_mov_b32_e32 v240, 0x8040
	s_mov_b32 s26, 2
	s_mov_b32 s47, s28
	s_mov_b32 s48, s34
	s_mov_b32 s49, s36
	v_mov_b32_e32 v83, v82
	v_mov_b32_e32 v84, v82
	v_mov_b32_e32 v85, v82
	v_mov_b32_e32 v102, v82
	v_mov_b32_e32 v103, v82
	v_mov_b32_e32 v104, v82
	v_mov_b32_e32 v105, v82
	v_mov_b32_e32 v106, v82
	v_mov_b32_e32 v107, v82
	v_mov_b32_e32 v108, v82
	v_mov_b32_e32 v109, v82
	v_mov_b32_e32 v110, v82
	v_mov_b32_e32 v111, v82
	v_mov_b32_e32 v112, v82
	v_mov_b32_e32 v113, v82
	s_waitcnt vmcnt(4)
	ds_write_b128 v1, v[14:17] offset:32768
	s_waitcnt vmcnt(3)
	ds_write_b128 v1, v[18:21]
	ds_write_b128 v1, v[2:5] offset:40960
	ds_write_b128 v1, v[10:13] offset:8192
	ds_write_b128 v1, v[6:9] offset:16384
	s_waitcnt vmcnt(2)
	ds_write_b128 v1, v[22:25] offset:24576
	s_waitcnt vmcnt(1)
	ds_write_b128 v1, v[26:29] offset:49152
	s_waitcnt vmcnt(0)
	ds_write_b128 v1, v[30:33] offset:57344
	v_mov_b32_e32 v1, v0
	v_mov_b32_e32 v114, v82
	v_lshrrev_b32_e32 v2, 3, v1
	v_mul_lo_u32 v2, v2, s35
	v_lshlrev_b32_e32 v1, 3, v1
	v_and_or_b32 v1, v1, 56, v2
	v_lshlrev_b32_e32 v238, 1, v1
	v_lshl_add_u64 v[10:11], s[2:3], 0, v[238:239]
	v_add_co_u32_e32 v12, vcc, s37, v10
	v_lshl_add_u64 v[16:17], s[6:7], 0, v[238:239]
	s_nop 0
	v_addc_co_u32_e32 v13, vcc, 0, v11, vcc
	v_add_co_u32_e32 v14, vcc, s20, v10
	v_mov_b32_e32 v1, 0x10000
	s_nop 0
	v_addc_co_u32_e32 v15, vcc, 0, v11, vcc
	global_load_dwordx4 v[2:5], v[12:13], off offset:128
	global_load_dwordx4 v[6:9], v[14:15], off offset:128
	v_add_co_u32_e32 v14, vcc, s38, v10
	v_mov_b32_e32 v115, v82
	s_nop 0
	v_addc_co_u32_e32 v15, vcc, 0, v11, vcc
	v_add_co_u32_e32 v22, vcc, s37, v16
	v_mov_b32_e32 v116, v82
	s_nop 0
	v_addc_co_u32_e32 v23, vcc, 0, v17, vcc
	v_add_co_u32_e32 v34, vcc, s20, v16
	global_load_dwordx4 v[10:13], v[14:15], off offset:128
	global_load_dwordx4 v[18:21], v[22:23], off offset:128
	v_addc_co_u32_e32 v35, vcc, 0, v17, vcc
	v_add_co_u32_e32 v36, vcc, s38, v16
	v_mov_b32_e32 v117, v82
	s_nop 0
	v_addc_co_u32_e32 v37, vcc, 0, v17, vcc
	global_load_dwordx4 v[22:25], v[34:35], off offset:128
	global_load_dwordx4 v[26:29], v[36:37], off offset:128
	global_load_dwordx4 v[14:17], v238, s[2:3] offset:128
	global_load_dwordx4 v[30:33], v238, s[6:7] offset:128
	v_mov_b32_e32 v118, v82
	v_mov_b32_e32 v119, v82
	v_mov_b32_e32 v120, v82
	v_mov_b32_e32 v121, v82
	v_mov_b32_e32 v122, v82
	v_mov_b32_e32 v123, v82
	v_mov_b32_e32 v124, v82
	v_mov_b32_e32 v125, v82
	v_mov_b32_e32 v126, v82
	v_mov_b32_e32 v127, v82
	v_mov_b32_e32 v128, v82
	v_mov_b32_e32 v129, v82
	v_mov_b32_e32 v130, v82
	v_mov_b32_e32 v131, v82
	v_mov_b32_e32 v132, v82
	v_mov_b32_e32 v133, v82
	v_mov_b32_e32 v134, v82
	v_mov_b32_e32 v135, v82
	v_mov_b32_e32 v136, v82
	v_mov_b32_e32 v137, v82
	v_mov_b32_e32 v138, v82
	v_mov_b32_e32 v139, v82
	v_mov_b32_e32 v140, v82
	v_mov_b32_e32 v141, v82
	v_mov_b32_e32 v142, v82
	v_mov_b32_e32 v143, v82
	v_mov_b32_e32 v144, v82
	v_mov_b32_e32 v145, v82
	v_mov_b32_e32 v146, v82
	v_mov_b32_e32 v147, v82
	v_mov_b32_e32 v148, v82
	v_mov_b32_e32 v149, v82
	v_mov_b32_e32 v150, v82
	v_mov_b32_e32 v151, v82
	v_mov_b32_e32 v152, v82
	v_mov_b32_e32 v153, v82
	v_mov_b32_e32 v154, v82
	v_mov_b32_e32 v155, v82
	v_mov_b32_e32 v156, v82
	v_mov_b32_e32 v157, v82
	v_mov_b32_e32 v158, v82
	v_mov_b32_e32 v159, v82
	v_mov_b32_e32 v160, v82
	v_mov_b32_e32 v161, v82
	v_mov_b32_e32 v98, v82
	v_mov_b32_e32 v99, v82
	v_mov_b32_e32 v100, v82
	v_mov_b32_e32 v101, v82
	v_mov_b32_e32 v94, v82
	v_mov_b32_e32 v95, v82
	v_mov_b32_e32 v96, v82
	v_mov_b32_e32 v97, v82
	v_mov_b32_e32 v90, v82
	v_mov_b32_e32 v91, v82
	v_mov_b32_e32 v92, v82
	v_mov_b32_e32 v93, v82
	v_mov_b32_e32 v86, v82
	v_mov_b32_e32 v87, v82
	v_mov_b32_e32 v88, v82
	v_mov_b32_e32 v89, v82
	v_mov_b32_e32 v78, v82
	v_mov_b32_e32 v79, v82
	v_mov_b32_e32 v80, v82
	v_mov_b32_e32 v81, v82
	v_mov_b32_e32 v74, v82
	v_mov_b32_e32 v75, v82
	v_mov_b32_e32 v76, v82
	v_mov_b32_e32 v77, v82
	v_mov_b32_e32 v70, v82
	v_mov_b32_e32 v71, v82
	v_mov_b32_e32 v72, v82
	v_mov_b32_e32 v73, v82
	v_mov_b32_e32 v66, v82
	v_mov_b32_e32 v67, v82
	v_mov_b32_e32 v68, v82
	v_mov_b32_e32 v69, v82
	v_mov_b32_e32 v62, v82
	v_mov_b32_e32 v63, v82
	v_mov_b32_e32 v64, v82
	v_mov_b32_e32 v65, v82
	v_mov_b32_e32 v58, v82
	v_mov_b32_e32 v59, v82
	v_mov_b32_e32 v60, v82
	v_mov_b32_e32 v61, v82
	v_mov_b32_e32 v54, v82
	v_mov_b32_e32 v55, v82
	v_mov_b32_e32 v56, v82
	v_mov_b32_e32 v57, v82
	v_mov_b32_e32 v50, v82
	v_mov_b32_e32 v51, v82
	v_mov_b32_e32 v52, v82
	v_mov_b32_e32 v53, v82
	v_mov_b32_e32 v46, v82
	v_mov_b32_e32 v47, v82
	v_mov_b32_e32 v48, v82
	v_mov_b32_e32 v49, v82
	v_mov_b32_e32 v42, v82
	v_mov_b32_e32 v43, v82
	v_mov_b32_e32 v44, v82
	v_mov_b32_e32 v45, v82
	v_mov_b32_e32 v38, v82
	v_mov_b32_e32 v39, v82
	v_mov_b32_e32 v40, v82
	v_mov_b32_e32 v41, v82
	v_mov_b32_e32 v34, v82
	v_mov_b32_e32 v35, v82
	v_mov_b32_e32 v36, v82
	v_mov_b32_e32 v37, v82
	s_waitcnt lgkmcnt(0)
	s_barrier
	s_waitcnt vmcnt(0)
	s_branch .LBB0_1302

.Lnodef_J0_4:
	ds_read_b128 v[170:173], v255 offset:4096
	ds_read_b128 v[174:177], v253 offset:4096
	s_add_i32 s2, s39, -1
	s_cmp_lt_i32 s2, s41
	s_cselect_b64 s[22:23], -1, 0
	s_cmp_ge_i32 s2, s41
	s_waitcnt lgkmcnt(3)
	v_mfma_f32_16x16x32_bf16 v[158:161], v[178:181], v[162:165], v[158:161]
	v_mfma_f32_16x16x32_bf16 v[154:157], v[182:185], v[162:165], v[154:157]
	v_mfma_f32_16x16x32_bf16 v[150:153], v[186:189], v[162:165], v[150:153]
	v_mfma_f32_16x16x32_bf16 v[146:149], v[190:193], v[162:165], v[146:149]
	ds_read_b128 v[162:165], v255 offset:8192
	s_waitcnt lgkmcnt(3)
	v_mfma_f32_16x16x32_bf16 v[142:145], v[178:181], v[166:169], v[142:145]
	v_mfma_f32_16x16x32_bf16 v[138:141], v[182:185], v[166:169], v[138:141]
	v_mfma_f32_16x16x32_bf16 v[134:137], v[186:189], v[166:169], v[134:137]
	v_mfma_f32_16x16x32_bf16 v[130:133], v[190:193], v[166:169], v[130:133]
	ds_read_b128 v[166:169], v253 offset:8192
	s_waitcnt lgkmcnt(3)
	v_mfma_f32_16x16x32_bf16 v[126:129], v[178:181], v[170:173], v[126:129]
	v_mfma_f32_16x16x32_bf16 v[122:125], v[182:185], v[170:173], v[122:125]
	v_mfma_f32_16x16x32_bf16 v[118:121], v[186:189], v[170:173], v[118:121]
	v_mfma_f32_16x16x32_bf16 v[114:117], v[190:193], v[170:173], v[114:117]
	s_waitcnt vmcnt(6)
	ds_write_b128 v235, v[30:33]
	ds_write_b128 v235, v[26:29] offset:8192
.LBB0_1304:
	s_lshl_b32 s2, s49, 8
	s_mul_i32 s20, s49, 0xb0000
	s_mul_hi_i32 s21, s2, 0xb00
	s_lshl_b32 s2, s26, 6
	s_ashr_i32 s3, s2, 31
	s_lshl_b64 s[6:7], s[20:21], 1
	s_add_u32 s24, s29, s6
	s_addc_u32 s25, s30, s7
	s_lshl_b64 s[6:7], s[2:3], 1
	s_add_u32 s24, s24, s6
	s_addc_u32 s25, s25, s7
	global_load_dwordx4 v[26:29], v234, s[24:25]
	global_load_dwordx4 v[30:33], v233, s[24:25]
	s_andn2_b64 vcc, exec, s[22:23]
	ds_read_b128 v[170:173], v255 offset:12288
	s_waitcnt lgkmcnt(5)
	v_mfma_f32_16x16x32_bf16 v[110:113], v[178:181], v[174:177], v[110:113]
	v_mfma_f32_16x16x32_bf16 v[106:109], v[182:185], v[174:177], v[106:109]
	v_mfma_f32_16x16x32_bf16 v[102:105], v[186:189], v[174:177], v[102:105]
	v_mfma_f32_16x16x32_bf16 v[82:85], v[190:193], v[174:177], v[82:85]
	ds_read_b128 v[174:177], v253 offset:12288
	s_waitcnt lgkmcnt(5)
	v_mfma_f32_16x16x32_bf16 v[98:101], v[178:181], v[162:165], v[98:101]
	v_mfma_f32_16x16x32_bf16 v[94:97], v[182:185], v[162:165], v[94:97]
	v_mfma_f32_16x16x32_bf16 v[90:93], v[186:189], v[162:165], v[90:93]
	v_mfma_f32_16x16x32_bf16 v[86:89], v[190:193], v[162:165], v[86:89]
	s_waitcnt lgkmcnt(4)
	v_mfma_f32_16x16x32_bf16 v[78:81], v[178:181], v[166:169], v[78:81]
	v_mfma_f32_16x16x32_bf16 v[74:77], v[182:185], v[166:169], v[74:77]
	v_mfma_f32_16x16x32_bf16 v[70:73], v[186:189], v[166:169], v[70:73]
	v_mfma_f32_16x16x32_bf16 v[66:69], v[190:193], v[166:169], v[66:69]
	s_waitcnt vmcnt(6)
	ds_write_b128 v235, v[22:25] offset:16384
	ds_write_b128 v235, v[18:21] offset:24576
.LBB0_1306:
	global_load_dwordx4 v[18:21], v232, s[24:25]
	global_load_dwordx4 v[22:25], v231, s[24:25]
	s_and_b64 vcc, exec, s[2:3]
	ds_read_b128 v[194:197], v243
	ds_read_b128 v[198:201], v241
	ds_read_b128 v[202:205], v243 offset:4096
	ds_read_b128 v[206:209], v241 offset:4096
	ds_read_b128 v[162:165], v247
	ds_read_b128 v[166:169], v245
	s_waitcnt lgkmcnt(9)
	v_mfma_f32_16x16x32_bf16 v[62:65], v[178:181], v[170:173], v[62:65]
	v_mfma_f32_16x16x32_bf16 v[58:61], v[182:185], v[170:173], v[58:61]
	v_mfma_f32_16x16x32_bf16 v[54:57], v[186:189], v[170:173], v[54:57]
	v_mfma_f32_16x16x32_bf16 v[50:53], v[190:193], v[170:173], v[50:53]
	ds_read_b128 v[170:173], v247 offset:4096
	s_waitcnt lgkmcnt(9)
	v_mfma_f32_16x16x32_bf16 v[46:49], v[178:181], v[174:177], v[46:49]
	v_mfma_f32_16x16x32_bf16 v[42:45], v[182:185], v[174:177], v[42:45]
	v_mfma_f32_16x16x32_bf16 v[38:41], v[186:189], v[174:177], v[38:41]
	v_mfma_f32_16x16x32_bf16 v[34:37], v[190:193], v[174:177], v[34:37]
	s_waitcnt vmcnt(6)
	ds_write_b128 v235, v[14:17] offset:32768
	ds_write_b128 v235, v[10:13] offset:40960
.LBB0_1308:
	s_lshl_b32 s23, s48, 8
	s_mul_i32 s22, s48, 0xb0000
	s_mul_hi_i32 s23, s23, 0xb00
	s_lshl_b64 s[24:25], s[22:23], 1
	s_add_u32 s24, s31, s24
	s_addc_u32 s25, s33, s25
	s_add_u32 s6, s24, s6
	s_addc_u32 s7, s25, s7
	global_load_dwordx4 v[10:13], v234, s[6:7]
	global_load_dwordx4 v[14:17], v233, s[6:7]
	s_and_b64 vcc, exec, s[2:3]
	ds_read_b128 v[174:177], v245 offset:4096
	s_waitcnt lgkmcnt(5)
	v_mfma_f32_16x16x32_bf16 v[158:161], v[194:197], v[162:165], v[158:161]
	v_mfma_f32_16x16x32_bf16 v[154:157], v[198:201], v[162:165], v[154:157]
	v_mfma_f32_16x16x32_bf16 v[150:153], v[202:205], v[162:165], v[150:153]
	v_mfma_f32_16x16x32_bf16 v[146:149], v[206:209], v[162:165], v[146:149]
	ds_read_b128 v[162:165], v247 offset:8192
	s_waitcnt lgkmcnt(5)
	v_mfma_f32_16x16x32_bf16 v[142:145], v[194:197], v[166:169], v[142:145]
	v_mfma_f32_16x16x32_bf16 v[138:141], v[198:201], v[166:169], v[138:141]
	v_mfma_f32_16x16x32_bf16 v[134:137], v[202:205], v[166:169], v[134:137]
	v_mfma_f32_16x16x32_bf16 v[130:133], v[206:209], v[166:169], v[130:133]
	ds_read_b128 v[166:169], v245 offset:8192
	s_waitcnt lgkmcnt(5)
	v_mfma_f32_16x16x32_bf16 v[126:129], v[194:197], v[170:173], v[126:129]
	v_mfma_f32_16x16x32_bf16 v[122:125], v[198:201], v[170:173], v[122:125]
	v_mfma_f32_16x16x32_bf16 v[118:121], v[202:205], v[170:173], v[118:121]
	v_mfma_f32_16x16x32_bf16 v[114:117], v[206:209], v[170:173], v[114:117]
	s_waitcnt vmcnt(6)
	ds_write_b128 v235, v[6:9] offset:49152
	ds_write_b128 v235, v[2:5] offset:57344
.LBB0_1310:
	global_load_dwordx4 v[2:5], v232, s[6:7]
	global_load_dwordx4 v[6:9], v231, s[6:7]
	ds_read_b128 v[170:173], v247 offset:12288
	s_waitcnt lgkmcnt(5)
	v_mfma_f32_16x16x32_bf16 v[110:113], v[194:197], v[174:177], v[110:113]
	v_mfma_f32_16x16x32_bf16 v[106:109], v[198:201], v[174:177], v[106:109]
	v_mfma_f32_16x16x32_bf16 v[102:105], v[202:205], v[174:177], v[102:105]
	v_mfma_f32_16x16x32_bf16 v[82:85], v[206:209], v[174:177], v[82:85]
	ds_read_b128 v[174:177], v245 offset:12288
	s_waitcnt lgkmcnt(5)
	v_mfma_f32_16x16x32_bf16 v[98:101], v[194:197], v[162:165], v[98:101]
	v_mfma_f32_16x16x32_bf16 v[94:97], v[198:201], v[162:165], v[94:97]
	v_mfma_f32_16x16x32_bf16 v[90:93], v[202:205], v[162:165], v[90:93]
	v_mfma_f32_16x16x32_bf16 v[86:89], v[206:209], v[162:165], v[86:89]
	s_waitcnt lgkmcnt(4)
	v_mfma_f32_16x16x32_bf16 v[78:81], v[194:197], v[166:169], v[78:81]
	v_mfma_f32_16x16x32_bf16 v[74:77], v[198:201], v[166:169], v[74:77]
	v_mfma_f32_16x16x32_bf16 v[70:73], v[202:205], v[166:169], v[70:73]
	v_mfma_f32_16x16x32_bf16 v[66:69], v[206:209], v[166:169], v[66:69]
	s_add_i32 s51, s26, 1
	s_cmp_lg_u32 s51, 44
	s_cbranch_scc1 .LBB0_1314
	s_add_i32 s28, s28, s11
	s_cmp_gt_i32 s28, 31
	s_cbranch_scc1 .LBB0_1313
	s_ashr_i32 s3, s28, 31
	s_lshr_b32 s3, s3, 27
	s_add_i32 s3, s28, s3
	s_ashr_i32 s3, s3, 5
	s_mov_b32 s2, s10
	s_lshl_b32 s6, s3, 6
	s_lshl_b32 s7, s28, 1
	s_sub_i32 s6, s7, s6
	s_and_b32 s2, s2, 7
	s_and_b32 s6, s6, -8
	s_lshl_b32 s3, s3, 2
	s_and_b32 s7, s28, 3
	s_or_b32 s49, s2, s6
	s_or_b32 s48, s3, s7
	s_lshl_b32 s2, s49, 8
	s_mul_hi_i32 s21, s2, 0xb00
	s_lshl_b32 s2, s48, 8
	s_mul_i32 s20, s49, 0xb0000
	s_mul_i32 s22, s48, 0xb0000
	s_mul_hi_i32 s23, s2, 0xb00

.LBB0_1314:
	s_waitcnt lgkmcnt(0)
	s_barrier
	ds_read_b128 v[178:181], v250
	ds_read_b128 v[182:185], v248
	ds_read_b128 v[186:189], v250 offset:4096
	ds_read_b128 v[190:193], v248 offset:4096
	ds_read_b128 v[162:165], v254
	ds_read_b128 v[166:169], v252
	v_mfma_f32_16x16x32_bf16 v[62:65], v[194:197], v[170:173], v[62:65]
	v_mfma_f32_16x16x32_bf16 v[58:61], v[198:201], v[170:173], v[58:61]
	v_mfma_f32_16x16x32_bf16 v[54:57], v[202:205], v[170:173], v[54:57]
	v_mfma_f32_16x16x32_bf16 v[50:53], v[206:209], v[170:173], v[50:53]
	v_mfma_f32_16x16x32_bf16 v[46:49], v[194:197], v[174:177], v[46:49]
	v_mfma_f32_16x16x32_bf16 v[42:45], v[198:201], v[174:177], v[42:45]
	v_mfma_f32_16x16x32_bf16 v[38:41], v[202:205], v[174:177], v[38:41]
	v_mfma_f32_16x16x32_bf16 v[34:37], v[206:209], v[174:177], v[34:37]
	ds_read_b128 v[170:173], v254 offset:4096
	ds_read_b128 v[174:177], v252 offset:4096
	s_cmp_lt_i32 s39, s41
	s_cselect_b64 s[24:25], -1, 0
	s_cmp_ge_i32 s39, s41
	s_cselect_b64 s[6:7], -1, 0
	s_and_b64 vcc, exec, s[6:7]
	s_waitcnt lgkmcnt(3)
	v_mfma_f32_16x16x32_bf16 v[158:161], v[178:181], v[162:165], v[158:161]
	v_mfma_f32_16x16x32_bf16 v[154:157], v[182:185], v[162:165], v[154:157]
	v_mfma_f32_16x16x32_bf16 v[150:153], v[186:189], v[162:165], v[150:153]
	v_mfma_f32_16x16x32_bf16 v[146:149], v[190:193], v[162:165], v[146:149]
	ds_read_b128 v[162:165], v254 offset:8192
	s_waitcnt lgkmcnt(3)
	v_mfma_f32_16x16x32_bf16 v[142:145], v[178:181], v[166:169], v[142:145]
	v_mfma_f32_16x16x32_bf16 v[138:141], v[182:185], v[166:169], v[138:141]
	v_mfma_f32_16x16x32_bf16 v[134:137], v[186:189], v[166:169], v[134:137]
	v_mfma_f32_16x16x32_bf16 v[130:133], v[190:193], v[166:169], v[130:133]
	ds_read_b128 v[166:169], v252 offset:8192
	s_waitcnt lgkmcnt(3)
	v_mfma_f32_16x16x32_bf16 v[126:129], v[178:181], v[170:173], v[126:129]
	v_mfma_f32_16x16x32_bf16 v[122:125], v[182:185], v[170:173], v[122:125]
	v_mfma_f32_16x16x32_bf16 v[118:121], v[186:189], v[170:173], v[118:121]
	v_mfma_f32_16x16x32_bf16 v[114:117], v[190:193], v[170:173], v[114:117]
	s_waitcnt vmcnt(6)
	ds_write_b128 v236, v[26:29]
	ds_write_b128 v236, v[30:33] offset:8192
.LBB0_1316:
	s_lshl_b32 s2, s51, 6
	s_ashr_i32 s3, s2, 31
	s_lshl_b64 s[20:21], s[20:21], 1
	s_add_u32 s26, s29, s20
	s_addc_u32 s27, s30, s21
	s_lshl_b64 s[20:21], s[2:3], 1
	s_add_u32 s26, s26, s20
	s_addc_u32 s27, s27, s21
	global_load_dwordx4 v[30:33], v234, s[26:27]
	global_load_dwordx4 v[26:29], v233, s[26:27]
	s_andn2_b64 vcc, exec, s[24:25]
	ds_read_b128 v[170:173], v254 offset:12288
	s_waitcnt lgkmcnt(5)
	v_mfma_f32_16x16x32_bf16 v[110:113], v[178:181], v[174:177], v[110:113]
	v_mfma_f32_16x16x32_bf16 v[106:109], v[182:185], v[174:177], v[106:109]
	v_mfma_f32_16x16x32_bf16 v[102:105], v[186:189], v[174:177], v[102:105]
	v_mfma_f32_16x16x32_bf16 v[82:85], v[190:193], v[174:177], v[82:85]
	ds_read_b128 v[174:177], v252 offset:12288
	s_waitcnt lgkmcnt(5)
	v_mfma_f32_16x16x32_bf16 v[98:101], v[178:181], v[162:165], v[98:101]
	v_mfma_f32_16x16x32_bf16 v[94:97], v[182:185], v[162:165], v[94:97]
	v_mfma_f32_16x16x32_bf16 v[90:93], v[186:189], v[162:165], v[90:93]
	v_mfma_f32_16x16x32_bf16 v[86:89], v[190:193], v[162:165], v[86:89]
	s_waitcnt lgkmcnt(4)
	v_mfma_f32_16x16x32_bf16 v[78:81], v[178:181], v[166:169], v[78:81]
	v_mfma_f32_16x16x32_bf16 v[74:77], v[182:185], v[166:169], v[74:77]
	v_mfma_f32_16x16x32_bf16 v[70:73], v[186:189], v[166:169], v[70:73]
	v_mfma_f32_16x16x32_bf16 v[66:69], v[190:193], v[166:169], v[66:69]
	s_waitcnt vmcnt(6)
	ds_write_b128 v236, v[18:21] offset:16384
	ds_write_b128 v236, v[22:25] offset:24576
.LBB0_1318:
	global_load_dwordx4 v[22:25], v232, s[26:27]
	global_load_dwordx4 v[18:21], v231, s[26:27]
	s_and_b64 vcc, exec, s[2:3]
	ds_read_b128 v[194:197], v242
	ds_read_b128 v[198:201], v237
	ds_read_b128 v[202:205], v242 offset:4096
	ds_read_b128 v[206:209], v237 offset:4096
	ds_read_b128 v[162:165], v246
	ds_read_b128 v[166:169], v244
	s_waitcnt lgkmcnt(9)
	v_mfma_f32_16x16x32_bf16 v[62:65], v[178:181], v[170:173], v[62:65]
	v_mfma_f32_16x16x32_bf16 v[58:61], v[182:185], v[170:173], v[58:61]
	v_mfma_f32_16x16x32_bf16 v[54:57], v[186:189], v[170:173], v[54:57]
	v_mfma_f32_16x16x32_bf16 v[50:53], v[190:193], v[170:173], v[50:53]
	ds_read_b128 v[170:173], v246 offset:4096
	s_waitcnt lgkmcnt(9)
	v_mfma_f32_16x16x32_bf16 v[46:49], v[178:181], v[174:177], v[46:49]
	v_mfma_f32_16x16x32_bf16 v[42:45], v[182:185], v[174:177], v[42:45]
	v_mfma_f32_16x16x32_bf16 v[38:41], v[186:189], v[174:177], v[38:41]
	v_mfma_f32_16x16x32_bf16 v[34:37], v[190:193], v[174:177], v[34:37]
	s_waitcnt vmcnt(6)
	ds_write_b128 v236, v[10:13] offset:32768
	ds_write_b128 v236, v[14:17] offset:40960
.LBB0_1320:
	s_lshl_b64 s[22:23], s[22:23], 1
	s_add_u32 s22, s31, s22
	s_addc_u32 s23, s33, s23
	s_add_u32 s20, s22, s20
	s_addc_u32 s21, s23, s21
	global_load_dwordx4 v[14:17], v234, s[20:21]
	global_load_dwordx4 v[10:13], v233, s[20:21]
	s_and_b64 vcc, exec, s[2:3]
	ds_read_b128 v[174:177], v244 offset:4096
	s_waitcnt lgkmcnt(5)
	v_mfma_f32_16x16x32_bf16 v[158:161], v[194:197], v[162:165], v[158:161]
	v_mfma_f32_16x16x32_bf16 v[154:157], v[198:201], v[162:165], v[154:157]
	v_mfma_f32_16x16x32_bf16 v[150:153], v[202:205], v[162:165], v[150:153]
	v_mfma_f32_16x16x32_bf16 v[146:149], v[206:209], v[162:165], v[146:149]
	ds_read_b128 v[162:165], v246 offset:8192
	s_waitcnt lgkmcnt(5)
	v_mfma_f32_16x16x32_bf16 v[142:145], v[194:197], v[166:169], v[142:145]
	v_mfma_f32_16x16x32_bf16 v[138:141], v[198:201], v[166:169], v[138:141]
	v_mfma_f32_16x16x32_bf16 v[134:137], v[202:205], v[166:169], v[134:137]
	v_mfma_f32_16x16x32_bf16 v[130:133], v[206:209], v[166:169], v[130:133]
	ds_read_b128 v[166:169], v244 offset:8192
	s_waitcnt lgkmcnt(5)
	v_mfma_f32_16x16x32_bf16 v[126:129], v[194:197], v[170:173], v[126:129]
	v_mfma_f32_16x16x32_bf16 v[122:125], v[198:201], v[170:173], v[122:125]
	v_mfma_f32_16x16x32_bf16 v[118:121], v[202:205], v[170:173], v[118:121]
	v_mfma_f32_16x16x32_bf16 v[114:117], v[206:209], v[170:173], v[114:117]
	s_waitcnt vmcnt(6)
	ds_write_b128 v236, v[2:5] offset:49152
	ds_write_b128 v236, v[6:9] offset:57344
.LBB0_1322:
	global_load_dwordx4 v[6:9], v232, s[20:21]
	global_load_dwordx4 v[2:5], v231, s[20:21]
	ds_read_b128 v[170:173], v246 offset:12288
	s_waitcnt lgkmcnt(5)
	v_mfma_f32_16x16x32_bf16 v[110:113], v[194:197], v[174:177], v[110:113]
	v_mfma_f32_16x16x32_bf16 v[106:109], v[198:201], v[174:177], v[106:109]
	v_mfma_f32_16x16x32_bf16 v[102:105], v[202:205], v[174:177], v[102:105]
	v_mfma_f32_16x16x32_bf16 v[82:85], v[206:209], v[174:177], v[82:85]
	ds_read_b128 v[174:177], v244 offset:12288
	s_waitcnt lgkmcnt(5)
	v_mfma_f32_16x16x32_bf16 v[98:101], v[194:197], v[162:165], v[98:101]
	v_mfma_f32_16x16x32_bf16 v[94:97], v[198:201], v[162:165], v[94:97]
	v_mfma_f32_16x16x32_bf16 v[90:93], v[202:205], v[162:165], v[90:93]
	v_mfma_f32_16x16x32_bf16 v[86:89], v[206:209], v[162:165], v[86:89]
	s_waitcnt lgkmcnt(4)
	v_mfma_f32_16x16x32_bf16 v[78:81], v[194:197], v[166:169], v[78:81]
	v_mfma_f32_16x16x32_bf16 v[74:77], v[198:201], v[166:169], v[74:77]
	v_mfma_f32_16x16x32_bf16 v[70:73], v[202:205], v[166:169], v[70:73]
	v_mfma_f32_16x16x32_bf16 v[66:69], v[206:209], v[166:169], v[66:69]
	s_add_i32 s26, s51, 1
	s_cmp_lg_u32 s26, 44
	s_cbranch_scc1 .LBB0_1326
	s_add_i32 s28, s28, s11
	s_cmp_gt_i32 s28, 31
	s_cbranch_scc1 .LBB0_1325
	s_ashr_i32 s3, s28, 31
	s_lshr_b32 s3, s3, 27
	s_add_i32 s3, s28, s3
	s_ashr_i32 s3, s3, 5
	s_mov_b32 s2, s10
	s_lshl_b32 s20, s3, 6
	s_lshl_b32 s21, s28, 1
	s_sub_i32 s20, s21, s20
	s_and_b32 s2, s2, 7
	s_and_b32 s20, s20, -8
	s_lshl_b32 s3, s3, 2
	s_and_b32 s21, s28, 3
	s_or_b32 s48, s3, s21
	s_or_b32 s49, s2, s20

.LBB0_1326:
	s_add_i32 s50, s50, 2
	s_cmp_lg_u32 s50, 44
	s_waitcnt lgkmcnt(0)
	s_mov_b32 s98, 1
	s_cbranch_scc1 .LBB0_1301
	s_mov_b32 s98, 0
	v_mfma_f32_16x16x32_bf16 v[62:65], v[194:197], v[170:173], v[62:65]
	v_mfma_f32_16x16x32_bf16 v[58:61], v[198:201], v[170:173], v[58:61]
	v_mfma_f32_16x16x32_bf16 v[54:57], v[202:205], v[170:173], v[54:57]
	v_mfma_f32_16x16x32_bf16 v[50:53], v[206:209], v[170:173], v[50:53]
	v_mfma_f32_16x16x32_bf16 v[46:49], v[194:197], v[174:177], v[46:49]
	v_mfma_f32_16x16x32_bf16 v[42:45], v[198:201], v[174:177], v[42:45]
	v_mfma_f32_16x16x32_bf16 v[38:41], v[202:205], v[174:177], v[38:41]
	v_mfma_f32_16x16x32_bf16 v[34:37], v[206:209], v[174:177], v[34:37]
	s_nop 7
	s_nop 7
	v_mov_b32_e32 v172, v0
	s_nop 0
	v_ashrrev_i32_e32 v162, 1, v172
	v_and_b32_e32 v162, 0xffffff80, v162
	v_lshl_add_u32 v162, s36, 8, v162
	v_and_or_b32 v164, v172, 15, v162
	v_add_u32_e32 v162, 0xffffe000, v162
	v_ashrrev_i32_e32 v162, 11, v162
	v_mad_i32_i24 v162, v162, s45, s45
	v_cmp_lt_i32_e32 vcc, s46, v164
	v_ashrrev_i32_e32 v163, 31, v162
	s_and_saveexec_b64 s[2:3], vcc
	s_xor_b64 s[2:3], exec, s[2:3]
	v_add_u32_e32 v238, 0xffffe000, v164
	v_lshlrev_b64 v[166:167], 12, v[238:239]
	v_mov_b32_e32 v165, v239
	v_lshl_add_u64 v[168:169], s[12:13], 0, v[166:167]
	v_lshlrev_b64 v[170:171], 12, v[164:165]
	v_mov_b64_e32 v[166:167], v[162:163]
	s_andn2_saveexec_b64 s[2:3], s[2:3]
	v_ashrrev_i32_e32 v165, 31, v164
	v_lshlrev_b64 v[170:171], 12, v[164:165]
	v_lshl_add_u64 v[168:169], s[4:5], 0, v[170:171]
	v_mov_b64_e32 v[166:167], 0
	s_or_b64 exec, exec, s[2:3]
	v_and_b32_e32 v165, 0xc0, v172
	v_lshrrev_b32_e32 v172, 2, v172
	s_lshl_b32 s2, s34, 8
	v_and_b32_e32 v172, 12, v172
	v_or3_b32 v172, v165, s2, v172
	v_ashrrev_i32_e32 v173, 31, v172
	v_lshl_add_u64 v[176:177], v[166:167], 2, s[14:15]
	v_lshlrev_b64 v[166:167], 2, v[172:173]
	v_lshl_add_u64 v[180:181], v[168:169], 0, v[166:167]
	v_lshl_add_u64 v[182:183], v[176:177], 0, v[166:167]
	global_load_dwordx4 v[172:175], v[180:181], off
	global_load_dwordx4 v[176:179], v[182:183], off
	v_lshl_add_u64 v[168:169], s[4:5], 0, v[170:171]
	v_lshl_add_u64 v[184:185], v[168:169], 0, v[166:167]
	s_waitcnt vmcnt(0)
	v_pk_fma_f32 v[160:161], v[160:161], v[178:179], v[174:175]
	v_pk_fma_f32 v[158:159], v[158:159], v[176:177], v[172:173]
	global_store_dwordx4 v[184:185], v[158:161], off
	global_load_dwordx4 v[158:161], v[180:181], off offset:64
	s_nop 0
	global_load_dwordx4 v[168:171], v[182:183], off offset:64
	s_waitcnt vmcnt(0)
	v_pk_fma_f32 v[156:157], v[156:157], v[170:171], v[160:161]
	v_pk_fma_f32 v[154:155], v[154:155], v[168:169], v[158:159]
	global_store_dwordx4 v[184:185], v[154:157], off offset:64
	global_load_dwordx4 v[154:157], v[180:181], off offset:128
	s_nop 0
	global_load_dwordx4 v[158:161], v[182:183], off offset:128
	s_waitcnt vmcnt(0)
	v_pk_fma_f32 v[152:153], v[152:153], v[160:161], v[156:157]
	v_pk_fma_f32 v[150:151], v[150:151], v[158:159], v[154:155]
	global_store_dwordx4 v[184:185], v[150:153], off offset:128
	global_load_dwordx4 v[152:155], v[180:181], off offset:192
	s_nop 0
	global_load_dwordx4 v[156:159], v[182:183], off offset:192
	v_or_b32_e32 v150, 16, v164
	v_cmp_lt_i32_e32 vcc, s46, v150
	s_waitcnt vmcnt(0)
	v_pk_fma_f32 v[148:149], v[148:149], v[158:159], v[154:155]
	v_pk_fma_f32 v[146:147], v[146:147], v[156:157], v[152:153]
	global_store_dwordx4 v[184:185], v[146:149], off offset:192
	s_and_saveexec_b64 s[2:3], vcc
	s_xor_b64 s[2:3], exec, s[2:3]
	v_add_u32_e32 v238, 0xffffe010, v164
	v_lshlrev_b64 v[146:147], 12, v[238:239]
	v_mov_b32_e32 v151, v239
	v_lshl_add_u64 v[146:147], s[12:13], 0, v[146:147]
	v_lshlrev_b64 v[148:149], 12, v[150:151]
	v_mov_b64_e32 v[152:153], v[162:163]
	s_andn2_saveexec_b64 s[2:3], s[2:3]
	v_ashrrev_i32_e32 v151, 31, v150
	v_lshlrev_b64 v[148:149], 12, v[150:151]
	v_lshl_add_u64 v[146:147], s[4:5], 0, v[148:149]
	v_mov_b64_e32 v[152:153], 0
	s_or_b64 exec, exec, s[2:3]
	v_lshl_add_u64 v[154:155], v[152:153], 2, s[14:15]
	v_lshl_add_u64 v[158:159], v[146:147], 0, v[166:167]
	v_lshl_add_u64 v[160:161], v[154:155], 0, v[166:167]
	global_load_dwordx4 v[150:153], v[158:159], off
	global_load_dwordx4 v[154:157], v[160:161], off
	v_lshl_add_u64 v[146:147], s[4:5], 0, v[148:149]
	v_lshl_add_u64 v[168:169], v[146:147], 0, v[166:167]
	s_waitcnt vmcnt(0)
	v_pk_fma_f32 v[144:145], v[144:145], v[156:157], v[152:153]
	v_pk_fma_f32 v[142:143], v[142:143], v[154:155], v[150:151]
	global_store_dwordx4 v[168:169], v[142:145], off
	global_load_dwordx4 v[142:145], v[158:159], off offset:64
	s_nop 0
	global_load_dwordx4 v[146:149], v[160:161], off offset:64
	s_waitcnt vmcnt(0)
	v_pk_fma_f32 v[140:141], v[140:141], v[148:149], v[144:145]
	v_pk_fma_f32 v[138:139], v[138:139], v[146:147], v[142:143]
	global_store_dwordx4 v[168:169], v[138:141], off offset:64
	global_load_dwordx4 v[138:141], v[158:159], off offset:128
	s_nop 0
	global_load_dwordx4 v[142:145], v[160:161], off offset:128
	s_waitcnt vmcnt(0)
	v_pk_fma_f32 v[136:137], v[136:137], v[144:145], v[140:141]
	v_pk_fma_f32 v[134:135], v[134:135], v[142:143], v[138:139]
	global_store_dwordx4 v[168:169], v[134:137], off offset:128
	global_load_dwordx4 v[136:139], v[158:159], off offset:192
	s_nop 0
	global_load_dwordx4 v[140:143], v[160:161], off offset:192
	v_or_b32_e32 v134, 32, v164
	v_cmp_lt_i32_e32 vcc, s46, v134
	s_waitcnt vmcnt(0)
	v_pk_fma_f32 v[132:133], v[132:133], v[142:143], v[138:139]
	v_pk_fma_f32 v[130:131], v[130:131], v[140:141], v[136:137]
	global_store_dwordx4 v[168:169], v[130:133], off offset:192
	s_and_saveexec_b64 s[2:3], vcc
	s_xor_b64 s[2:3], exec, s[2:3]
	v_add_u32_e32 v238, 0xffffe020, v164
	v_lshlrev_b64 v[130:131], 12, v[238:239]
	v_mov_b32_e32 v135, v239
	v_lshl_add_u64 v[130:131], s[12:13], 0, v[130:131]
	v_lshlrev_b64 v[132:133], 12, v[134:135]
	v_mov_b64_e32 v[136:137], v[162:163]
	s_andn2_saveexec_b64 s[2:3], s[2:3]
	v_ashrrev_i32_e32 v135, 31, v134
	v_lshlrev_b64 v[132:133], 12, v[134:135]
	v_lshl_add_u64 v[130:131], s[4:5], 0, v[132:133]
	v_mov_b64_e32 v[136:137], 0
	s_or_b64 exec, exec, s[2:3]
	v_lshl_add_u64 v[138:139], v[136:137], 2, s[14:15]
	v_lshl_add_u64 v[142:143], v[130:131], 0, v[166:167]
	v_lshl_add_u64 v[144:145], v[138:139], 0, v[166:167]
	global_load_dwordx4 v[134:137], v[142:143], off
	global_load_dwordx4 v[138:141], v[144:145], off
	v_lshl_add_u64 v[130:131], s[4:5], 0, v[132:133]
	v_lshl_add_u64 v[146:147], v[130:131], 0, v[166:167]
	s_waitcnt vmcnt(0)
	v_pk_fma_f32 v[128:129], v[128:129], v[140:141], v[136:137]
	v_pk_fma_f32 v[126:127], v[126:127], v[138:139], v[134:135]
	global_store_dwordx4 v[146:147], v[126:129], off
	global_load_dwordx4 v[126:129], v[142:143], off offset:64
	s_nop 0
	global_load_dwordx4 v[130:133], v[144:145], off offset:64
	s_waitcnt vmcnt(0)
	v_pk_fma_f32 v[124:125], v[124:125], v[132:133], v[128:129]
	v_pk_fma_f32 v[122:123], v[122:123], v[130:131], v[126:127]
	global_store_dwordx4 v[146:147], v[122:125], off offset:64
	global_load_dwordx4 v[122:125], v[142:143], off offset:128
	s_nop 0
	global_load_dwordx4 v[126:129], v[144:145], off offset:128
	s_waitcnt vmcnt(0)
	v_pk_fma_f32 v[120:121], v[120:121], v[128:129], v[124:125]
	v_pk_fma_f32 v[118:119], v[118:119], v[126:127], v[122:123]
	global_store_dwordx4 v[146:147], v[118:121], off offset:128
	global_load_dwordx4 v[120:123], v[142:143], off offset:192
	s_nop 0
	global_load_dwordx4 v[124:127], v[144:145], off offset:192
	v_or_b32_e32 v118, 48, v164
	v_cmp_lt_i32_e32 vcc, s46, v118
	s_waitcnt vmcnt(0)
	v_pk_fma_f32 v[116:117], v[116:117], v[126:127], v[122:123]
	v_pk_fma_f32 v[114:115], v[114:115], v[124:125], v[120:121]
	global_store_dwordx4 v[146:147], v[114:117], off offset:192
	s_and_saveexec_b64 s[2:3], vcc
	s_xor_b64 s[2:3], exec, s[2:3]
	v_add_u32_e32 v238, 0xffffe030, v164
	v_lshlrev_b64 v[114:115], 12, v[238:239]
	v_mov_b32_e32 v119, v239
	v_lshl_add_u64 v[114:115], s[12:13], 0, v[114:115]
	v_lshlrev_b64 v[116:117], 12, v[118:119]
	v_mov_b64_e32 v[120:121], v[162:163]
	s_andn2_saveexec_b64 s[2:3], s[2:3]
	v_ashrrev_i32_e32 v119, 31, v118
	v_lshlrev_b64 v[116:117], 12, v[118:119]
	v_lshl_add_u64 v[114:115], s[4:5], 0, v[116:117]
	v_mov_b64_e32 v[120:121], 0
	s_or_b64 exec, exec, s[2:3]
	v_lshl_add_u64 v[122:123], v[120:121], 2, s[14:15]
	v_lshl_add_u64 v[126:127], v[114:115], 0, v[166:167]
	v_lshl_add_u64 v[128:129], v[122:123], 0, v[166:167]
	global_load_dwordx4 v[118:121], v[126:127], off
	global_load_dwordx4 v[122:125], v[128:129], off
	v_lshl_add_u64 v[114:115], s[4:5], 0, v[116:117]
	v_lshl_add_u64 v[130:131], v[114:115], 0, v[166:167]
	s_waitcnt vmcnt(0)
	v_pk_fma_f32 v[112:113], v[112:113], v[124:125], v[120:121]
	v_pk_fma_f32 v[110:111], v[110:111], v[122:123], v[118:119]
	global_store_dwordx4 v[130:131], v[110:113], off
	global_load_dwordx4 v[110:113], v[126:127], off offset:64
	s_nop 0
	global_load_dwordx4 v[114:117], v[128:129], off offset:64
	s_waitcnt vmcnt(0)
	v_pk_fma_f32 v[108:109], v[108:109], v[116:117], v[112:113]
	v_pk_fma_f32 v[106:107], v[106:107], v[114:115], v[110:111]
	global_store_dwordx4 v[130:131], v[106:109], off offset:64
	global_load_dwordx4 v[106:109], v[126:127], off offset:128
	s_nop 0
	global_load_dwordx4 v[110:113], v[128:129], off offset:128
	s_waitcnt vmcnt(0)
	v_pk_fma_f32 v[104:105], v[104:105], v[112:113], v[108:109]
	v_pk_fma_f32 v[102:103], v[102:103], v[110:111], v[106:107]
	global_store_dwordx4 v[130:131], v[102:105], off offset:128
	global_load_dwordx4 v[104:107], v[126:127], off offset:192
	s_nop 0
	global_load_dwordx4 v[108:111], v[128:129], off offset:192
	v_or_b32_e32 v102, 64, v164
	v_cmp_lt_i32_e32 vcc, s46, v102
	s_waitcnt vmcnt(0)
	v_pk_fma_f32 v[84:85], v[84:85], v[110:111], v[106:107]
	v_pk_fma_f32 v[82:83], v[82:83], v[108:109], v[104:105]
	global_store_dwordx4 v[130:131], v[82:85], off offset:192
	s_and_saveexec_b64 s[2:3], vcc
	s_xor_b64 s[2:3], exec, s[2:3]
	v_add_u32_e32 v238, 0xffffe040, v164
	v_lshlrev_b64 v[82:83], 12, v[238:239]
	v_mov_b32_e32 v103, v239
	v_lshl_add_u64 v[82:83], s[12:13], 0, v[82:83]
	v_lshlrev_b64 v[84:85], 12, v[102:103]
	v_mov_b64_e32 v[104:105], v[162:163]
	s_andn2_saveexec_b64 s[2:3], s[2:3]
	v_ashrrev_i32_e32 v103, 31, v102
	v_lshlrev_b64 v[84:85], 12, v[102:103]
	v_lshl_add_u64 v[82:83], s[4:5], 0, v[84:85]
	v_mov_b64_e32 v[104:105], 0
	s_or_b64 exec, exec, s[2:3]
	v_lshl_add_u64 v[106:107], v[104:105], 2, s[14:15]
	v_lshl_add_u64 v[110:111], v[82:83], 0, v[166:167]
	v_lshl_add_u64 v[112:113], v[106:107], 0, v[166:167]
	global_load_dwordx4 v[102:105], v[110:111], off
	global_load_dwordx4 v[106:109], v[112:113], off
	v_lshl_add_u64 v[82:83], s[4:5], 0, v[84:85]
	v_lshl_add_u64 v[114:115], v[82:83], 0, v[166:167]
	s_waitcnt vmcnt(0)
	v_pk_fma_f32 v[84:85], v[100:101], v[108:109], v[104:105]
	v_pk_fma_f32 v[82:83], v[98:99], v[106:107], v[102:103]
	global_store_dwordx4 v[114:115], v[82:85], off
	global_load_dwordx4 v[82:85], v[110:111], off offset:64
	s_nop 0
	global_load_dwordx4 v[98:101], v[112:113], off offset:64
	s_waitcnt vmcnt(0)
	v_pk_fma_f32 v[84:85], v[96:97], v[100:101], v[84:85]
	v_pk_fma_f32 v[82:83], v[94:95], v[98:99], v[82:83]
	global_store_dwordx4 v[114:115], v[82:85], off offset:64
	global_load_dwordx4 v[82:85], v[110:111], off offset:128
	s_nop 0
	global_load_dwordx4 v[94:97], v[112:113], off offset:128
	s_waitcnt vmcnt(0)
	v_pk_fma_f32 v[84:85], v[92:93], v[96:97], v[84:85]
	v_pk_fma_f32 v[82:83], v[90:91], v[94:95], v[82:83]
	global_store_dwordx4 v[114:115], v[82:85], off offset:128
	global_load_dwordx4 v[90:93], v[110:111], off offset:192
	global_load_dwordx4 v[94:97], v[112:113], off offset:192
	v_or_b32_e32 v84, 0x50, v164
	v_cmp_lt_i32_e32 vcc, s46, v84
	s_waitcnt vmcnt(0)
	v_pk_fma_f32 v[88:89], v[88:89], v[96:97], v[92:93]
	v_pk_fma_f32 v[86:87], v[86:87], v[94:95], v[90:91]
	global_store_dwordx4 v[114:115], v[86:89], off offset:192
	s_and_saveexec_b64 s[2:3], vcc
	s_xor_b64 s[2:3], exec, s[2:3]
	v_add_u32_e32 v238, 0xffffe050, v164
	v_lshlrev_b64 v[82:83], 12, v[238:239]
	v_mov_b32_e32 v85, v239
	v_lshl_add_u64 v[82:83], s[12:13], 0, v[82:83]
	v_lshlrev_b64 v[86:87], 12, v[84:85]
	v_mov_b64_e32 v[88:89], v[162:163]
	s_andn2_saveexec_b64 s[2:3], s[2:3]
	v_ashrrev_i32_e32 v85, 31, v84
	v_lshlrev_b64 v[86:87], 12, v[84:85]
	v_lshl_add_u64 v[82:83], s[4:5], 0, v[86:87]
	v_mov_b64_e32 v[88:89], 0
	s_or_b64 exec, exec, s[2:3]
	v_lshl_add_u64 v[88:89], v[88:89], 2, s[14:15]
	v_lshl_add_u64 v[92:93], v[82:83], 0, v[166:167]
	v_lshl_add_u64 v[94:95], v[88:89], 0, v[166:167]
	global_load_dwordx4 v[82:85], v[92:93], off
	global_load_dwordx4 v[88:91], v[94:95], off
	v_lshl_add_u64 v[86:87], s[4:5], 0, v[86:87]
	v_lshl_add_u64 v[86:87], v[86:87], 0, v[166:167]
	s_waitcnt vmcnt(0)
	v_pk_fma_f32 v[80:81], v[80:81], v[90:91], v[84:85]
	v_pk_fma_f32 v[78:79], v[78:79], v[88:89], v[82:83]
	global_store_dwordx4 v[86:87], v[78:81], off
	global_load_dwordx4 v[78:81], v[92:93], off offset:64
	s_nop 0
	global_load_dwordx4 v[82:85], v[94:95], off offset:64
	s_waitcnt vmcnt(0)
	v_pk_fma_f32 v[76:77], v[76:77], v[84:85], v[80:81]
	v_pk_fma_f32 v[74:75], v[74:75], v[82:83], v[78:79]
	global_store_dwordx4 v[86:87], v[74:77], off offset:64
	global_load_dwordx4 v[74:77], v[92:93], off offset:128
	s_nop 0
	global_load_dwordx4 v[78:81], v[94:95], off offset:128
	s_waitcnt vmcnt(0)
	v_pk_fma_f32 v[72:73], v[72:73], v[80:81], v[76:77]
	v_pk_fma_f32 v[70:71], v[70:71], v[78:79], v[74:75]
	global_store_dwordx4 v[86:87], v[70:73], off offset:128
	global_load_dwordx4 v[72:75], v[92:93], off offset:192
	s_nop 0
	global_load_dwordx4 v[76:79], v[94:95], off offset:192
	v_or_b32_e32 v70, 0x60, v164
	v_cmp_lt_i32_e32 vcc, s46, v70
	s_waitcnt vmcnt(0)
	v_pk_fma_f32 v[68:69], v[68:69], v[78:79], v[74:75]
	v_pk_fma_f32 v[66:67], v[66:67], v[76:77], v[72:73]
	global_store_dwordx4 v[86:87], v[66:69], off offset:192
	s_and_saveexec_b64 s[2:3], vcc
	s_xor_b64 s[2:3], exec, s[2:3]
	v_add_u32_e32 v238, 0xffffe060, v164
	v_lshlrev_b64 v[66:67], 12, v[238:239]
	v_mov_b32_e32 v71, v239
	v_lshl_add_u64 v[66:67], s[12:13], 0, v[66:67]
	v_lshlrev_b64 v[68:69], 12, v[70:71]
	v_mov_b64_e32 v[72:73], v[162:163]
	s_andn2_saveexec_b64 s[2:3], s[2:3]
	v_ashrrev_i32_e32 v71, 31, v70
	v_lshlrev_b64 v[68:69], 12, v[70:71]
	v_lshl_add_u64 v[66:67], s[4:5], 0, v[68:69]
	v_mov_b64_e32 v[72:73], 0
	s_or_b64 exec, exec, s[2:3]
	v_lshl_add_u64 v[74:75], v[72:73], 2, s[14:15]
	v_lshl_add_u64 v[78:79], v[66:67], 0, v[166:167]
	v_lshl_add_u64 v[80:81], v[74:75], 0, v[166:167]
	global_load_dwordx4 v[70:73], v[78:79], off
	global_load_dwordx4 v[74:77], v[80:81], off
	v_lshl_add_u64 v[66:67], s[4:5], 0, v[68:69]
	v_lshl_add_u64 v[82:83], v[66:67], 0, v[166:167]
	s_waitcnt vmcnt(0)
	v_pk_fma_f32 v[64:65], v[64:65], v[76:77], v[72:73]
	v_pk_fma_f32 v[62:63], v[62:63], v[74:75], v[70:71]
	global_store_dwordx4 v[82:83], v[62:65], off
	global_load_dwordx4 v[62:65], v[78:79], off offset:64
	s_nop 0
	global_load_dwordx4 v[66:69], v[80:81], off offset:64
	s_waitcnt vmcnt(0)
	v_pk_fma_f32 v[60:61], v[60:61], v[68:69], v[64:65]
	v_pk_fma_f32 v[58:59], v[58:59], v[66:67], v[62:63]
	global_store_dwordx4 v[82:83], v[58:61], off offset:64
	global_load_dwordx4 v[58:61], v[78:79], off offset:128
	s_nop 0
	global_load_dwordx4 v[62:65], v[80:81], off offset:128
	s_waitcnt vmcnt(0)
	v_pk_fma_f32 v[56:57], v[56:57], v[64:65], v[60:61]
	v_pk_fma_f32 v[54:55], v[54:55], v[62:63], v[58:59]
	global_store_dwordx4 v[82:83], v[54:57], off offset:128
	global_load_dwordx4 v[56:59], v[78:79], off offset:192
	s_nop 0
	global_load_dwordx4 v[60:63], v[80:81], off offset:192
	v_or_b32_e32 v54, 0x70, v164
	v_cmp_lt_i32_e32 vcc, s46, v54
	s_waitcnt vmcnt(0)
	v_pk_fma_f32 v[52:53], v[52:53], v[62:63], v[58:59]
	v_pk_fma_f32 v[50:51], v[50:51], v[60:61], v[56:57]
	global_store_dwordx4 v[82:83], v[50:53], off offset:192
	s_and_saveexec_b64 s[2:3], vcc
	s_xor_b64 s[2:3], exec, s[2:3]
	v_add_u32_e32 v238, 0xffffe070, v164
	v_lshlrev_b64 v[50:51], 12, v[238:239]
	v_mov_b32_e32 v55, v239
	v_lshl_add_u64 v[50:51], s[12:13], 0, v[50:51]
	v_lshlrev_b64 v[52:53], 12, v[54:55]
	s_andn2_saveexec_b64 s[2:3], s[2:3]
	v_ashrrev_i32_e32 v55, 31, v54
	v_lshlrev_b64 v[52:53], 12, v[54:55]
	v_lshl_add_u64 v[50:51], s[4:5], 0, v[52:53]
	v_mov_b64_e32 v[162:163], 0
	s_or_b64 exec, exec, s[2:3]
	v_lshl_add_u64 v[58:59], v[162:163], 2, s[14:15]
	v_lshl_add_u64 v[62:63], v[50:51], 0, v[166:167]
	v_lshl_add_u64 v[64:65], v[58:59], 0, v[166:167]
	global_load_dwordx4 v[54:57], v[62:63], off
	global_load_dwordx4 v[58:61], v[64:65], off
	v_lshl_add_u64 v[50:51], s[4:5], 0, v[52:53]
	v_lshl_add_u64 v[66:67], v[50:51], 0, v[166:167]
	s_add_i32 s47, s47, s11
	s_cmp_gt_i32 s47, 31
	s_waitcnt vmcnt(0)
	v_pk_fma_f32 v[48:49], v[48:49], v[60:61], v[56:57]
	v_pk_fma_f32 v[46:47], v[46:47], v[58:59], v[54:55]
	global_store_dwordx4 v[66:67], v[46:49], off
	global_load_dwordx4 v[46:49], v[62:63], off offset:64
	s_nop 0
	global_load_dwordx4 v[50:53], v[64:65], off offset:64
	s_waitcnt vmcnt(0)
	v_pk_fma_f32 v[44:45], v[44:45], v[52:53], v[48:49]
	v_pk_fma_f32 v[42:43], v[42:43], v[50:51], v[46:47]
	global_store_dwordx4 v[66:67], v[42:45], off offset:64
	global_load_dwordx4 v[42:45], v[62:63], off offset:128
	s_nop 0
	global_load_dwordx4 v[46:49], v[64:65], off offset:128
	s_waitcnt vmcnt(0)
	v_pk_fma_f32 v[40:41], v[40:41], v[48:49], v[44:45]
	v_pk_fma_f32 v[38:39], v[38:39], v[46:47], v[42:43]
	global_store_dwordx4 v[66:67], v[38:41], off offset:128
	global_load_dwordx4 v[38:41], v[62:63], off offset:192
	s_nop 0
	global_load_dwordx4 v[42:45], v[64:65], off offset:192
	s_waitcnt vmcnt(0)
	v_pk_fma_f32 v[40:41], v[36:37], v[44:45], v[40:41]
	v_pk_fma_f32 v[38:39], v[34:35], v[42:43], v[38:39]
	v_mov_b32_e32 v37, 0
	global_store_dwordx4 v[66:67], v[38:41], off offset:192
	s_cbranch_scc1 .LBB0_1300
	s_ashr_i32 s3, s47, 31
	s_lshr_b32 s3, s3, 27
	s_add_i32 s3, s47, s3
	s_ashr_i32 s3, s3, 5
	s_mov_b32 s2, s10
	s_lshl_b32 s20, s3, 6
	s_lshl_b32 s21, s47, 1
	s_sub_i32 s20, s21, s20
	s_and_b32 s2, s2, 7
	s_and_b32 s20, s20, -8
	s_lshl_b32 s3, s3, 2
	s_and_b32 s21, s47, 3
	s_or_b32 s34, s3, s21
	s_or_b32 s36, s2, s20
	s_branch .LBB0_1300

.LBB0_1524:
	s_mov_b32 s98, 0
	v_mov_b32_e32 v255, 0x0
	v_bfe_u32 v1, v0, 0, 1
	v_lshlrev_b32_e32 v1, 7, v1
	v_xor_b32_e32 v255, v255, v1
	v_bfe_u32 v1, v0, 1, 3
	v_mul_u32_u24_e32 v1, 0x110, v1
	v_xor_b32_e32 v255, v255, v1
	v_bfe_u32 v1, v0, 4, 2
	v_lshlrev_b32_e32 v1, 4, v1
	v_xor_b32_e32 v255, v255, v1
	v_bfe_u32 v1, v0, 8, 1
	v_lshlrev_b32_e32 v1, 14, v1
	v_xor_b32_e32 v255, v255, v1
	v_mov_b32_e32 v254, 0x10000
	v_bfe_u32 v1, v0, 0, 1
	v_lshlrev_b32_e32 v1, 7, v1
	v_xor_b32_e32 v254, v254, v1
	v_bfe_u32 v1, v0, 1, 3
	v_mul_u32_u24_e32 v1, 0x110, v1
	v_xor_b32_e32 v254, v254, v1
	v_bfe_u32 v1, v0, 4, 2
	v_lshlrev_b32_e32 v1, 4, v1
	v_xor_b32_e32 v254, v254, v1
	v_bfe_u32 v1, v0, 8, 1
	v_lshlrev_b32_e32 v1, 14, v1
	v_xor_b32_e32 v254, v254, v1
	v_mov_b32_e32 v253, 0x880
	v_bfe_u32 v1, v0, 0, 1
	v_lshlrev_b32_e32 v1, 7, v1
	v_xor_b32_e32 v253, v253, v1
	v_bfe_u32 v1, v0, 1, 3
	v_mul_u32_u24_e32 v1, 0x110, v1
	v_xor_b32_e32 v253, v253, v1
	v_bfe_u32 v1, v0, 4, 2
	v_lshlrev_b32_e32 v1, 4, v1
	v_xor_b32_e32 v253, v253, v1
	v_bfe_u32 v1, v0, 8, 1
	v_lshlrev_b32_e32 v1, 14, v1
	v_xor_b32_e32 v253, v253, v1
	v_mov_b32_e32 v252, 0x10880
	v_bfe_u32 v1, v0, 0, 1
	v_lshlrev_b32_e32 v1, 7, v1
	v_xor_b32_e32 v252, v252, v1
	v_bfe_u32 v1, v0, 1, 3
	v_mul_u32_u24_e32 v1, 0x110, v1
	v_xor_b32_e32 v252, v252, v1
	v_bfe_u32 v1, v0, 4, 2
	v_lshlrev_b32_e32 v1, 4, v1
	v_xor_b32_e32 v252, v252, v1
	v_bfe_u32 v1, v0, 8, 1
	v_lshlrev_b32_e32 v1, 14, v1
	v_xor_b32_e32 v252, v252, v1
	v_mov_b32_e32 v251, 0x8000
	v_bfe_u32 v1, v0, 1, 3
	v_lshlrev_b32_e32 v1, 8, v1
	v_add_u32_e32 v251, v251, v1
	v_bfe_u32 v1, v0, 6, 2
	v_mul_u32_u24_e32 v1, 0x1800, v1
	v_add_u32_e32 v251, v251, v1
	v_mov_b32_e32 v2, 0x0
	v_bfe_u32 v1, v0, 0, 1
	v_lshlrev_b32_e32 v1, 7, v1
	v_xor_b32_e32 v2, v2, v1
	v_bfe_u32 v1, v0, 1, 3
	v_lshlrev_b32_e32 v1, 4, v1
	v_xor_b32_e32 v2, v2, v1
	v_bfe_u32 v1, v0, 4, 2
	v_lshlrev_b32_e32 v1, 4, v1
	v_xor_b32_e32 v2, v2, v1
	v_bfe_u32 v1, v0, 6, 1
	v_lshlrev_b32_e32 v1, 7, v1
	v_xor_b32_e32 v2, v2, v1
	v_add_u32_e32 v251, v251, v2
	v_mov_b32_e32 v250, 0x18000
	v_bfe_u32 v1, v0, 1, 3
	v_lshlrev_b32_e32 v1, 8, v1
	v_add_u32_e32 v250, v250, v1
	v_bfe_u32 v1, v0, 6, 2
	v_mul_u32_u24_e32 v1, 0x1800, v1
	v_add_u32_e32 v250, v250, v1
	v_mov_b32_e32 v2, 0x0
	v_bfe_u32 v1, v0, 0, 1
	v_lshlrev_b32_e32 v1, 7, v1
	v_xor_b32_e32 v2, v2, v1
	v_bfe_u32 v1, v0, 1, 3
	v_lshlrev_b32_e32 v1, 4, v1
	v_xor_b32_e32 v2, v2, v1
	v_bfe_u32 v1, v0, 4, 2
	v_lshlrev_b32_e32 v1, 4, v1
	v_xor_b32_e32 v2, v2, v1
	v_bfe_u32 v1, v0, 6, 1
	v_lshlrev_b32_e32 v1, 7, v1
	v_xor_b32_e32 v2, v2, v1
	v_add_u32_e32 v250, v250, v2
	v_mov_b32_e32 v249, 0x8800
	v_bfe_u32 v1, v0, 1, 3
	v_lshlrev_b32_e32 v1, 8, v1
	v_add_u32_e32 v249, v249, v1
	v_bfe_u32 v1, v0, 6, 2
	v_mul_u32_u24_e32 v1, 0x1800, v1
	v_add_u32_e32 v249, v249, v1
	v_mov_b32_e32 v2, 0x80
	v_bfe_u32 v1, v0, 0, 1
	v_lshlrev_b32_e32 v1, 7, v1
	v_xor_b32_e32 v2, v2, v1
	v_bfe_u32 v1, v0, 1, 3
	v_lshlrev_b32_e32 v1, 4, v1
	v_xor_b32_e32 v2, v2, v1
	v_bfe_u32 v1, v0, 4, 2
	v_lshlrev_b32_e32 v1, 4, v1
	v_xor_b32_e32 v2, v2, v1
	v_bfe_u32 v1, v0, 6, 1
	v_lshlrev_b32_e32 v1, 7, v1
	v_xor_b32_e32 v2, v2, v1
	v_add_u32_e32 v249, v249, v2
	v_mov_b32_e32 v248, 0x18800
	v_bfe_u32 v1, v0, 1, 3
	v_lshlrev_b32_e32 v1, 8, v1
	v_add_u32_e32 v248, v248, v1
	v_bfe_u32 v1, v0, 6, 2
	v_mul_u32_u24_e32 v1, 0x1800, v1
	v_add_u32_e32 v248, v248, v1
	v_mov_b32_e32 v2, 0x80
	v_bfe_u32 v1, v0, 0, 1
	v_lshlrev_b32_e32 v1, 7, v1
	v_xor_b32_e32 v2, v2, v1
	v_bfe_u32 v1, v0, 1, 3
	v_lshlrev_b32_e32 v1, 4, v1
	v_xor_b32_e32 v2, v2, v1
	v_bfe_u32 v1, v0, 4, 2
	v_lshlrev_b32_e32 v1, 4, v1
	v_xor_b32_e32 v2, v2, v1
	v_bfe_u32 v1, v0, 6, 1
	v_lshlrev_b32_e32 v1, 7, v1
	v_xor_b32_e32 v2, v2, v1
	v_add_u32_e32 v248, v248, v2
	v_mov_b32_e32 v247, 0x40
	v_bfe_u32 v1, v0, 0, 1
	v_lshlrev_b32_e32 v1, 7, v1
	v_xor_b32_e32 v247, v247, v1
	v_bfe_u32 v1, v0, 1, 3
	v_mul_u32_u24_e32 v1, 0x110, v1
	v_xor_b32_e32 v247, v247, v1
	v_bfe_u32 v1, v0, 4, 2
	v_lshlrev_b32_e32 v1, 4, v1
	v_xor_b32_e32 v247, v247, v1
	v_bfe_u32 v1, v0, 8, 1
	v_lshlrev_b32_e32 v1, 14, v1
	v_xor_b32_e32 v247, v247, v1
	v_mov_b32_e32 v246, 0x10040
	v_bfe_u32 v1, v0, 0, 1
	v_lshlrev_b32_e32 v1, 7, v1
	v_xor_b32_e32 v246, v246, v1
	v_bfe_u32 v1, v0, 1, 3
	v_mul_u32_u24_e32 v1, 0x110, v1
	v_xor_b32_e32 v246, v246, v1
	v_bfe_u32 v1, v0, 4, 2
	v_lshlrev_b32_e32 v1, 4, v1
	v_xor_b32_e32 v246, v246, v1
	v_bfe_u32 v1, v0, 8, 1
	v_lshlrev_b32_e32 v1, 14, v1
	v_xor_b32_e32 v246, v246, v1
	v_mov_b32_e32 v245, 0x8c0
	v_bfe_u32 v1, v0, 0, 1
	v_lshlrev_b32_e32 v1, 7, v1
	v_xor_b32_e32 v245, v245, v1
	v_bfe_u32 v1, v0, 1, 3
	v_mul_u32_u24_e32 v1, 0x110, v1
	v_xor_b32_e32 v245, v245, v1
	v_bfe_u32 v1, v0, 4, 2
	v_lshlrev_b32_e32 v1, 4, v1
	v_xor_b32_e32 v245, v245, v1
	v_bfe_u32 v1, v0, 8, 1
	v_lshlrev_b32_e32 v1, 14, v1
	v_xor_b32_e32 v245, v245, v1
	v_mov_b32_e32 v244, 0x108c0
	v_bfe_u32 v1, v0, 0, 1
	v_lshlrev_b32_e32 v1, 7, v1
	v_xor_b32_e32 v244, v244, v1
	v_bfe_u32 v1, v0, 1, 3
	v_mul_u32_u24_e32 v1, 0x110, v1
	v_xor_b32_e32 v244, v244, v1
	v_bfe_u32 v1, v0, 4, 2
	v_lshlrev_b32_e32 v1, 4, v1
	v_xor_b32_e32 v244, v244, v1
	v_bfe_u32 v1, v0, 8, 1
	v_lshlrev_b32_e32 v1, 14, v1
	v_xor_b32_e32 v244, v244, v1
	v_mov_b32_e32 v243, 0x8000
	v_bfe_u32 v1, v0, 1, 3
	v_lshlrev_b32_e32 v1, 8, v1
	v_add_u32_e32 v243, v243, v1
	v_bfe_u32 v1, v0, 6, 2
	v_mul_u32_u24_e32 v1, 0x1800, v1
	v_add_u32_e32 v243, v243, v1
	v_mov_b32_e32 v2, 0x40
	v_bfe_u32 v1, v0, 0, 1
	v_lshlrev_b32_e32 v1, 7, v1
	v_xor_b32_e32 v2, v2, v1
	v_bfe_u32 v1, v0, 1, 3
	v_lshlrev_b32_e32 v1, 4, v1
	v_xor_b32_e32 v2, v2, v1
	v_bfe_u32 v1, v0, 4, 2
	v_lshlrev_b32_e32 v1, 4, v1
	v_xor_b32_e32 v2, v2, v1
	v_bfe_u32 v1, v0, 6, 1
	v_lshlrev_b32_e32 v1, 7, v1
	v_xor_b32_e32 v2, v2, v1
	v_add_u32_e32 v243, v243, v2
	v_mov_b32_e32 v242, 0x18000
	v_bfe_u32 v1, v0, 1, 3
	v_lshlrev_b32_e32 v1, 8, v1
	v_add_u32_e32 v242, v242, v1
	v_bfe_u32 v1, v0, 6, 2
	v_mul_u32_u24_e32 v1, 0x1800, v1
	v_add_u32_e32 v242, v242, v1
	v_mov_b32_e32 v2, 0x40
	v_bfe_u32 v1, v0, 0, 1
	v_lshlrev_b32_e32 v1, 7, v1
	v_xor_b32_e32 v2, v2, v1
	v_bfe_u32 v1, v0, 1, 3
	v_lshlrev_b32_e32 v1, 4, v1
	v_xor_b32_e32 v2, v2, v1
	v_bfe_u32 v1, v0, 4, 2
	v_lshlrev_b32_e32 v1, 4, v1
	v_xor_b32_e32 v2, v2, v1
	v_bfe_u32 v1, v0, 6, 1
	v_lshlrev_b32_e32 v1, 7, v1
	v_xor_b32_e32 v2, v2, v1
	v_add_u32_e32 v242, v242, v2
	v_mov_b32_e32 v241, 0x8800
	v_bfe_u32 v1, v0, 1, 3
	v_lshlrev_b32_e32 v1, 8, v1
	v_add_u32_e32 v241, v241, v1
	v_bfe_u32 v1, v0, 6, 2
	v_mul_u32_u24_e32 v1, 0x1800, v1
	v_add_u32_e32 v241, v241, v1
	v_mov_b32_e32 v2, 0xc0
	v_bfe_u32 v1, v0, 0, 1
	v_lshlrev_b32_e32 v1, 7, v1
	v_xor_b32_e32 v2, v2, v1
	v_bfe_u32 v1, v0, 1, 3
	v_lshlrev_b32_e32 v1, 4, v1
	v_xor_b32_e32 v2, v2, v1
	v_bfe_u32 v1, v0, 4, 2
	v_lshlrev_b32_e32 v1, 4, v1
	v_xor_b32_e32 v2, v2, v1
	v_bfe_u32 v1, v0, 6, 1
	v_lshlrev_b32_e32 v1, 7, v1
	v_xor_b32_e32 v2, v2, v1
	v_add_u32_e32 v241, v241, v2
	v_mov_b32_e32 v240, 0x18800
	v_bfe_u32 v1, v0, 1, 3
	v_lshlrev_b32_e32 v1, 8, v1
	v_add_u32_e32 v240, v240, v1
	v_bfe_u32 v1, v0, 6, 2
	v_mul_u32_u24_e32 v1, 0x1800, v1
	v_add_u32_e32 v240, v240, v1
	v_mov_b32_e32 v2, 0xc0
	v_bfe_u32 v1, v0, 0, 1
	v_lshlrev_b32_e32 v1, 7, v1
	v_xor_b32_e32 v2, v2, v1
	v_bfe_u32 v1, v0, 1, 3
	v_lshlrev_b32_e32 v1, 4, v1
	v_xor_b32_e32 v2, v2, v1
	v_bfe_u32 v1, v0, 4, 2
	v_lshlrev_b32_e32 v1, 4, v1
	v_xor_b32_e32 v2, v2, v1
	v_bfe_u32 v1, v0, 6, 1
	v_lshlrev_b32_e32 v1, 7, v1
	v_xor_b32_e32 v2, v2, v1
	v_add_u32_e32 v240, v240, v2
	v_mov_b32_e32 v239, 0x0
	v_bfe_u32 v1, v0, 0, 4
	v_lshlrev_b32_e32 v1, 4, v1
	v_xor_b32_e32 v239, v239, v1
	v_bfe_u32 v1, v0, 4, 4
	v_mul_u32_u24_e32 v1, 0x110, v1
	v_xor_b32_e32 v239, v239, v1
	v_bfe_u32 v1, v0, 8, 1
	v_lshlrev_b32_e32 v1, 12, v1
	v_xor_b32_e32 v239, v239, v1
	v_mov_b32_e32 v238, 0x10000
	v_bfe_u32 v1, v0, 0, 4
	v_lshlrev_b32_e32 v1, 4, v1
	v_xor_b32_e32 v238, v238, v1
	v_bfe_u32 v1, v0, 4, 4
	v_mul_u32_u24_e32 v1, 0x110, v1
	v_xor_b32_e32 v238, v238, v1
	v_bfe_u32 v1, v0, 8, 1
	v_lshlrev_b32_e32 v1, 12, v1
	v_xor_b32_e32 v238, v238, v1
	v_mov_b32_e32 v237, 0x0
	v_bfe_u32 v1, v0, 0, 3
	v_lshlrev_b32_e32 v1, 4, v1
	v_add_u32_e32 v237, v237, v1
	v_bfe_u32 v1, v0, 3, 6
	v_lshlrev_b32_e32 v1, 11, v1
	v_add_u32_e32 v237, v237, v1
	v_mov_b32_e32 v236, 0x20000
	v_bfe_u32 v1, v0, 0, 3
	v_lshlrev_b32_e32 v1, 4, v1
	v_add_u32_e32 v236, v236, v1
	v_bfe_u32 v1, v0, 3, 6
	v_lshlrev_b32_e32 v1, 11, v1
	v_add_u32_e32 v236, v236, v1
	v_mov_b32_e32 v235, 0x40000
	v_bfe_u32 v1, v0, 0, 3
	v_lshlrev_b32_e32 v1, 4, v1
	v_add_u32_e32 v235, v235, v1
	v_bfe_u32 v1, v0, 3, 6
	v_lshlrev_b32_e32 v1, 11, v1
	v_add_u32_e32 v235, v235, v1
	v_mov_b32_e32 v234, 0x60000
	v_bfe_u32 v1, v0, 0, 3
	v_lshlrev_b32_e32 v1, 4, v1
	v_add_u32_e32 v234, v234, v1
	v_bfe_u32 v1, v0, 3, 6
	v_lshlrev_b32_e32 v1, 11, v1
	v_add_u32_e32 v234, v234, v1
	v_mov_b32_e32 v1, v0
	s_load_dword s2, s[0:1], 0xe0
	s_mov_b32 s3, s10
	v_mov_b32_e32 v1, v0
	s_waitcnt lgkmcnt(0)
	s_lshr_b32 s11, s2, 3
	s_waitcnt vmcnt(0)
	v_cvt_f32_u32_e32 v2, s11
	s_mov_b32 s2, s10
	s_ashr_i32 s3, s2, 3
	v_rcp_iflag_f32_e32 v2, v2
	s_ashr_i32 s4, s2, 31
	s_sub_i32 s2, 0, s11
	s_abs_i32 s3, s3
	v_mul_f32_e32 v1, 0x4f7ffffe, v2
	v_cvt_u32_f32_e32 v1, v1
	s_mov_b32 s45, 0
	v_readfirstlane_b32 s5, v1
	s_mul_i32 s2, s2, s5
	s_mul_hi_u32 s2, s5, s2
	s_add_i32 s2, s5, s2
	s_mul_hi_u32 s5, s3, s2
	s_mul_i32 s5, s5, s11
	s_sub_i32 s3, s3, s5
	s_sub_i32 s5, s3, s11
	s_cmp_ge_u32 s3, s11
	s_cselect_b32 s3, s5, s3
	s_sub_i32 s5, s3, s11
	s_cmp_ge_u32 s3, s11
	s_cselect_b32 s3, s5, s3
	s_xor_b32 s3, s3, s4
	s_sub_i32 s24, s3, s4
	s_mov_b32 s3, s10
	s_cmpk_gt_i32 s24, 0x5f
	s_cbranch_scc1 .LBB0_1604
	s_load_dwordx2 s[4:5], s[16:17], 0xd0
	s_mov_b32 s3, s10
	v_mov_b32_e32 v54, 0
	v_mov_b32_e32 v1, v0
	s_waitcnt lgkmcnt(0)
	s_add_u32 s25, s4, 0x17f0000
	s_addc_u32 s26, s5, 0
	s_add_u32 s8, s4, 0x37f0000
	s_addc_u32 s9, s5, 0
	s_add_u32 s27, s4, 0x50000
	s_addc_u32 s28, s5, 0
	s_ashr_i32 s4, s24, 31
	s_lshr_b32 s4, s4, 27
	s_add_i32 s4, s24, s4
	s_ashr_i32 s4, s4, 5
	s_lshl_b32 s5, s24, 1
	s_lshl_b32 s12, s4, 6
	s_sub_i32 s5, s5, s12
	s_lshl_b32 s4, s4, 2
	s_and_b32 s12, s24, 3
	s_or_b32 s29, s4, s12
	s_sub_i32 s4, s11, s24
	s_addk_i32 s4, 0x5f
	s_mul_hi_u32 s2, s4, s2
	s_mul_i32 s12, s2, s11
	s_sub_i32 s4, s4, s12
	s_add_i32 s12, s2, 1
	s_sub_i32 s13, s4, s11
	s_cmp_ge_u32 s4, s11
	s_cselect_b32 s2, s12, s2
	s_cselect_b32 s4, s13, s4
	s_add_i32 s12, s2, 1
	s_cmp_ge_u32 s4, s11
	s_cselect_b32 s2, s12, s2
	s_and_b32 s3, s3, 7
	s_and_b32 s4, s5, -8
	s_lshl_b32 s30, s2, 4
	s_mul_i32 s2, s29, 0xc0
	s_or_b32 s31, s3, s4
	s_ashr_i32 s3, s2, 31
	s_lshl_b64 s[2:3], s[2:3], 11
	v_lshlrev_b32_e32 v2, 8, v1
	v_lshlrev_b32_e32 v1, 4, v1
	s_add_u32 s2, s27, s2
	v_and_b32_e32 v1, 0x70, v1
	s_movk_i32 s33, 0xf800
	v_mov_b32_e32 v175, 0
	s_addc_u32 s3, s28, s3
	v_and_or_b32 v174, v2, s33, v1
	s_lshl_b32 s4, s31, 8
	v_lshl_add_u64 v[2:3], s[2:3], 0, v[174:175]
	s_mov_b32 s12, 0x40000
	s_ashr_i32 s5, s4, 31
	v_add_co_u32_e32 v14, vcc, s12, v2
	s_lshl_b64 s[4:5], s[4:5], 11
	s_nop 0
	v_addc_co_u32_e32 v15, vcc, 0, v3, vcc
	s_mov_b32 s34, 0x20000
	s_add_u32 s4, s25, s4
	v_add_co_u32_e32 v16, vcc, s34, v2
	s_addc_u32 s5, s26, s5
	s_nop 0
	v_addc_co_u32_e32 v17, vcc, 0, v3, vcc
	global_load_dwordx4 v[2:5], v[14:15], off
	global_load_dwordx4 v[6:9], v[16:17], off
	global_load_dwordx4 v[10:13], v174, s[2:3]
	v_lshl_add_u64 v[14:15], s[4:5], 0, v[174:175]
	s_mov_b32 s13, 0x60000
	v_add_co_u32_e32 v30, vcc, s13, v14
	v_mov_b32_e32 v1, v0
	s_nop 0
	v_addc_co_u32_e32 v31, vcc, 0, v15, vcc
	v_add_co_u32_e32 v32, vcc, s12, v14
	s_movk_i32 s36, 0xf0
	s_nop 0
	v_addc_co_u32_e32 v33, vcc, 0, v15, vcc
	v_add_co_u32_e32 v34, vcc, s34, v14
	s_mov_b32 s35, 2
	s_nop 0
	v_addc_co_u32_e32 v35, vcc, 0, v15, vcc
	global_load_dwordx4 v[14:17], v174, s[4:5]
	global_load_dwordx4 v[18:21], v[34:35], off
	global_load_dwordx4 v[22:25], v[32:33], off
	global_load_dwordx4 v[26:29], v[30:31], off
	v_mov_b32_e32 v30, v0
	v_ashrrev_i32_e32 v31, 4, v1
	v_xor_b32_e32 v1, v31, v1
	v_lshlrev_b32_e32 v31, 8, v31
	v_lshlrev_b32_e32 v1, 4, v1
	v_and_or_b32 v1, v1, s36, v31
	s_movk_i32 s37, 0xff80
	s_mov_b32 s38, 0x10000
	s_mov_b32 s39, 0x18000
	s_movk_i32 s40, 0x8a0
	s_movk_i32 s41, 0x1140
	v_mov_b32_e32 v176, 0x18000
	s_mov_b32 s22, 2
	s_mov_b32 s42, s24
	s_mov_b32 s43, s29
	s_mov_b32 s44, s31
	v_mov_b32_e32 v55, v54
	v_mov_b32_e32 v56, v54
	v_mov_b32_e32 v57, v54
	v_mov_b32_e32 v82, v54
	v_mov_b32_e32 v83, v54
	v_mov_b32_e32 v84, v54
	v_mov_b32_e32 v85, v54
	v_mov_b32_e32 v86, v54
	v_mov_b32_e32 v87, v54
	v_mov_b32_e32 v88, v54
	v_mov_b32_e32 v89, v54
	v_mov_b32_e32 v90, v54
	v_mov_b32_e32 v91, v54
	v_mov_b32_e32 v92, v54
	v_mov_b32_e32 v93, v54
	v_mov_b32_e32 v94, v54
	v_mov_b32_e32 v95, v54
	v_mov_b32_e32 v96, v54
	v_mov_b32_e32 v97, v54
	s_waitcnt vmcnt(4)
	ds_write_b128 v1, v[10:13] offset:32768
	ds_write_b128 v1, v[6:9] offset:40960
	ds_write_b128 v1, v[2:5] offset:49152
	s_waitcnt vmcnt(3)
	ds_write_b128 v1, v[14:17]
	s_waitcnt vmcnt(2)
	ds_write_b128 v1, v[18:21] offset:8192
	s_waitcnt vmcnt(1)
	ds_write_b128 v1, v[22:25] offset:16384
	s_waitcnt vmcnt(0)
	ds_write_b128 v1, v[26:29] offset:24576
	v_mov_b32_e32 v98, v54
	v_lshlrev_b32_e32 v2, 4, v30
	v_lshlrev_b32_e32 v1, 8, v30
	v_and_b32_e32 v2, 0x70, v2
	v_and_or_b32 v174, v1, s33, v2
	v_lshl_add_u64 v[2:3], s[2:3], 0, v[174:175]
	v_add_co_u32_e32 v10, vcc, s12, v2
	v_mov_b32_e32 v1, 0x10000
	s_nop 0
	v_addc_co_u32_e32 v11, vcc, 0, v3, vcc
	v_add_co_u32_e32 v12, vcc, s34, v2
	v_mov_b32_e32 v99, v54
	s_nop 0
	v_addc_co_u32_e32 v13, vcc, 0, v3, vcc
	global_load_dwordx4 v[2:5], v[10:11], off offset:128
	global_load_dwordx4 v[6:9], v[12:13], off offset:128
	v_lshl_add_u64 v[10:11], s[4:5], 0, v[174:175]
	v_add_co_u32_e32 v12, vcc, s13, v10
	v_mov_b32_e32 v100, v54
	s_nop 0
	v_addc_co_u32_e32 v13, vcc, 0, v11, vcc
	v_add_co_u32_e32 v22, vcc, s12, v10
	v_mov_b32_e32 v101, v54
	s_nop 0
	v_addc_co_u32_e32 v23, vcc, 0, v11, vcc
	v_add_co_u32_e32 v30, vcc, s34, v10
	global_load_dwordx4 v[14:17], v[12:13], off offset:128
	global_load_dwordx4 v[18:21], v[22:23], off offset:128
	v_addc_co_u32_e32 v31, vcc, 0, v11, vcc
	global_load_dwordx4 v[10:13], v174, s[2:3] offset:128
	global_load_dwordx4 v[22:25], v[30:31], off offset:128
	global_load_dwordx4 v[26:29], v174, s[4:5] offset:128
	v_mov_b32_e32 v102, v54
	v_mov_b32_e32 v103, v54
	v_mov_b32_e32 v104, v54
	v_mov_b32_e32 v105, v54
	v_mov_b32_e32 v106, v54
	v_mov_b32_e32 v107, v54
	v_mov_b32_e32 v108, v54
	v_mov_b32_e32 v109, v54
	v_mov_b32_e32 v110, v54
	v_mov_b32_e32 v111, v54
	v_mov_b32_e32 v112, v54
	v_mov_b32_e32 v113, v54
	v_mov_b32_e32 v114, v54
	v_mov_b32_e32 v115, v54
	v_mov_b32_e32 v116, v54
	v_mov_b32_e32 v117, v54
	v_mov_b32_e32 v118, v54
	v_mov_b32_e32 v119, v54
	v_mov_b32_e32 v120, v54
	v_mov_b32_e32 v121, v54
	v_mov_b32_e32 v122, v54
	v_mov_b32_e32 v123, v54
	v_mov_b32_e32 v124, v54
	v_mov_b32_e32 v125, v54
	v_mov_b32_e32 v78, v54
	v_mov_b32_e32 v79, v54
	v_mov_b32_e32 v80, v54
	v_mov_b32_e32 v81, v54
	v_mov_b32_e32 v74, v54
	v_mov_b32_e32 v75, v54
	v_mov_b32_e32 v76, v54
	v_mov_b32_e32 v77, v54
	v_mov_b32_e32 v70, v54
	v_mov_b32_e32 v71, v54
	v_mov_b32_e32 v72, v54
	v_mov_b32_e32 v73, v54
	v_mov_b32_e32 v66, v54
	v_mov_b32_e32 v67, v54
	v_mov_b32_e32 v68, v54
	v_mov_b32_e32 v69, v54
	v_mov_b32_e32 v62, v54
	v_mov_b32_e32 v63, v54
	v_mov_b32_e32 v64, v54
	v_mov_b32_e32 v65, v54
	v_mov_b32_e32 v58, v54
	v_mov_b32_e32 v59, v54
	v_mov_b32_e32 v60, v54
	v_mov_b32_e32 v61, v54
	v_mov_b32_e32 v50, v54
	v_mov_b32_e32 v51, v54
	v_mov_b32_e32 v52, v54
	v_mov_b32_e32 v53, v54
	v_mov_b32_e32 v46, v54
	v_mov_b32_e32 v47, v54
	v_mov_b32_e32 v48, v54
	v_mov_b32_e32 v49, v54
	v_mov_b32_e32 v42, v54
	v_mov_b32_e32 v43, v54
	v_mov_b32_e32 v44, v54
	v_mov_b32_e32 v45, v54
	v_mov_b32_e32 v38, v54
	v_mov_b32_e32 v39, v54
	v_mov_b32_e32 v40, v54
	v_mov_b32_e32 v41, v54
	v_mov_b32_e32 v34, v54
	v_mov_b32_e32 v35, v54
	v_mov_b32_e32 v36, v54
	v_mov_b32_e32 v37, v54
	v_mov_b32_e32 v30, v54
	v_mov_b32_e32 v31, v54
	v_mov_b32_e32 v32, v54
	v_mov_b32_e32 v33, v54
	s_waitcnt lgkmcnt(0)
	s_barrier
	s_waitcnt vmcnt(0)
	s_branch .LBB0_1528

.LBB0_2199:
	s_mov_b32 s98, 0
	v_mov_b32_e32 v255, 0x0
	v_bfe_u32 v1, v0, 0, 1
	v_lshlrev_b32_e32 v1, 7, v1
	v_xor_b32_e32 v255, v255, v1
	v_bfe_u32 v1, v0, 1, 3
	v_mul_u32_u24_e32 v1, 0x110, v1
	v_xor_b32_e32 v255, v255, v1
	v_bfe_u32 v1, v0, 4, 2
	v_lshlrev_b32_e32 v1, 4, v1
	v_xor_b32_e32 v255, v255, v1
	v_bfe_u32 v1, v0, 8, 1
	v_lshlrev_b32_e32 v1, 14, v1
	v_xor_b32_e32 v255, v255, v1
	v_mov_b32_e32 v254, 0x10000
	v_bfe_u32 v1, v0, 0, 1
	v_lshlrev_b32_e32 v1, 7, v1
	v_xor_b32_e32 v254, v254, v1
	v_bfe_u32 v1, v0, 1, 3
	v_mul_u32_u24_e32 v1, 0x110, v1
	v_xor_b32_e32 v254, v254, v1
	v_bfe_u32 v1, v0, 4, 2
	v_lshlrev_b32_e32 v1, 4, v1
	v_xor_b32_e32 v254, v254, v1
	v_bfe_u32 v1, v0, 8, 1
	v_lshlrev_b32_e32 v1, 14, v1
	v_xor_b32_e32 v254, v254, v1
	v_mov_b32_e32 v253, 0x880
	v_bfe_u32 v1, v0, 0, 1
	v_lshlrev_b32_e32 v1, 7, v1
	v_xor_b32_e32 v253, v253, v1
	v_bfe_u32 v1, v0, 1, 3
	v_mul_u32_u24_e32 v1, 0x110, v1
	v_xor_b32_e32 v253, v253, v1
	v_bfe_u32 v1, v0, 4, 2
	v_lshlrev_b32_e32 v1, 4, v1
	v_xor_b32_e32 v253, v253, v1
	v_bfe_u32 v1, v0, 8, 1
	v_lshlrev_b32_e32 v1, 14, v1
	v_xor_b32_e32 v253, v253, v1
	v_mov_b32_e32 v252, 0x10880
	v_bfe_u32 v1, v0, 0, 1
	v_lshlrev_b32_e32 v1, 7, v1
	v_xor_b32_e32 v252, v252, v1
	v_bfe_u32 v1, v0, 1, 3
	v_mul_u32_u24_e32 v1, 0x110, v1
	v_xor_b32_e32 v252, v252, v1
	v_bfe_u32 v1, v0, 4, 2
	v_lshlrev_b32_e32 v1, 4, v1
	v_xor_b32_e32 v252, v252, v1
	v_bfe_u32 v1, v0, 8, 1
	v_lshlrev_b32_e32 v1, 14, v1
	v_xor_b32_e32 v252, v252, v1
	v_mov_b32_e32 v251, 0x8000
	v_bfe_u32 v1, v0, 0, 1
	v_lshlrev_b32_e32 v1, 7, v1
	v_xor_b32_e32 v251, v251, v1
	v_bfe_u32 v1, v0, 1, 3
	v_mul_u32_u24_e32 v1, 0x110, v1
	v_xor_b32_e32 v251, v251, v1
	v_bfe_u32 v1, v0, 4, 2
	v_lshlrev_b32_e32 v1, 4, v1
	v_xor_b32_e32 v251, v251, v1
	v_bfe_u32 v1, v0, 6, 2
	v_lshlrev_b32_e32 v1, 13, v1
	v_xor_b32_e32 v251, v251, v1
	v_mov_b32_e32 v250, 0x18000
	v_bfe_u32 v1, v0, 0, 1
	v_lshlrev_b32_e32 v1, 7, v1
	v_xor_b32_e32 v250, v250, v1
	v_bfe_u32 v1, v0, 1, 3
	v_mul_u32_u24_e32 v1, 0x110, v1
	v_xor_b32_e32 v250, v250, v1
	v_bfe_u32 v1, v0, 4, 2
	v_lshlrev_b32_e32 v1, 4, v1
	v_xor_b32_e32 v250, v250, v1
	v_bfe_u32 v1, v0, 6, 2
	v_lshlrev_b32_e32 v1, 13, v1
	v_xor_b32_e32 v250, v250, v1
	v_mov_b32_e32 v249, 0x8880
	v_bfe_u32 v1, v0, 0, 1
	v_lshlrev_b32_e32 v1, 7, v1
	v_xor_b32_e32 v249, v249, v1
	v_bfe_u32 v1, v0, 1, 3
	v_mul_u32_u24_e32 v1, 0x110, v1
	v_xor_b32_e32 v249, v249, v1
	v_bfe_u32 v1, v0, 4, 2
	v_lshlrev_b32_e32 v1, 4, v1
	v_xor_b32_e32 v249, v249, v1
	v_bfe_u32 v1, v0, 6, 2
	v_lshlrev_b32_e32 v1, 13, v1
	v_xor_b32_e32 v249, v249, v1
	v_mov_b32_e32 v248, 0x18880
	v_bfe_u32 v1, v0, 0, 1
	v_lshlrev_b32_e32 v1, 7, v1
	v_xor_b32_e32 v248, v248, v1
	v_bfe_u32 v1, v0, 1, 3
	v_mul_u32_u24_e32 v1, 0x110, v1
	v_xor_b32_e32 v248, v248, v1
	v_bfe_u32 v1, v0, 4, 2
	v_lshlrev_b32_e32 v1, 4, v1
	v_xor_b32_e32 v248, v248, v1
	v_bfe_u32 v1, v0, 6, 2
	v_lshlrev_b32_e32 v1, 13, v1
	v_xor_b32_e32 v248, v248, v1
	v_mov_b32_e32 v247, 0x40
	v_bfe_u32 v1, v0, 0, 1
	v_lshlrev_b32_e32 v1, 7, v1
	v_xor_b32_e32 v247, v247, v1
	v_bfe_u32 v1, v0, 1, 3
	v_mul_u32_u24_e32 v1, 0x110, v1
	v_xor_b32_e32 v247, v247, v1
	v_bfe_u32 v1, v0, 4, 2
	v_lshlrev_b32_e32 v1, 4, v1
	v_xor_b32_e32 v247, v247, v1
	v_bfe_u32 v1, v0, 8, 1
	v_lshlrev_b32_e32 v1, 14, v1
	v_xor_b32_e32 v247, v247, v1
	v_mov_b32_e32 v246, 0x10040
	v_bfe_u32 v1, v0, 0, 1
	v_lshlrev_b32_e32 v1, 7, v1
	v_xor_b32_e32 v246, v246, v1
	v_bfe_u32 v1, v0, 1, 3
	v_mul_u32_u24_e32 v1, 0x110, v1
	v_xor_b32_e32 v246, v246, v1
	v_bfe_u32 v1, v0, 4, 2
	v_lshlrev_b32_e32 v1, 4, v1
	v_xor_b32_e32 v246, v246, v1
	v_bfe_u32 v1, v0, 8, 1
	v_lshlrev_b32_e32 v1, 14, v1
	v_xor_b32_e32 v246, v246, v1
	v_mov_b32_e32 v245, 0x8c0
	v_bfe_u32 v1, v0, 0, 1
	v_lshlrev_b32_e32 v1, 7, v1
	v_xor_b32_e32 v245, v245, v1
	v_bfe_u32 v1, v0, 1, 3
	v_mul_u32_u24_e32 v1, 0x110, v1
	v_xor_b32_e32 v245, v245, v1
	v_bfe_u32 v1, v0, 4, 2
	v_lshlrev_b32_e32 v1, 4, v1
	v_xor_b32_e32 v245, v245, v1
	v_bfe_u32 v1, v0, 8, 1
	v_lshlrev_b32_e32 v1, 14, v1
	v_xor_b32_e32 v245, v245, v1
	v_mov_b32_e32 v244, 0x108c0
	v_bfe_u32 v1, v0, 0, 1
	v_lshlrev_b32_e32 v1, 7, v1
	v_xor_b32_e32 v244, v244, v1
	v_bfe_u32 v1, v0, 1, 3
	v_mul_u32_u24_e32 v1, 0x110, v1
	v_xor_b32_e32 v244, v244, v1
	v_bfe_u32 v1, v0, 4, 2
	v_lshlrev_b32_e32 v1, 4, v1
	v_xor_b32_e32 v244, v244, v1
	v_bfe_u32 v1, v0, 8, 1
	v_lshlrev_b32_e32 v1, 14, v1
	v_xor_b32_e32 v244, v244, v1
	v_mov_b32_e32 v243, 0x8040
	v_bfe_u32 v1, v0, 0, 1
	v_lshlrev_b32_e32 v1, 7, v1
	v_xor_b32_e32 v243, v243, v1
	v_bfe_u32 v1, v0, 1, 3
	v_mul_u32_u24_e32 v1, 0x110, v1
	v_xor_b32_e32 v243, v243, v1
	v_bfe_u32 v1, v0, 4, 2
	v_lshlrev_b32_e32 v1, 4, v1
	v_xor_b32_e32 v243, v243, v1
	v_bfe_u32 v1, v0, 6, 2
	v_lshlrev_b32_e32 v1, 13, v1
	v_xor_b32_e32 v243, v243, v1
	v_mov_b32_e32 v242, 0x18040
	v_bfe_u32 v1, v0, 0, 1
	v_lshlrev_b32_e32 v1, 7, v1
	v_xor_b32_e32 v242, v242, v1
	v_bfe_u32 v1, v0, 1, 3
	v_mul_u32_u24_e32 v1, 0x110, v1
	v_xor_b32_e32 v242, v242, v1
	v_bfe_u32 v1, v0, 4, 2
	v_lshlrev_b32_e32 v1, 4, v1
	v_xor_b32_e32 v242, v242, v1
	v_bfe_u32 v1, v0, 6, 2
	v_lshlrev_b32_e32 v1, 13, v1
	v_xor_b32_e32 v242, v242, v1
	v_mov_b32_e32 v241, 0x88c0
	v_bfe_u32 v1, v0, 0, 1
	v_lshlrev_b32_e32 v1, 7, v1
	v_xor_b32_e32 v241, v241, v1
	v_bfe_u32 v1, v0, 1, 3
	v_mul_u32_u24_e32 v1, 0x110, v1
	v_xor_b32_e32 v241, v241, v1
	v_bfe_u32 v1, v0, 4, 2
	v_lshlrev_b32_e32 v1, 4, v1
	v_xor_b32_e32 v241, v241, v1
	v_bfe_u32 v1, v0, 6, 2
	v_lshlrev_b32_e32 v1, 13, v1
	v_xor_b32_e32 v241, v241, v1
	v_mov_b32_e32 v237, 0x188c0
	v_bfe_u32 v1, v0, 0, 1
	v_lshlrev_b32_e32 v1, 7, v1
	v_xor_b32_e32 v237, v237, v1
	v_bfe_u32 v1, v0, 1, 3
	v_mul_u32_u24_e32 v1, 0x110, v1
	v_xor_b32_e32 v237, v237, v1
	v_bfe_u32 v1, v0, 4, 2
	v_lshlrev_b32_e32 v1, 4, v1
	v_xor_b32_e32 v237, v237, v1
	v_bfe_u32 v1, v0, 6, 2
	v_lshlrev_b32_e32 v1, 13, v1
	v_xor_b32_e32 v237, v237, v1
	v_mov_b32_e32 v236, 0x0
	v_bfe_u32 v1, v0, 0, 4
	v_lshlrev_b32_e32 v1, 4, v1
	v_xor_b32_e32 v236, v236, v1
	v_bfe_u32 v1, v0, 4, 4
	v_mul_u32_u24_e32 v1, 0x110, v1
	v_xor_b32_e32 v236, v236, v1
	v_bfe_u32 v1, v0, 8, 1
	v_lshlrev_b32_e32 v1, 12, v1
	v_xor_b32_e32 v236, v236, v1
	v_mov_b32_e32 v235, 0x10000
	v_bfe_u32 v1, v0, 0, 4
	v_lshlrev_b32_e32 v1, 4, v1
	v_xor_b32_e32 v235, v235, v1
	v_bfe_u32 v1, v0, 4, 4
	v_mul_u32_u24_e32 v1, 0x110, v1
	v_xor_b32_e32 v235, v235, v1
	v_bfe_u32 v1, v0, 8, 1
	v_lshlrev_b32_e32 v1, 12, v1
	v_xor_b32_e32 v235, v235, v1
	v_mov_b32_e32 v234, 0x0
	v_bfe_u32 v1, v0, 0, 3
	v_lshlrev_b32_e32 v1, 4, v1
	v_add_u32_e32 v234, v234, v1
	v_bfe_u32 v1, v0, 3, 6
	v_lshlrev_b32_e32 v1, 11, v1
	v_add_u32_e32 v234, v234, v1
	v_mov_b32_e32 v233, 0x20000
	v_bfe_u32 v1, v0, 0, 3
	v_lshlrev_b32_e32 v1, 4, v1
	v_add_u32_e32 v233, v233, v1
	v_bfe_u32 v1, v0, 3, 6
	v_lshlrev_b32_e32 v1, 11, v1
	v_add_u32_e32 v233, v233, v1
	v_mov_b32_e32 v232, 0x40000
	v_bfe_u32 v1, v0, 0, 3
	v_lshlrev_b32_e32 v1, 4, v1
	v_add_u32_e32 v232, v232, v1
	v_bfe_u32 v1, v0, 3, 6
	v_lshlrev_b32_e32 v1, 11, v1
	v_add_u32_e32 v232, v232, v1
	v_mov_b32_e32 v231, 0x60000
	v_bfe_u32 v1, v0, 0, 3
	v_lshlrev_b32_e32 v1, 4, v1
	v_add_u32_e32 v231, v231, v1
	v_bfe_u32 v1, v0, 3, 6
	v_lshlrev_b32_e32 v1, 11, v1
	v_add_u32_e32 v231, v231, v1
	v_mov_b32_e32 v1, v0
	s_load_dword s2, s[0:1], 0xe0
	s_mov_b32 s3, s10
	v_mov_b32_e32 v1, v0
	s_waitcnt lgkmcnt(0)
	s_lshr_b32 s11, s2, 3
	s_waitcnt vmcnt(0)
	v_cvt_f32_u32_e32 v2, s11
	s_mov_b32 s2, s10
	s_ashr_i32 s3, s2, 3
	v_rcp_iflag_f32_e32 v2, v2
	s_ashr_i32 s4, s2, 31
	s_sub_i32 s2, 0, s11
	s_abs_i32 s3, s3
	v_mul_f32_e32 v1, 0x4f7ffffe, v2
	v_cvt_u32_f32_e32 v1, v1
	s_mov_b32 s50, 0
	v_readfirstlane_b32 s5, v1
	s_mul_i32 s2, s2, s5
	s_mul_hi_u32 s2, s5, s2
	s_add_i32 s2, s5, s2
	s_mul_hi_u32 s5, s3, s2
	s_mul_i32 s5, s5, s11
	s_sub_i32 s3, s3, s5
	s_sub_i32 s5, s3, s11
	s_cmp_ge_u32 s3, s11
	s_cselect_b32 s3, s5, s3
	s_sub_i32 s5, s3, s11
	s_cmp_ge_u32 s3, s11
	s_cselect_b32 s3, s5, s3
	s_xor_b32 s3, s3, s4
	s_sub_i32 s28, s3, s4
	s_mov_b32 s3, s10
	s_cmp_gt_i32 s28, 31
	s_cbranch_scc1 .LBB0_2263
	s_load_dwordx4 s[4:7], s[16:17], 0xc8
	s_mov_b32 s3, s10
	v_mov_b32_e32 v82, 0
	v_mov_b32_e32 v1, v0
	s_waitcnt lgkmcnt(0)
	s_add_u32 s29, s6, 0x17f0000
	s_addc_u32 s30, s7, 0
	s_add_u32 s12, s4, 0x2000000
	s_addc_u32 s13, s5, 0
	s_add_u32 s14, s6, 0x24000
	s_addc_u32 s15, s7, 0
	s_add_u32 s31, s6, 0x570000
	s_addc_u32 s33, s7, 0
	s_ashr_i32 s6, s28, 31
	s_lshr_b32 s6, s6, 27
	s_add_i32 s6, s28, s6
	s_ashr_i32 s6, s6, 5
	s_lshl_b32 s7, s28, 1
	s_lshl_b32 s20, s6, 6
	s_sub_i32 s7, s7, s20
	s_lshl_b32 s6, s6, 2
	s_and_b32 s20, s28, 3
	s_or_b32 s34, s6, s20
	s_sub_i32 s6, s11, s28
	s_add_i32 s6, s6, 31
	s_mul_hi_u32 s2, s6, s2
	s_mul_i32 s20, s2, s11
	s_sub_i32 s6, s6, s20
	s_add_i32 s20, s2, 1
	s_sub_i32 s21, s6, s11
	s_cmp_ge_u32 s6, s11
	s_cselect_b32 s2, s20, s2
	s_cselect_b32 s6, s21, s6
	s_add_i32 s20, s2, 1
	s_cmp_ge_u32 s6, s11
	s_cselect_b32 s2, s20, s2
	s_and_b32 s3, s3, 7
	s_and_b32 s6, s7, -8
	s_lshl_b32 s35, s2, 4
	s_lshl_b32 s2, s34, 8
	s_or_b32 s36, s3, s6
	s_ashr_i32 s3, s2, 31
	s_lshl_b64 s[2:3], s[2:3], 11
	v_lshlrev_b32_e32 v2, 8, v1
	v_lshlrev_b32_e32 v1, 4, v1
	s_add_u32 s2, s31, s2
	v_and_b32_e32 v1, 0x70, v1
	s_movk_i32 s37, 0xf800
	v_mov_b32_e32 v239, 0
	s_addc_u32 s3, s33, s3
	v_and_or_b32 v238, v2, s37, v1
	v_lshl_add_u64 v[10:11], s[2:3], 0, v[238:239]
	s_mov_b32 s38, 0x60000
	v_add_co_u32_e32 v12, vcc, s38, v10
	s_lshl_b32 s6, s36, 8
	s_nop 0
	v_addc_co_u32_e32 v13, vcc, 0, v11, vcc
	s_mov_b32 s20, 0x40000
	s_ashr_i32 s7, s6, 31
	v_add_co_u32_e32 v14, vcc, s20, v10
	s_lshl_b64 s[6:7], s[6:7], 11
	s_nop 0
	v_addc_co_u32_e32 v15, vcc, 0, v11, vcc
	s_mov_b32 s39, 0x20000
	s_add_u32 s6, s29, s6
	v_add_co_u32_e32 v18, vcc, s39, v10
	s_addc_u32 s7, s30, s7
	s_nop 0
	v_addc_co_u32_e32 v19, vcc, 0, v11, vcc
	v_lshl_add_u64 v[30:31], s[6:7], 0, v[238:239]
	v_add_co_u32_e32 v32, vcc, s20, v30
	global_load_dwordx4 v[2:5], v[12:13], off
	global_load_dwordx4 v[6:9], v[14:15], off
	v_addc_co_u32_e32 v33, vcc, 0, v31, vcc
	v_add_co_u32_e32 v34, vcc, s39, v30
	global_load_dwordx4 v[10:13], v[18:19], off
	global_load_dwordx4 v[14:17], v238, s[2:3]
	v_addc_co_u32_e32 v35, vcc, 0, v31, vcc
	global_load_dwordx4 v[18:21], v[32:33], off
	global_load_dwordx4 v[22:25], v[34:35], off
	global_load_dwordx4 v[26:29], v238, s[6:7]
	v_add_co_u32_e32 v30, vcc, s38, v30
	v_mov_b32_e32 v1, v0
	s_nop 0
	v_addc_co_u32_e32 v31, vcc, 0, v31, vcc
	global_load_dwordx4 v[30:33], v[30:31], off
	s_movk_i32 s41, 0xf0
	v_ashrrev_i32_e32 v35, 4, v1
	v_xor_b32_e32 v1, v35, v1
	v_lshlrev_b32_e32 v35, 8, v35
	v_lshlrev_b32_e32 v1, 4, v1
	v_mov_b32_e32 v34, v0
	v_and_or_b32 v1, v1, s41, v35
	s_mov_b32 s40, 2
	s_movk_i32 s42, 0xff80
	s_mov_b32 s43, 0x10000
	s_mov_b32 s44, 0x11000
	s_movk_i32 s45, 0x1800
	s_movk_i32 s46, 0x1fff
	v_mov_b32_e32 v240, 0x8040
	s_mov_b32 s26, 2
	s_mov_b32 s47, s28
	s_mov_b32 s48, s34
	s_mov_b32 s49, s36
	v_mov_b32_e32 v83, v82
	v_mov_b32_e32 v84, v82
	v_mov_b32_e32 v85, v82
	v_mov_b32_e32 v102, v82
	v_mov_b32_e32 v103, v82
	v_mov_b32_e32 v104, v82
	v_mov_b32_e32 v105, v82
	v_mov_b32_e32 v106, v82
	v_mov_b32_e32 v107, v82
	v_mov_b32_e32 v108, v82
	v_mov_b32_e32 v109, v82
	v_mov_b32_e32 v110, v82
	v_mov_b32_e32 v111, v82
	s_waitcnt vmcnt(4)
	ds_write_b128 v1, v[14:17] offset:32768
	ds_write_b128 v1, v[10:13] offset:40960
	ds_write_b128 v1, v[6:9] offset:49152
	ds_write_b128 v1, v[2:5] offset:57344
	s_waitcnt vmcnt(1)
	ds_write_b128 v1, v[26:29]
	ds_write_b128 v1, v[22:25] offset:8192
	ds_write_b128 v1, v[18:21] offset:16384
	s_waitcnt vmcnt(0)
	ds_write_b128 v1, v[30:33] offset:24576
	v_mov_b32_e32 v112, v82
	v_lshlrev_b32_e32 v2, 4, v34
	v_lshlrev_b32_e32 v1, 8, v34
	v_and_b32_e32 v2, 0x70, v2
	v_and_or_b32 v238, v1, s37, v2
	v_lshl_add_u64 v[10:11], s[2:3], 0, v[238:239]
	v_add_co_u32_e32 v12, vcc, s38, v10
	v_lshl_add_u64 v[16:17], s[6:7], 0, v[238:239]
	s_nop 0
	v_addc_co_u32_e32 v13, vcc, 0, v11, vcc
	v_add_co_u32_e32 v14, vcc, s20, v10
	v_mov_b32_e32 v1, 0x10000
	s_nop 0
	v_addc_co_u32_e32 v15, vcc, 0, v11, vcc
	global_load_dwordx4 v[2:5], v[12:13], off offset:128
	global_load_dwordx4 v[6:9], v[14:15], off offset:128
	v_add_co_u32_e32 v14, vcc, s39, v10
	v_mov_b32_e32 v113, v82
	s_nop 0
	v_addc_co_u32_e32 v15, vcc, 0, v11, vcc
	v_add_co_u32_e32 v22, vcc, s38, v16
	v_mov_b32_e32 v114, v82
	s_nop 0
	v_addc_co_u32_e32 v23, vcc, 0, v17, vcc
	v_add_co_u32_e32 v34, vcc, s20, v16
	global_load_dwordx4 v[10:13], v[14:15], off offset:128
	global_load_dwordx4 v[18:21], v[22:23], off offset:128
	v_addc_co_u32_e32 v35, vcc, 0, v17, vcc
	v_add_co_u32_e32 v36, vcc, s39, v16
	v_mov_b32_e32 v115, v82
	s_nop 0
	v_addc_co_u32_e32 v37, vcc, 0, v17, vcc
	global_load_dwordx4 v[22:25], v[34:35], off offset:128
	global_load_dwordx4 v[26:29], v[36:37], off offset:128
	global_load_dwordx4 v[14:17], v238, s[2:3] offset:128
	global_load_dwordx4 v[30:33], v238, s[6:7] offset:128
	v_mov_b32_e32 v116, v82
	v_mov_b32_e32 v117, v82
	v_mov_b32_e32 v118, v82
	v_mov_b32_e32 v119, v82
	v_mov_b32_e32 v120, v82
	v_mov_b32_e32 v121, v82
	v_mov_b32_e32 v122, v82
	v_mov_b32_e32 v123, v82
	v_mov_b32_e32 v124, v82
	v_mov_b32_e32 v125, v82
	v_mov_b32_e32 v126, v82
	v_mov_b32_e32 v127, v82
	v_mov_b32_e32 v128, v82
	v_mov_b32_e32 v129, v82
	v_mov_b32_e32 v130, v82
	v_mov_b32_e32 v131, v82
	v_mov_b32_e32 v132, v82
	v_mov_b32_e32 v133, v82
	v_mov_b32_e32 v134, v82
	v_mov_b32_e32 v135, v82
	v_mov_b32_e32 v136, v82
	v_mov_b32_e32 v137, v82
	v_mov_b32_e32 v138, v82
	v_mov_b32_e32 v139, v82
	v_mov_b32_e32 v140, v82
	v_mov_b32_e32 v141, v82
	v_mov_b32_e32 v142, v82
	v_mov_b32_e32 v143, v82
	v_mov_b32_e32 v144, v82
	v_mov_b32_e32 v145, v82
	v_mov_b32_e32 v146, v82
	v_mov_b32_e32 v147, v82
	v_mov_b32_e32 v148, v82
	v_mov_b32_e32 v149, v82
	v_mov_b32_e32 v150, v82
	v_mov_b32_e32 v151, v82
	v_mov_b32_e32 v152, v82
	v_mov_b32_e32 v153, v82
	v_mov_b32_e32 v154, v82
	v_mov_b32_e32 v155, v82
	v_mov_b32_e32 v156, v82
	v_mov_b32_e32 v157, v82
	v_mov_b32_e32 v158, v82
	v_mov_b32_e32 v159, v82
	v_mov_b32_e32 v160, v82
	v_mov_b32_e32 v161, v82
	v_mov_b32_e32 v98, v82
	v_mov_b32_e32 v99, v82
	v_mov_b32_e32 v100, v82
	v_mov_b32_e32 v101, v82
	v_mov_b32_e32 v94, v82
	v_mov_b32_e32 v95, v82
	v_mov_b32_e32 v96, v82
	v_mov_b32_e32 v97, v82
	v_mov_b32_e32 v90, v82
	v_mov_b32_e32 v91, v82
	v_mov_b32_e32 v92, v82
	v_mov_b32_e32 v93, v82
	v_mov_b32_e32 v86, v82
	v_mov_b32_e32 v87, v82
	v_mov_b32_e32 v88, v82
	v_mov_b32_e32 v89, v82
	v_mov_b32_e32 v78, v82
	v_mov_b32_e32 v79, v82
	v_mov_b32_e32 v80, v82
	v_mov_b32_e32 v81, v82
	v_mov_b32_e32 v74, v82
	v_mov_b32_e32 v75, v82
	v_mov_b32_e32 v76, v82
	v_mov_b32_e32 v77, v82
	v_mov_b32_e32 v70, v82
	v_mov_b32_e32 v71, v82
	v_mov_b32_e32 v72, v82
	v_mov_b32_e32 v73, v82
	v_mov_b32_e32 v66, v82
	v_mov_b32_e32 v67, v82
	v_mov_b32_e32 v68, v82
	v_mov_b32_e32 v69, v82
	v_mov_b32_e32 v62, v82
	v_mov_b32_e32 v63, v82
	v_mov_b32_e32 v64, v82
	v_mov_b32_e32 v65, v82
	v_mov_b32_e32 v58, v82
	v_mov_b32_e32 v59, v82
	v_mov_b32_e32 v60, v82
	v_mov_b32_e32 v61, v82
	v_mov_b32_e32 v54, v82
	v_mov_b32_e32 v55, v82
	v_mov_b32_e32 v56, v82
	v_mov_b32_e32 v57, v82
	v_mov_b32_e32 v50, v82
	v_mov_b32_e32 v51, v82
	v_mov_b32_e32 v52, v82
	v_mov_b32_e32 v53, v82
	v_mov_b32_e32 v46, v82
	v_mov_b32_e32 v47, v82
	v_mov_b32_e32 v48, v82
	v_mov_b32_e32 v49, v82
	v_mov_b32_e32 v42, v82
	v_mov_b32_e32 v43, v82
	v_mov_b32_e32 v44, v82
	v_mov_b32_e32 v45, v82
	v_mov_b32_e32 v38, v82
	v_mov_b32_e32 v39, v82
	v_mov_b32_e32 v40, v82
	v_mov_b32_e32 v41, v82
	v_mov_b32_e32 v34, v82
	v_mov_b32_e32 v35, v82
	v_mov_b32_e32 v36, v82
	v_mov_b32_e32 v37, v82
	s_waitcnt lgkmcnt(0)
	s_barrier
	s_waitcnt vmcnt(0)
	s_branch .LBB0_2203

.Lnodef_G1_6:
	ds_read_b128 v[170:173], v255 offset:4096
	ds_read_b128 v[174:177], v253 offset:4096
	s_add_i32 s2, s40, -1
	s_cmp_lt_i32 s2, s35
	s_cselect_b64 s[22:23], -1, 0
	s_cmp_ge_i32 s2, s35
	s_waitcnt lgkmcnt(3)
	v_mfma_f32_16x16x32_bf16 v[158:161], v[178:181], v[162:165], v[158:161]
	v_mfma_f32_16x16x32_bf16 v[154:157], v[182:185], v[162:165], v[154:157]
	v_mfma_f32_16x16x32_bf16 v[150:153], v[186:189], v[162:165], v[150:153]
	v_mfma_f32_16x16x32_bf16 v[146:149], v[190:193], v[162:165], v[146:149]
	ds_read_b128 v[162:165], v255 offset:8192
	s_waitcnt lgkmcnt(3)
	v_mfma_f32_16x16x32_bf16 v[142:145], v[178:181], v[166:169], v[142:145]
	v_mfma_f32_16x16x32_bf16 v[138:141], v[182:185], v[166:169], v[138:141]
	v_mfma_f32_16x16x32_bf16 v[134:137], v[186:189], v[166:169], v[134:137]
	v_mfma_f32_16x16x32_bf16 v[130:133], v[190:193], v[166:169], v[130:133]
	ds_read_b128 v[166:169], v253 offset:8192
	s_waitcnt lgkmcnt(3)
	v_mfma_f32_16x16x32_bf16 v[126:129], v[178:181], v[170:173], v[126:129]
	v_mfma_f32_16x16x32_bf16 v[122:125], v[182:185], v[170:173], v[122:125]
	v_mfma_f32_16x16x32_bf16 v[118:121], v[186:189], v[170:173], v[118:121]
	v_mfma_f32_16x16x32_bf16 v[114:117], v[190:193], v[170:173], v[114:117]
	s_waitcnt vmcnt(6)
	ds_write_b128 v235, v[30:33]
	ds_write_b128 v235, v[26:29] offset:8192
.LBB0_2205:
	s_lshl_b32 s6, s49, 8
	s_ashr_i32 s7, s6, 31
	s_lshl_b32 s2, s26, 6
	s_ashr_i32 s3, s2, 31
	s_lshl_b64 s[20:21], s[6:7], 11
	s_add_u32 s24, s29, s20
	s_addc_u32 s25, s30, s21
	s_lshl_b64 s[20:21], s[2:3], 1
	s_add_u32 s24, s24, s20
	s_addc_u32 s25, s25, s21
	global_load_dwordx4 v[30:33], v233, s[24:25]
	global_load_dwordx4 v[26:29], v234, s[24:25]
	s_andn2_b64 vcc, exec, s[22:23]
	ds_read_b128 v[170:173], v255 offset:12288
	s_waitcnt lgkmcnt(5)
	v_mfma_f32_16x16x32_bf16 v[110:113], v[178:181], v[174:177], v[110:113]
	v_mfma_f32_16x16x32_bf16 v[106:109], v[182:185], v[174:177], v[106:109]
	v_mfma_f32_16x16x32_bf16 v[102:105], v[186:189], v[174:177], v[102:105]
	v_mfma_f32_16x16x32_bf16 v[82:85], v[190:193], v[174:177], v[82:85]
	ds_read_b128 v[174:177], v253 offset:12288
	s_waitcnt lgkmcnt(5)
	v_mfma_f32_16x16x32_bf16 v[98:101], v[178:181], v[162:165], v[98:101]
	v_mfma_f32_16x16x32_bf16 v[94:97], v[182:185], v[162:165], v[94:97]
	v_mfma_f32_16x16x32_bf16 v[90:93], v[186:189], v[162:165], v[90:93]
	v_mfma_f32_16x16x32_bf16 v[86:89], v[190:193], v[162:165], v[86:89]
	s_waitcnt lgkmcnt(4)
	v_mfma_f32_16x16x32_bf16 v[78:81], v[178:181], v[166:169], v[78:81]
	v_mfma_f32_16x16x32_bf16 v[74:77], v[182:185], v[166:169], v[74:77]
	v_mfma_f32_16x16x32_bf16 v[70:73], v[186:189], v[166:169], v[70:73]
	v_mfma_f32_16x16x32_bf16 v[66:69], v[190:193], v[166:169], v[66:69]
	s_waitcnt vmcnt(6)
	ds_write_b128 v235, v[22:25] offset:16384
	ds_write_b128 v235, v[18:21] offset:24576

.LBB0_2209:
	s_lshl_b32 s22, s48, 8
	s_ashr_i32 s23, s22, 31
	s_lshl_b64 s[24:25], s[22:23], 11
	s_add_u32 s24, s31, s24
	s_addc_u32 s25, s33, s25
	s_add_u32 s20, s24, s20
	s_addc_u32 s21, s25, s21
	global_load_dwordx4 v[10:13], v234, s[20:21]
	global_load_dwordx4 v[14:17], v233, s[20:21]
	s_and_b64 vcc, exec, s[2:3]
	ds_read_b128 v[174:177], v245 offset:4096
	s_waitcnt lgkmcnt(5)
	v_mfma_f32_16x16x32_bf16 v[158:161], v[194:197], v[162:165], v[158:161]
	v_mfma_f32_16x16x32_bf16 v[154:157], v[198:201], v[162:165], v[154:157]
	v_mfma_f32_16x16x32_bf16 v[150:153], v[202:205], v[162:165], v[150:153]
	v_mfma_f32_16x16x32_bf16 v[146:149], v[206:209], v[162:165], v[146:149]
	ds_read_b128 v[162:165], v247 offset:8192
	s_waitcnt lgkmcnt(5)
	v_mfma_f32_16x16x32_bf16 v[142:145], v[194:197], v[166:169], v[142:145]
	v_mfma_f32_16x16x32_bf16 v[138:141], v[198:201], v[166:169], v[138:141]
	v_mfma_f32_16x16x32_bf16 v[134:137], v[202:205], v[166:169], v[134:137]
	v_mfma_f32_16x16x32_bf16 v[130:133], v[206:209], v[166:169], v[130:133]
	ds_read_b128 v[166:169], v245 offset:8192
	s_waitcnt lgkmcnt(5)
	v_mfma_f32_16x16x32_bf16 v[126:129], v[194:197], v[170:173], v[126:129]
	v_mfma_f32_16x16x32_bf16 v[122:125], v[198:201], v[170:173], v[122:125]
	v_mfma_f32_16x16x32_bf16 v[118:121], v[202:205], v[170:173], v[118:121]
	v_mfma_f32_16x16x32_bf16 v[114:117], v[206:209], v[170:173], v[114:117]
	s_waitcnt vmcnt(6)
	ds_write_b128 v235, v[6:9] offset:49152
	ds_write_b128 v235, v[2:5] offset:57344
.LBB0_2211:
	global_load_dwordx4 v[2:5], v232, s[20:21]
	global_load_dwordx4 v[6:9], v231, s[20:21]
	ds_read_b128 v[170:173], v247 offset:12288
	s_waitcnt lgkmcnt(5)
	v_mfma_f32_16x16x32_bf16 v[110:113], v[194:197], v[174:177], v[110:113]
	v_mfma_f32_16x16x32_bf16 v[106:109], v[198:201], v[174:177], v[106:109]
	v_mfma_f32_16x16x32_bf16 v[102:105], v[202:205], v[174:177], v[102:105]
	v_mfma_f32_16x16x32_bf16 v[82:85], v[206:209], v[174:177], v[82:85]
	ds_read_b128 v[174:177], v245 offset:12288
	s_waitcnt lgkmcnt(5)
	v_mfma_f32_16x16x32_bf16 v[98:101], v[194:197], v[162:165], v[98:101]
	v_mfma_f32_16x16x32_bf16 v[94:97], v[198:201], v[162:165], v[94:97]
	v_mfma_f32_16x16x32_bf16 v[90:93], v[202:205], v[162:165], v[90:93]
	v_mfma_f32_16x16x32_bf16 v[86:89], v[206:209], v[162:165], v[86:89]
	s_waitcnt lgkmcnt(4)
	v_mfma_f32_16x16x32_bf16 v[78:81], v[194:197], v[166:169], v[78:81]
	v_mfma_f32_16x16x32_bf16 v[74:77], v[198:201], v[166:169], v[74:77]
	v_mfma_f32_16x16x32_bf16 v[70:73], v[202:205], v[166:169], v[70:73]
	v_mfma_f32_16x16x32_bf16 v[66:69], v[206:209], v[166:169], v[66:69]
	s_lshl_b64 s[2:3], s[6:7], 10
	s_lshl_b64 s[20:21], s[22:23], 10
	s_add_i32 s51, s26, 1
	s_cmp_lg_u32 s51, 16
	s_cbranch_scc1 .LBB0_2215
	s_add_i32 s28, s28, s11
	s_cmp_gt_i32 s28, 31
	s_cbranch_scc1 .LBB0_2214
	s_ashr_i32 s3, s28, 31
	s_lshr_b32 s3, s3, 27
	s_add_i32 s3, s28, s3
	s_ashr_i32 s3, s3, 5
	s_mov_b32 s2, s10
	s_lshl_b32 s6, s3, 6
	s_lshl_b32 s7, s28, 1
	s_sub_i32 s6, s7, s6
	s_and_b32 s2, s2, 7
	s_and_b32 s6, s6, -8
	s_lshl_b32 s3, s3, 2
	s_and_b32 s7, s28, 3
	s_or_b32 s48, s3, s7
	s_or_b32 s49, s2, s6
	s_lshl_b32 s2, s49, 8
	s_lshl_b32 s6, s48, 8
	s_ashr_i32 s3, s2, 31
	s_ashr_i32 s7, s6, 31
	s_lshl_b64 s[2:3], s[2:3], 10
	s_lshl_b64 s[20:21], s[6:7], 10

.LBB0_2215:
	s_waitcnt lgkmcnt(0)
	s_barrier
	ds_read_b128 v[178:181], v250
	ds_read_b128 v[182:185], v248
	ds_read_b128 v[186:189], v250 offset:4096
	ds_read_b128 v[190:193], v248 offset:4096
	ds_read_b128 v[162:165], v254
	ds_read_b128 v[166:169], v252
	v_mfma_f32_16x16x32_bf16 v[62:65], v[194:197], v[170:173], v[62:65]
	v_mfma_f32_16x16x32_bf16 v[58:61], v[198:201], v[170:173], v[58:61]
	v_mfma_f32_16x16x32_bf16 v[54:57], v[202:205], v[170:173], v[54:57]
	v_mfma_f32_16x16x32_bf16 v[50:53], v[206:209], v[170:173], v[50:53]
	v_mfma_f32_16x16x32_bf16 v[46:49], v[194:197], v[174:177], v[46:49]
	v_mfma_f32_16x16x32_bf16 v[42:45], v[198:201], v[174:177], v[42:45]
	v_mfma_f32_16x16x32_bf16 v[38:41], v[202:205], v[174:177], v[38:41]
	v_mfma_f32_16x16x32_bf16 v[34:37], v[206:209], v[174:177], v[34:37]
	ds_read_b128 v[170:173], v254 offset:4096
	ds_read_b128 v[174:177], v252 offset:4096
	s_cmp_lt_i32 s40, s35
	s_cselect_b64 s[24:25], -1, 0
	s_cmp_ge_i32 s40, s35
	s_cselect_b64 s[6:7], -1, 0
	s_and_b64 vcc, exec, s[6:7]
	s_waitcnt lgkmcnt(3)
	v_mfma_f32_16x16x32_bf16 v[158:161], v[178:181], v[162:165], v[158:161]
	v_mfma_f32_16x16x32_bf16 v[154:157], v[182:185], v[162:165], v[154:157]
	v_mfma_f32_16x16x32_bf16 v[150:153], v[186:189], v[162:165], v[150:153]
	v_mfma_f32_16x16x32_bf16 v[146:149], v[190:193], v[162:165], v[146:149]
	ds_read_b128 v[162:165], v254 offset:8192
	s_waitcnt lgkmcnt(3)
	v_mfma_f32_16x16x32_bf16 v[142:145], v[178:181], v[166:169], v[142:145]
	v_mfma_f32_16x16x32_bf16 v[138:141], v[182:185], v[166:169], v[138:141]
	v_mfma_f32_16x16x32_bf16 v[134:137], v[186:189], v[166:169], v[134:137]
	v_mfma_f32_16x16x32_bf16 v[130:133], v[190:193], v[166:169], v[130:133]
	ds_read_b128 v[166:169], v252 offset:8192
	s_waitcnt lgkmcnt(3)
	v_mfma_f32_16x16x32_bf16 v[126:129], v[178:181], v[170:173], v[126:129]
	v_mfma_f32_16x16x32_bf16 v[122:125], v[182:185], v[170:173], v[122:125]
	v_mfma_f32_16x16x32_bf16 v[118:121], v[186:189], v[170:173], v[118:121]
	v_mfma_f32_16x16x32_bf16 v[114:117], v[190:193], v[170:173], v[114:117]
	s_waitcnt vmcnt(6)
	ds_write_b128 v236, v[26:29]
	ds_write_b128 v236, v[30:33] offset:8192
.LBB0_2217:
	s_lshl_b32 s22, s51, 6
	s_ashr_i32 s23, s22, 31
	s_lshl_b64 s[2:3], s[2:3], 1
	s_add_u32 s2, s29, s2
	s_addc_u32 s3, s30, s3
	s_lshl_b64 s[22:23], s[22:23], 1
	s_add_u32 s26, s2, s22
	s_addc_u32 s27, s3, s23
	global_load_dwordx4 v[30:33], v234, s[26:27]
	global_load_dwordx4 v[26:29], v233, s[26:27]
	s_andn2_b64 vcc, exec, s[24:25]
	ds_read_b128 v[170:173], v254 offset:12288
	s_waitcnt lgkmcnt(5)
	v_mfma_f32_16x16x32_bf16 v[110:113], v[178:181], v[174:177], v[110:113]
	v_mfma_f32_16x16x32_bf16 v[106:109], v[182:185], v[174:177], v[106:109]
	v_mfma_f32_16x16x32_bf16 v[102:105], v[186:189], v[174:177], v[102:105]
	v_mfma_f32_16x16x32_bf16 v[82:85], v[190:193], v[174:177], v[82:85]
	ds_read_b128 v[174:177], v252 offset:12288
	s_waitcnt lgkmcnt(5)
	v_mfma_f32_16x16x32_bf16 v[98:101], v[178:181], v[162:165], v[98:101]
	v_mfma_f32_16x16x32_bf16 v[94:97], v[182:185], v[162:165], v[94:97]
	v_mfma_f32_16x16x32_bf16 v[90:93], v[186:189], v[162:165], v[90:93]
	v_mfma_f32_16x16x32_bf16 v[86:89], v[190:193], v[162:165], v[86:89]
	s_waitcnt lgkmcnt(4)
	v_mfma_f32_16x16x32_bf16 v[78:81], v[178:181], v[166:169], v[78:81]
	v_mfma_f32_16x16x32_bf16 v[74:77], v[182:185], v[166:169], v[74:77]
	v_mfma_f32_16x16x32_bf16 v[70:73], v[186:189], v[166:169], v[70:73]
	v_mfma_f32_16x16x32_bf16 v[66:69], v[190:193], v[166:169], v[66:69]
	s_waitcnt vmcnt(6)
	ds_write_b128 v236, v[18:21] offset:16384
	ds_write_b128 v236, v[22:25] offset:24576

.LBB0_2221:
	s_lshl_b64 s[20:21], s[20:21], 1
	s_add_u32 s20, s31, s20
	s_addc_u32 s21, s33, s21
	s_add_u32 s20, s20, s22
	s_addc_u32 s21, s21, s23
	global_load_dwordx4 v[14:17], v234, s[20:21]
	global_load_dwordx4 v[10:13], v233, s[20:21]
	s_and_b64 vcc, exec, s[2:3]
	ds_read_b128 v[174:177], v244 offset:4096
	s_waitcnt lgkmcnt(5)
	v_mfma_f32_16x16x32_bf16 v[158:161], v[194:197], v[162:165], v[158:161]
	v_mfma_f32_16x16x32_bf16 v[154:157], v[198:201], v[162:165], v[154:157]
	v_mfma_f32_16x16x32_bf16 v[150:153], v[202:205], v[162:165], v[150:153]
	v_mfma_f32_16x16x32_bf16 v[146:149], v[206:209], v[162:165], v[146:149]
	ds_read_b128 v[162:165], v246 offset:8192
	s_waitcnt lgkmcnt(5)
	v_mfma_f32_16x16x32_bf16 v[142:145], v[194:197], v[166:169], v[142:145]
	v_mfma_f32_16x16x32_bf16 v[138:141], v[198:201], v[166:169], v[138:141]
	v_mfma_f32_16x16x32_bf16 v[134:137], v[202:205], v[166:169], v[134:137]
	v_mfma_f32_16x16x32_bf16 v[130:133], v[206:209], v[166:169], v[130:133]
	ds_read_b128 v[166:169], v244 offset:8192
	s_waitcnt lgkmcnt(5)
	v_mfma_f32_16x16x32_bf16 v[126:129], v[194:197], v[170:173], v[126:129]
	v_mfma_f32_16x16x32_bf16 v[122:125], v[198:201], v[170:173], v[122:125]
	v_mfma_f32_16x16x32_bf16 v[118:121], v[202:205], v[170:173], v[118:121]
	v_mfma_f32_16x16x32_bf16 v[114:117], v[206:209], v[170:173], v[114:117]
	s_waitcnt vmcnt(6)
	ds_write_b128 v236, v[2:5] offset:49152
	ds_write_b128 v236, v[6:9] offset:57344
.LBB0_2223:
	global_load_dwordx4 v[6:9], v232, s[20:21]
	global_load_dwordx4 v[2:5], v231, s[20:21]
	ds_read_b128 v[170:173], v246 offset:12288
	s_waitcnt lgkmcnt(5)
	v_mfma_f32_16x16x32_bf16 v[110:113], v[194:197], v[174:177], v[110:113]
	v_mfma_f32_16x16x32_bf16 v[106:109], v[198:201], v[174:177], v[106:109]
	v_mfma_f32_16x16x32_bf16 v[102:105], v[202:205], v[174:177], v[102:105]
	v_mfma_f32_16x16x32_bf16 v[82:85], v[206:209], v[174:177], v[82:85]
	ds_read_b128 v[174:177], v244 offset:12288
	s_waitcnt lgkmcnt(5)
	v_mfma_f32_16x16x32_bf16 v[98:101], v[194:197], v[162:165], v[98:101]
	v_mfma_f32_16x16x32_bf16 v[94:97], v[198:201], v[162:165], v[94:97]
	v_mfma_f32_16x16x32_bf16 v[90:93], v[202:205], v[162:165], v[90:93]
	v_mfma_f32_16x16x32_bf16 v[86:89], v[206:209], v[162:165], v[86:89]
	s_waitcnt lgkmcnt(4)
	v_mfma_f32_16x16x32_bf16 v[78:81], v[194:197], v[166:169], v[78:81]
	v_mfma_f32_16x16x32_bf16 v[74:77], v[198:201], v[166:169], v[74:77]
	v_mfma_f32_16x16x32_bf16 v[70:73], v[202:205], v[166:169], v[70:73]
	v_mfma_f32_16x16x32_bf16 v[66:69], v[206:209], v[166:169], v[66:69]
	s_add_i32 s26, s51, 1
	s_cmp_lg_u32 s26, 16
	s_cbranch_scc1 .LBB0_2227
	s_add_i32 s28, s28, s11
	s_cmp_gt_i32 s28, 31
	s_cbranch_scc1 .LBB0_2226
	s_ashr_i32 s3, s28, 31
	s_lshr_b32 s3, s3, 27
	s_add_i32 s3, s28, s3
	s_ashr_i32 s3, s3, 5
	s_mov_b32 s2, s10
	s_lshl_b32 s20, s3, 6
	s_lshl_b32 s21, s28, 1
	s_sub_i32 s20, s21, s20
	s_and_b32 s2, s2, 7
	s_and_b32 s20, s20, -8
	s_lshl_b32 s3, s3, 2
	s_and_b32 s21, s28, 3
	s_or_b32 s48, s3, s21
	s_or_b32 s49, s2, s20

.LBB0_2227:
	s_add_i32 s50, s50, 2
	s_cmp_lg_u32 s50, 16
	s_waitcnt lgkmcnt(0)
	s_mov_b32 s98, 1
	s_cbranch_scc1 .LBB0_2202
	s_mov_b32 s98, 0
	v_mfma_f32_16x16x32_bf16 v[62:65], v[194:197], v[170:173], v[62:65]
	v_mfma_f32_16x16x32_bf16 v[58:61], v[198:201], v[170:173], v[58:61]
	v_mfma_f32_16x16x32_bf16 v[54:57], v[202:205], v[170:173], v[54:57]
	v_mfma_f32_16x16x32_bf16 v[50:53], v[206:209], v[170:173], v[50:53]
	v_mfma_f32_16x16x32_bf16 v[46:49], v[194:197], v[174:177], v[46:49]
	v_mfma_f32_16x16x32_bf16 v[42:45], v[198:201], v[174:177], v[42:45]
	v_mfma_f32_16x16x32_bf16 v[38:41], v[202:205], v[174:177], v[38:41]
	v_mfma_f32_16x16x32_bf16 v[34:37], v[206:209], v[174:177], v[34:37]
	s_nop 7
	s_nop 7
	v_mov_b32_e32 v172, v0
	s_nop 0
	v_ashrrev_i32_e32 v162, 1, v172
	v_and_b32_e32 v162, 0xffffff80, v162
	v_lshl_add_u32 v162, s36, 8, v162
	v_and_or_b32 v164, v172, 15, v162
	v_add_u32_e32 v162, 0xffffe000, v162
	v_ashrrev_i32_e32 v162, 11, v162
	v_mad_i32_i24 v162, v162, s45, s45
	v_cmp_lt_i32_e32 vcc, s46, v164
	v_ashrrev_i32_e32 v163, 31, v162
	s_and_saveexec_b64 s[2:3], vcc
	s_xor_b64 s[2:3], exec, s[2:3]
	v_add_u32_e32 v238, 0xffffe000, v164
	v_lshlrev_b64 v[166:167], 12, v[238:239]
	v_mov_b32_e32 v165, v239
	v_lshl_add_u64 v[168:169], s[12:13], 0, v[166:167]
	v_lshlrev_b64 v[170:171], 12, v[164:165]
	v_mov_b64_e32 v[166:167], v[162:163]
	s_andn2_saveexec_b64 s[2:3], s[2:3]
	v_ashrrev_i32_e32 v165, 31, v164
	v_lshlrev_b64 v[170:171], 12, v[164:165]
	v_lshl_add_u64 v[168:169], s[4:5], 0, v[170:171]
	v_mov_b64_e32 v[166:167], 0
	s_or_b64 exec, exec, s[2:3]
	v_and_b32_e32 v165, 0xc0, v172
	v_lshrrev_b32_e32 v172, 2, v172
	s_lshl_b32 s2, s34, 8
	v_and_b32_e32 v172, 12, v172
	v_or3_b32 v172, v165, s2, v172
	v_ashrrev_i32_e32 v173, 31, v172
	v_lshl_add_u64 v[176:177], v[166:167], 2, s[14:15]
	v_lshlrev_b64 v[166:167], 2, v[172:173]
	v_lshl_add_u64 v[180:181], v[168:169], 0, v[166:167]
	v_lshl_add_u64 v[182:183], v[176:177], 0, v[166:167]
	global_load_dwordx4 v[172:175], v[180:181], off
	global_load_dwordx4 v[176:179], v[182:183], off
	v_lshl_add_u64 v[168:169], s[4:5], 0, v[170:171]
	v_lshl_add_u64 v[184:185], v[168:169], 0, v[166:167]
	s_waitcnt vmcnt(0)
	v_pk_fma_f32 v[160:161], v[160:161], v[178:179], v[174:175]
	v_pk_fma_f32 v[158:159], v[158:159], v[176:177], v[172:173]
	global_store_dwordx4 v[184:185], v[158:161], off
	global_load_dwordx4 v[158:161], v[180:181], off offset:64
	s_nop 0
	global_load_dwordx4 v[168:171], v[182:183], off offset:64
	s_waitcnt vmcnt(0)
	v_pk_fma_f32 v[156:157], v[156:157], v[170:171], v[160:161]
	v_pk_fma_f32 v[154:155], v[154:155], v[168:169], v[158:159]
	global_store_dwordx4 v[184:185], v[154:157], off offset:64
	global_load_dwordx4 v[154:157], v[180:181], off offset:128
	s_nop 0
	global_load_dwordx4 v[158:161], v[182:183], off offset:128
	s_waitcnt vmcnt(0)
	v_pk_fma_f32 v[152:153], v[152:153], v[160:161], v[156:157]
	v_pk_fma_f32 v[150:151], v[150:151], v[158:159], v[154:155]
	global_store_dwordx4 v[184:185], v[150:153], off offset:128
	global_load_dwordx4 v[152:155], v[180:181], off offset:192
	s_nop 0
	global_load_dwordx4 v[156:159], v[182:183], off offset:192
	v_or_b32_e32 v150, 16, v164
	v_cmp_lt_i32_e32 vcc, s46, v150
	s_waitcnt vmcnt(0)
	v_pk_fma_f32 v[148:149], v[148:149], v[158:159], v[154:155]
	v_pk_fma_f32 v[146:147], v[146:147], v[156:157], v[152:153]
	global_store_dwordx4 v[184:185], v[146:149], off offset:192
	s_and_saveexec_b64 s[2:3], vcc
	s_xor_b64 s[2:3], exec, s[2:3]
	v_add_u32_e32 v238, 0xffffe010, v164
	v_lshlrev_b64 v[146:147], 12, v[238:239]
	v_mov_b32_e32 v151, v239
	v_lshl_add_u64 v[146:147], s[12:13], 0, v[146:147]
	v_lshlrev_b64 v[148:149], 12, v[150:151]
	v_mov_b64_e32 v[152:153], v[162:163]
	s_andn2_saveexec_b64 s[2:3], s[2:3]
	v_ashrrev_i32_e32 v151, 31, v150
	v_lshlrev_b64 v[148:149], 12, v[150:151]
	v_lshl_add_u64 v[146:147], s[4:5], 0, v[148:149]
	v_mov_b64_e32 v[152:153], 0
	s_or_b64 exec, exec, s[2:3]
	v_lshl_add_u64 v[154:155], v[152:153], 2, s[14:15]
	v_lshl_add_u64 v[158:159], v[146:147], 0, v[166:167]
	v_lshl_add_u64 v[160:161], v[154:155], 0, v[166:167]
	global_load_dwordx4 v[150:153], v[158:159], off
	global_load_dwordx4 v[154:157], v[160:161], off
	v_lshl_add_u64 v[146:147], s[4:5], 0, v[148:149]
	v_lshl_add_u64 v[168:169], v[146:147], 0, v[166:167]
	s_waitcnt vmcnt(0)
	v_pk_fma_f32 v[144:145], v[144:145], v[156:157], v[152:153]
	v_pk_fma_f32 v[142:143], v[142:143], v[154:155], v[150:151]
	global_store_dwordx4 v[168:169], v[142:145], off
	global_load_dwordx4 v[142:145], v[158:159], off offset:64
	s_nop 0
	global_load_dwordx4 v[146:149], v[160:161], off offset:64
	s_waitcnt vmcnt(0)
	v_pk_fma_f32 v[140:141], v[140:141], v[148:149], v[144:145]
	v_pk_fma_f32 v[138:139], v[138:139], v[146:147], v[142:143]
	global_store_dwordx4 v[168:169], v[138:141], off offset:64
	global_load_dwordx4 v[138:141], v[158:159], off offset:128
	s_nop 0
	global_load_dwordx4 v[142:145], v[160:161], off offset:128
	s_waitcnt vmcnt(0)
	v_pk_fma_f32 v[136:137], v[136:137], v[144:145], v[140:141]
	v_pk_fma_f32 v[134:135], v[134:135], v[142:143], v[138:139]
	global_store_dwordx4 v[168:169], v[134:137], off offset:128
	global_load_dwordx4 v[136:139], v[158:159], off offset:192
	s_nop 0
	global_load_dwordx4 v[140:143], v[160:161], off offset:192
	v_or_b32_e32 v134, 32, v164
	v_cmp_lt_i32_e32 vcc, s46, v134
	s_waitcnt vmcnt(0)
	v_pk_fma_f32 v[132:133], v[132:133], v[142:143], v[138:139]
	v_pk_fma_f32 v[130:131], v[130:131], v[140:141], v[136:137]
	global_store_dwordx4 v[168:169], v[130:133], off offset:192
	s_and_saveexec_b64 s[2:3], vcc
	s_xor_b64 s[2:3], exec, s[2:3]
	v_add_u32_e32 v238, 0xffffe020, v164
	v_lshlrev_b64 v[130:131], 12, v[238:239]
	v_mov_b32_e32 v135, v239
	v_lshl_add_u64 v[130:131], s[12:13], 0, v[130:131]
	v_lshlrev_b64 v[132:133], 12, v[134:135]
	v_mov_b64_e32 v[136:137], v[162:163]
	s_andn2_saveexec_b64 s[2:3], s[2:3]
	v_ashrrev_i32_e32 v135, 31, v134
	v_lshlrev_b64 v[132:133], 12, v[134:135]
	v_lshl_add_u64 v[130:131], s[4:5], 0, v[132:133]
	v_mov_b64_e32 v[136:137], 0
	s_or_b64 exec, exec, s[2:3]
	v_lshl_add_u64 v[138:139], v[136:137], 2, s[14:15]
	v_lshl_add_u64 v[142:143], v[130:131], 0, v[166:167]
	v_lshl_add_u64 v[144:145], v[138:139], 0, v[166:167]
	global_load_dwordx4 v[134:137], v[142:143], off
	global_load_dwordx4 v[138:141], v[144:145], off
	v_lshl_add_u64 v[130:131], s[4:5], 0, v[132:133]
	v_lshl_add_u64 v[146:147], v[130:131], 0, v[166:167]
	s_waitcnt vmcnt(0)
	v_pk_fma_f32 v[128:129], v[128:129], v[140:141], v[136:137]
	v_pk_fma_f32 v[126:127], v[126:127], v[138:139], v[134:135]
	global_store_dwordx4 v[146:147], v[126:129], off
	global_load_dwordx4 v[126:129], v[142:143], off offset:64
	s_nop 0
	global_load_dwordx4 v[130:133], v[144:145], off offset:64
	s_waitcnt vmcnt(0)
	v_pk_fma_f32 v[124:125], v[124:125], v[132:133], v[128:129]
	v_pk_fma_f32 v[122:123], v[122:123], v[130:131], v[126:127]
	global_store_dwordx4 v[146:147], v[122:125], off offset:64
	global_load_dwordx4 v[122:125], v[142:143], off offset:128
	s_nop 0
	global_load_dwordx4 v[126:129], v[144:145], off offset:128
	s_waitcnt vmcnt(0)
	v_pk_fma_f32 v[120:121], v[120:121], v[128:129], v[124:125]
	v_pk_fma_f32 v[118:119], v[118:119], v[126:127], v[122:123]
	global_store_dwordx4 v[146:147], v[118:121], off offset:128
	global_load_dwordx4 v[120:123], v[142:143], off offset:192
	s_nop 0
	global_load_dwordx4 v[124:127], v[144:145], off offset:192
	v_or_b32_e32 v118, 48, v164
	v_cmp_lt_i32_e32 vcc, s46, v118
	s_waitcnt vmcnt(0)
	v_pk_fma_f32 v[116:117], v[116:117], v[126:127], v[122:123]
	v_pk_fma_f32 v[114:115], v[114:115], v[124:125], v[120:121]
	global_store_dwordx4 v[146:147], v[114:117], off offset:192
	s_and_saveexec_b64 s[2:3], vcc
	s_xor_b64 s[2:3], exec, s[2:3]
	v_add_u32_e32 v238, 0xffffe030, v164
	v_lshlrev_b64 v[114:115], 12, v[238:239]
	v_mov_b32_e32 v119, v239
	v_lshl_add_u64 v[114:115], s[12:13], 0, v[114:115]
	v_lshlrev_b64 v[116:117], 12, v[118:119]
	v_mov_b64_e32 v[120:121], v[162:163]
	s_andn2_saveexec_b64 s[2:3], s[2:3]
	v_ashrrev_i32_e32 v119, 31, v118
	v_lshlrev_b64 v[116:117], 12, v[118:119]
	v_lshl_add_u64 v[114:115], s[4:5], 0, v[116:117]
	v_mov_b64_e32 v[120:121], 0
	s_or_b64 exec, exec, s[2:3]
	v_lshl_add_u64 v[122:123], v[120:121], 2, s[14:15]
	v_lshl_add_u64 v[126:127], v[114:115], 0, v[166:167]
	v_lshl_add_u64 v[128:129], v[122:123], 0, v[166:167]
	global_load_dwordx4 v[118:121], v[126:127], off
	global_load_dwordx4 v[122:125], v[128:129], off
	v_lshl_add_u64 v[114:115], s[4:5], 0, v[116:117]
	v_lshl_add_u64 v[130:131], v[114:115], 0, v[166:167]
	s_waitcnt vmcnt(0)
	v_pk_fma_f32 v[112:113], v[112:113], v[124:125], v[120:121]
	v_pk_fma_f32 v[110:111], v[110:111], v[122:123], v[118:119]
	global_store_dwordx4 v[130:131], v[110:113], off
	global_load_dwordx4 v[110:113], v[126:127], off offset:64
	s_nop 0
	global_load_dwordx4 v[114:117], v[128:129], off offset:64
	s_waitcnt vmcnt(0)
	v_pk_fma_f32 v[108:109], v[108:109], v[116:117], v[112:113]
	v_pk_fma_f32 v[106:107], v[106:107], v[114:115], v[110:111]
	global_store_dwordx4 v[130:131], v[106:109], off offset:64
	global_load_dwordx4 v[106:109], v[126:127], off offset:128
	s_nop 0
	global_load_dwordx4 v[110:113], v[128:129], off offset:128
	s_waitcnt vmcnt(0)
	v_pk_fma_f32 v[104:105], v[104:105], v[112:113], v[108:109]
	v_pk_fma_f32 v[102:103], v[102:103], v[110:111], v[106:107]
	global_store_dwordx4 v[130:131], v[102:105], off offset:128
	global_load_dwordx4 v[104:107], v[126:127], off offset:192
	s_nop 0
	global_load_dwordx4 v[108:111], v[128:129], off offset:192
	v_or_b32_e32 v102, 64, v164
	v_cmp_lt_i32_e32 vcc, s46, v102
	s_waitcnt vmcnt(0)
	v_pk_fma_f32 v[84:85], v[84:85], v[110:111], v[106:107]
	v_pk_fma_f32 v[82:83], v[82:83], v[108:109], v[104:105]
	global_store_dwordx4 v[130:131], v[82:85], off offset:192
	s_and_saveexec_b64 s[2:3], vcc
	s_xor_b64 s[2:3], exec, s[2:3]
	v_add_u32_e32 v238, 0xffffe040, v164
	v_lshlrev_b64 v[82:83], 12, v[238:239]
	v_mov_b32_e32 v103, v239
	v_lshl_add_u64 v[82:83], s[12:13], 0, v[82:83]
	v_lshlrev_b64 v[84:85], 12, v[102:103]
	v_mov_b64_e32 v[104:105], v[162:163]
	s_andn2_saveexec_b64 s[2:3], s[2:3]
	v_ashrrev_i32_e32 v103, 31, v102
	v_lshlrev_b64 v[84:85], 12, v[102:103]
	v_lshl_add_u64 v[82:83], s[4:5], 0, v[84:85]
	v_mov_b64_e32 v[104:105], 0
	s_or_b64 exec, exec, s[2:3]
	v_lshl_add_u64 v[106:107], v[104:105], 2, s[14:15]
	v_lshl_add_u64 v[110:111], v[82:83], 0, v[166:167]
	v_lshl_add_u64 v[112:113], v[106:107], 0, v[166:167]
	global_load_dwordx4 v[102:105], v[110:111], off
	global_load_dwordx4 v[106:109], v[112:113], off
	v_lshl_add_u64 v[82:83], s[4:5], 0, v[84:85]
	v_lshl_add_u64 v[114:115], v[82:83], 0, v[166:167]
	s_waitcnt vmcnt(0)
	v_pk_fma_f32 v[84:85], v[100:101], v[108:109], v[104:105]
	v_pk_fma_f32 v[82:83], v[98:99], v[106:107], v[102:103]
	global_store_dwordx4 v[114:115], v[82:85], off
	global_load_dwordx4 v[82:85], v[110:111], off offset:64
	s_nop 0
	global_load_dwordx4 v[98:101], v[112:113], off offset:64
	s_waitcnt vmcnt(0)
	v_pk_fma_f32 v[84:85], v[96:97], v[100:101], v[84:85]
	v_pk_fma_f32 v[82:83], v[94:95], v[98:99], v[82:83]
	global_store_dwordx4 v[114:115], v[82:85], off offset:64
	global_load_dwordx4 v[82:85], v[110:111], off offset:128
	s_nop 0
	global_load_dwordx4 v[94:97], v[112:113], off offset:128
	s_waitcnt vmcnt(0)
	v_pk_fma_f32 v[84:85], v[92:93], v[96:97], v[84:85]
	v_pk_fma_f32 v[82:83], v[90:91], v[94:95], v[82:83]
	global_store_dwordx4 v[114:115], v[82:85], off offset:128
	global_load_dwordx4 v[90:93], v[110:111], off offset:192
	global_load_dwordx4 v[94:97], v[112:113], off offset:192
	v_or_b32_e32 v84, 0x50, v164
	v_cmp_lt_i32_e32 vcc, s46, v84
	s_waitcnt vmcnt(0)
	v_pk_fma_f32 v[88:89], v[88:89], v[96:97], v[92:93]
	v_pk_fma_f32 v[86:87], v[86:87], v[94:95], v[90:91]
	global_store_dwordx4 v[114:115], v[86:89], off offset:192
	s_and_saveexec_b64 s[2:3], vcc
	s_xor_b64 s[2:3], exec, s[2:3]
	v_add_u32_e32 v238, 0xffffe050, v164
	v_lshlrev_b64 v[82:83], 12, v[238:239]
	v_mov_b32_e32 v85, v239
	v_lshl_add_u64 v[82:83], s[12:13], 0, v[82:83]
	v_lshlrev_b64 v[86:87], 12, v[84:85]
	v_mov_b64_e32 v[88:89], v[162:163]
	s_andn2_saveexec_b64 s[2:3], s[2:3]
	v_ashrrev_i32_e32 v85, 31, v84
	v_lshlrev_b64 v[86:87], 12, v[84:85]
	v_lshl_add_u64 v[82:83], s[4:5], 0, v[86:87]
	v_mov_b64_e32 v[88:89], 0
	s_or_b64 exec, exec, s[2:3]
	v_lshl_add_u64 v[88:89], v[88:89], 2, s[14:15]
	v_lshl_add_u64 v[92:93], v[82:83], 0, v[166:167]
	v_lshl_add_u64 v[94:95], v[88:89], 0, v[166:167]
	global_load_dwordx4 v[82:85], v[92:93], off
	global_load_dwordx4 v[88:91], v[94:95], off
	v_lshl_add_u64 v[86:87], s[4:5], 0, v[86:87]
	v_lshl_add_u64 v[86:87], v[86:87], 0, v[166:167]
	s_waitcnt vmcnt(0)
	v_pk_fma_f32 v[80:81], v[80:81], v[90:91], v[84:85]
	v_pk_fma_f32 v[78:79], v[78:79], v[88:89], v[82:83]
	global_store_dwordx4 v[86:87], v[78:81], off
	global_load_dwordx4 v[78:81], v[92:93], off offset:64
	s_nop 0
	global_load_dwordx4 v[82:85], v[94:95], off offset:64
	s_waitcnt vmcnt(0)
	v_pk_fma_f32 v[76:77], v[76:77], v[84:85], v[80:81]
	v_pk_fma_f32 v[74:75], v[74:75], v[82:83], v[78:79]
	global_store_dwordx4 v[86:87], v[74:77], off offset:64
	global_load_dwordx4 v[74:77], v[92:93], off offset:128
	s_nop 0
	global_load_dwordx4 v[78:81], v[94:95], off offset:128
	s_waitcnt vmcnt(0)
	v_pk_fma_f32 v[72:73], v[72:73], v[80:81], v[76:77]
	v_pk_fma_f32 v[70:71], v[70:71], v[78:79], v[74:75]
	global_store_dwordx4 v[86:87], v[70:73], off offset:128
	global_load_dwordx4 v[72:75], v[92:93], off offset:192
	s_nop 0
	global_load_dwordx4 v[76:79], v[94:95], off offset:192
	v_or_b32_e32 v70, 0x60, v164
	v_cmp_lt_i32_e32 vcc, s46, v70
	s_waitcnt vmcnt(0)
	v_pk_fma_f32 v[68:69], v[68:69], v[78:79], v[74:75]
	v_pk_fma_f32 v[66:67], v[66:67], v[76:77], v[72:73]
	global_store_dwordx4 v[86:87], v[66:69], off offset:192
	s_and_saveexec_b64 s[2:3], vcc
	s_xor_b64 s[2:3], exec, s[2:3]
	v_add_u32_e32 v238, 0xffffe060, v164
	v_lshlrev_b64 v[66:67], 12, v[238:239]
	v_mov_b32_e32 v71, v239
	v_lshl_add_u64 v[66:67], s[12:13], 0, v[66:67]
	v_lshlrev_b64 v[68:69], 12, v[70:71]
	v_mov_b64_e32 v[72:73], v[162:163]
	s_andn2_saveexec_b64 s[2:3], s[2:3]
	v_ashrrev_i32_e32 v71, 31, v70
	v_lshlrev_b64 v[68:69], 12, v[70:71]
	v_lshl_add_u64 v[66:67], s[4:5], 0, v[68:69]
	v_mov_b64_e32 v[72:73], 0
	s_or_b64 exec, exec, s[2:3]
	v_lshl_add_u64 v[74:75], v[72:73], 2, s[14:15]
	v_lshl_add_u64 v[78:79], v[66:67], 0, v[166:167]
	v_lshl_add_u64 v[80:81], v[74:75], 0, v[166:167]
	global_load_dwordx4 v[70:73], v[78:79], off
	global_load_dwordx4 v[74:77], v[80:81], off
	v_lshl_add_u64 v[66:67], s[4:5], 0, v[68:69]
	v_lshl_add_u64 v[82:83], v[66:67], 0, v[166:167]
	s_waitcnt vmcnt(0)
	v_pk_fma_f32 v[64:65], v[64:65], v[76:77], v[72:73]
	v_pk_fma_f32 v[62:63], v[62:63], v[74:75], v[70:71]
	global_store_dwordx4 v[82:83], v[62:65], off
	global_load_dwordx4 v[62:65], v[78:79], off offset:64
	s_nop 0
	global_load_dwordx4 v[66:69], v[80:81], off offset:64
	s_waitcnt vmcnt(0)
	v_pk_fma_f32 v[60:61], v[60:61], v[68:69], v[64:65]
	v_pk_fma_f32 v[58:59], v[58:59], v[66:67], v[62:63]
	global_store_dwordx4 v[82:83], v[58:61], off offset:64
	global_load_dwordx4 v[58:61], v[78:79], off offset:128
	s_nop 0
	global_load_dwordx4 v[62:65], v[80:81], off offset:128
	s_waitcnt vmcnt(0)
	v_pk_fma_f32 v[56:57], v[56:57], v[64:65], v[60:61]
	v_pk_fma_f32 v[54:55], v[54:55], v[62:63], v[58:59]
	global_store_dwordx4 v[82:83], v[54:57], off offset:128
	global_load_dwordx4 v[56:59], v[78:79], off offset:192
	s_nop 0
	global_load_dwordx4 v[60:63], v[80:81], off offset:192
	v_or_b32_e32 v54, 0x70, v164
	v_cmp_lt_i32_e32 vcc, s46, v54
	s_waitcnt vmcnt(0)
	v_pk_fma_f32 v[52:53], v[52:53], v[62:63], v[58:59]
	v_pk_fma_f32 v[50:51], v[50:51], v[60:61], v[56:57]
	global_store_dwordx4 v[82:83], v[50:53], off offset:192
	s_and_saveexec_b64 s[2:3], vcc
	s_xor_b64 s[2:3], exec, s[2:3]
	v_add_u32_e32 v238, 0xffffe070, v164
	v_lshlrev_b64 v[50:51], 12, v[238:239]
	v_mov_b32_e32 v55, v239
	v_lshl_add_u64 v[50:51], s[12:13], 0, v[50:51]
	v_lshlrev_b64 v[52:53], 12, v[54:55]
	s_andn2_saveexec_b64 s[2:3], s[2:3]
	v_ashrrev_i32_e32 v55, 31, v54
	v_lshlrev_b64 v[52:53], 12, v[54:55]
	v_lshl_add_u64 v[50:51], s[4:5], 0, v[52:53]
	v_mov_b64_e32 v[162:163], 0
	s_or_b64 exec, exec, s[2:3]
	v_lshl_add_u64 v[58:59], v[162:163], 2, s[14:15]
	v_lshl_add_u64 v[62:63], v[50:51], 0, v[166:167]
	v_lshl_add_u64 v[64:65], v[58:59], 0, v[166:167]
	global_load_dwordx4 v[54:57], v[62:63], off
	global_load_dwordx4 v[58:61], v[64:65], off
	v_lshl_add_u64 v[50:51], s[4:5], 0, v[52:53]
	v_lshl_add_u64 v[66:67], v[50:51], 0, v[166:167]
	s_add_i32 s47, s47, s11
	s_cmp_gt_i32 s47, 31
	s_waitcnt vmcnt(0)
	v_pk_fma_f32 v[48:49], v[48:49], v[60:61], v[56:57]
	v_pk_fma_f32 v[46:47], v[46:47], v[58:59], v[54:55]
	global_store_dwordx4 v[66:67], v[46:49], off
	global_load_dwordx4 v[46:49], v[62:63], off offset:64
	s_nop 0
	global_load_dwordx4 v[50:53], v[64:65], off offset:64
	s_waitcnt vmcnt(0)
	v_pk_fma_f32 v[44:45], v[44:45], v[52:53], v[48:49]
	v_pk_fma_f32 v[42:43], v[42:43], v[50:51], v[46:47]
	global_store_dwordx4 v[66:67], v[42:45], off offset:64
	global_load_dwordx4 v[42:45], v[62:63], off offset:128
	s_nop 0
	global_load_dwordx4 v[46:49], v[64:65], off offset:128
	s_waitcnt vmcnt(0)
	v_pk_fma_f32 v[40:41], v[40:41], v[48:49], v[44:45]
	v_pk_fma_f32 v[38:39], v[38:39], v[46:47], v[42:43]
	global_store_dwordx4 v[66:67], v[38:41], off offset:128
	global_load_dwordx4 v[38:41], v[62:63], off offset:192
	s_nop 0
	global_load_dwordx4 v[42:45], v[64:65], off offset:192
	s_waitcnt vmcnt(0)
	v_pk_fma_f32 v[40:41], v[36:37], v[44:45], v[40:41]
	v_pk_fma_f32 v[38:39], v[34:35], v[42:43], v[38:39]
	v_mov_b32_e32 v37, 0
	global_store_dwordx4 v[66:67], v[38:41], off offset:192
	s_cbranch_scc1 .LBB0_2201
	s_ashr_i32 s3, s47, 31
	s_lshr_b32 s3, s3, 27
	s_add_i32 s3, s47, s3
	s_ashr_i32 s3, s3, 5
	s_mov_b32 s2, s10
	s_lshl_b32 s20, s3, 6
	s_lshl_b32 s21, s47, 1
	s_sub_i32 s20, s21, s20
	s_and_b32 s2, s2, 7
	s_and_b32 s20, s20, -8
	s_lshl_b32 s3, s3, 2
	s_and_b32 s21, s47, 3
	s_or_b32 s34, s3, s21
	s_or_b32 s36, s2, s20
	s_branch .LBB0_2201

.LBB0_2541:
	s_mov_b32 s98, 0
	v_mov_b32_e32 v255, 0x0
	v_bfe_u32 v1, v0, 0, 1
	v_lshlrev_b32_e32 v1, 7, v1
	v_xor_b32_e32 v255, v255, v1
	v_bfe_u32 v1, v0, 1, 3
	v_mul_u32_u24_e32 v1, 0x110, v1
	v_xor_b32_e32 v255, v255, v1
	v_bfe_u32 v1, v0, 4, 2
	v_lshlrev_b32_e32 v1, 4, v1
	v_xor_b32_e32 v255, v255, v1
	v_bfe_u32 v1, v0, 8, 1
	v_lshlrev_b32_e32 v1, 14, v1
	v_xor_b32_e32 v255, v255, v1
	v_mov_b32_e32 v254, 0x10000
	v_bfe_u32 v1, v0, 0, 1
	v_lshlrev_b32_e32 v1, 7, v1
	v_xor_b32_e32 v254, v254, v1
	v_bfe_u32 v1, v0, 1, 3
	v_mul_u32_u24_e32 v1, 0x110, v1
	v_xor_b32_e32 v254, v254, v1
	v_bfe_u32 v1, v0, 4, 2
	v_lshlrev_b32_e32 v1, 4, v1
	v_xor_b32_e32 v254, v254, v1
	v_bfe_u32 v1, v0, 8, 1
	v_lshlrev_b32_e32 v1, 14, v1
	v_xor_b32_e32 v254, v254, v1
	v_mov_b32_e32 v253, 0x880
	v_bfe_u32 v1, v0, 0, 1
	v_lshlrev_b32_e32 v1, 7, v1
	v_xor_b32_e32 v253, v253, v1
	v_bfe_u32 v1, v0, 1, 3
	v_mul_u32_u24_e32 v1, 0x110, v1
	v_xor_b32_e32 v253, v253, v1
	v_bfe_u32 v1, v0, 4, 2
	v_lshlrev_b32_e32 v1, 4, v1
	v_xor_b32_e32 v253, v253, v1
	v_bfe_u32 v1, v0, 8, 1
	v_lshlrev_b32_e32 v1, 14, v1
	v_xor_b32_e32 v253, v253, v1
	v_mov_b32_e32 v252, 0x10880
	v_bfe_u32 v1, v0, 0, 1
	v_lshlrev_b32_e32 v1, 7, v1
	v_xor_b32_e32 v252, v252, v1
	v_bfe_u32 v1, v0, 1, 3
	v_mul_u32_u24_e32 v1, 0x110, v1
	v_xor_b32_e32 v252, v252, v1
	v_bfe_u32 v1, v0, 4, 2
	v_lshlrev_b32_e32 v1, 4, v1
	v_xor_b32_e32 v252, v252, v1
	v_bfe_u32 v1, v0, 8, 1
	v_lshlrev_b32_e32 v1, 14, v1
	v_xor_b32_e32 v252, v252, v1
	v_mov_b32_e32 v251, 0x8000
	v_bfe_u32 v1, v0, 0, 1
	v_lshlrev_b32_e32 v1, 7, v1
	v_xor_b32_e32 v251, v251, v1
	v_bfe_u32 v1, v0, 1, 3
	v_mul_u32_u24_e32 v1, 0x110, v1
	v_xor_b32_e32 v251, v251, v1
	v_bfe_u32 v1, v0, 4, 2
	v_lshlrev_b32_e32 v1, 4, v1
	v_xor_b32_e32 v251, v251, v1
	v_bfe_u32 v1, v0, 6, 2
	v_lshlrev_b32_e32 v1, 13, v1
	v_xor_b32_e32 v251, v251, v1
	v_mov_b32_e32 v250, 0x18000
	v_bfe_u32 v1, v0, 0, 1
	v_lshlrev_b32_e32 v1, 7, v1
	v_xor_b32_e32 v250, v250, v1
	v_bfe_u32 v1, v0, 1, 3
	v_mul_u32_u24_e32 v1, 0x110, v1
	v_xor_b32_e32 v250, v250, v1
	v_bfe_u32 v1, v0, 4, 2
	v_lshlrev_b32_e32 v1, 4, v1
	v_xor_b32_e32 v250, v250, v1
	v_bfe_u32 v1, v0, 6, 2
	v_lshlrev_b32_e32 v1, 13, v1
	v_xor_b32_e32 v250, v250, v1
	v_mov_b32_e32 v249, 0x8880
	v_bfe_u32 v1, v0, 0, 1
	v_lshlrev_b32_e32 v1, 7, v1
	v_xor_b32_e32 v249, v249, v1
	v_bfe_u32 v1, v0, 1, 3
	v_mul_u32_u24_e32 v1, 0x110, v1
	v_xor_b32_e32 v249, v249, v1
	v_bfe_u32 v1, v0, 4, 2
	v_lshlrev_b32_e32 v1, 4, v1
	v_xor_b32_e32 v249, v249, v1
	v_bfe_u32 v1, v0, 6, 2
	v_lshlrev_b32_e32 v1, 13, v1
	v_xor_b32_e32 v249, v249, v1
	v_mov_b32_e32 v248, 0x18880
	v_bfe_u32 v1, v0, 0, 1
	v_lshlrev_b32_e32 v1, 7, v1
	v_xor_b32_e32 v248, v248, v1
	v_bfe_u32 v1, v0, 1, 3
	v_mul_u32_u24_e32 v1, 0x110, v1
	v_xor_b32_e32 v248, v248, v1
	v_bfe_u32 v1, v0, 4, 2
	v_lshlrev_b32_e32 v1, 4, v1
	v_xor_b32_e32 v248, v248, v1
	v_bfe_u32 v1, v0, 6, 2
	v_lshlrev_b32_e32 v1, 13, v1
	v_xor_b32_e32 v248, v248, v1
	v_mov_b32_e32 v247, 0x40
	v_bfe_u32 v1, v0, 0, 1
	v_lshlrev_b32_e32 v1, 7, v1
	v_xor_b32_e32 v247, v247, v1
	v_bfe_u32 v1, v0, 1, 3
	v_mul_u32_u24_e32 v1, 0x110, v1
	v_xor_b32_e32 v247, v247, v1
	v_bfe_u32 v1, v0, 4, 2
	v_lshlrev_b32_e32 v1, 4, v1
	v_xor_b32_e32 v247, v247, v1
	v_bfe_u32 v1, v0, 8, 1
	v_lshlrev_b32_e32 v1, 14, v1
	v_xor_b32_e32 v247, v247, v1
	v_mov_b32_e32 v246, 0x10040
	v_bfe_u32 v1, v0, 0, 1
	v_lshlrev_b32_e32 v1, 7, v1
	v_xor_b32_e32 v246, v246, v1
	v_bfe_u32 v1, v0, 1, 3
	v_mul_u32_u24_e32 v1, 0x110, v1
	v_xor_b32_e32 v246, v246, v1
	v_bfe_u32 v1, v0, 4, 2
	v_lshlrev_b32_e32 v1, 4, v1
	v_xor_b32_e32 v246, v246, v1
	v_bfe_u32 v1, v0, 8, 1
	v_lshlrev_b32_e32 v1, 14, v1
	v_xor_b32_e32 v246, v246, v1
	v_mov_b32_e32 v245, 0x8c0
	v_bfe_u32 v1, v0, 0, 1
	v_lshlrev_b32_e32 v1, 7, v1
	v_xor_b32_e32 v245, v245, v1
	v_bfe_u32 v1, v0, 1, 3
	v_mul_u32_u24_e32 v1, 0x110, v1
	v_xor_b32_e32 v245, v245, v1
	v_bfe_u32 v1, v0, 4, 2
	v_lshlrev_b32_e32 v1, 4, v1
	v_xor_b32_e32 v245, v245, v1
	v_bfe_u32 v1, v0, 8, 1
	v_lshlrev_b32_e32 v1, 14, v1
	v_xor_b32_e32 v245, v245, v1
	v_mov_b32_e32 v244, 0x108c0
	v_bfe_u32 v1, v0, 0, 1
	v_lshlrev_b32_e32 v1, 7, v1
	v_xor_b32_e32 v244, v244, v1
	v_bfe_u32 v1, v0, 1, 3
	v_mul_u32_u24_e32 v1, 0x110, v1
	v_xor_b32_e32 v244, v244, v1
	v_bfe_u32 v1, v0, 4, 2
	v_lshlrev_b32_e32 v1, 4, v1
	v_xor_b32_e32 v244, v244, v1
	v_bfe_u32 v1, v0, 8, 1
	v_lshlrev_b32_e32 v1, 14, v1
	v_xor_b32_e32 v244, v244, v1
	v_mov_b32_e32 v243, 0x8040
	v_bfe_u32 v1, v0, 0, 1
	v_lshlrev_b32_e32 v1, 7, v1
	v_xor_b32_e32 v243, v243, v1
	v_bfe_u32 v1, v0, 1, 3
	v_mul_u32_u24_e32 v1, 0x110, v1
	v_xor_b32_e32 v243, v243, v1
	v_bfe_u32 v1, v0, 4, 2
	v_lshlrev_b32_e32 v1, 4, v1
	v_xor_b32_e32 v243, v243, v1
	v_bfe_u32 v1, v0, 6, 2
	v_lshlrev_b32_e32 v1, 13, v1
	v_xor_b32_e32 v243, v243, v1
	v_mov_b32_e32 v242, 0x18040
	v_bfe_u32 v1, v0, 0, 1
	v_lshlrev_b32_e32 v1, 7, v1
	v_xor_b32_e32 v242, v242, v1
	v_bfe_u32 v1, v0, 1, 3
	v_mul_u32_u24_e32 v1, 0x110, v1
	v_xor_b32_e32 v242, v242, v1
	v_bfe_u32 v1, v0, 4, 2
	v_lshlrev_b32_e32 v1, 4, v1
	v_xor_b32_e32 v242, v242, v1
	v_bfe_u32 v1, v0, 6, 2
	v_lshlrev_b32_e32 v1, 13, v1
	v_xor_b32_e32 v242, v242, v1
	v_mov_b32_e32 v241, 0x88c0
	v_bfe_u32 v1, v0, 0, 1
	v_lshlrev_b32_e32 v1, 7, v1
	v_xor_b32_e32 v241, v241, v1
	v_bfe_u32 v1, v0, 1, 3
	v_mul_u32_u24_e32 v1, 0x110, v1
	v_xor_b32_e32 v241, v241, v1
	v_bfe_u32 v1, v0, 4, 2
	v_lshlrev_b32_e32 v1, 4, v1
	v_xor_b32_e32 v241, v241, v1
	v_bfe_u32 v1, v0, 6, 2
	v_lshlrev_b32_e32 v1, 13, v1
	v_xor_b32_e32 v241, v241, v1
	v_mov_b32_e32 v237, 0x188c0
	v_bfe_u32 v1, v0, 0, 1
	v_lshlrev_b32_e32 v1, 7, v1
	v_xor_b32_e32 v237, v237, v1
	v_bfe_u32 v1, v0, 1, 3
	v_mul_u32_u24_e32 v1, 0x110, v1
	v_xor_b32_e32 v237, v237, v1
	v_bfe_u32 v1, v0, 4, 2
	v_lshlrev_b32_e32 v1, 4, v1
	v_xor_b32_e32 v237, v237, v1
	v_bfe_u32 v1, v0, 6, 2
	v_lshlrev_b32_e32 v1, 13, v1
	v_xor_b32_e32 v237, v237, v1
	v_mov_b32_e32 v236, 0x0
	v_bfe_u32 v1, v0, 0, 4
	v_lshlrev_b32_e32 v1, 4, v1
	v_xor_b32_e32 v236, v236, v1
	v_bfe_u32 v1, v0, 4, 4
	v_mul_u32_u24_e32 v1, 0x110, v1
	v_xor_b32_e32 v236, v236, v1
	v_bfe_u32 v1, v0, 8, 1
	v_lshlrev_b32_e32 v1, 12, v1
	v_xor_b32_e32 v236, v236, v1
	v_mov_b32_e32 v235, 0x10000
	v_bfe_u32 v1, v0, 0, 4
	v_lshlrev_b32_e32 v1, 4, v1
	v_xor_b32_e32 v235, v235, v1
	v_bfe_u32 v1, v0, 4, 4
	v_mul_u32_u24_e32 v1, 0x110, v1
	v_xor_b32_e32 v235, v235, v1
	v_bfe_u32 v1, v0, 8, 1
	v_lshlrev_b32_e32 v1, 12, v1
	v_xor_b32_e32 v235, v235, v1
	v_mov_b32_e32 v234, 0x0
	v_bfe_u32 v1, v0, 0, 3
	v_lshlrev_b32_e32 v1, 4, v1
	v_add_u32_e32 v234, v234, v1
	v_bfe_u32 v1, v0, 3, 6
	v_mul_u32_u24_e32 v1, 0x1600, v1
	v_add_u32_e32 v234, v234, v1
	v_mov_b32_e32 v233, 0x58000
	v_bfe_u32 v1, v0, 0, 3
	v_lshlrev_b32_e32 v1, 4, v1
	v_add_u32_e32 v233, v233, v1
	v_bfe_u32 v1, v0, 3, 6
	v_mul_u32_u24_e32 v1, 0x1600, v1
	v_add_u32_e32 v233, v233, v1
	v_mov_b32_e32 v232, 0xb0000
	v_bfe_u32 v1, v0, 0, 3
	v_lshlrev_b32_e32 v1, 4, v1
	v_add_u32_e32 v232, v232, v1
	v_bfe_u32 v1, v0, 3, 6
	v_mul_u32_u24_e32 v1, 0x1600, v1
	v_add_u32_e32 v232, v232, v1
	v_mov_b32_e32 v231, 0x108000
	v_bfe_u32 v1, v0, 0, 3
	v_lshlrev_b32_e32 v1, 4, v1
	v_add_u32_e32 v231, v231, v1
	v_bfe_u32 v1, v0, 3, 6
	v_mul_u32_u24_e32 v1, 0x1600, v1
	v_add_u32_e32 v231, v231, v1
	v_mov_b32_e32 v1, v0
	s_load_dword s0, s[0:1], 0xe0
	s_mov_b32 s1, s10
	v_mov_b32_e32 v1, v0
	s_waitcnt lgkmcnt(0)
	s_lshr_b32 s11, s0, 3
	s_waitcnt vmcnt(0)
	v_cvt_f32_u32_e32 v2, s11
	s_mov_b32 s0, s10
	s_ashr_i32 s1, s0, 3
	v_rcp_iflag_f32_e32 v2, v2
	s_ashr_i32 s2, s0, 31
	s_sub_i32 s0, 0, s11
	s_abs_i32 s1, s1
	v_mul_f32_e32 v1, 0x4f7ffffe, v2
	v_cvt_u32_f32_e32 v1, v1
	s_mov_b32 s42, 0
	v_readfirstlane_b32 s3, v1
	s_mul_i32 s0, s0, s3
	s_mul_hi_u32 s0, s3, s0
	s_add_i32 s0, s3, s0
	s_mul_hi_u32 s3, s1, s0
	s_mul_i32 s3, s3, s11
	s_sub_i32 s1, s1, s3
	s_sub_i32 s3, s1, s11
	s_cmp_ge_u32 s1, s11
	s_cselect_b32 s1, s3, s1
	s_sub_i32 s3, s1, s11
	s_cmp_ge_u32 s1, s11
	s_cselect_b32 s1, s3, s1
	s_xor_b32 s1, s1, s2
	s_sub_i32 s20, s1, s2
	s_mov_b32 s1, s10
	s_cmp_gt_i32 s20, 31
	s_cbranch_scc1 .LBB0_2605
	s_load_dwordx4 s[4:7], s[16:17], 0xc8
	s_mov_b32 s1, s10
	v_mov_b32_e32 v82, 0
	v_mov_b32_e32 v1, v0
	s_waitcnt lgkmcnt(0)
	s_add_u32 s2, s4, 0x2000000
	s_addc_u32 s3, s5, 0
	s_add_u32 s8, s6, 0x27000
	s_addc_u32 s9, s7, 0
	s_add_u32 s21, s6, 0x37f0000
	s_addc_u32 s22, s7, 0
	s_add_u32 s23, s6, 0x1270000
	s_addc_u32 s24, s7, 0
	s_ashr_i32 s6, s20, 31
	s_lshr_b32 s6, s6, 27
	s_add_i32 s6, s20, s6
	s_ashr_i32 s6, s6, 5
	s_lshl_b32 s7, s20, 1
	s_lshl_b32 s12, s6, 6
	s_sub_i32 s7, s7, s12
	s_lshl_b32 s6, s6, 2
	s_and_b32 s12, s20, 3
	s_or_b32 s25, s6, s12
	s_sub_i32 s6, s11, s20
	s_add_i32 s6, s6, 31
	s_mul_hi_u32 s0, s6, s0
	s_mul_i32 s12, s0, s11
	s_sub_i32 s6, s6, s12
	s_add_i32 s12, s0, 1
	s_sub_i32 s13, s6, s11
	s_cmp_ge_u32 s6, s11
	s_cselect_b32 s0, s12, s0
	s_cselect_b32 s6, s13, s6
	s_add_i32 s12, s0, 1
	s_cmp_ge_u32 s6, s11
	s_cselect_b32 s33, s12, s0
	s_and_b32 s0, s1, 7
	s_and_b32 s1, s7, -8
	s_movk_i32 s26, 0xb00
	v_lshrrev_b32_e32 v2, 3, v1
	s_or_b32 s27, s0, s1
	s_lshl_b32 s0, s25, 8
	s_mul_i32 s1, s25, 0x160000
	v_mul_lo_u32 v2, v2, s26
	v_lshlrev_b32_e32 v1, 3, v1
	s_mul_hi_i32 s6, s0, 0x1600
	s_add_u32 s0, s23, s1
	v_and_or_b32 v1, v1, 56, v2
	v_mov_b32_e32 v239, 0
	s_addc_u32 s1, s24, s6
	v_lshlrev_b32_e32 v238, 1, v1
	v_lshl_add_u64 v[2:3], s[0:1], 0, v[238:239]
	s_mov_b32 s28, 0x108000
	v_add_co_u32_e32 v34, vcc, s28, v2
	s_mov_b32 s12, 0xb0000
	s_nop 0
	v_addc_co_u32_e32 v35, vcc, 0, v3, vcc
	v_add_co_u32_e32 v36, vcc, s12, v2
	s_lshl_b32 s6, s27, 8
	s_mul_i32 s7, s27, 0x160000
	v_addc_co_u32_e32 v37, vcc, 0, v3, vcc
	s_mov_b32 s29, 0x58000
	s_mul_hi_i32 s13, s6, 0x1600
	s_add_u32 s6, s21, s7
	v_add_co_u32_e32 v2, vcc, s29, v2
	s_addc_u32 s7, s22, s13
	s_nop 0
	v_addc_co_u32_e32 v3, vcc, 0, v3, vcc
	v_lshl_add_u64 v[22:23], s[6:7], 0, v[238:239]
	v_add_co_u32_e32 v24, vcc, s12, v22
	global_load_dwordx4 v[2:5], v[2:3], off
	s_nop 0
	v_addc_co_u32_e32 v25, vcc, 0, v23, vcc
	v_add_co_u32_e32 v26, vcc, s29, v22
	v_mov_b32_e32 v1, v0
	s_nop 0
	v_addc_co_u32_e32 v27, vcc, 0, v23, vcc
	v_add_co_u32_e32 v38, vcc, s28, v22
	global_load_dwordx4 v[6:9], v[24:25], off
	global_load_dwordx4 v[10:13], v[26:27], off
	global_load_dwordx4 v[14:17], v238, s[0:1]
	global_load_dwordx4 v[18:21], v238, s[6:7]
	v_addc_co_u32_e32 v39, vcc, 0, v23, vcc
	global_load_dwordx4 v[22:25], v[38:39], off
	global_load_dwordx4 v[26:29], v[36:37], off
	global_load_dwordx4 v[30:33], v[34:35], off
	s_movk_i32 s31, 0xf0
	v_ashrrev_i32_e32 v34, 4, v1
	v_xor_b32_e32 v1, v34, v1
	v_lshlrev_b32_e32 v34, 8, v34
	v_lshlrev_b32_e32 v1, 4, v1
	v_and_or_b32 v1, v1, s31, v34
	s_mov_b32 s30, 2
	s_mul_i32 s33, s33, 44
	s_movk_i32 s34, 0xff80
	s_mov_b32 s35, 0x10000
	s_mov_b32 s36, 0x11000
	s_movk_i32 s37, 0x1800
	s_movk_i32 s38, 0x1fff
	v_mov_b32_e32 v240, 0x8040
	s_mov_b32 s18, 2
	s_mov_b32 s39, s20
	s_mov_b32 s40, s25
	s_mov_b32 s41, s27
	v_mov_b32_e32 v83, v82
	v_mov_b32_e32 v84, v82
	v_mov_b32_e32 v85, v82
	v_mov_b32_e32 v102, v82
	v_mov_b32_e32 v103, v82
	v_mov_b32_e32 v104, v82
	v_mov_b32_e32 v105, v82
	v_mov_b32_e32 v106, v82
	v_mov_b32_e32 v107, v82
	v_mov_b32_e32 v108, v82
	v_mov_b32_e32 v109, v82
	v_mov_b32_e32 v110, v82
	v_mov_b32_e32 v111, v82
	v_mov_b32_e32 v112, v82
	v_mov_b32_e32 v113, v82
	s_waitcnt vmcnt(4)
	ds_write_b128 v1, v[14:17] offset:32768
	s_waitcnt vmcnt(3)
	ds_write_b128 v1, v[18:21]
	ds_write_b128 v1, v[2:5] offset:40960
	ds_write_b128 v1, v[10:13] offset:8192
	ds_write_b128 v1, v[6:9] offset:16384
	s_waitcnt vmcnt(2)
	ds_write_b128 v1, v[22:25] offset:24576
	s_waitcnt vmcnt(1)
	ds_write_b128 v1, v[26:29] offset:49152
	s_waitcnt vmcnt(0)
	ds_write_b128 v1, v[30:33] offset:57344
	v_mov_b32_e32 v1, v0
	v_mov_b32_e32 v114, v82
	v_lshrrev_b32_e32 v2, 3, v1
	v_mul_lo_u32 v2, v2, s26
	v_lshlrev_b32_e32 v1, 3, v1
	v_and_or_b32 v1, v1, 56, v2
	v_lshlrev_b32_e32 v238, 1, v1
	v_lshl_add_u64 v[10:11], s[0:1], 0, v[238:239]
	v_add_co_u32_e32 v12, vcc, s28, v10
	v_lshl_add_u64 v[16:17], s[6:7], 0, v[238:239]
	s_nop 0
	v_addc_co_u32_e32 v13, vcc, 0, v11, vcc
	v_add_co_u32_e32 v14, vcc, s12, v10
	v_mov_b32_e32 v1, 0x10000
	s_nop 0
	v_addc_co_u32_e32 v15, vcc, 0, v11, vcc
	global_load_dwordx4 v[2:5], v[12:13], off offset:128
	global_load_dwordx4 v[6:9], v[14:15], off offset:128
	v_add_co_u32_e32 v14, vcc, s29, v10
	v_mov_b32_e32 v115, v82
	s_nop 0
	v_addc_co_u32_e32 v15, vcc, 0, v11, vcc
	v_add_co_u32_e32 v22, vcc, s28, v16
	v_mov_b32_e32 v116, v82
	s_nop 0
	v_addc_co_u32_e32 v23, vcc, 0, v17, vcc
	v_add_co_u32_e32 v34, vcc, s12, v16
	global_load_dwordx4 v[10:13], v[14:15], off offset:128
	global_load_dwordx4 v[18:21], v[22:23], off offset:128
	v_addc_co_u32_e32 v35, vcc, 0, v17, vcc
	v_add_co_u32_e32 v36, vcc, s29, v16
	v_mov_b32_e32 v117, v82
	s_nop 0
	v_addc_co_u32_e32 v37, vcc, 0, v17, vcc
	global_load_dwordx4 v[22:25], v[34:35], off offset:128
	global_load_dwordx4 v[26:29], v[36:37], off offset:128
	global_load_dwordx4 v[14:17], v238, s[0:1] offset:128
	global_load_dwordx4 v[30:33], v238, s[6:7] offset:128
	v_mov_b32_e32 v118, v82
	v_mov_b32_e32 v119, v82
	v_mov_b32_e32 v120, v82
	v_mov_b32_e32 v121, v82
	v_mov_b32_e32 v122, v82
	v_mov_b32_e32 v123, v82
	v_mov_b32_e32 v124, v82
	v_mov_b32_e32 v125, v82
	v_mov_b32_e32 v126, v82
	v_mov_b32_e32 v127, v82
	v_mov_b32_e32 v128, v82
	v_mov_b32_e32 v129, v82
	v_mov_b32_e32 v130, v82
	v_mov_b32_e32 v131, v82
	v_mov_b32_e32 v132, v82
	v_mov_b32_e32 v133, v82
	v_mov_b32_e32 v134, v82
	v_mov_b32_e32 v135, v82
	v_mov_b32_e32 v136, v82
	v_mov_b32_e32 v137, v82
	v_mov_b32_e32 v138, v82
	v_mov_b32_e32 v139, v82
	v_mov_b32_e32 v140, v82
	v_mov_b32_e32 v141, v82
	v_mov_b32_e32 v142, v82
	v_mov_b32_e32 v143, v82
	v_mov_b32_e32 v144, v82
	v_mov_b32_e32 v145, v82
	v_mov_b32_e32 v146, v82
	v_mov_b32_e32 v147, v82
	v_mov_b32_e32 v148, v82
	v_mov_b32_e32 v149, v82
	v_mov_b32_e32 v150, v82
	v_mov_b32_e32 v151, v82
	v_mov_b32_e32 v152, v82
	v_mov_b32_e32 v153, v82
	v_mov_b32_e32 v154, v82
	v_mov_b32_e32 v155, v82
	v_mov_b32_e32 v156, v82
	v_mov_b32_e32 v157, v82
	v_mov_b32_e32 v158, v82
	v_mov_b32_e32 v159, v82
	v_mov_b32_e32 v160, v82
	v_mov_b32_e32 v161, v82
	v_mov_b32_e32 v98, v82
	v_mov_b32_e32 v99, v82
	v_mov_b32_e32 v100, v82
	v_mov_b32_e32 v101, v82
	v_mov_b32_e32 v94, v82
	v_mov_b32_e32 v95, v82
	v_mov_b32_e32 v96, v82
	v_mov_b32_e32 v97, v82
	v_mov_b32_e32 v90, v82
	v_mov_b32_e32 v91, v82
	v_mov_b32_e32 v92, v82
	v_mov_b32_e32 v93, v82
	v_mov_b32_e32 v86, v82
	v_mov_b32_e32 v87, v82
	v_mov_b32_e32 v88, v82
	v_mov_b32_e32 v89, v82
	v_mov_b32_e32 v78, v82
	v_mov_b32_e32 v79, v82
	v_mov_b32_e32 v80, v82
	v_mov_b32_e32 v81, v82
	v_mov_b32_e32 v74, v82
	v_mov_b32_e32 v75, v82
	v_mov_b32_e32 v76, v82
	v_mov_b32_e32 v77, v82
	v_mov_b32_e32 v70, v82
	v_mov_b32_e32 v71, v82
	v_mov_b32_e32 v72, v82
	v_mov_b32_e32 v73, v82
	v_mov_b32_e32 v66, v82
	v_mov_b32_e32 v67, v82
	v_mov_b32_e32 v68, v82
	v_mov_b32_e32 v69, v82
	v_mov_b32_e32 v62, v82
	v_mov_b32_e32 v63, v82
	v_mov_b32_e32 v64, v82
	v_mov_b32_e32 v65, v82
	v_mov_b32_e32 v58, v82
	v_mov_b32_e32 v59, v82
	v_mov_b32_e32 v60, v82
	v_mov_b32_e32 v61, v82
	v_mov_b32_e32 v54, v82
	v_mov_b32_e32 v55, v82
	v_mov_b32_e32 v56, v82
	v_mov_b32_e32 v57, v82
	v_mov_b32_e32 v50, v82
	v_mov_b32_e32 v51, v82
	v_mov_b32_e32 v52, v82
	v_mov_b32_e32 v53, v82
	v_mov_b32_e32 v46, v82
	v_mov_b32_e32 v47, v82
	v_mov_b32_e32 v48, v82
	v_mov_b32_e32 v49, v82
	v_mov_b32_e32 v42, v82
	v_mov_b32_e32 v43, v82
	v_mov_b32_e32 v44, v82
	v_mov_b32_e32 v45, v82
	v_mov_b32_e32 v38, v82
	v_mov_b32_e32 v39, v82
	v_mov_b32_e32 v40, v82
	v_mov_b32_e32 v41, v82
	v_mov_b32_e32 v34, v82
	v_mov_b32_e32 v35, v82
	v_mov_b32_e32 v36, v82
	v_mov_b32_e32 v37, v82
	s_waitcnt lgkmcnt(0)
	s_barrier
	s_waitcnt vmcnt(0)
	s_branch .LBB0_2545

.Lnodef_J1_9:
	ds_read_b128 v[170:173], v255 offset:4096
	ds_read_b128 v[174:177], v253 offset:4096
	s_add_i32 s0, s30, -1
	s_cmp_lt_i32 s0, s33
	s_cselect_b64 s[14:15], -1, 0
	s_cmp_ge_i32 s0, s33
	s_waitcnt lgkmcnt(3)
	v_mfma_f32_16x16x32_bf16 v[158:161], v[178:181], v[162:165], v[158:161]
	v_mfma_f32_16x16x32_bf16 v[154:157], v[182:185], v[162:165], v[154:157]
	v_mfma_f32_16x16x32_bf16 v[150:153], v[186:189], v[162:165], v[150:153]
	v_mfma_f32_16x16x32_bf16 v[146:149], v[190:193], v[162:165], v[146:149]
	ds_read_b128 v[162:165], v255 offset:8192
	s_waitcnt lgkmcnt(3)
	v_mfma_f32_16x16x32_bf16 v[142:145], v[178:181], v[166:169], v[142:145]
	v_mfma_f32_16x16x32_bf16 v[138:141], v[182:185], v[166:169], v[138:141]
	v_mfma_f32_16x16x32_bf16 v[134:137], v[186:189], v[166:169], v[134:137]
	v_mfma_f32_16x16x32_bf16 v[130:133], v[190:193], v[166:169], v[130:133]
	ds_read_b128 v[166:169], v253 offset:8192
	s_waitcnt lgkmcnt(3)
	v_mfma_f32_16x16x32_bf16 v[126:129], v[178:181], v[170:173], v[126:129]
	v_mfma_f32_16x16x32_bf16 v[122:125], v[182:185], v[170:173], v[122:125]
	v_mfma_f32_16x16x32_bf16 v[118:121], v[186:189], v[170:173], v[118:121]
	v_mfma_f32_16x16x32_bf16 v[114:117], v[190:193], v[170:173], v[114:117]
	s_waitcnt vmcnt(6)
	ds_write_b128 v235, v[30:33]
	ds_write_b128 v235, v[26:29] offset:8192
.LBB0_2547:
	s_lshl_b32 s0, s41, 8
	s_mul_i32 s12, s41, 0xb0000
	s_mul_hi_i32 s13, s0, 0xb00
	s_lshl_b32 s0, s18, 6
	s_ashr_i32 s1, s0, 31
	s_lshl_b64 s[6:7], s[12:13], 1
	s_add_u32 s16, s21, s6
	s_addc_u32 s17, s22, s7
	s_lshl_b64 s[6:7], s[0:1], 1
	s_add_u32 s16, s16, s6
	s_addc_u32 s17, s17, s7
	global_load_dwordx4 v[26:29], v234, s[16:17]
	global_load_dwordx4 v[30:33], v233, s[16:17]
	s_andn2_b64 vcc, exec, s[14:15]
	ds_read_b128 v[170:173], v255 offset:12288
	s_waitcnt lgkmcnt(5)
	v_mfma_f32_16x16x32_bf16 v[110:113], v[178:181], v[174:177], v[110:113]
	v_mfma_f32_16x16x32_bf16 v[106:109], v[182:185], v[174:177], v[106:109]
	v_mfma_f32_16x16x32_bf16 v[102:105], v[186:189], v[174:177], v[102:105]
	v_mfma_f32_16x16x32_bf16 v[82:85], v[190:193], v[174:177], v[82:85]
	ds_read_b128 v[174:177], v253 offset:12288
	s_waitcnt lgkmcnt(5)
	v_mfma_f32_16x16x32_bf16 v[98:101], v[178:181], v[162:165], v[98:101]
	v_mfma_f32_16x16x32_bf16 v[94:97], v[182:185], v[162:165], v[94:97]
	v_mfma_f32_16x16x32_bf16 v[90:93], v[186:189], v[162:165], v[90:93]
	v_mfma_f32_16x16x32_bf16 v[86:89], v[190:193], v[162:165], v[86:89]
	s_waitcnt lgkmcnt(4)
	v_mfma_f32_16x16x32_bf16 v[78:81], v[178:181], v[166:169], v[78:81]
	v_mfma_f32_16x16x32_bf16 v[74:77], v[182:185], v[166:169], v[74:77]
	v_mfma_f32_16x16x32_bf16 v[70:73], v[186:189], v[166:169], v[70:73]
	v_mfma_f32_16x16x32_bf16 v[66:69], v[190:193], v[166:169], v[66:69]
	s_waitcnt vmcnt(6)
	ds_write_b128 v235, v[22:25] offset:16384
	ds_write_b128 v235, v[18:21] offset:24576
.LBB0_2549:
	global_load_dwordx4 v[18:21], v232, s[16:17]
	global_load_dwordx4 v[22:25], v231, s[16:17]
	s_and_b64 vcc, exec, s[0:1]
	ds_read_b128 v[194:197], v243
	ds_read_b128 v[198:201], v241
	ds_read_b128 v[202:205], v243 offset:4096
	ds_read_b128 v[206:209], v241 offset:4096
	ds_read_b128 v[162:165], v247
	ds_read_b128 v[166:169], v245
	s_waitcnt lgkmcnt(9)
	v_mfma_f32_16x16x32_bf16 v[62:65], v[178:181], v[170:173], v[62:65]
	v_mfma_f32_16x16x32_bf16 v[58:61], v[182:185], v[170:173], v[58:61]
	v_mfma_f32_16x16x32_bf16 v[54:57], v[186:189], v[170:173], v[54:57]
	v_mfma_f32_16x16x32_bf16 v[50:53], v[190:193], v[170:173], v[50:53]
	ds_read_b128 v[170:173], v247 offset:4096
	s_waitcnt lgkmcnt(9)
	v_mfma_f32_16x16x32_bf16 v[46:49], v[178:181], v[174:177], v[46:49]
	v_mfma_f32_16x16x32_bf16 v[42:45], v[182:185], v[174:177], v[42:45]
	v_mfma_f32_16x16x32_bf16 v[38:41], v[186:189], v[174:177], v[38:41]
	v_mfma_f32_16x16x32_bf16 v[34:37], v[190:193], v[174:177], v[34:37]
	s_waitcnt vmcnt(6)
	ds_write_b128 v235, v[14:17] offset:32768
	ds_write_b128 v235, v[10:13] offset:40960
.LBB0_2551:
	s_lshl_b32 s15, s40, 8
	s_mul_i32 s14, s40, 0xb0000
	s_mul_hi_i32 s15, s15, 0xb00
	s_lshl_b64 s[16:17], s[14:15], 1
	s_add_u32 s16, s23, s16
	s_addc_u32 s17, s24, s17
	s_add_u32 s6, s16, s6
	s_addc_u32 s7, s17, s7
	global_load_dwordx4 v[10:13], v234, s[6:7]
	global_load_dwordx4 v[14:17], v233, s[6:7]
	s_and_b64 vcc, exec, s[0:1]
	ds_read_b128 v[174:177], v245 offset:4096
	s_waitcnt lgkmcnt(5)
	v_mfma_f32_16x16x32_bf16 v[158:161], v[194:197], v[162:165], v[158:161]
	v_mfma_f32_16x16x32_bf16 v[154:157], v[198:201], v[162:165], v[154:157]
	v_mfma_f32_16x16x32_bf16 v[150:153], v[202:205], v[162:165], v[150:153]
	v_mfma_f32_16x16x32_bf16 v[146:149], v[206:209], v[162:165], v[146:149]
	ds_read_b128 v[162:165], v247 offset:8192
	s_waitcnt lgkmcnt(5)
	v_mfma_f32_16x16x32_bf16 v[142:145], v[194:197], v[166:169], v[142:145]
	v_mfma_f32_16x16x32_bf16 v[138:141], v[198:201], v[166:169], v[138:141]
	v_mfma_f32_16x16x32_bf16 v[134:137], v[202:205], v[166:169], v[134:137]
	v_mfma_f32_16x16x32_bf16 v[130:133], v[206:209], v[166:169], v[130:133]
	ds_read_b128 v[166:169], v245 offset:8192
	s_waitcnt lgkmcnt(5)
	v_mfma_f32_16x16x32_bf16 v[126:129], v[194:197], v[170:173], v[126:129]
	v_mfma_f32_16x16x32_bf16 v[122:125], v[198:201], v[170:173], v[122:125]
	v_mfma_f32_16x16x32_bf16 v[118:121], v[202:205], v[170:173], v[118:121]
	v_mfma_f32_16x16x32_bf16 v[114:117], v[206:209], v[170:173], v[114:117]
	s_waitcnt vmcnt(6)
	ds_write_b128 v235, v[6:9] offset:49152
	ds_write_b128 v235, v[2:5] offset:57344
.LBB0_2553:
	global_load_dwordx4 v[2:5], v232, s[6:7]
	global_load_dwordx4 v[6:9], v231, s[6:7]
	ds_read_b128 v[170:173], v247 offset:12288
	s_waitcnt lgkmcnt(5)
	v_mfma_f32_16x16x32_bf16 v[110:113], v[194:197], v[174:177], v[110:113]
	v_mfma_f32_16x16x32_bf16 v[106:109], v[198:201], v[174:177], v[106:109]
	v_mfma_f32_16x16x32_bf16 v[102:105], v[202:205], v[174:177], v[102:105]
	v_mfma_f32_16x16x32_bf16 v[82:85], v[206:209], v[174:177], v[82:85]
	ds_read_b128 v[174:177], v245 offset:12288
	s_waitcnt lgkmcnt(5)
	v_mfma_f32_16x16x32_bf16 v[98:101], v[194:197], v[162:165], v[98:101]
	v_mfma_f32_16x16x32_bf16 v[94:97], v[198:201], v[162:165], v[94:97]
	v_mfma_f32_16x16x32_bf16 v[90:93], v[202:205], v[162:165], v[90:93]
	v_mfma_f32_16x16x32_bf16 v[86:89], v[206:209], v[162:165], v[86:89]
	s_waitcnt lgkmcnt(4)
	v_mfma_f32_16x16x32_bf16 v[78:81], v[194:197], v[166:169], v[78:81]
	v_mfma_f32_16x16x32_bf16 v[74:77], v[198:201], v[166:169], v[74:77]
	v_mfma_f32_16x16x32_bf16 v[70:73], v[202:205], v[166:169], v[70:73]
	v_mfma_f32_16x16x32_bf16 v[66:69], v[206:209], v[166:169], v[66:69]
	s_add_i32 s43, s18, 1
	s_cmp_lg_u32 s43, 44
	s_cbranch_scc1 .LBB0_2557
	s_add_i32 s20, s20, s11
	s_cmp_gt_i32 s20, 31
	s_cbranch_scc1 .LBB0_2556
	s_ashr_i32 s1, s20, 31
	s_lshr_b32 s1, s1, 27
	s_add_i32 s1, s20, s1
	s_ashr_i32 s1, s1, 5
	s_mov_b32 s0, s10
	s_lshl_b32 s6, s1, 6
	s_lshl_b32 s7, s20, 1
	s_sub_i32 s6, s7, s6
	s_and_b32 s0, s0, 7
	s_and_b32 s6, s6, -8
	s_lshl_b32 s1, s1, 2
	s_and_b32 s7, s20, 3
	s_or_b32 s41, s0, s6
	s_or_b32 s40, s1, s7
	s_lshl_b32 s0, s41, 8
	s_mul_hi_i32 s13, s0, 0xb00
	s_lshl_b32 s0, s40, 8
	s_mul_i32 s12, s41, 0xb0000
	s_mul_i32 s14, s40, 0xb0000
	s_mul_hi_i32 s15, s0, 0xb00

.LBB0_2557:
	s_waitcnt lgkmcnt(0)
	s_barrier
	ds_read_b128 v[178:181], v250
	ds_read_b128 v[182:185], v248
	ds_read_b128 v[186:189], v250 offset:4096
	ds_read_b128 v[190:193], v248 offset:4096
	ds_read_b128 v[162:165], v254
	ds_read_b128 v[166:169], v252
	v_mfma_f32_16x16x32_bf16 v[62:65], v[194:197], v[170:173], v[62:65]
	v_mfma_f32_16x16x32_bf16 v[58:61], v[198:201], v[170:173], v[58:61]
	v_mfma_f32_16x16x32_bf16 v[54:57], v[202:205], v[170:173], v[54:57]
	v_mfma_f32_16x16x32_bf16 v[50:53], v[206:209], v[170:173], v[50:53]
	v_mfma_f32_16x16x32_bf16 v[46:49], v[194:197], v[174:177], v[46:49]
	v_mfma_f32_16x16x32_bf16 v[42:45], v[198:201], v[174:177], v[42:45]
	v_mfma_f32_16x16x32_bf16 v[38:41], v[202:205], v[174:177], v[38:41]
	v_mfma_f32_16x16x32_bf16 v[34:37], v[206:209], v[174:177], v[34:37]
	ds_read_b128 v[170:173], v254 offset:4096
	ds_read_b128 v[174:177], v252 offset:4096
	s_cmp_lt_i32 s30, s33
	s_cselect_b64 s[16:17], -1, 0
	s_cmp_ge_i32 s30, s33
	s_cselect_b64 s[6:7], -1, 0
	s_and_b64 vcc, exec, s[6:7]
	s_waitcnt lgkmcnt(3)
	v_mfma_f32_16x16x32_bf16 v[158:161], v[178:181], v[162:165], v[158:161]
	v_mfma_f32_16x16x32_bf16 v[154:157], v[182:185], v[162:165], v[154:157]
	v_mfma_f32_16x16x32_bf16 v[150:153], v[186:189], v[162:165], v[150:153]
	v_mfma_f32_16x16x32_bf16 v[146:149], v[190:193], v[162:165], v[146:149]
	ds_read_b128 v[162:165], v254 offset:8192
	s_waitcnt lgkmcnt(3)
	v_mfma_f32_16x16x32_bf16 v[142:145], v[178:181], v[166:169], v[142:145]
	v_mfma_f32_16x16x32_bf16 v[138:141], v[182:185], v[166:169], v[138:141]
	v_mfma_f32_16x16x32_bf16 v[134:137], v[186:189], v[166:169], v[134:137]
	v_mfma_f32_16x16x32_bf16 v[130:133], v[190:193], v[166:169], v[130:133]
	ds_read_b128 v[166:169], v252 offset:8192
	s_waitcnt lgkmcnt(3)
	v_mfma_f32_16x16x32_bf16 v[126:129], v[178:181], v[170:173], v[126:129]
	v_mfma_f32_16x16x32_bf16 v[122:125], v[182:185], v[170:173], v[122:125]
	v_mfma_f32_16x16x32_bf16 v[118:121], v[186:189], v[170:173], v[118:121]
	v_mfma_f32_16x16x32_bf16 v[114:117], v[190:193], v[170:173], v[114:117]
	s_waitcnt vmcnt(6)
	ds_write_b128 v236, v[26:29]
	ds_write_b128 v236, v[30:33] offset:8192
.LBB0_2559:
	s_lshl_b32 s0, s43, 6
	s_ashr_i32 s1, s0, 31
	s_lshl_b64 s[12:13], s[12:13], 1
	s_add_u32 s18, s21, s12
	s_addc_u32 s19, s22, s13
	s_lshl_b64 s[12:13], s[0:1], 1
	s_add_u32 s18, s18, s12
	s_addc_u32 s19, s19, s13
	global_load_dwordx4 v[30:33], v234, s[18:19]
	global_load_dwordx4 v[26:29], v233, s[18:19]
	s_andn2_b64 vcc, exec, s[16:17]
	ds_read_b128 v[170:173], v254 offset:12288
	s_waitcnt lgkmcnt(5)
	v_mfma_f32_16x16x32_bf16 v[110:113], v[178:181], v[174:177], v[110:113]
	v_mfma_f32_16x16x32_bf16 v[106:109], v[182:185], v[174:177], v[106:109]
	v_mfma_f32_16x16x32_bf16 v[102:105], v[186:189], v[174:177], v[102:105]
	v_mfma_f32_16x16x32_bf16 v[82:85], v[190:193], v[174:177], v[82:85]
	ds_read_b128 v[174:177], v252 offset:12288
	s_waitcnt lgkmcnt(5)
	v_mfma_f32_16x16x32_bf16 v[98:101], v[178:181], v[162:165], v[98:101]
	v_mfma_f32_16x16x32_bf16 v[94:97], v[182:185], v[162:165], v[94:97]
	v_mfma_f32_16x16x32_bf16 v[90:93], v[186:189], v[162:165], v[90:93]
	v_mfma_f32_16x16x32_bf16 v[86:89], v[190:193], v[162:165], v[86:89]
	s_waitcnt lgkmcnt(4)
	v_mfma_f32_16x16x32_bf16 v[78:81], v[178:181], v[166:169], v[78:81]
	v_mfma_f32_16x16x32_bf16 v[74:77], v[182:185], v[166:169], v[74:77]
	v_mfma_f32_16x16x32_bf16 v[70:73], v[186:189], v[166:169], v[70:73]
	v_mfma_f32_16x16x32_bf16 v[66:69], v[190:193], v[166:169], v[66:69]
	s_waitcnt vmcnt(6)
	ds_write_b128 v236, v[18:21] offset:16384
	ds_write_b128 v236, v[22:25] offset:24576
.LBB0_2561:
	global_load_dwordx4 v[22:25], v232, s[18:19]
	global_load_dwordx4 v[18:21], v231, s[18:19]
	s_and_b64 vcc, exec, s[0:1]
	ds_read_b128 v[194:197], v242
	ds_read_b128 v[198:201], v237
	ds_read_b128 v[202:205], v242 offset:4096
	ds_read_b128 v[206:209], v237 offset:4096
	ds_read_b128 v[162:165], v246
	ds_read_b128 v[166:169], v244
	s_waitcnt lgkmcnt(9)
	v_mfma_f32_16x16x32_bf16 v[62:65], v[178:181], v[170:173], v[62:65]
	v_mfma_f32_16x16x32_bf16 v[58:61], v[182:185], v[170:173], v[58:61]
	v_mfma_f32_16x16x32_bf16 v[54:57], v[186:189], v[170:173], v[54:57]
	v_mfma_f32_16x16x32_bf16 v[50:53], v[190:193], v[170:173], v[50:53]
	ds_read_b128 v[170:173], v246 offset:4096
	s_waitcnt lgkmcnt(9)
	v_mfma_f32_16x16x32_bf16 v[46:49], v[178:181], v[174:177], v[46:49]
	v_mfma_f32_16x16x32_bf16 v[42:45], v[182:185], v[174:177], v[42:45]
	v_mfma_f32_16x16x32_bf16 v[38:41], v[186:189], v[174:177], v[38:41]
	v_mfma_f32_16x16x32_bf16 v[34:37], v[190:193], v[174:177], v[34:37]
	s_waitcnt vmcnt(6)
	ds_write_b128 v236, v[10:13] offset:32768
	ds_write_b128 v236, v[14:17] offset:40960
.LBB0_2563:
	s_lshl_b64 s[14:15], s[14:15], 1
	s_add_u32 s14, s23, s14
	s_addc_u32 s15, s24, s15
	s_add_u32 s12, s14, s12
	s_addc_u32 s13, s15, s13
	global_load_dwordx4 v[14:17], v234, s[12:13]
	global_load_dwordx4 v[10:13], v233, s[12:13]
	s_and_b64 vcc, exec, s[0:1]
	ds_read_b128 v[174:177], v244 offset:4096
	s_waitcnt lgkmcnt(5)
	v_mfma_f32_16x16x32_bf16 v[158:161], v[194:197], v[162:165], v[158:161]
	v_mfma_f32_16x16x32_bf16 v[154:157], v[198:201], v[162:165], v[154:157]
	v_mfma_f32_16x16x32_bf16 v[150:153], v[202:205], v[162:165], v[150:153]
	v_mfma_f32_16x16x32_bf16 v[146:149], v[206:209], v[162:165], v[146:149]
	ds_read_b128 v[162:165], v246 offset:8192
	s_waitcnt lgkmcnt(5)
	v_mfma_f32_16x16x32_bf16 v[142:145], v[194:197], v[166:169], v[142:145]
	v_mfma_f32_16x16x32_bf16 v[138:141], v[198:201], v[166:169], v[138:141]
	v_mfma_f32_16x16x32_bf16 v[134:137], v[202:205], v[166:169], v[134:137]
	v_mfma_f32_16x16x32_bf16 v[130:133], v[206:209], v[166:169], v[130:133]
	ds_read_b128 v[166:169], v244 offset:8192
	s_waitcnt lgkmcnt(5)
	v_mfma_f32_16x16x32_bf16 v[126:129], v[194:197], v[170:173], v[126:129]
	v_mfma_f32_16x16x32_bf16 v[122:125], v[198:201], v[170:173], v[122:125]
	v_mfma_f32_16x16x32_bf16 v[118:121], v[202:205], v[170:173], v[118:121]
	v_mfma_f32_16x16x32_bf16 v[114:117], v[206:209], v[170:173], v[114:117]
	s_waitcnt vmcnt(6)
	ds_write_b128 v236, v[2:5] offset:49152
	ds_write_b128 v236, v[6:9] offset:57344
.LBB0_2565:
	global_load_dwordx4 v[6:9], v232, s[12:13]
	global_load_dwordx4 v[2:5], v231, s[12:13]
	ds_read_b128 v[170:173], v246 offset:12288
	s_waitcnt lgkmcnt(5)
	v_mfma_f32_16x16x32_bf16 v[110:113], v[194:197], v[174:177], v[110:113]
	v_mfma_f32_16x16x32_bf16 v[106:109], v[198:201], v[174:177], v[106:109]
	v_mfma_f32_16x16x32_bf16 v[102:105], v[202:205], v[174:177], v[102:105]
	v_mfma_f32_16x16x32_bf16 v[82:85], v[206:209], v[174:177], v[82:85]
	ds_read_b128 v[174:177], v244 offset:12288
	s_waitcnt lgkmcnt(5)
	v_mfma_f32_16x16x32_bf16 v[98:101], v[194:197], v[162:165], v[98:101]
	v_mfma_f32_16x16x32_bf16 v[94:97], v[198:201], v[162:165], v[94:97]
	v_mfma_f32_16x16x32_bf16 v[90:93], v[202:205], v[162:165], v[90:93]
	v_mfma_f32_16x16x32_bf16 v[86:89], v[206:209], v[162:165], v[86:89]
	s_waitcnt lgkmcnt(4)
	v_mfma_f32_16x16x32_bf16 v[78:81], v[194:197], v[166:169], v[78:81]
	v_mfma_f32_16x16x32_bf16 v[74:77], v[198:201], v[166:169], v[74:77]
	v_mfma_f32_16x16x32_bf16 v[70:73], v[202:205], v[166:169], v[70:73]
	v_mfma_f32_16x16x32_bf16 v[66:69], v[206:209], v[166:169], v[66:69]
	s_add_i32 s18, s43, 1
	s_cmp_lg_u32 s18, 44
	s_cbranch_scc1 .LBB0_2569
	s_add_i32 s20, s20, s11
	s_cmp_gt_i32 s20, 31
	s_cbranch_scc1 .LBB0_2568
	s_ashr_i32 s1, s20, 31
	s_lshr_b32 s1, s1, 27
	s_add_i32 s1, s20, s1
	s_ashr_i32 s1, s1, 5
	s_mov_b32 s0, s10
	s_lshl_b32 s12, s1, 6
	s_lshl_b32 s13, s20, 1
	s_sub_i32 s12, s13, s12
	s_and_b32 s0, s0, 7
	s_and_b32 s12, s12, -8
	s_lshl_b32 s1, s1, 2
	s_and_b32 s13, s20, 3
	s_or_b32 s40, s1, s13
	s_or_b32 s41, s0, s12

.LBB0_2569:
	s_add_i32 s42, s42, 2
	s_cmp_lg_u32 s42, 44
	s_waitcnt lgkmcnt(0)
	s_mov_b32 s98, 1
	s_cbranch_scc1 .LBB0_2544
	s_mov_b32 s98, 0
	v_mfma_f32_16x16x32_bf16 v[62:65], v[194:197], v[170:173], v[62:65]
	v_mfma_f32_16x16x32_bf16 v[58:61], v[198:201], v[170:173], v[58:61]
	v_mfma_f32_16x16x32_bf16 v[54:57], v[202:205], v[170:173], v[54:57]
	v_mfma_f32_16x16x32_bf16 v[50:53], v[206:209], v[170:173], v[50:53]
	v_mfma_f32_16x16x32_bf16 v[46:49], v[194:197], v[174:177], v[46:49]
	v_mfma_f32_16x16x32_bf16 v[42:45], v[198:201], v[174:177], v[42:45]
	v_mfma_f32_16x16x32_bf16 v[38:41], v[202:205], v[174:177], v[38:41]
	v_mfma_f32_16x16x32_bf16 v[34:37], v[206:209], v[174:177], v[34:37]
	s_nop 7
	s_nop 7
	v_mov_b32_e32 v172, v0
	s_nop 0
	v_ashrrev_i32_e32 v162, 1, v172
	v_and_b32_e32 v162, 0xffffff80, v162
	v_lshl_add_u32 v162, s27, 8, v162
	v_and_or_b32 v164, v172, 15, v162
	v_add_u32_e32 v162, 0xffffe000, v162
	v_ashrrev_i32_e32 v162, 11, v162
	v_mad_i32_i24 v162, v162, s37, s37
	v_cmp_lt_i32_e32 vcc, s38, v164
	v_ashrrev_i32_e32 v163, 31, v162
	s_and_saveexec_b64 s[0:1], vcc
	s_xor_b64 s[0:1], exec, s[0:1]
	v_add_u32_e32 v238, 0xffffe000, v164
	v_lshlrev_b64 v[166:167], 12, v[238:239]
	v_mov_b32_e32 v165, v239
	v_lshl_add_u64 v[168:169], s[2:3], 0, v[166:167]
	v_lshlrev_b64 v[170:171], 12, v[164:165]
	v_mov_b64_e32 v[166:167], v[162:163]
	s_andn2_saveexec_b64 s[0:1], s[0:1]
	v_ashrrev_i32_e32 v165, 31, v164
	v_lshlrev_b64 v[170:171], 12, v[164:165]
	v_lshl_add_u64 v[168:169], s[4:5], 0, v[170:171]
	v_mov_b64_e32 v[166:167], 0
	s_or_b64 exec, exec, s[0:1]
	v_and_b32_e32 v165, 0xc0, v172
	v_lshrrev_b32_e32 v172, 2, v172
	s_lshl_b32 s0, s25, 8
	v_and_b32_e32 v172, 12, v172
	v_or3_b32 v172, v165, s0, v172
	v_ashrrev_i32_e32 v173, 31, v172
	v_lshl_add_u64 v[176:177], v[166:167], 2, s[8:9]
	v_lshlrev_b64 v[166:167], 2, v[172:173]
	v_lshl_add_u64 v[180:181], v[168:169], 0, v[166:167]
	v_lshl_add_u64 v[182:183], v[176:177], 0, v[166:167]
	global_load_dwordx4 v[172:175], v[180:181], off
	global_load_dwordx4 v[176:179], v[182:183], off
	v_lshl_add_u64 v[168:169], s[4:5], 0, v[170:171]
	v_lshl_add_u64 v[184:185], v[168:169], 0, v[166:167]
	s_waitcnt vmcnt(0)
	v_pk_fma_f32 v[160:161], v[160:161], v[178:179], v[174:175]
	v_pk_fma_f32 v[158:159], v[158:159], v[176:177], v[172:173]
	global_store_dwordx4 v[184:185], v[158:161], off
	global_load_dwordx4 v[158:161], v[180:181], off offset:64
	s_nop 0
	global_load_dwordx4 v[168:171], v[182:183], off offset:64
	s_waitcnt vmcnt(0)
	v_pk_fma_f32 v[156:157], v[156:157], v[170:171], v[160:161]
	v_pk_fma_f32 v[154:155], v[154:155], v[168:169], v[158:159]
	global_store_dwordx4 v[184:185], v[154:157], off offset:64
	global_load_dwordx4 v[154:157], v[180:181], off offset:128
	s_nop 0
	global_load_dwordx4 v[158:161], v[182:183], off offset:128
	s_waitcnt vmcnt(0)
	v_pk_fma_f32 v[152:153], v[152:153], v[160:161], v[156:157]
	v_pk_fma_f32 v[150:151], v[150:151], v[158:159], v[154:155]
	global_store_dwordx4 v[184:185], v[150:153], off offset:128
	global_load_dwordx4 v[152:155], v[180:181], off offset:192
	s_nop 0
	global_load_dwordx4 v[156:159], v[182:183], off offset:192
	v_or_b32_e32 v150, 16, v164
	v_cmp_lt_i32_e32 vcc, s38, v150
	s_waitcnt vmcnt(0)
	v_pk_fma_f32 v[148:149], v[148:149], v[158:159], v[154:155]
	v_pk_fma_f32 v[146:147], v[146:147], v[156:157], v[152:153]
	global_store_dwordx4 v[184:185], v[146:149], off offset:192
	s_and_saveexec_b64 s[0:1], vcc
	s_xor_b64 s[0:1], exec, s[0:1]
	v_add_u32_e32 v238, 0xffffe010, v164
	v_lshlrev_b64 v[146:147], 12, v[238:239]
	v_mov_b32_e32 v151, v239
	v_lshl_add_u64 v[146:147], s[2:3], 0, v[146:147]
	v_lshlrev_b64 v[148:149], 12, v[150:151]
	v_mov_b64_e32 v[152:153], v[162:163]
	s_andn2_saveexec_b64 s[0:1], s[0:1]
	v_ashrrev_i32_e32 v151, 31, v150
	v_lshlrev_b64 v[148:149], 12, v[150:151]
	v_lshl_add_u64 v[146:147], s[4:5], 0, v[148:149]
	v_mov_b64_e32 v[152:153], 0
	s_or_b64 exec, exec, s[0:1]
	v_lshl_add_u64 v[154:155], v[152:153], 2, s[8:9]
	v_lshl_add_u64 v[158:159], v[146:147], 0, v[166:167]
	v_lshl_add_u64 v[160:161], v[154:155], 0, v[166:167]
	global_load_dwordx4 v[150:153], v[158:159], off
	global_load_dwordx4 v[154:157], v[160:161], off
	v_lshl_add_u64 v[146:147], s[4:5], 0, v[148:149]
	v_lshl_add_u64 v[168:169], v[146:147], 0, v[166:167]
	s_waitcnt vmcnt(0)
	v_pk_fma_f32 v[144:145], v[144:145], v[156:157], v[152:153]
	v_pk_fma_f32 v[142:143], v[142:143], v[154:155], v[150:151]
	global_store_dwordx4 v[168:169], v[142:145], off
	global_load_dwordx4 v[142:145], v[158:159], off offset:64
	s_nop 0
	global_load_dwordx4 v[146:149], v[160:161], off offset:64
	s_waitcnt vmcnt(0)
	v_pk_fma_f32 v[140:141], v[140:141], v[148:149], v[144:145]
	v_pk_fma_f32 v[138:139], v[138:139], v[146:147], v[142:143]
	global_store_dwordx4 v[168:169], v[138:141], off offset:64
	global_load_dwordx4 v[138:141], v[158:159], off offset:128
	s_nop 0
	global_load_dwordx4 v[142:145], v[160:161], off offset:128
	s_waitcnt vmcnt(0)
	v_pk_fma_f32 v[136:137], v[136:137], v[144:145], v[140:141]
	v_pk_fma_f32 v[134:135], v[134:135], v[142:143], v[138:139]
	global_store_dwordx4 v[168:169], v[134:137], off offset:128
	global_load_dwordx4 v[136:139], v[158:159], off offset:192
	s_nop 0
	global_load_dwordx4 v[140:143], v[160:161], off offset:192
	v_or_b32_e32 v134, 32, v164
	v_cmp_lt_i32_e32 vcc, s38, v134
	s_waitcnt vmcnt(0)
	v_pk_fma_f32 v[132:133], v[132:133], v[142:143], v[138:139]
	v_pk_fma_f32 v[130:131], v[130:131], v[140:141], v[136:137]
	global_store_dwordx4 v[168:169], v[130:133], off offset:192
	s_and_saveexec_b64 s[0:1], vcc
	s_xor_b64 s[0:1], exec, s[0:1]
	v_add_u32_e32 v238, 0xffffe020, v164
	v_lshlrev_b64 v[130:131], 12, v[238:239]
	v_mov_b32_e32 v135, v239
	v_lshl_add_u64 v[130:131], s[2:3], 0, v[130:131]
	v_lshlrev_b64 v[132:133], 12, v[134:135]
	v_mov_b64_e32 v[136:137], v[162:163]
	s_andn2_saveexec_b64 s[0:1], s[0:1]
	v_ashrrev_i32_e32 v135, 31, v134
	v_lshlrev_b64 v[132:133], 12, v[134:135]
	v_lshl_add_u64 v[130:131], s[4:5], 0, v[132:133]
	v_mov_b64_e32 v[136:137], 0
	s_or_b64 exec, exec, s[0:1]
	v_lshl_add_u64 v[138:139], v[136:137], 2, s[8:9]
	v_lshl_add_u64 v[142:143], v[130:131], 0, v[166:167]
	v_lshl_add_u64 v[144:145], v[138:139], 0, v[166:167]
	global_load_dwordx4 v[134:137], v[142:143], off
	global_load_dwordx4 v[138:141], v[144:145], off
	v_lshl_add_u64 v[130:131], s[4:5], 0, v[132:133]
	v_lshl_add_u64 v[146:147], v[130:131], 0, v[166:167]
	s_waitcnt vmcnt(0)
	v_pk_fma_f32 v[128:129], v[128:129], v[140:141], v[136:137]
	v_pk_fma_f32 v[126:127], v[126:127], v[138:139], v[134:135]
	global_store_dwordx4 v[146:147], v[126:129], off
	global_load_dwordx4 v[126:129], v[142:143], off offset:64
	s_nop 0
	global_load_dwordx4 v[130:133], v[144:145], off offset:64
	s_waitcnt vmcnt(0)
	v_pk_fma_f32 v[124:125], v[124:125], v[132:133], v[128:129]
	v_pk_fma_f32 v[122:123], v[122:123], v[130:131], v[126:127]
	global_store_dwordx4 v[146:147], v[122:125], off offset:64
	global_load_dwordx4 v[122:125], v[142:143], off offset:128
	s_nop 0
	global_load_dwordx4 v[126:129], v[144:145], off offset:128
	s_waitcnt vmcnt(0)
	v_pk_fma_f32 v[120:121], v[120:121], v[128:129], v[124:125]
	v_pk_fma_f32 v[118:119], v[118:119], v[126:127], v[122:123]
	global_store_dwordx4 v[146:147], v[118:121], off offset:128
	global_load_dwordx4 v[120:123], v[142:143], off offset:192
	s_nop 0
	global_load_dwordx4 v[124:127], v[144:145], off offset:192
	v_or_b32_e32 v118, 48, v164
	v_cmp_lt_i32_e32 vcc, s38, v118
	s_waitcnt vmcnt(0)
	v_pk_fma_f32 v[116:117], v[116:117], v[126:127], v[122:123]
	v_pk_fma_f32 v[114:115], v[114:115], v[124:125], v[120:121]
	global_store_dwordx4 v[146:147], v[114:117], off offset:192
	s_and_saveexec_b64 s[0:1], vcc
	s_xor_b64 s[0:1], exec, s[0:1]
	v_add_u32_e32 v238, 0xffffe030, v164
	v_lshlrev_b64 v[114:115], 12, v[238:239]
	v_mov_b32_e32 v119, v239
	v_lshl_add_u64 v[114:115], s[2:3], 0, v[114:115]
	v_lshlrev_b64 v[116:117], 12, v[118:119]
	v_mov_b64_e32 v[120:121], v[162:163]
	s_andn2_saveexec_b64 s[0:1], s[0:1]
	v_ashrrev_i32_e32 v119, 31, v118
	v_lshlrev_b64 v[116:117], 12, v[118:119]
	v_lshl_add_u64 v[114:115], s[4:5], 0, v[116:117]
	v_mov_b64_e32 v[120:121], 0
	s_or_b64 exec, exec, s[0:1]
	v_lshl_add_u64 v[122:123], v[120:121], 2, s[8:9]
	v_lshl_add_u64 v[126:127], v[114:115], 0, v[166:167]
	v_lshl_add_u64 v[128:129], v[122:123], 0, v[166:167]
	global_load_dwordx4 v[118:121], v[126:127], off
	global_load_dwordx4 v[122:125], v[128:129], off
	v_lshl_add_u64 v[114:115], s[4:5], 0, v[116:117]
	v_lshl_add_u64 v[130:131], v[114:115], 0, v[166:167]
	s_waitcnt vmcnt(0)
	v_pk_fma_f32 v[112:113], v[112:113], v[124:125], v[120:121]
	v_pk_fma_f32 v[110:111], v[110:111], v[122:123], v[118:119]
	global_store_dwordx4 v[130:131], v[110:113], off
	global_load_dwordx4 v[110:113], v[126:127], off offset:64
	s_nop 0
	global_load_dwordx4 v[114:117], v[128:129], off offset:64
	s_waitcnt vmcnt(0)
	v_pk_fma_f32 v[108:109], v[108:109], v[116:117], v[112:113]
	v_pk_fma_f32 v[106:107], v[106:107], v[114:115], v[110:111]
	global_store_dwordx4 v[130:131], v[106:109], off offset:64
	global_load_dwordx4 v[106:109], v[126:127], off offset:128
	s_nop 0
	global_load_dwordx4 v[110:113], v[128:129], off offset:128
	s_waitcnt vmcnt(0)
	v_pk_fma_f32 v[104:105], v[104:105], v[112:113], v[108:109]
	v_pk_fma_f32 v[102:103], v[102:103], v[110:111], v[106:107]
	global_store_dwordx4 v[130:131], v[102:105], off offset:128
	global_load_dwordx4 v[104:107], v[126:127], off offset:192
	s_nop 0
	global_load_dwordx4 v[108:111], v[128:129], off offset:192
	v_or_b32_e32 v102, 64, v164
	v_cmp_lt_i32_e32 vcc, s38, v102
	s_waitcnt vmcnt(0)
	v_pk_fma_f32 v[84:85], v[84:85], v[110:111], v[106:107]
	v_pk_fma_f32 v[82:83], v[82:83], v[108:109], v[104:105]
	global_store_dwordx4 v[130:131], v[82:85], off offset:192
	s_and_saveexec_b64 s[0:1], vcc
	s_xor_b64 s[0:1], exec, s[0:1]
	v_add_u32_e32 v238, 0xffffe040, v164
	v_lshlrev_b64 v[82:83], 12, v[238:239]
	v_mov_b32_e32 v103, v239
	v_lshl_add_u64 v[82:83], s[2:3], 0, v[82:83]
	v_lshlrev_b64 v[84:85], 12, v[102:103]
	v_mov_b64_e32 v[104:105], v[162:163]
	s_andn2_saveexec_b64 s[0:1], s[0:1]
	v_ashrrev_i32_e32 v103, 31, v102
	v_lshlrev_b64 v[84:85], 12, v[102:103]
	v_lshl_add_u64 v[82:83], s[4:5], 0, v[84:85]
	v_mov_b64_e32 v[104:105], 0
	s_or_b64 exec, exec, s[0:1]
	v_lshl_add_u64 v[106:107], v[104:105], 2, s[8:9]
	v_lshl_add_u64 v[110:111], v[82:83], 0, v[166:167]
	v_lshl_add_u64 v[112:113], v[106:107], 0, v[166:167]
	global_load_dwordx4 v[102:105], v[110:111], off
	global_load_dwordx4 v[106:109], v[112:113], off
	v_lshl_add_u64 v[82:83], s[4:5], 0, v[84:85]
	v_lshl_add_u64 v[114:115], v[82:83], 0, v[166:167]
	s_waitcnt vmcnt(0)
	v_pk_fma_f32 v[84:85], v[100:101], v[108:109], v[104:105]
	v_pk_fma_f32 v[82:83], v[98:99], v[106:107], v[102:103]
	global_store_dwordx4 v[114:115], v[82:85], off
	global_load_dwordx4 v[82:85], v[110:111], off offset:64
	s_nop 0
	global_load_dwordx4 v[98:101], v[112:113], off offset:64
	s_waitcnt vmcnt(0)
	v_pk_fma_f32 v[84:85], v[96:97], v[100:101], v[84:85]
	v_pk_fma_f32 v[82:83], v[94:95], v[98:99], v[82:83]
	global_store_dwordx4 v[114:115], v[82:85], off offset:64
	global_load_dwordx4 v[82:85], v[110:111], off offset:128
	s_nop 0
	global_load_dwordx4 v[94:97], v[112:113], off offset:128
	s_waitcnt vmcnt(0)
	v_pk_fma_f32 v[84:85], v[92:93], v[96:97], v[84:85]
	v_pk_fma_f32 v[82:83], v[90:91], v[94:95], v[82:83]
	global_store_dwordx4 v[114:115], v[82:85], off offset:128
	global_load_dwordx4 v[90:93], v[110:111], off offset:192
	global_load_dwordx4 v[94:97], v[112:113], off offset:192
	v_or_b32_e32 v84, 0x50, v164
	v_cmp_lt_i32_e32 vcc, s38, v84
	s_waitcnt vmcnt(0)
	v_pk_fma_f32 v[88:89], v[88:89], v[96:97], v[92:93]
	v_pk_fma_f32 v[86:87], v[86:87], v[94:95], v[90:91]
	global_store_dwordx4 v[114:115], v[86:89], off offset:192
	s_and_saveexec_b64 s[0:1], vcc
	s_xor_b64 s[0:1], exec, s[0:1]
	v_add_u32_e32 v238, 0xffffe050, v164
	v_lshlrev_b64 v[82:83], 12, v[238:239]
	v_mov_b32_e32 v85, v239
	v_lshl_add_u64 v[82:83], s[2:3], 0, v[82:83]
	v_lshlrev_b64 v[86:87], 12, v[84:85]
	v_mov_b64_e32 v[88:89], v[162:163]
	s_andn2_saveexec_b64 s[0:1], s[0:1]
	v_ashrrev_i32_e32 v85, 31, v84
	v_lshlrev_b64 v[86:87], 12, v[84:85]
	v_lshl_add_u64 v[82:83], s[4:5], 0, v[86:87]
	v_mov_b64_e32 v[88:89], 0
	s_or_b64 exec, exec, s[0:1]
	v_lshl_add_u64 v[88:89], v[88:89], 2, s[8:9]
	v_lshl_add_u64 v[92:93], v[82:83], 0, v[166:167]
	v_lshl_add_u64 v[94:95], v[88:89], 0, v[166:167]
	global_load_dwordx4 v[82:85], v[92:93], off
	global_load_dwordx4 v[88:91], v[94:95], off
	v_lshl_add_u64 v[86:87], s[4:5], 0, v[86:87]
	v_lshl_add_u64 v[86:87], v[86:87], 0, v[166:167]
	s_waitcnt vmcnt(0)
	v_pk_fma_f32 v[80:81], v[80:81], v[90:91], v[84:85]
	v_pk_fma_f32 v[78:79], v[78:79], v[88:89], v[82:83]
	global_store_dwordx4 v[86:87], v[78:81], off
	global_load_dwordx4 v[78:81], v[92:93], off offset:64
	s_nop 0
	global_load_dwordx4 v[82:85], v[94:95], off offset:64
	s_waitcnt vmcnt(0)
	v_pk_fma_f32 v[76:77], v[76:77], v[84:85], v[80:81]
	v_pk_fma_f32 v[74:75], v[74:75], v[82:83], v[78:79]
	global_store_dwordx4 v[86:87], v[74:77], off offset:64
	global_load_dwordx4 v[74:77], v[92:93], off offset:128
	s_nop 0
	global_load_dwordx4 v[78:81], v[94:95], off offset:128
	s_waitcnt vmcnt(0)
	v_pk_fma_f32 v[72:73], v[72:73], v[80:81], v[76:77]
	v_pk_fma_f32 v[70:71], v[70:71], v[78:79], v[74:75]
	global_store_dwordx4 v[86:87], v[70:73], off offset:128
	global_load_dwordx4 v[72:75], v[92:93], off offset:192
	s_nop 0
	global_load_dwordx4 v[76:79], v[94:95], off offset:192
	v_or_b32_e32 v70, 0x60, v164
	v_cmp_lt_i32_e32 vcc, s38, v70
	s_waitcnt vmcnt(0)
	v_pk_fma_f32 v[68:69], v[68:69], v[78:79], v[74:75]
	v_pk_fma_f32 v[66:67], v[66:67], v[76:77], v[72:73]
	global_store_dwordx4 v[86:87], v[66:69], off offset:192
	s_and_saveexec_b64 s[0:1], vcc
	s_xor_b64 s[0:1], exec, s[0:1]
	v_add_u32_e32 v238, 0xffffe060, v164
	v_lshlrev_b64 v[66:67], 12, v[238:239]
	v_mov_b32_e32 v71, v239
	v_lshl_add_u64 v[66:67], s[2:3], 0, v[66:67]
	v_lshlrev_b64 v[68:69], 12, v[70:71]
	v_mov_b64_e32 v[72:73], v[162:163]
	s_andn2_saveexec_b64 s[0:1], s[0:1]
	v_ashrrev_i32_e32 v71, 31, v70
	v_lshlrev_b64 v[68:69], 12, v[70:71]
	v_lshl_add_u64 v[66:67], s[4:5], 0, v[68:69]
	v_mov_b64_e32 v[72:73], 0
	s_or_b64 exec, exec, s[0:1]
	v_lshl_add_u64 v[74:75], v[72:73], 2, s[8:9]
	v_lshl_add_u64 v[78:79], v[66:67], 0, v[166:167]
	v_lshl_add_u64 v[80:81], v[74:75], 0, v[166:167]
	global_load_dwordx4 v[70:73], v[78:79], off
	global_load_dwordx4 v[74:77], v[80:81], off
	v_lshl_add_u64 v[66:67], s[4:5], 0, v[68:69]
	v_lshl_add_u64 v[82:83], v[66:67], 0, v[166:167]
	s_waitcnt vmcnt(0)
	v_pk_fma_f32 v[64:65], v[64:65], v[76:77], v[72:73]
	v_pk_fma_f32 v[62:63], v[62:63], v[74:75], v[70:71]
	global_store_dwordx4 v[82:83], v[62:65], off
	global_load_dwordx4 v[62:65], v[78:79], off offset:64
	s_nop 0
	global_load_dwordx4 v[66:69], v[80:81], off offset:64
	s_waitcnt vmcnt(0)
	v_pk_fma_f32 v[60:61], v[60:61], v[68:69], v[64:65]
	v_pk_fma_f32 v[58:59], v[58:59], v[66:67], v[62:63]
	global_store_dwordx4 v[82:83], v[58:61], off offset:64
	global_load_dwordx4 v[58:61], v[78:79], off offset:128
	s_nop 0
	global_load_dwordx4 v[62:65], v[80:81], off offset:128
	s_waitcnt vmcnt(0)
	v_pk_fma_f32 v[56:57], v[56:57], v[64:65], v[60:61]
	v_pk_fma_f32 v[54:55], v[54:55], v[62:63], v[58:59]
	global_store_dwordx4 v[82:83], v[54:57], off offset:128
	global_load_dwordx4 v[56:59], v[78:79], off offset:192
	s_nop 0
	global_load_dwordx4 v[60:63], v[80:81], off offset:192
	v_or_b32_e32 v54, 0x70, v164
	v_cmp_lt_i32_e32 vcc, s38, v54
	s_waitcnt vmcnt(0)
	v_pk_fma_f32 v[52:53], v[52:53], v[62:63], v[58:59]
	v_pk_fma_f32 v[50:51], v[50:51], v[60:61], v[56:57]
	global_store_dwordx4 v[82:83], v[50:53], off offset:192
	s_and_saveexec_b64 s[0:1], vcc
	s_xor_b64 s[0:1], exec, s[0:1]
	v_add_u32_e32 v238, 0xffffe070, v164
	v_lshlrev_b64 v[50:51], 12, v[238:239]
	v_mov_b32_e32 v55, v239
	v_lshl_add_u64 v[50:51], s[2:3], 0, v[50:51]
	v_lshlrev_b64 v[52:53], 12, v[54:55]
	s_andn2_saveexec_b64 s[0:1], s[0:1]
	v_ashrrev_i32_e32 v55, 31, v54
	v_lshlrev_b64 v[52:53], 12, v[54:55]
	v_lshl_add_u64 v[50:51], s[4:5], 0, v[52:53]
	v_mov_b64_e32 v[162:163], 0
	s_or_b64 exec, exec, s[0:1]
	v_lshl_add_u64 v[58:59], v[162:163], 2, s[8:9]
	v_lshl_add_u64 v[62:63], v[50:51], 0, v[166:167]
	v_lshl_add_u64 v[64:65], v[58:59], 0, v[166:167]
	global_load_dwordx4 v[54:57], v[62:63], off
	global_load_dwordx4 v[58:61], v[64:65], off
	v_lshl_add_u64 v[50:51], s[4:5], 0, v[52:53]
	v_lshl_add_u64 v[66:67], v[50:51], 0, v[166:167]
	s_add_i32 s39, s39, s11
	s_cmp_gt_i32 s39, 31
	s_waitcnt vmcnt(0)
	v_pk_fma_f32 v[48:49], v[48:49], v[60:61], v[56:57]
	v_pk_fma_f32 v[46:47], v[46:47], v[58:59], v[54:55]
	global_store_dwordx4 v[66:67], v[46:49], off
	global_load_dwordx4 v[46:49], v[62:63], off offset:64
	s_nop 0
	global_load_dwordx4 v[50:53], v[64:65], off offset:64
	s_waitcnt vmcnt(0)
	v_pk_fma_f32 v[44:45], v[44:45], v[52:53], v[48:49]
	v_pk_fma_f32 v[42:43], v[42:43], v[50:51], v[46:47]
	global_store_dwordx4 v[66:67], v[42:45], off offset:64
	global_load_dwordx4 v[42:45], v[62:63], off offset:128
	s_nop 0
	global_load_dwordx4 v[46:49], v[64:65], off offset:128
	s_waitcnt vmcnt(0)
	v_pk_fma_f32 v[40:41], v[40:41], v[48:49], v[44:45]
	v_pk_fma_f32 v[38:39], v[38:39], v[46:47], v[42:43]
	global_store_dwordx4 v[66:67], v[38:41], off offset:128
	global_load_dwordx4 v[38:41], v[62:63], off offset:192
	s_nop 0
	global_load_dwordx4 v[42:45], v[64:65], off offset:192
	s_waitcnt vmcnt(0)
	v_pk_fma_f32 v[40:41], v[36:37], v[44:45], v[40:41]
	v_pk_fma_f32 v[38:39], v[34:35], v[42:43], v[38:39]
	v_mov_b32_e32 v37, 0
	global_store_dwordx4 v[66:67], v[38:41], off offset:192
	s_cbranch_scc1 .LBB0_2543
	s_ashr_i32 s1, s39, 31
	s_lshr_b32 s1, s1, 27
	s_add_i32 s1, s39, s1
	s_ashr_i32 s1, s1, 5
	s_mov_b32 s0, s10
	s_lshl_b32 s12, s1, 6
	s_lshl_b32 s13, s39, 1
	s_sub_i32 s12, s13, s12
	s_and_b32 s0, s0, 7
	s_and_b32 s12, s12, -8
	s_lshl_b32 s1, s1, 2
	s_and_b32 s13, s39, 3
	s_or_b32 s25, s1, s13
	s_or_b32 s27, s0, s12
	s_branch .LBB0_2543

	.amdhsa_kernel _Z10mk_forward6Paramsii
		.amdhsa_group_segment_fixed_size 135168
		.amdhsa_private_segment_fixed_size 0
		.amdhsa_kernarg_size 480
		.amdhsa_user_sgpr_count 2
		.amdhsa_user_sgpr_dispatch_ptr 0
		.amdhsa_user_sgpr_queue_ptr 0
		.amdhsa_user_sgpr_kernarg_segment_ptr 1
		.amdhsa_user_sgpr_dispatch_id 0
		.amdhsa_user_sgpr_kernarg_preload_length 0
		.amdhsa_user_sgpr_kernarg_preload_offset 0
		.amdhsa_user_sgpr_private_segment_size 0
		.amdhsa_uses_dynamic_stack 0
		.amdhsa_enable_private_segment 0
		.amdhsa_system_sgpr_workgroup_id_x 1
		.amdhsa_system_sgpr_workgroup_id_y 0
		.amdhsa_system_sgpr_workgroup_id_z 0
		.amdhsa_system_sgpr_workgroup_info 0
		.amdhsa_system_vgpr_workitem_id 0
		.amdhsa_next_free_vgpr 256
		.amdhsa_next_free_sgpr 100
		.amdhsa_accum_offset 256
		.amdhsa_reserve_vcc 1
		.amdhsa_float_round_mode_32 0
		.amdhsa_float_round_mode_16_64 0
		.amdhsa_float_denorm_mode_32 3
		.amdhsa_float_denorm_mode_16_64 3
		.amdhsa_dx10_clamp 1
		.amdhsa_ieee_mode 1
		.amdhsa_fp16_overflow 0
		.amdhsa_tg_split 0
		.amdhsa_exception_fp_ieee_invalid_op 0
		.amdhsa_exception_fp_denorm_src 0
		.amdhsa_exception_fp_ieee_div_zero 0
		.amdhsa_exception_fp_ieee_overflow 0
		.amdhsa_exception_fp_ieee_underflow 0
		.amdhsa_exception_fp_ieee_inexact 0
		.amdhsa_exception_int_div_zero 0
	.end_amdhsa_kernel

amdhsa.kernels:
  - .agpr_count:     0
    .args:
      - .offset:         0
        .size:           216
        .value_kind:     by_value
      - .offset:         216
        .size:           4
        .value_kind:     by_value
      - .offset:         220
        .size:           4
        .value_kind:     by_value
      - .offset:         224
        .size:           4
        .value_kind:     hidden_block_count_x
      - .offset:         228
        .size:           4
        .value_kind:     hidden_block_count_y
      - .offset:         232
        .size:           4
        .value_kind:     hidden_block_count_z
      - .offset:         236
        .size:           2
        .value_kind:     hidden_group_size_x
      - .offset:         238
        .size:           2
        .value_kind:     hidden_group_size_y
      - .offset:         240
        .size:           2
        .value_kind:     hidden_group_size_z
      - .offset:         242
        .size:           2
        .value_kind:     hidden_remainder_x
      - .offset:         244
        .size:           2
        .value_kind:     hidden_remainder_y
      - .offset:         246
        .size:           2
        .value_kind:     hidden_remainder_z
      - .offset:         264
        .size:           8
        .value_kind:     hidden_global_offset_x
      - .offset:         272
        .size:           8
        .value_kind:     hidden_global_offset_y
      - .offset:         280
        .size:           8
        .value_kind:     hidden_global_offset_z
      - .offset:         288
        .size:           2
        .value_kind:     hidden_grid_dims
    .group_segment_fixed_size: 135168
    .kernarg_segment_align: 8
    .kernarg_segment_size: 480
    .language:       OpenCL C
    .language_version:
      - 2
      - 0
    .max_flat_workgroup_size: 512
    .name:           _Z10mk_forward6Paramsii
    .private_segment_fixed_size: 0
    .sgpr_count:     106
    .sgpr_spill_count: 0
    .symbol:         _Z10mk_forward6Paramsii.kd
    .uniform_work_group_size: 1
    .uses_dynamic_stack: false
    .vgpr_count:     256
    .vgpr_spill_count: 0
    .wavefront_size: 64
